# stack8 + first K-tile of every in-place GEMM K-loop peeled with C=0 on the first MFMA per accumulator quad: no accumulator zeroing at all (12 instances; 2 keep the stack9 peel)
# speedup vs baseline: 1.0126x; 1.0126x over previous
; #define PG8_STAGE(bufoff, gbase, voff) do { _Pragma("unroll") for (int _i = 0; _i < 2; ++_i) \
;         __builtin_amdgcn_global_load_lds((const unsigned*)((const char*)(gbase) + (voff)[_i]), (PG8_LAS unsigned*)(lds + (bufoff) + ldsw + _i * 8192), 16, 0, 0); } while (0)
; #define PG8_LDA(dst, b, h) do { _Pragma("unroll") for (int m = 0; m < 4; ++m) _Pragma("unroll") for (int k = 0; k < 2; ++k) dst[m][k] = *(const PG8_LAS bf16x8*)(lds + PG8_SA(b, h) + aoff + m * 2048 + k * 1024); } while (0)
; #define PG8_LDB(dst, b, h) do { _Pragma("unroll") for (int n = 0; n < 2; ++n) _Pragma("unroll") for (int k = 0; k < 2; ++k) dst[n][k] = *(const PG8_LAS bf16x8*)(lds + PG8_SB(b, h) + boff + n * 2048 + k * 1024); } while (0)
; #define PG8_WAIT_V(n) asm volatile("s_waitcnt vmcnt(" #n ")" ::: "memory")
; #define PG8_WAIT_L(n) asm volatile("s_waitcnt lgkmcnt(" #n ")" ::: "memory")
; #define PG8_BAR __builtin_amdgcn_s_barrier()
; template <class Epi, class Sched, bool ALIGN_EPI = false, bool SP2 = false, bool ABLK = false, bool BBLK = false>
; __device__ __forceinline__ void gemm_phase(PG8_LAS unsigned char* lds, const Gemm g, const Sched& S, const Epi& E) {
;     ...
;     for (;;) {
;         const bool has_next = S.next(ui + 1, nxt);
;         const char* nA = has_next ? (const char*)g.A + (size_t)nxt.pm * tstepA : cA; const char* nB = has_next ? (const char*)g.Bt + (size_t)nxt.pn * tstepB : cB;
;         for (int t = 0; t < nt; t += 2) {
;             const bool last = (t == nt - 2);
;             const char* a1 = cA + (size_t)(t + 1) * kstepA;
;             const char* a2 = last ? nA : cA + (size_t)(t + 2) * kstepA; const char* b2 = last ? nB : cB + (size_t)(t + 2) * kstepB;
;             const char* a3 = a2 + kstepA; const char* b3 = b2 + kstepB;
;             if (last && has_next) S.a_ready(nxt);
;             if constexpr (SP2) {
;             PG8_LDB(B0, 0, 0); PG8_LDB(B1, 0, 1); PG8_SCHED; PG8_LDA(At, 0, 0); PG8_STAGE(PG8_SA(1, 1), a1 + hstepA, voffA);
;             PG8_WAIT_V(8); PG8_WAIT_L(0); PG8_BAR; PG8_MMA(0, 0, At, B0); PG8_MMA(0, 1, At, B1); PG8_BAR; PG8_SCHED;
;             PG8_LDA(At, 0, 1); PG8_STAGE(PG8_SB(0, 0), b2, voffB); PG8_STAGE(PG8_SB(0, 1), b2 + hstepB, voffB); PG8_STAGE(PG8_SA(0, 0), a2, voffA);
;             PG8_WAIT_V(8); PG8_WAIT_L(0); PG8_BAR; PG8_MMA(1, 0, At, B0); PG8_MMA(1, 1, At, B1); PG8_BAR; PG8_SCHED;
.LBB0_215:
	s_ashr_i32 s15, s14, 31
	s_lshl_b64 s[18:19], s[14:15], 20
	s_add_u32 s18, s35, s18
	s_addc_u32 s19, s36, s19
	s_and_b64 s[20:21], s[4:5], exec
	s_cselect_b32 s15, s19, s23
	s_cselect_b32 s65, s18, s22
	s_ashr_i32 s13, s12, 31
	s_lshl_b64 s[20:21], s[12:13], 20
	s_add_u32 s20, s37, s20
	s_addc_u32 s21, s40, s21
	s_and_b64 s[26:27], s[4:5], exec
	s_cselect_b32 s13, s21, s25
	s_cselect_b32 s68, s20, s24
	s_add_u32 s22, s22, 0xc000
	s_addc_u32 s23, s23, 0
	s_add_u32 s72, s24, 0x10000
	v_mov_b32_e32 v2, 0
	s_addc_u32 s73, s25, 0
	s_mov_b32 s81, -2
	s_add_u32 s24, s22, 0x4000
	s_addc_u32 s25, s23, 0
	s_cmp_eq_u32 s81, 28
	s_cselect_b32 s28, s65, s24
	s_cselect_b32 s29, s15, s25
	s_cselect_b32 s26, s68, s72
	s_cselect_b32 s27, s13, s73
	s_add_u32 s24, s28, 0x8000
	s_addc_u32 s25, s29, 0
	s_add_i32 s75, 0, 0x10000
	v_add_u32_e32 v142, s75, v145
	s_add_i32 s80, 0, 0x14000
	ds_read_b128 v[148:151], v142
	ds_read_b128 v[152:155], v142 offset:1024
	ds_read_b128 v[156:159], v142 offset:2048
	ds_read_b128 v[160:163], v142 offset:3072
	v_add_u32_e32 v142, s80, v145
	ds_read_b128 v[164:167], v142
	ds_read_b128 v[168:171], v142 offset:1024
	ds_read_b128 v[172:175], v142 offset:2048
	ds_read_b128 v[176:179], v142 offset:3072
	v_lshl_add_u64 v[142:143], s[22:23], 0, v[138:139]
	s_add_i32 m0, s43, 0xc000
	ds_read_b128 v[180:183], v146
	ds_read_b128 v[196:199], v146 offset:1024
	ds_read_b128 v[200:203], v146 offset:2048
	ds_read_b128 v[204:207], v146 offset:3072
	ds_read_b128 v[208:211], v146 offset:4096
	ds_read_b128 v[212:215], v146 offset:5120
	ds_read_b128 v[216:219], v146 offset:6144
	ds_read_b128 v[220:223], v146 offset:7168
	global_load_lds_dwordx4 v[142:143], off
	v_lshl_add_u64 v[142:143], s[22:23], 0, v[140:141]
	s_add_i32 m0, s43, 0xe000
	s_nop 0
	global_load_lds_dwordx4 v[142:143], off
	s_waitcnt vmcnt(8)
	s_waitcnt lgkmcnt(0)
	s_barrier
	s_setprio 1
	s_waitcnt lgkmcnt(0)
	v_mfma_f32_16x16x32_bf16 v[126:129], v[148:151], v[180:183], 0
	v_mfma_f32_16x16x32_bf16 v[118:121], v[156:159], v[180:183], 0
	v_mfma_f32_16x16x32_bf16 v[110:113], v[148:151], v[200:203], 0
	v_mfma_f32_16x16x32_bf16 v[102:105], v[156:159], v[200:203], 0
	v_mfma_f32_16x16x32_bf16 v[94:97], v[148:151], v[208:211], 0
	v_mfma_f32_16x16x32_bf16 v[86:89], v[156:159], v[208:211], 0
	v_mfma_f32_16x16x32_bf16 v[78:81], v[148:151], v[216:219], 0
	v_mfma_f32_16x16x32_bf16 v[70:73], v[156:159], v[216:219], 0
	v_mfma_f32_16x16x32_bf16 v[126:129], v[152:155], v[196:199], v[126:129]
	v_mfma_f32_16x16x32_bf16 v[118:121], v[160:163], v[196:199], v[118:121]
	v_mfma_f32_16x16x32_bf16 v[110:113], v[152:155], v[204:207], v[110:113]
	v_mfma_f32_16x16x32_bf16 v[102:105], v[160:163], v[204:207], v[102:105]
	v_mfma_f32_16x16x32_bf16 v[94:97], v[152:155], v[212:215], v[94:97]
	v_mfma_f32_16x16x32_bf16 v[86:89], v[160:163], v[212:215], v[86:89]
	v_mfma_f32_16x16x32_bf16 v[78:81], v[152:155], v[220:223], v[78:81]
	v_mfma_f32_16x16x32_bf16 v[70:73], v[160:163], v[220:223], v[70:73]
	s_setprio 0
	s_setprio 1
	v_mfma_f32_16x16x32_bf16 v[122:125], v[164:167], v[180:183], 0
	v_mfma_f32_16x16x32_bf16 v[114:117], v[172:175], v[180:183], 0
	v_mfma_f32_16x16x32_bf16 v[106:109], v[164:167], v[200:203], 0
	v_mfma_f32_16x16x32_bf16 v[98:101], v[172:175], v[200:203], 0
	v_mfma_f32_16x16x32_bf16 v[90:93], v[164:167], v[208:211], 0
	v_mfma_f32_16x16x32_bf16 v[82:85], v[172:175], v[208:211], 0
	v_mfma_f32_16x16x32_bf16 v[74:77], v[164:167], v[216:219], 0
	v_mfma_f32_16x16x32_bf16 v[66:69], v[172:175], v[216:219], 0
	v_mfma_f32_16x16x32_bf16 v[122:125], v[168:171], v[196:199], v[122:125]
	v_mfma_f32_16x16x32_bf16 v[114:117], v[176:179], v[196:199], v[114:117]
	v_mfma_f32_16x16x32_bf16 v[106:109], v[168:171], v[204:207], v[106:109]
	v_mfma_f32_16x16x32_bf16 v[98:101], v[176:179], v[204:207], v[98:101]
	v_mfma_f32_16x16x32_bf16 v[90:93], v[168:171], v[212:215], v[90:93]
	v_mfma_f32_16x16x32_bf16 v[82:85], v[176:179], v[212:215], v[82:85]
	v_mfma_f32_16x16x32_bf16 v[74:77], v[168:171], v[220:223], v[74:77]
	v_mfma_f32_16x16x32_bf16 v[66:69], v[176:179], v[220:223], v[66:69]
	s_setprio 0
	s_barrier
	s_add_i32 s75, s75, s41
	v_lshl_add_u64 v[142:143], s[26:27], 0, v[134:135]
	s_mov_b32 m0, s75
	ds_read_b128 v[180:183], v146 offset:16384
	ds_read_b128 v[196:199], v146 offset:17408
	ds_read_b128 v[200:203], v146 offset:18432
	ds_read_b128 v[204:207], v146 offset:19456
	ds_read_b128 v[208:211], v146 offset:20480
	ds_read_b128 v[212:215], v146 offset:21504
	ds_read_b128 v[216:219], v146 offset:22528
	ds_read_b128 v[220:223], v146 offset:23552
	global_load_lds_dwordx4 v[142:143], off
	s_add_i32 m0, s75, 0x2000
	s_add_u32 s82, s26, 0x4000
	v_lshl_add_u64 v[142:143], s[26:27], 0, v[130:131]
	s_addc_u32 s83, s27, 0
	s_add_i32 s75, s80, s41
	global_load_lds_dwordx4 v[142:143], off
	v_lshl_add_u64 v[142:143], s[82:83], 0, v[134:135]
	s_mov_b32 m0, s75
	s_nop 0
	global_load_lds_dwordx4 v[142:143], off
	v_lshl_add_u64 v[142:143], s[82:83], 0, v[130:131]
	s_add_i32 m0, s75, 0x2000
	s_nop 0
	global_load_lds_dwordx4 v[142:143], off
	v_lshl_add_u64 v[142:143], s[28:29], 0, v[136:137]
	s_mov_b32 m0, s43
	s_nop 0
	global_load_lds_dwordx4 v[142:143], off
	v_lshl_add_u64 v[142:143], s[28:29], 0, v[132:133]
	s_mov_b32 m0, s44
	s_nop 0
	global_load_lds_dwordx4 v[142:143], off
	s_waitcnt vmcnt(8)
	s_waitcnt lgkmcnt(0)
	s_barrier
; #define PG8_STAGE(bufoff, gbase, voff) do { _Pragma("unroll") for (int _i = 0; _i < 2; ++_i) \
;         __builtin_amdgcn_global_load_lds((const unsigned*)((const char*)(gbase) + (voff)[_i]), (PG8_LAS unsigned*)(lds + (bufoff) + ldsw + _i * 8192), 16, 0, 0); } while (0)
; #define PG8_LDA(dst, b, h) do { _Pragma("unroll") for (int m = 0; m < 4; ++m) _Pragma("unroll") for (int k = 0; k < 2; ++k) dst[m][k] = *(const PG8_LAS bf16x8*)(lds + PG8_SA(b, h) + aoff + m * 2048 + k * 1024); } while (0)
; #define PG8_LDB(dst, b, h) do { _Pragma("unroll") for (int n = 0; n < 2; ++n) _Pragma("unroll") for (int k = 0; k < 2; ++k) dst[n][k] = *(const PG8_LAS bf16x8*)(lds + PG8_SB(b, h) + boff + n * 2048 + k * 1024); } while (0)
; #define PG8_MMA(ai, bj, At, Bt) do { __builtin_amdgcn_s_setprio(1); _Pragma("unroll") for (int m = 0; m < 4; ++m) _Pragma("unroll") for (int n = 0; n < 2; ++n) _Pragma("unroll") for (int k = 0; k < 2; ++k) \
;         acc[ai][bj][m][n] = __builtin_amdgcn_mfma_f32_16x16x32_bf16(Bt[n][k], At[m][k], acc[ai][bj][m][n], 0, 0, 0); __builtin_amdgcn_s_setprio(0); } while (0)
; #define PG8_WAIT_V(n) asm volatile("s_waitcnt vmcnt(" #n ")" ::: "memory")
; template <class Epi, class Sched, bool ALIGN_EPI = false, bool SP2 = false, bool ABLK = false, bool BBLK = false>
; __device__ __forceinline__ void gemm_phase(PG8_LAS unsigned char* lds, const Gemm g, const Sched& S, const Epi& E) {
;     ...
;         for (int t = 0; t < nt; t += 2) {
;             const bool last = (t == nt - 2);
;             const char* a1 = cA + (size_t)(t + 1) * kstepA;
;             const char* a2 = last ? nA : cA + (size_t)(t + 2) * kstepA; const char* b2 = last ? nB : cB + (size_t)(t + 2) * kstepB;
;             const char* a3 = a2 + kstepA; const char* b3 = b2 + kstepB;
;             if (last && has_next) S.a_ready(nxt);
;             if constexpr (SP2) {
;             PG8_LDB(B0, 0, 0); PG8_LDB(B1, 0, 1); PG8_SCHED; PG8_LDA(At, 0, 0); PG8_STAGE(PG8_SA(1, 1), a1 + hstepA, voffA);
;             PG8_WAIT_V(8); PG8_WAIT_L(0); PG8_BAR; PG8_MMA(0, 0, At, B0); PG8_MMA(0, 1, At, B1); PG8_BAR; PG8_SCHED;
;             PG8_LDA(At, 0, 1); PG8_STAGE(PG8_SB(0, 0), b2, voffB); PG8_STAGE(PG8_SB(0, 1), b2 + hstepB, voffB); PG8_STAGE(PG8_SA(0, 0), a2, voffA);
;             PG8_WAIT_V(8); PG8_WAIT_L(0); PG8_BAR; PG8_MMA(1, 0, At, B0); PG8_MMA(1, 1, At, B1); PG8_BAR; PG8_SCHED;
	s_setprio 1
	s_waitcnt lgkmcnt(0)
	v_mfma_f32_16x16x32_bf16 v[62:65], v[148:151], v[180:183], 0
	v_mfma_f32_16x16x32_bf16 v[54:57], v[156:159], v[180:183], 0
	v_mfma_f32_16x16x32_bf16 v[46:49], v[148:151], v[200:203], 0
	v_mfma_f32_16x16x32_bf16 v[38:41], v[156:159], v[200:203], 0
	v_mfma_f32_16x16x32_bf16 v[30:33], v[148:151], v[208:211], 0
	v_mfma_f32_16x16x32_bf16 v[22:25], v[156:159], v[208:211], 0
	v_mfma_f32_16x16x32_bf16 v[14:17], v[148:151], v[216:219], 0
	v_mfma_f32_16x16x32_bf16 v[6:9], v[156:159], v[216:219], 0
	v_mfma_f32_16x16x32_bf16 v[62:65], v[152:155], v[196:199], v[62:65]
	v_mfma_f32_16x16x32_bf16 v[54:57], v[160:163], v[196:199], v[54:57]
	v_mfma_f32_16x16x32_bf16 v[46:49], v[152:155], v[204:207], v[46:49]
	v_mfma_f32_16x16x32_bf16 v[38:41], v[160:163], v[204:207], v[38:41]
	v_mfma_f32_16x16x32_bf16 v[30:33], v[152:155], v[212:215], v[30:33]
	v_mfma_f32_16x16x32_bf16 v[22:25], v[160:163], v[212:215], v[22:25]
	v_mfma_f32_16x16x32_bf16 v[14:17], v[152:155], v[220:223], v[14:17]
	v_mfma_f32_16x16x32_bf16 v[6:9], v[160:163], v[220:223], v[6:9]
	s_setprio 0
	s_setprio 1
	v_mfma_f32_16x16x32_bf16 v[58:61], v[164:167], v[180:183], 0
	v_mfma_f32_16x16x32_bf16 v[50:53], v[172:175], v[180:183], 0
	v_mfma_f32_16x16x32_bf16 v[42:45], v[164:167], v[200:203], 0
	v_mfma_f32_16x16x32_bf16 v[34:37], v[172:175], v[200:203], 0
	v_mfma_f32_16x16x32_bf16 v[26:29], v[164:167], v[208:211], 0
	v_mfma_f32_16x16x32_bf16 v[18:21], v[172:175], v[208:211], 0
	v_mfma_f32_16x16x32_bf16 v[10:13], v[164:167], v[216:219], 0
	v_mfma_f32_16x16x32_bf16 v[2:5], v[172:175], v[216:219], 0
	v_mfma_f32_16x16x32_bf16 v[58:61], v[168:171], v[196:199], v[58:61]
	v_mfma_f32_16x16x32_bf16 v[50:53], v[176:179], v[196:199], v[50:53]
	v_mfma_f32_16x16x32_bf16 v[42:45], v[168:171], v[204:207], v[42:45]
	v_mfma_f32_16x16x32_bf16 v[34:37], v[176:179], v[204:207], v[34:37]
	v_mfma_f32_16x16x32_bf16 v[26:29], v[168:171], v[212:215], v[26:29]
	v_mfma_f32_16x16x32_bf16 v[18:21], v[176:179], v[212:215], v[18:21]
	v_mfma_f32_16x16x32_bf16 v[10:13], v[168:171], v[220:223], v[10:13]
	v_mfma_f32_16x16x32_bf16 v[2:5], v[176:179], v[220:223], v[2:5]
	s_setprio 0
	s_barrier
	s_branch .Lmid_216
.LBB0_216:
	s_add_u32 s24, s22, 0x4000
	s_addc_u32 s25, s23, 0
	s_cmp_eq_u32 s81, 28
	s_cselect_b32 s28, s65, s24
	s_cselect_b32 s29, s15, s25
	s_cselect_b32 s26, s68, s72
	s_cselect_b32 s27, s13, s73
	s_add_u32 s24, s28, 0x8000
	s_addc_u32 s25, s29, 0
	s_add_i32 s75, 0, 0x10000
	v_add_u32_e32 v142, s75, v145
	s_add_i32 s80, 0, 0x14000
	ds_read_b128 v[148:151], v142
	ds_read_b128 v[152:155], v142 offset:1024
	ds_read_b128 v[156:159], v142 offset:2048
	ds_read_b128 v[160:163], v142 offset:3072
	v_add_u32_e32 v142, s80, v145
	ds_read_b128 v[164:167], v142
	ds_read_b128 v[168:171], v142 offset:1024
	ds_read_b128 v[172:175], v142 offset:2048
	ds_read_b128 v[176:179], v142 offset:3072
	v_lshl_add_u64 v[142:143], s[22:23], 0, v[138:139]
	s_add_i32 m0, s43, 0xc000
	ds_read_b128 v[180:183], v146
	ds_read_b128 v[196:199], v146 offset:1024
	ds_read_b128 v[200:203], v146 offset:2048
	ds_read_b128 v[204:207], v146 offset:3072
	ds_read_b128 v[208:211], v146 offset:4096
	ds_read_b128 v[212:215], v146 offset:5120
	ds_read_b128 v[216:219], v146 offset:6144
	ds_read_b128 v[220:223], v146 offset:7168
	global_load_lds_dwordx4 v[142:143], off
	v_lshl_add_u64 v[142:143], s[22:23], 0, v[140:141]
	s_add_i32 m0, s43, 0xe000
	s_nop 0
	global_load_lds_dwordx4 v[142:143], off
	s_waitcnt vmcnt(8)
	s_waitcnt lgkmcnt(0)
	s_barrier
	s_setprio 1
	s_waitcnt lgkmcnt(0)
	v_mfma_f32_16x16x32_bf16 v[126:129], v[148:151], v[180:183], v[126:129]
	v_mfma_f32_16x16x32_bf16 v[118:121], v[156:159], v[180:183], v[118:121]
	v_mfma_f32_16x16x32_bf16 v[110:113], v[148:151], v[200:203], v[110:113]
	v_mfma_f32_16x16x32_bf16 v[102:105], v[156:159], v[200:203], v[102:105]
	v_mfma_f32_16x16x32_bf16 v[94:97], v[148:151], v[208:211], v[94:97]
	v_mfma_f32_16x16x32_bf16 v[86:89], v[156:159], v[208:211], v[86:89]
	v_mfma_f32_16x16x32_bf16 v[78:81], v[148:151], v[216:219], v[78:81]
	v_mfma_f32_16x16x32_bf16 v[70:73], v[156:159], v[216:219], v[70:73]
	v_mfma_f32_16x16x32_bf16 v[126:129], v[152:155], v[196:199], v[126:129]
	v_mfma_f32_16x16x32_bf16 v[118:121], v[160:163], v[196:199], v[118:121]
	v_mfma_f32_16x16x32_bf16 v[110:113], v[152:155], v[204:207], v[110:113]
	v_mfma_f32_16x16x32_bf16 v[102:105], v[160:163], v[204:207], v[102:105]
	v_mfma_f32_16x16x32_bf16 v[94:97], v[152:155], v[212:215], v[94:97]
	v_mfma_f32_16x16x32_bf16 v[86:89], v[160:163], v[212:215], v[86:89]
	v_mfma_f32_16x16x32_bf16 v[78:81], v[152:155], v[220:223], v[78:81]
	v_mfma_f32_16x16x32_bf16 v[70:73], v[160:163], v[220:223], v[70:73]
	s_setprio 0
	s_setprio 1
	v_mfma_f32_16x16x32_bf16 v[122:125], v[164:167], v[180:183], v[122:125]
	v_mfma_f32_16x16x32_bf16 v[114:117], v[172:175], v[180:183], v[114:117]
	v_mfma_f32_16x16x32_bf16 v[106:109], v[164:167], v[200:203], v[106:109]
	v_mfma_f32_16x16x32_bf16 v[98:101], v[172:175], v[200:203], v[98:101]
	v_mfma_f32_16x16x32_bf16 v[90:93], v[164:167], v[208:211], v[90:93]
	v_mfma_f32_16x16x32_bf16 v[82:85], v[172:175], v[208:211], v[82:85]
	v_mfma_f32_16x16x32_bf16 v[74:77], v[164:167], v[216:219], v[74:77]
	v_mfma_f32_16x16x32_bf16 v[66:69], v[172:175], v[216:219], v[66:69]
	v_mfma_f32_16x16x32_bf16 v[122:125], v[168:171], v[196:199], v[122:125]
	v_mfma_f32_16x16x32_bf16 v[114:117], v[176:179], v[196:199], v[114:117]
	v_mfma_f32_16x16x32_bf16 v[106:109], v[168:171], v[204:207], v[106:109]
	v_mfma_f32_16x16x32_bf16 v[98:101], v[176:179], v[204:207], v[98:101]
	v_mfma_f32_16x16x32_bf16 v[90:93], v[168:171], v[212:215], v[90:93]
	v_mfma_f32_16x16x32_bf16 v[82:85], v[176:179], v[212:215], v[82:85]
	v_mfma_f32_16x16x32_bf16 v[74:77], v[168:171], v[220:223], v[74:77]
	v_mfma_f32_16x16x32_bf16 v[66:69], v[176:179], v[220:223], v[66:69]
	s_setprio 0
	s_barrier
; #define PG8_STAGE(bufoff, gbase, voff) do { _Pragma("unroll") for (int _i = 0; _i < 2; ++_i) \
;         __builtin_amdgcn_global_load_lds((const unsigned*)((const char*)(gbase) + (voff)[_i]), (PG8_LAS unsigned*)(lds + (bufoff) + ldsw + _i * 8192), 16, 0, 0); } while (0)
; #define PG8_LDA(dst, b, h) do { _Pragma("unroll") for (int m = 0; m < 4; ++m) _Pragma("unroll") for (int k = 0; k < 2; ++k) dst[m][k] = *(const PG8_LAS bf16x8*)(lds + PG8_SA(b, h) + aoff + m * 2048 + k * 1024); } while (0)
; #define PG8_LDB(dst, b, h) do { _Pragma("unroll") for (int n = 0; n < 2; ++n) _Pragma("unroll") for (int k = 0; k < 2; ++k) dst[n][k] = *(const PG8_LAS bf16x8*)(lds + PG8_SB(b, h) + boff + n * 2048 + k * 1024); } while (0)
; #define PG8_MMA(ai, bj, At, Bt) do { __builtin_amdgcn_s_setprio(1); _Pragma("unroll") for (int m = 0; m < 4; ++m) _Pragma("unroll") for (int n = 0; n < 2; ++n) _Pragma("unroll") for (int k = 0; k < 2; ++k) \
;         acc[ai][bj][m][n] = __builtin_amdgcn_mfma_f32_16x16x32_bf16(Bt[n][k], At[m][k], acc[ai][bj][m][n], 0, 0, 0); __builtin_amdgcn_s_setprio(0); } while (0)
; #define PG8_WAIT_V(n) asm volatile("s_waitcnt vmcnt(" #n ")" ::: "memory")
; #define PG8_WAIT_L(n) asm volatile("s_waitcnt lgkmcnt(" #n ")" ::: "memory")
; #define PG8_BAR __builtin_amdgcn_s_barrier()
; #define PG8_SCHED __builtin_amdgcn_sched_barrier(0)
; template <class Epi, class Sched, bool ALIGN_EPI = false, bool SP2 = false, bool ABLK = false, bool BBLK = false>
; __device__ __forceinline__ void gemm_phase(PG8_LAS unsigned char* lds, const Gemm g, const Sched& S, const Epi& E) {
;     ...
;             PG8_LDA(At, 0, 1); PG8_STAGE(PG8_SB(0, 0), b2, voffB); PG8_STAGE(PG8_SB(0, 1), b2 + hstepB, voffB); PG8_STAGE(PG8_SA(0, 0), a2, voffA);
;             PG8_WAIT_V(8); PG8_WAIT_L(0); PG8_BAR; PG8_MMA(1, 0, At, B0); PG8_MMA(1, 1, At, B1); PG8_BAR; PG8_SCHED;
;             PG8_LDB(B0, 1, 0); PG8_LDB(B1, 1, 1); PG8_SCHED; PG8_LDA(At, 1, 0); PG8_STAGE(PG8_SA(0, 1), a2 + hstepA, voffA);
;             PG8_WAIT_V(8); PG8_WAIT_L(0); PG8_BAR; PG8_MMA(0, 0, At, B0); PG8_MMA(0, 1, At, B1); PG8_BAR; PG8_SCHED;
;             PG8_LDA(At, 1, 1); PG8_STAGE(PG8_SB(1, 0), b3, voffB); PG8_STAGE(PG8_SB(1, 1), b3 + hstepB, voffB); PG8_STAGE(PG8_SA(1, 0), a3, voffA);
	s_add_i32 s75, s75, s41
	v_lshl_add_u64 v[142:143], s[26:27], 0, v[134:135]
	s_mov_b32 m0, s75
	ds_read_b128 v[180:183], v146 offset:16384
	ds_read_b128 v[196:199], v146 offset:17408
	ds_read_b128 v[200:203], v146 offset:18432
	ds_read_b128 v[204:207], v146 offset:19456
	ds_read_b128 v[208:211], v146 offset:20480
	ds_read_b128 v[212:215], v146 offset:21504
	ds_read_b128 v[216:219], v146 offset:22528
	ds_read_b128 v[220:223], v146 offset:23552
	global_load_lds_dwordx4 v[142:143], off
	s_add_i32 m0, s75, 0x2000
	s_add_u32 s82, s26, 0x4000
	v_lshl_add_u64 v[142:143], s[26:27], 0, v[130:131]
	s_addc_u32 s83, s27, 0
	s_add_i32 s75, s80, s41
	global_load_lds_dwordx4 v[142:143], off
	v_lshl_add_u64 v[142:143], s[82:83], 0, v[134:135]
	s_mov_b32 m0, s75
	s_nop 0
	global_load_lds_dwordx4 v[142:143], off
	v_lshl_add_u64 v[142:143], s[82:83], 0, v[130:131]
	s_add_i32 m0, s75, 0x2000
	s_nop 0
	global_load_lds_dwordx4 v[142:143], off
	v_lshl_add_u64 v[142:143], s[28:29], 0, v[136:137]
	s_mov_b32 m0, s43
	s_nop 0
	global_load_lds_dwordx4 v[142:143], off
	v_lshl_add_u64 v[142:143], s[28:29], 0, v[132:133]
	s_mov_b32 m0, s44
	s_nop 0
	global_load_lds_dwordx4 v[142:143], off
	s_waitcnt vmcnt(8)
	s_waitcnt lgkmcnt(0)
	s_barrier
	s_setprio 1
	s_waitcnt lgkmcnt(0)
	v_mfma_f32_16x16x32_bf16 v[62:65], v[148:151], v[180:183], v[62:65]
	v_mfma_f32_16x16x32_bf16 v[54:57], v[156:159], v[180:183], v[54:57]
	v_mfma_f32_16x16x32_bf16 v[46:49], v[148:151], v[200:203], v[46:49]
	v_mfma_f32_16x16x32_bf16 v[38:41], v[156:159], v[200:203], v[38:41]
	v_mfma_f32_16x16x32_bf16 v[30:33], v[148:151], v[208:211], v[30:33]
	v_mfma_f32_16x16x32_bf16 v[22:25], v[156:159], v[208:211], v[22:25]
	v_mfma_f32_16x16x32_bf16 v[14:17], v[148:151], v[216:219], v[14:17]
	v_mfma_f32_16x16x32_bf16 v[6:9], v[156:159], v[216:219], v[6:9]
	v_mfma_f32_16x16x32_bf16 v[62:65], v[152:155], v[196:199], v[62:65]
	v_mfma_f32_16x16x32_bf16 v[54:57], v[160:163], v[196:199], v[54:57]
	v_mfma_f32_16x16x32_bf16 v[46:49], v[152:155], v[204:207], v[46:49]
	v_mfma_f32_16x16x32_bf16 v[38:41], v[160:163], v[204:207], v[38:41]
	v_mfma_f32_16x16x32_bf16 v[30:33], v[152:155], v[212:215], v[30:33]
	v_mfma_f32_16x16x32_bf16 v[22:25], v[160:163], v[212:215], v[22:25]
	v_mfma_f32_16x16x32_bf16 v[14:17], v[152:155], v[220:223], v[14:17]
	v_mfma_f32_16x16x32_bf16 v[6:9], v[160:163], v[220:223], v[6:9]
	s_setprio 0
	s_setprio 1
	v_mfma_f32_16x16x32_bf16 v[58:61], v[164:167], v[180:183], v[58:61]
	v_mfma_f32_16x16x32_bf16 v[50:53], v[172:175], v[180:183], v[50:53]
	v_mfma_f32_16x16x32_bf16 v[42:45], v[164:167], v[200:203], v[42:45]
	v_mfma_f32_16x16x32_bf16 v[34:37], v[172:175], v[200:203], v[34:37]
	v_mfma_f32_16x16x32_bf16 v[26:29], v[164:167], v[208:211], v[26:29]
	v_mfma_f32_16x16x32_bf16 v[18:21], v[172:175], v[208:211], v[18:21]
	v_mfma_f32_16x16x32_bf16 v[10:13], v[164:167], v[216:219], v[10:13]
	v_mfma_f32_16x16x32_bf16 v[2:5], v[172:175], v[216:219], v[2:5]
	v_mfma_f32_16x16x32_bf16 v[58:61], v[168:171], v[196:199], v[58:61]
	v_mfma_f32_16x16x32_bf16 v[50:53], v[176:179], v[196:199], v[50:53]
	v_mfma_f32_16x16x32_bf16 v[42:45], v[168:171], v[204:207], v[42:45]
	v_mfma_f32_16x16x32_bf16 v[34:37], v[176:179], v[204:207], v[34:37]
	v_mfma_f32_16x16x32_bf16 v[26:29], v[168:171], v[212:215], v[26:29]
	v_mfma_f32_16x16x32_bf16 v[18:21], v[176:179], v[212:215], v[18:21]
	v_mfma_f32_16x16x32_bf16 v[10:13], v[168:171], v[220:223], v[10:13]
	v_mfma_f32_16x16x32_bf16 v[2:5], v[176:179], v[220:223], v[2:5]
	s_setprio 0
	s_barrier
.Lmid_216:
	s_add_i32 s75, 0, 0x18000
	v_add_u32_e32 v142, s75, v145
	s_add_i32 s80, 0, 0x1c000
	ds_read_b128 v[148:151], v142
	ds_read_b128 v[152:155], v142 offset:1024
	ds_read_b128 v[156:159], v142 offset:2048
	ds_read_b128 v[160:163], v142 offset:3072
	v_add_u32_e32 v142, s80, v145
	ds_read_b128 v[164:167], v142
	ds_read_b128 v[168:171], v142 offset:1024
	ds_read_b128 v[172:175], v142 offset:2048
	ds_read_b128 v[176:179], v142 offset:3072
	s_add_u32 s28, s28, 0x4000
	s_addc_u32 s29, s29, 0
	s_mov_b32 m0, s45
	v_lshl_add_u64 v[142:143], s[28:29], 0, v[136:137]
	ds_read_b128 v[180:183], v146 offset:32768
	ds_read_b128 v[196:199], v146 offset:33792
	ds_read_b128 v[200:203], v146 offset:34816
	ds_read_b128 v[204:207], v146 offset:35840
	ds_read_b128 v[208:211], v146 offset:36864
	ds_read_b128 v[212:215], v146 offset:37888
	ds_read_b128 v[216:219], v146 offset:38912
	ds_read_b128 v[220:223], v146 offset:39936
	global_load_lds_dwordx4 v[142:143], off
	v_lshl_add_u64 v[142:143], s[28:29], 0, v[132:133]
	s_mov_b32 m0, s46
	s_nop 0
	global_load_lds_dwordx4 v[142:143], off
	s_waitcnt vmcnt(8)
	s_waitcnt lgkmcnt(0)
	s_barrier
; #define PG8_STAGE(bufoff, gbase, voff) do { _Pragma("unroll") for (int _i = 0; _i < 2; ++_i) \
;         __builtin_amdgcn_global_load_lds((const unsigned*)((const char*)(gbase) + (voff)[_i]), (PG8_LAS unsigned*)(lds + (bufoff) + ldsw + _i * 8192), 16, 0, 0); } while (0)
; #define PG8_LDA(dst, b, h) do { _Pragma("unroll") for (int m = 0; m < 4; ++m) _Pragma("unroll") for (int k = 0; k < 2; ++k) dst[m][k] = *(const PG8_LAS bf16x8*)(lds + PG8_SA(b, h) + aoff + m * 2048 + k * 1024); } while (0)
; #define PG8_LDB(dst, b, h) do { _Pragma("unroll") for (int n = 0; n < 2; ++n) _Pragma("unroll") for (int k = 0; k < 2; ++k) dst[n][k] = *(const PG8_LAS bf16x8*)(lds + PG8_SB(b, h) + boff + n * 2048 + k * 1024); } while (0)
; #define PG8_MMA(ai, bj, At, Bt) do { __builtin_amdgcn_s_setprio(1); _Pragma("unroll") for (int m = 0; m < 4; ++m) _Pragma("unroll") for (int n = 0; n < 2; ++n) _Pragma("unroll") for (int k = 0; k < 2; ++k) \
;         acc[ai][bj][m][n] = __builtin_amdgcn_mfma_f32_16x16x32_bf16(Bt[n][k], At[m][k], acc[ai][bj][m][n], 0, 0, 0); __builtin_amdgcn_s_setprio(0); } while (0)
; #define PG8_WAIT_V(n) asm volatile("s_waitcnt vmcnt(" #n ")" ::: "memory")
; #define PG8_BAR __builtin_amdgcn_s_barrier()
; template <class Epi, class Sched, bool ALIGN_EPI = false, bool SP2 = false, bool ABLK = false, bool BBLK = false>
; __device__ __forceinline__ void gemm_phase(PG8_LAS unsigned char* lds, const Gemm g, const Sched& S, const Epi& E) {
;     ...
;         for (int t = 0; t < nt; t += 2) {
;             const bool last = (t == nt - 2);
;             const char* a1 = cA + (size_t)(t + 1) * kstepA;
;             const char* a2 = last ? nA : cA + (size_t)(t + 2) * kstepA; const char* b2 = last ? nB : cB + (size_t)(t + 2) * kstepB;
;             const char* a3 = a2 + kstepA; const char* b3 = b2 + kstepB;
;             if (last && has_next) S.a_ready(nxt);
;     ...
;             PG8_LDB(B0, 1, 0); PG8_LDB(B1, 1, 1); PG8_SCHED; PG8_LDA(At, 1, 0); PG8_STAGE(PG8_SA(0, 1), a2 + hstepA, voffA);
;             PG8_WAIT_V(8); PG8_WAIT_L(0); PG8_BAR; PG8_MMA(0, 0, At, B0); PG8_MMA(0, 1, At, B1); PG8_BAR; PG8_SCHED;
;             PG8_LDA(At, 1, 1); PG8_STAGE(PG8_SB(1, 0), b3, voffB); PG8_STAGE(PG8_SB(1, 1), b3 + hstepB, voffB); PG8_STAGE(PG8_SA(1, 0), a3, voffA);
;             PG8_WAIT_V(8); PG8_WAIT_L(0); PG8_BAR; PG8_MMA(1, 0, At, B0); PG8_MMA(1, 1, At, B1); PG8_BAR; PG8_SCHED;
	s_setprio 1
	s_waitcnt lgkmcnt(0)
	v_mfma_f32_16x16x32_bf16 v[126:129], v[148:151], v[180:183], v[126:129]
	v_mfma_f32_16x16x32_bf16 v[118:121], v[156:159], v[180:183], v[118:121]
	v_mfma_f32_16x16x32_bf16 v[110:113], v[148:151], v[200:203], v[110:113]
	v_mfma_f32_16x16x32_bf16 v[102:105], v[156:159], v[200:203], v[102:105]
	v_mfma_f32_16x16x32_bf16 v[94:97], v[148:151], v[208:211], v[94:97]
	v_mfma_f32_16x16x32_bf16 v[86:89], v[156:159], v[208:211], v[86:89]
	v_mfma_f32_16x16x32_bf16 v[78:81], v[148:151], v[216:219], v[78:81]
	v_mfma_f32_16x16x32_bf16 v[70:73], v[156:159], v[216:219], v[70:73]
	v_mfma_f32_16x16x32_bf16 v[126:129], v[152:155], v[196:199], v[126:129]
	v_mfma_f32_16x16x32_bf16 v[118:121], v[160:163], v[196:199], v[118:121]
	v_mfma_f32_16x16x32_bf16 v[110:113], v[152:155], v[204:207], v[110:113]
	v_mfma_f32_16x16x32_bf16 v[102:105], v[160:163], v[204:207], v[102:105]
	v_mfma_f32_16x16x32_bf16 v[94:97], v[152:155], v[212:215], v[94:97]
	v_mfma_f32_16x16x32_bf16 v[86:89], v[160:163], v[212:215], v[86:89]
	v_mfma_f32_16x16x32_bf16 v[78:81], v[152:155], v[220:223], v[78:81]
	v_mfma_f32_16x16x32_bf16 v[70:73], v[160:163], v[220:223], v[70:73]
	s_setprio 0
	s_setprio 1
	v_mfma_f32_16x16x32_bf16 v[122:125], v[164:167], v[180:183], v[122:125]
	v_mfma_f32_16x16x32_bf16 v[114:117], v[172:175], v[180:183], v[114:117]
	v_mfma_f32_16x16x32_bf16 v[106:109], v[164:167], v[200:203], v[106:109]
	v_mfma_f32_16x16x32_bf16 v[98:101], v[172:175], v[200:203], v[98:101]
	v_mfma_f32_16x16x32_bf16 v[90:93], v[164:167], v[208:211], v[90:93]
	v_mfma_f32_16x16x32_bf16 v[82:85], v[172:175], v[208:211], v[82:85]
	v_mfma_f32_16x16x32_bf16 v[74:77], v[164:167], v[216:219], v[74:77]
	v_mfma_f32_16x16x32_bf16 v[66:69], v[172:175], v[216:219], v[66:69]
	v_mfma_f32_16x16x32_bf16 v[122:125], v[168:171], v[196:199], v[122:125]
	v_mfma_f32_16x16x32_bf16 v[114:117], v[176:179], v[196:199], v[114:117]
	v_mfma_f32_16x16x32_bf16 v[106:109], v[168:171], v[204:207], v[106:109]
	v_mfma_f32_16x16x32_bf16 v[98:101], v[176:179], v[204:207], v[98:101]
	v_mfma_f32_16x16x32_bf16 v[90:93], v[168:171], v[212:215], v[90:93]
	v_mfma_f32_16x16x32_bf16 v[82:85], v[176:179], v[212:215], v[82:85]
	v_mfma_f32_16x16x32_bf16 v[74:77], v[168:171], v[220:223], v[74:77]
	v_mfma_f32_16x16x32_bf16 v[66:69], v[176:179], v[220:223], v[66:69]
	s_setprio 0
	s_barrier
	s_add_u32 s28, s26, 0x8000
	s_addc_u32 s29, s27, 0
	s_add_i32 s75, s75, s41
	v_lshl_add_u64 v[142:143], s[28:29], 0, v[134:135]
	s_mov_b32 m0, s75
	ds_read_b128 v[180:183], v146 offset:49152
	ds_read_b128 v[196:199], v146 offset:50176
	ds_read_b128 v[200:203], v146 offset:51200
	ds_read_b128 v[204:207], v146 offset:52224
	ds_read_b128 v[208:211], v146 offset:53248
	ds_read_b128 v[212:215], v146 offset:54272
	ds_read_b128 v[216:219], v146 offset:55296
	ds_read_b128 v[220:223], v146 offset:56320
	global_load_lds_dwordx4 v[142:143], off
	s_add_i32 m0, s75, 0x2000
	s_add_u32 s26, s26, 0xc000
	v_lshl_add_u64 v[142:143], s[28:29], 0, v[130:131]
	s_addc_u32 s27, s27, 0
	s_add_i32 s28, s80, s41
	global_load_lds_dwordx4 v[142:143], off
	v_lshl_add_u64 v[142:143], s[26:27], 0, v[134:135]
	s_mov_b32 m0, s28
	s_nop 0
	global_load_lds_dwordx4 v[142:143], off
	v_lshl_add_u64 v[142:143], s[26:27], 0, v[130:131]
	s_add_i32 m0, s28, 0x2000
	s_nop 0
	global_load_lds_dwordx4 v[142:143], off
	v_lshl_add_u64 v[142:143], s[24:25], 0, v[136:137]
	s_mov_b32 m0, s51
	s_nop 0
	global_load_lds_dwordx4 v[142:143], off
	v_lshl_add_u64 v[142:143], s[24:25], 0, v[132:133]
	s_mov_b32 m0, s53
	s_nop 0
	global_load_lds_dwordx4 v[142:143], off
	s_waitcnt vmcnt(8)
	s_waitcnt lgkmcnt(0)
	s_barrier
	s_setprio 1
	s_waitcnt lgkmcnt(0)
	v_mfma_f32_16x16x32_bf16 v[62:65], v[148:151], v[180:183], v[62:65]
	v_mfma_f32_16x16x32_bf16 v[54:57], v[156:159], v[180:183], v[54:57]
	v_mfma_f32_16x16x32_bf16 v[46:49], v[148:151], v[200:203], v[46:49]
	v_mfma_f32_16x16x32_bf16 v[38:41], v[156:159], v[200:203], v[38:41]
	v_mfma_f32_16x16x32_bf16 v[30:33], v[148:151], v[208:211], v[30:33]
	v_mfma_f32_16x16x32_bf16 v[22:25], v[156:159], v[208:211], v[22:25]
	v_mfma_f32_16x16x32_bf16 v[14:17], v[148:151], v[216:219], v[14:17]
	v_mfma_f32_16x16x32_bf16 v[6:9], v[156:159], v[216:219], v[6:9]
	v_mfma_f32_16x16x32_bf16 v[62:65], v[152:155], v[196:199], v[62:65]
	v_mfma_f32_16x16x32_bf16 v[54:57], v[160:163], v[196:199], v[54:57]
	v_mfma_f32_16x16x32_bf16 v[46:49], v[152:155], v[204:207], v[46:49]
	v_mfma_f32_16x16x32_bf16 v[38:41], v[160:163], v[204:207], v[38:41]
	v_mfma_f32_16x16x32_bf16 v[30:33], v[152:155], v[212:215], v[30:33]
	v_mfma_f32_16x16x32_bf16 v[22:25], v[160:163], v[212:215], v[22:25]
	v_mfma_f32_16x16x32_bf16 v[14:17], v[152:155], v[220:223], v[14:17]
	v_mfma_f32_16x16x32_bf16 v[6:9], v[160:163], v[220:223], v[6:9]
	s_setprio 0
	s_setprio 1
	v_mfma_f32_16x16x32_bf16 v[58:61], v[164:167], v[180:183], v[58:61]
	v_mfma_f32_16x16x32_bf16 v[50:53], v[172:175], v[180:183], v[50:53]
	v_mfma_f32_16x16x32_bf16 v[42:45], v[164:167], v[200:203], v[42:45]
	v_mfma_f32_16x16x32_bf16 v[34:37], v[172:175], v[200:203], v[34:37]
	v_mfma_f32_16x16x32_bf16 v[26:29], v[164:167], v[208:211], v[26:29]
	v_mfma_f32_16x16x32_bf16 v[18:21], v[172:175], v[208:211], v[18:21]
	v_mfma_f32_16x16x32_bf16 v[10:13], v[164:167], v[216:219], v[10:13]
	v_mfma_f32_16x16x32_bf16 v[2:5], v[172:175], v[216:219], v[2:5]
	v_mfma_f32_16x16x32_bf16 v[58:61], v[168:171], v[196:199], v[58:61]
	v_mfma_f32_16x16x32_bf16 v[50:53], v[176:179], v[196:199], v[50:53]
	v_mfma_f32_16x16x32_bf16 v[42:45], v[168:171], v[204:207], v[42:45]
	v_mfma_f32_16x16x32_bf16 v[34:37], v[176:179], v[204:207], v[34:37]
	v_mfma_f32_16x16x32_bf16 v[26:29], v[168:171], v[212:215], v[26:29]
	v_mfma_f32_16x16x32_bf16 v[18:21], v[176:179], v[212:215], v[18:21]
	v_mfma_f32_16x16x32_bf16 v[10:13], v[168:171], v[220:223], v[10:13]
	v_mfma_f32_16x16x32_bf16 v[2:5], v[176:179], v[220:223], v[2:5]
	s_setprio 0
	s_barrier
	s_add_i32 s81, s81, 2
	s_add_u32 s22, s22, 0x10000
	s_addc_u32 s23, s23, 0
	s_add_u32 s72, s72, 0x10000
	s_addc_u32 s73, s73, 0
	s_cmp_gt_u32 s81, 29
	s_cbranch_scc0 .LBB0_216
	s_and_b64 vcc, exec, s[10:11]
	s_cbranch_vccz .LBB0_219
	s_barrier

; #define PG8_STAGE(bufoff, gbase, voff) do { _Pragma("unroll") for (int _i = 0; _i < 2; ++_i) \
;         __builtin_amdgcn_global_load_lds((const unsigned*)((const char*)(gbase) + (voff)[_i]), (PG8_LAS unsigned*)(lds + (bufoff) + ldsw + _i * 8192), 16, 0, 0); } while (0)
; #define PG8_LDA(dst, b, h) do { _Pragma("unroll") for (int m = 0; m < 4; ++m) _Pragma("unroll") for (int k = 0; k < 2; ++k) dst[m][k] = *(const PG8_LAS bf16x8*)(lds + PG8_SA(b, h) + aoff + m * 2048 + k * 1024); } while (0)
; #define PG8_LDB(dst, b, h) do { _Pragma("unroll") for (int n = 0; n < 2; ++n) _Pragma("unroll") for (int k = 0; k < 2; ++k) dst[n][k] = *(const PG8_LAS bf16x8*)(lds + PG8_SB(b, h) + boff + n * 2048 + k * 1024); } while (0)
; #define PG8_WAIT_V(n) asm volatile("s_waitcnt vmcnt(" #n ")" ::: "memory")
; #define PG8_WAIT_L(n) asm volatile("s_waitcnt lgkmcnt(" #n ")" ::: "memory")
; #define PG8_BAR __builtin_amdgcn_s_barrier()
; template <class Epi, class Sched, bool ALIGN_EPI = false, bool SP2 = false, bool ABLK = false, bool BBLK = false>
; __device__ __forceinline__ void gemm_phase(PG8_LAS unsigned char* lds, const Gemm g, const Sched& S, const Epi& E) {
;     ...
;     for (;;) {
;         const bool has_next = S.next(ui + 1, nxt);
;         const char* nA = has_next ? (const char*)g.A + (size_t)nxt.pm * tstepA : cA; const char* nB = has_next ? (const char*)g.Bt + (size_t)nxt.pn * tstepB : cB;
;         for (int t = 0; t < nt; t += 2) {
;             const bool last = (t == nt - 2);
;             const char* a1 = cA + (size_t)(t + 1) * kstepA;
;             const char* a2 = last ? nA : cA + (size_t)(t + 2) * kstepA; const char* b2 = last ? nB : cB + (size_t)(t + 2) * kstepB;
;             const char* a3 = a2 + kstepA; const char* b3 = b2 + kstepB;
;             if (last && has_next) S.a_ready(nxt);
;             if constexpr (SP2) {
;             PG8_LDB(B0, 0, 0); PG8_LDB(B1, 0, 1); PG8_SCHED; PG8_LDA(At, 0, 0); PG8_STAGE(PG8_SA(1, 1), a1 + hstepA, voffA);
;             PG8_WAIT_V(8); PG8_WAIT_L(0); PG8_BAR; PG8_MMA(0, 0, At, B0); PG8_MMA(0, 1, At, B1); PG8_BAR; PG8_SCHED;
;             PG8_LDA(At, 0, 1); PG8_STAGE(PG8_SB(0, 0), b2, voffB); PG8_STAGE(PG8_SB(0, 1), b2 + hstepB, voffB); PG8_STAGE(PG8_SA(0, 0), a2, voffA);
;             PG8_WAIT_V(8); PG8_WAIT_L(0); PG8_BAR; PG8_MMA(1, 0, At, B0); PG8_MMA(1, 1, At, B1); PG8_BAR; PG8_SCHED;
.LBB0_304:
	s_add_u32 s0, s0, 0xc000
	s_addc_u32 s1, s1, 0
	s_add_u32 s29, s34, 0x10000
	v_mov_b32_e32 v2, 0
	s_addc_u32 s31, s35, 0
	s_mov_b32 s33, -2
	s_add_u32 s8, s0, 0x4000
	s_addc_u32 s9, s1, 0
	s_cmpk_eq_i32 s33, 0x54
	s_cselect_b32 s36, s24, s8
	s_cselect_b32 s37, s25, s9
	s_cselect_b32 s34, s26, s29
	s_cselect_b32 s35, s27, s31
	s_add_u32 s8, s36, 0x8000
	s_addc_u32 s9, s37, 0
	s_add_i32 s40, 0, 0x10000
	s_add_i32 s44, 0, 0x14000
	v_add_u32_e32 v142, s40, v206
	v_add_u32_e32 v158, s44, v206
	ds_read_b128 v[130:133], v142
	ds_read_b128 v[134:137], v142 offset:1024
	ds_read_b128 v[138:141], v142 offset:2048
	ds_read_b128 v[142:145], v142 offset:3072
	ds_read_b128 v[146:149], v158
	ds_read_b128 v[150:153], v158 offset:1024
	ds_read_b128 v[154:157], v158 offset:2048
	ds_read_b128 v[158:161], v158 offset:3072
	v_lshl_add_u64 v[202:203], s[0:1], 0, v[184:185]
	s_add_i32 m0, s3, 0xc000
	ds_read_b128 v[162:165], v207
	ds_read_b128 v[166:169], v207 offset:1024
	ds_read_b128 v[170:173], v207 offset:2048
	ds_read_b128 v[174:177], v207 offset:3072
	ds_read_b128 v[198:201], v207 offset:4096
	ds_read_b128 v[208:211], v207 offset:5120
	ds_read_b128 v[212:215], v207 offset:6144
	ds_read_b128 v[216:219], v207 offset:7168
	global_load_lds_dwordx4 v[202:203], off
	v_lshl_add_u64 v[202:203], s[0:1], 0, v[196:197]
	s_add_i32 m0, s3, 0xe000
	s_nop 0
	global_load_lds_dwordx4 v[202:203], off
	s_waitcnt vmcnt(8)
	s_waitcnt lgkmcnt(0)
	s_barrier
	s_setprio 1
	s_waitcnt lgkmcnt(0)
	v_mfma_f32_16x16x32_bf16 v[30:33], v[130:133], v[162:165], 0
	v_mfma_f32_16x16x32_bf16 v[22:25], v[138:141], v[162:165], 0
	v_mfma_f32_16x16x32_bf16 v[10:13], v[130:133], v[170:173], 0
	v_mfma_f32_16x16x32_bf16 v[6:9], v[138:141], v[170:173], 0
	v_mfma_f32_16x16x32_bf16 v[50:53], v[130:133], v[198:201], 0
	v_mfma_f32_16x16x32_bf16 v[54:57], v[138:141], v[198:201], 0
	v_mfma_f32_16x16x32_bf16 v[74:77], v[130:133], v[212:215], 0
	v_mfma_f32_16x16x32_bf16 v[78:81], v[138:141], v[212:215], 0
	v_mfma_f32_16x16x32_bf16 v[30:33], v[134:137], v[166:169], v[30:33]
	v_mfma_f32_16x16x32_bf16 v[22:25], v[142:145], v[166:169], v[22:25]
	v_mfma_f32_16x16x32_bf16 v[10:13], v[134:137], v[174:177], v[10:13]
	v_mfma_f32_16x16x32_bf16 v[6:9], v[142:145], v[174:177], v[6:9]
	v_mfma_f32_16x16x32_bf16 v[50:53], v[134:137], v[208:211], v[50:53]
	v_mfma_f32_16x16x32_bf16 v[54:57], v[142:145], v[208:211], v[54:57]
	v_mfma_f32_16x16x32_bf16 v[74:77], v[134:137], v[216:219], v[74:77]
	v_mfma_f32_16x16x32_bf16 v[78:81], v[142:145], v[216:219], v[78:81]
	s_setprio 0
	s_setprio 1
	v_mfma_f32_16x16x32_bf16 v[26:29], v[146:149], v[162:165], 0
	v_mfma_f32_16x16x32_bf16 v[18:21], v[154:157], v[162:165], 0
	v_mfma_f32_16x16x32_bf16 v[42:45], v[146:149], v[170:173], 0
	v_mfma_f32_16x16x32_bf16 v[46:49], v[154:157], v[170:173], 0
	v_mfma_f32_16x16x32_bf16 v[66:69], v[146:149], v[198:201], 0
	v_mfma_f32_16x16x32_bf16 v[70:73], v[154:157], v[198:201], 0
	v_mfma_f32_16x16x32_bf16 v[82:85], v[146:149], v[212:215], 0
	v_mfma_f32_16x16x32_bf16 v[86:89], v[154:157], v[212:215], 0
	v_mfma_f32_16x16x32_bf16 v[26:29], v[150:153], v[166:169], v[26:29]
	v_mfma_f32_16x16x32_bf16 v[18:21], v[158:161], v[166:169], v[18:21]
	v_mfma_f32_16x16x32_bf16 v[42:45], v[150:153], v[174:177], v[42:45]
	v_mfma_f32_16x16x32_bf16 v[46:49], v[158:161], v[174:177], v[46:49]
	v_mfma_f32_16x16x32_bf16 v[66:69], v[150:153], v[208:211], v[66:69]
	v_mfma_f32_16x16x32_bf16 v[70:73], v[158:161], v[208:211], v[70:73]
	v_mfma_f32_16x16x32_bf16 v[82:85], v[150:153], v[216:219], v[82:85]
	v_mfma_f32_16x16x32_bf16 v[86:89], v[158:161], v[216:219], v[86:89]
	s_setprio 0
	s_barrier
	s_add_i32 s40, s40, s2
	v_lshl_add_u64 v[202:203], s[34:35], 0, v[186:187]
	s_mov_b32 m0, s40
	ds_read_b128 v[162:165], v207 offset:16384
	ds_read_b128 v[166:169], v207 offset:17408
	ds_read_b128 v[170:173], v207 offset:18432
	ds_read_b128 v[174:177], v207 offset:19456
	ds_read_b128 v[198:201], v207 offset:20480
	ds_read_b128 v[208:211], v207 offset:21504
	ds_read_b128 v[212:215], v207 offset:22528
	ds_read_b128 v[216:219], v207 offset:23552
	global_load_lds_dwordx4 v[202:203], off
	s_add_i32 m0, s40, 0x2000
	s_add_u32 s40, s34, 0x4000
	v_lshl_add_u64 v[202:203], s[34:35], 0, v[182:183]
	s_addc_u32 s41, s35, 0
	s_add_i32 s44, s44, s2
	global_load_lds_dwordx4 v[202:203], off
	v_lshl_add_u64 v[202:203], s[40:41], 0, v[186:187]
	s_mov_b32 m0, s44
	s_nop 0
	global_load_lds_dwordx4 v[202:203], off
	v_lshl_add_u64 v[202:203], s[40:41], 0, v[182:183]
	s_add_i32 m0, s44, 0x2000
	s_nop 0
	global_load_lds_dwordx4 v[202:203], off
	v_lshl_add_u64 v[202:203], s[36:37], 0, v[178:179]
	s_mov_b32 m0, s3
	s_nop 0
	global_load_lds_dwordx4 v[202:203], off
	v_lshl_add_u64 v[202:203], s[36:37], 0, v[180:181]
	s_mov_b32 m0, s42
	s_nop 0
	global_load_lds_dwordx4 v[202:203], off
	s_waitcnt vmcnt(8)
	s_waitcnt lgkmcnt(0)
	s_barrier
; #define PG8_STAGE(bufoff, gbase, voff) do { _Pragma("unroll") for (int _i = 0; _i < 2; ++_i) \
;         __builtin_amdgcn_global_load_lds((const unsigned*)((const char*)(gbase) + (voff)[_i]), (PG8_LAS unsigned*)(lds + (bufoff) + ldsw + _i * 8192), 16, 0, 0); } while (0)
; #define PG8_LDA(dst, b, h) do { _Pragma("unroll") for (int m = 0; m < 4; ++m) _Pragma("unroll") for (int k = 0; k < 2; ++k) dst[m][k] = *(const PG8_LAS bf16x8*)(lds + PG8_SA(b, h) + aoff + m * 2048 + k * 1024); } while (0)
; #define PG8_LDB(dst, b, h) do { _Pragma("unroll") for (int n = 0; n < 2; ++n) _Pragma("unroll") for (int k = 0; k < 2; ++k) dst[n][k] = *(const PG8_LAS bf16x8*)(lds + PG8_SB(b, h) + boff + n * 2048 + k * 1024); } while (0)
; #define PG8_MMA(ai, bj, At, Bt) do { __builtin_amdgcn_s_setprio(1); _Pragma("unroll") for (int m = 0; m < 4; ++m) _Pragma("unroll") for (int n = 0; n < 2; ++n) _Pragma("unroll") for (int k = 0; k < 2; ++k) \
;         acc[ai][bj][m][n] = __builtin_amdgcn_mfma_f32_16x16x32_bf16(Bt[n][k], At[m][k], acc[ai][bj][m][n], 0, 0, 0); __builtin_amdgcn_s_setprio(0); } while (0)
; #define PG8_WAIT_V(n) asm volatile("s_waitcnt vmcnt(" #n ")" ::: "memory")
; template <class Epi, class Sched, bool ALIGN_EPI = false, bool SP2 = false, bool ABLK = false, bool BBLK = false>
; __device__ __forceinline__ void gemm_phase(PG8_LAS unsigned char* lds, const Gemm g, const Sched& S, const Epi& E) {
;     ...
;         for (int t = 0; t < nt; t += 2) {
;             const bool last = (t == nt - 2);
;             const char* a1 = cA + (size_t)(t + 1) * kstepA;
;             const char* a2 = last ? nA : cA + (size_t)(t + 2) * kstepA; const char* b2 = last ? nB : cB + (size_t)(t + 2) * kstepB;
;             const char* a3 = a2 + kstepA; const char* b3 = b2 + kstepB;
;             if (last && has_next) S.a_ready(nxt);
;             if constexpr (SP2) {
;             PG8_LDB(B0, 0, 0); PG8_LDB(B1, 0, 1); PG8_SCHED; PG8_LDA(At, 0, 0); PG8_STAGE(PG8_SA(1, 1), a1 + hstepA, voffA);
;             PG8_WAIT_V(8); PG8_WAIT_L(0); PG8_BAR; PG8_MMA(0, 0, At, B0); PG8_MMA(0, 1, At, B1); PG8_BAR; PG8_SCHED;
;             PG8_LDA(At, 0, 1); PG8_STAGE(PG8_SB(0, 0), b2, voffB); PG8_STAGE(PG8_SB(0, 1), b2 + hstepB, voffB); PG8_STAGE(PG8_SA(0, 0), a2, voffA);
;             PG8_WAIT_V(8); PG8_WAIT_L(0); PG8_BAR; PG8_MMA(1, 0, At, B0); PG8_MMA(1, 1, At, B1); PG8_BAR; PG8_SCHED;
	s_setprio 1
	s_waitcnt lgkmcnt(0)
	v_mfma_f32_16x16x32_bf16 v[106:109], v[130:133], v[162:165], 0
	v_mfma_f32_16x16x32_bf16 v[110:113], v[138:141], v[162:165], 0
	v_mfma_f32_16x16x32_bf16 v[122:125], v[130:133], v[170:173], 0
	v_mfma_f32_16x16x32_bf16 v[126:129], v[138:141], v[170:173], 0
	v_mfma_f32_16x16x32_bf16 v[94:97], v[130:133], v[198:201], 0
	v_mfma_f32_16x16x32_bf16 v[90:93], v[138:141], v[198:201], 0
	v_mfma_f32_16x16x32_bf16 v[38:41], v[130:133], v[212:215], 0
	v_mfma_f32_16x16x32_bf16 v[34:37], v[138:141], v[212:215], 0
	v_mfma_f32_16x16x32_bf16 v[106:109], v[134:137], v[166:169], v[106:109]
	v_mfma_f32_16x16x32_bf16 v[110:113], v[142:145], v[166:169], v[110:113]
	v_mfma_f32_16x16x32_bf16 v[122:125], v[134:137], v[174:177], v[122:125]
	v_mfma_f32_16x16x32_bf16 v[126:129], v[142:145], v[174:177], v[126:129]
	v_mfma_f32_16x16x32_bf16 v[94:97], v[134:137], v[208:211], v[94:97]
	v_mfma_f32_16x16x32_bf16 v[90:93], v[142:145], v[208:211], v[90:93]
	v_mfma_f32_16x16x32_bf16 v[38:41], v[134:137], v[216:219], v[38:41]
	v_mfma_f32_16x16x32_bf16 v[34:37], v[142:145], v[216:219], v[34:37]
	s_setprio 0
	s_setprio 1
	v_mfma_f32_16x16x32_bf16 v[114:117], v[146:149], v[162:165], 0
	v_mfma_f32_16x16x32_bf16 v[118:121], v[154:157], v[162:165], 0
	v_mfma_f32_16x16x32_bf16 v[102:105], v[146:149], v[170:173], 0
	v_mfma_f32_16x16x32_bf16 v[98:101], v[154:157], v[170:173], 0
	v_mfma_f32_16x16x32_bf16 v[62:65], v[146:149], v[198:201], 0
	v_mfma_f32_16x16x32_bf16 v[58:61], v[154:157], v[198:201], 0
	v_mfma_f32_16x16x32_bf16 v[14:17], v[146:149], v[212:215], 0
	v_mfma_f32_16x16x32_bf16 v[2:5], v[154:157], v[212:215], 0
	v_mfma_f32_16x16x32_bf16 v[114:117], v[150:153], v[166:169], v[114:117]
	v_mfma_f32_16x16x32_bf16 v[118:121], v[158:161], v[166:169], v[118:121]
	v_mfma_f32_16x16x32_bf16 v[102:105], v[150:153], v[174:177], v[102:105]
	v_mfma_f32_16x16x32_bf16 v[98:101], v[158:161], v[174:177], v[98:101]
	v_mfma_f32_16x16x32_bf16 v[62:65], v[150:153], v[208:211], v[62:65]
	v_mfma_f32_16x16x32_bf16 v[58:61], v[158:161], v[208:211], v[58:61]
	v_mfma_f32_16x16x32_bf16 v[14:17], v[150:153], v[216:219], v[14:17]
	v_mfma_f32_16x16x32_bf16 v[2:5], v[158:161], v[216:219], v[2:5]
	s_setprio 0
	s_barrier
	s_branch .Lmid_305
.LBB0_305:
	s_add_u32 s8, s0, 0x4000
	s_addc_u32 s9, s1, 0
	s_cmpk_eq_i32 s33, 0x54
	s_cselect_b32 s36, s24, s8
	s_cselect_b32 s37, s25, s9
	s_cselect_b32 s34, s26, s29
	s_cselect_b32 s35, s27, s31
	s_add_u32 s8, s36, 0x8000
	s_addc_u32 s9, s37, 0
	s_add_i32 s40, 0, 0x10000
	s_add_i32 s44, 0, 0x14000
	v_add_u32_e32 v142, s40, v206
	v_add_u32_e32 v158, s44, v206
	ds_read_b128 v[130:133], v142
	ds_read_b128 v[134:137], v142 offset:1024
	ds_read_b128 v[138:141], v142 offset:2048
	ds_read_b128 v[142:145], v142 offset:3072
	ds_read_b128 v[146:149], v158
	ds_read_b128 v[150:153], v158 offset:1024
	ds_read_b128 v[154:157], v158 offset:2048
	ds_read_b128 v[158:161], v158 offset:3072
	v_lshl_add_u64 v[202:203], s[0:1], 0, v[184:185]
	s_add_i32 m0, s3, 0xc000
	ds_read_b128 v[162:165], v207
	ds_read_b128 v[166:169], v207 offset:1024
	ds_read_b128 v[170:173], v207 offset:2048
	ds_read_b128 v[174:177], v207 offset:3072
	ds_read_b128 v[198:201], v207 offset:4096
	ds_read_b128 v[208:211], v207 offset:5120
	ds_read_b128 v[212:215], v207 offset:6144
	ds_read_b128 v[216:219], v207 offset:7168
	global_load_lds_dwordx4 v[202:203], off
	v_lshl_add_u64 v[202:203], s[0:1], 0, v[196:197]
	s_add_i32 m0, s3, 0xe000
	s_nop 0
	global_load_lds_dwordx4 v[202:203], off
	s_waitcnt vmcnt(8)
	s_waitcnt lgkmcnt(0)
	s_barrier
	s_setprio 1
	s_waitcnt lgkmcnt(0)
	v_mfma_f32_16x16x32_bf16 v[30:33], v[130:133], v[162:165], v[30:33]
	v_mfma_f32_16x16x32_bf16 v[22:25], v[138:141], v[162:165], v[22:25]
	v_mfma_f32_16x16x32_bf16 v[10:13], v[130:133], v[170:173], v[10:13]
	v_mfma_f32_16x16x32_bf16 v[6:9], v[138:141], v[170:173], v[6:9]
	v_mfma_f32_16x16x32_bf16 v[50:53], v[130:133], v[198:201], v[50:53]
	v_mfma_f32_16x16x32_bf16 v[54:57], v[138:141], v[198:201], v[54:57]
	v_mfma_f32_16x16x32_bf16 v[74:77], v[130:133], v[212:215], v[74:77]
	v_mfma_f32_16x16x32_bf16 v[78:81], v[138:141], v[212:215], v[78:81]
	v_mfma_f32_16x16x32_bf16 v[30:33], v[134:137], v[166:169], v[30:33]
	v_mfma_f32_16x16x32_bf16 v[22:25], v[142:145], v[166:169], v[22:25]
	v_mfma_f32_16x16x32_bf16 v[10:13], v[134:137], v[174:177], v[10:13]
	v_mfma_f32_16x16x32_bf16 v[6:9], v[142:145], v[174:177], v[6:9]
	v_mfma_f32_16x16x32_bf16 v[50:53], v[134:137], v[208:211], v[50:53]
	v_mfma_f32_16x16x32_bf16 v[54:57], v[142:145], v[208:211], v[54:57]
	v_mfma_f32_16x16x32_bf16 v[74:77], v[134:137], v[216:219], v[74:77]
	v_mfma_f32_16x16x32_bf16 v[78:81], v[142:145], v[216:219], v[78:81]
	s_setprio 0
	s_setprio 1
	v_mfma_f32_16x16x32_bf16 v[26:29], v[146:149], v[162:165], v[26:29]
	v_mfma_f32_16x16x32_bf16 v[18:21], v[154:157], v[162:165], v[18:21]
	v_mfma_f32_16x16x32_bf16 v[42:45], v[146:149], v[170:173], v[42:45]
	v_mfma_f32_16x16x32_bf16 v[46:49], v[154:157], v[170:173], v[46:49]
	v_mfma_f32_16x16x32_bf16 v[66:69], v[146:149], v[198:201], v[66:69]
	v_mfma_f32_16x16x32_bf16 v[70:73], v[154:157], v[198:201], v[70:73]
	v_mfma_f32_16x16x32_bf16 v[82:85], v[146:149], v[212:215], v[82:85]
	v_mfma_f32_16x16x32_bf16 v[86:89], v[154:157], v[212:215], v[86:89]
	v_mfma_f32_16x16x32_bf16 v[26:29], v[150:153], v[166:169], v[26:29]
	v_mfma_f32_16x16x32_bf16 v[18:21], v[158:161], v[166:169], v[18:21]
	v_mfma_f32_16x16x32_bf16 v[42:45], v[150:153], v[174:177], v[42:45]
	v_mfma_f32_16x16x32_bf16 v[46:49], v[158:161], v[174:177], v[46:49]
	v_mfma_f32_16x16x32_bf16 v[66:69], v[150:153], v[208:211], v[66:69]
	v_mfma_f32_16x16x32_bf16 v[70:73], v[158:161], v[208:211], v[70:73]
	v_mfma_f32_16x16x32_bf16 v[82:85], v[150:153], v[216:219], v[82:85]
	v_mfma_f32_16x16x32_bf16 v[86:89], v[158:161], v[216:219], v[86:89]
	s_setprio 0
	s_barrier
; #define PG8_STAGE(bufoff, gbase, voff) do { _Pragma("unroll") for (int _i = 0; _i < 2; ++_i) \
;         __builtin_amdgcn_global_load_lds((const unsigned*)((const char*)(gbase) + (voff)[_i]), (PG8_LAS unsigned*)(lds + (bufoff) + ldsw + _i * 8192), 16, 0, 0); } while (0)
; #define PG8_LDA(dst, b, h) do { _Pragma("unroll") for (int m = 0; m < 4; ++m) _Pragma("unroll") for (int k = 0; k < 2; ++k) dst[m][k] = *(const PG8_LAS bf16x8*)(lds + PG8_SA(b, h) + aoff + m * 2048 + k * 1024); } while (0)
; #define PG8_LDB(dst, b, h) do { _Pragma("unroll") for (int n = 0; n < 2; ++n) _Pragma("unroll") for (int k = 0; k < 2; ++k) dst[n][k] = *(const PG8_LAS bf16x8*)(lds + PG8_SB(b, h) + boff + n * 2048 + k * 1024); } while (0)
; #define PG8_MMA(ai, bj, At, Bt) do { __builtin_amdgcn_s_setprio(1); _Pragma("unroll") for (int m = 0; m < 4; ++m) _Pragma("unroll") for (int n = 0; n < 2; ++n) _Pragma("unroll") for (int k = 0; k < 2; ++k) \
;         acc[ai][bj][m][n] = __builtin_amdgcn_mfma_f32_16x16x32_bf16(Bt[n][k], At[m][k], acc[ai][bj][m][n], 0, 0, 0); __builtin_amdgcn_s_setprio(0); } while (0)
; #define PG8_WAIT_V(n) asm volatile("s_waitcnt vmcnt(" #n ")" ::: "memory")
; #define PG8_WAIT_L(n) asm volatile("s_waitcnt lgkmcnt(" #n ")" ::: "memory")
; #define PG8_BAR __builtin_amdgcn_s_barrier()
; #define PG8_SCHED __builtin_amdgcn_sched_barrier(0)
; template <class Epi, class Sched, bool ALIGN_EPI = false, bool SP2 = false, bool ABLK = false, bool BBLK = false>
; __device__ __forceinline__ void gemm_phase(PG8_LAS unsigned char* lds, const Gemm g, const Sched& S, const Epi& E) {
;     ...
;             PG8_LDA(At, 0, 1); PG8_STAGE(PG8_SB(0, 0), b2, voffB); PG8_STAGE(PG8_SB(0, 1), b2 + hstepB, voffB); PG8_STAGE(PG8_SA(0, 0), a2, voffA);
;             PG8_WAIT_V(8); PG8_WAIT_L(0); PG8_BAR; PG8_MMA(1, 0, At, B0); PG8_MMA(1, 1, At, B1); PG8_BAR; PG8_SCHED;
;             PG8_LDB(B0, 1, 0); PG8_LDB(B1, 1, 1); PG8_SCHED; PG8_LDA(At, 1, 0); PG8_STAGE(PG8_SA(0, 1), a2 + hstepA, voffA);
;             PG8_WAIT_V(8); PG8_WAIT_L(0); PG8_BAR; PG8_MMA(0, 0, At, B0); PG8_MMA(0, 1, At, B1); PG8_BAR; PG8_SCHED;
;             PG8_LDA(At, 1, 1); PG8_STAGE(PG8_SB(1, 0), b3, voffB); PG8_STAGE(PG8_SB(1, 1), b3 + hstepB, voffB); PG8_STAGE(PG8_SA(1, 0), a3, voffA);
	s_add_i32 s40, s40, s2
	v_lshl_add_u64 v[202:203], s[34:35], 0, v[186:187]
	s_mov_b32 m0, s40
	ds_read_b128 v[162:165], v207 offset:16384
	ds_read_b128 v[166:169], v207 offset:17408
	ds_read_b128 v[170:173], v207 offset:18432
	ds_read_b128 v[174:177], v207 offset:19456
	ds_read_b128 v[198:201], v207 offset:20480
	ds_read_b128 v[208:211], v207 offset:21504
	ds_read_b128 v[212:215], v207 offset:22528
	ds_read_b128 v[216:219], v207 offset:23552
	global_load_lds_dwordx4 v[202:203], off
	s_add_i32 m0, s40, 0x2000
	s_add_u32 s40, s34, 0x4000
	v_lshl_add_u64 v[202:203], s[34:35], 0, v[182:183]
	s_addc_u32 s41, s35, 0
	s_add_i32 s44, s44, s2
	global_load_lds_dwordx4 v[202:203], off
	v_lshl_add_u64 v[202:203], s[40:41], 0, v[186:187]
	s_mov_b32 m0, s44
	s_nop 0
	global_load_lds_dwordx4 v[202:203], off
	v_lshl_add_u64 v[202:203], s[40:41], 0, v[182:183]
	s_add_i32 m0, s44, 0x2000
	s_nop 0
	global_load_lds_dwordx4 v[202:203], off
	v_lshl_add_u64 v[202:203], s[36:37], 0, v[178:179]
	s_mov_b32 m0, s3
	s_nop 0
	global_load_lds_dwordx4 v[202:203], off
	v_lshl_add_u64 v[202:203], s[36:37], 0, v[180:181]
	s_mov_b32 m0, s42
	s_nop 0
	global_load_lds_dwordx4 v[202:203], off
	s_waitcnt vmcnt(8)
	s_waitcnt lgkmcnt(0)
	s_barrier
	s_setprio 1
	s_waitcnt lgkmcnt(0)
	v_mfma_f32_16x16x32_bf16 v[106:109], v[130:133], v[162:165], v[106:109]
	v_mfma_f32_16x16x32_bf16 v[110:113], v[138:141], v[162:165], v[110:113]
	v_mfma_f32_16x16x32_bf16 v[122:125], v[130:133], v[170:173], v[122:125]
	v_mfma_f32_16x16x32_bf16 v[126:129], v[138:141], v[170:173], v[126:129]
	v_mfma_f32_16x16x32_bf16 v[94:97], v[130:133], v[198:201], v[94:97]
	v_mfma_f32_16x16x32_bf16 v[90:93], v[138:141], v[198:201], v[90:93]
	v_mfma_f32_16x16x32_bf16 v[38:41], v[130:133], v[212:215], v[38:41]
	v_mfma_f32_16x16x32_bf16 v[34:37], v[138:141], v[212:215], v[34:37]
	v_mfma_f32_16x16x32_bf16 v[106:109], v[134:137], v[166:169], v[106:109]
	v_mfma_f32_16x16x32_bf16 v[110:113], v[142:145], v[166:169], v[110:113]
	v_mfma_f32_16x16x32_bf16 v[122:125], v[134:137], v[174:177], v[122:125]
	v_mfma_f32_16x16x32_bf16 v[126:129], v[142:145], v[174:177], v[126:129]
	v_mfma_f32_16x16x32_bf16 v[94:97], v[134:137], v[208:211], v[94:97]
	v_mfma_f32_16x16x32_bf16 v[90:93], v[142:145], v[208:211], v[90:93]
	v_mfma_f32_16x16x32_bf16 v[38:41], v[134:137], v[216:219], v[38:41]
	v_mfma_f32_16x16x32_bf16 v[34:37], v[142:145], v[216:219], v[34:37]
	s_setprio 0
	s_setprio 1
	v_mfma_f32_16x16x32_bf16 v[114:117], v[146:149], v[162:165], v[114:117]
	v_mfma_f32_16x16x32_bf16 v[118:121], v[154:157], v[162:165], v[118:121]
	v_mfma_f32_16x16x32_bf16 v[102:105], v[146:149], v[170:173], v[102:105]
	v_mfma_f32_16x16x32_bf16 v[98:101], v[154:157], v[170:173], v[98:101]
	v_mfma_f32_16x16x32_bf16 v[62:65], v[146:149], v[198:201], v[62:65]
	v_mfma_f32_16x16x32_bf16 v[58:61], v[154:157], v[198:201], v[58:61]
	v_mfma_f32_16x16x32_bf16 v[14:17], v[146:149], v[212:215], v[14:17]
	v_mfma_f32_16x16x32_bf16 v[2:5], v[154:157], v[212:215], v[2:5]
	v_mfma_f32_16x16x32_bf16 v[114:117], v[150:153], v[166:169], v[114:117]
	v_mfma_f32_16x16x32_bf16 v[118:121], v[158:161], v[166:169], v[118:121]
	v_mfma_f32_16x16x32_bf16 v[102:105], v[150:153], v[174:177], v[102:105]
	v_mfma_f32_16x16x32_bf16 v[98:101], v[158:161], v[174:177], v[98:101]
	v_mfma_f32_16x16x32_bf16 v[62:65], v[150:153], v[208:211], v[62:65]
	v_mfma_f32_16x16x32_bf16 v[58:61], v[158:161], v[208:211], v[58:61]
	v_mfma_f32_16x16x32_bf16 v[14:17], v[150:153], v[216:219], v[14:17]
	v_mfma_f32_16x16x32_bf16 v[2:5], v[158:161], v[216:219], v[2:5]
	s_setprio 0
	s_barrier
.Lmid_305:
	s_add_i32 s40, 0, 0x18000
	s_add_i32 s41, 0, 0x1c000
	v_add_u32_e32 v142, s40, v206
	v_add_u32_e32 v158, s41, v206
	ds_read_b128 v[130:133], v142
	ds_read_b128 v[134:137], v142 offset:1024
	ds_read_b128 v[138:141], v142 offset:2048
	ds_read_b128 v[142:145], v142 offset:3072
	ds_read_b128 v[146:149], v158
	ds_read_b128 v[150:153], v158 offset:1024
	ds_read_b128 v[154:157], v158 offset:2048
	ds_read_b128 v[158:161], v158 offset:3072
	s_add_u32 s36, s36, 0x4000
	s_addc_u32 s37, s37, 0
	s_mov_b32 m0, s43
	v_lshl_add_u64 v[202:203], s[36:37], 0, v[178:179]
	ds_read_b128 v[162:165], v207 offset:32768
	ds_read_b128 v[166:169], v207 offset:33792
	ds_read_b128 v[170:173], v207 offset:34816
	ds_read_b128 v[174:177], v207 offset:35840
	ds_read_b128 v[198:201], v207 offset:36864
	ds_read_b128 v[208:211], v207 offset:37888
	ds_read_b128 v[212:215], v207 offset:38912
	ds_read_b128 v[216:219], v207 offset:39936
	global_load_lds_dwordx4 v[202:203], off
	v_lshl_add_u64 v[202:203], s[36:37], 0, v[180:181]
	s_mov_b32 m0, s53
	s_nop 0
	global_load_lds_dwordx4 v[202:203], off
	s_waitcnt vmcnt(8)
	s_waitcnt lgkmcnt(0)
	s_barrier
; #define PG8_STAGE(bufoff, gbase, voff) do { _Pragma("unroll") for (int _i = 0; _i < 2; ++_i) \
;         __builtin_amdgcn_global_load_lds((const unsigned*)((const char*)(gbase) + (voff)[_i]), (PG8_LAS unsigned*)(lds + (bufoff) + ldsw + _i * 8192), 16, 0, 0); } while (0)
; #define PG8_LDA(dst, b, h) do { _Pragma("unroll") for (int m = 0; m < 4; ++m) _Pragma("unroll") for (int k = 0; k < 2; ++k) dst[m][k] = *(const PG8_LAS bf16x8*)(lds + PG8_SA(b, h) + aoff + m * 2048 + k * 1024); } while (0)
; #define PG8_LDB(dst, b, h) do { _Pragma("unroll") for (int n = 0; n < 2; ++n) _Pragma("unroll") for (int k = 0; k < 2; ++k) dst[n][k] = *(const PG8_LAS bf16x8*)(lds + PG8_SB(b, h) + boff + n * 2048 + k * 1024); } while (0)
; #define PG8_MMA(ai, bj, At, Bt) do { __builtin_amdgcn_s_setprio(1); _Pragma("unroll") for (int m = 0; m < 4; ++m) _Pragma("unroll") for (int n = 0; n < 2; ++n) _Pragma("unroll") for (int k = 0; k < 2; ++k) \
;         acc[ai][bj][m][n] = __builtin_amdgcn_mfma_f32_16x16x32_bf16(Bt[n][k], At[m][k], acc[ai][bj][m][n], 0, 0, 0); __builtin_amdgcn_s_setprio(0); } while (0)
; #define PG8_WAIT_V(n) asm volatile("s_waitcnt vmcnt(" #n ")" ::: "memory")
; #define PG8_BAR __builtin_amdgcn_s_barrier()
; template <class Epi, class Sched, bool ALIGN_EPI = false, bool SP2 = false, bool ABLK = false, bool BBLK = false>
; __device__ __forceinline__ void gemm_phase(PG8_LAS unsigned char* lds, const Gemm g, const Sched& S, const Epi& E) {
;     ...
;         for (int t = 0; t < nt; t += 2) {
;             const bool last = (t == nt - 2);
;             const char* a1 = cA + (size_t)(t + 1) * kstepA;
;             const char* a2 = last ? nA : cA + (size_t)(t + 2) * kstepA; const char* b2 = last ? nB : cB + (size_t)(t + 2) * kstepB;
;             const char* a3 = a2 + kstepA; const char* b3 = b2 + kstepB;
;             if (last && has_next) S.a_ready(nxt);
;     ...
;             PG8_LDB(B0, 1, 0); PG8_LDB(B1, 1, 1); PG8_SCHED; PG8_LDA(At, 1, 0); PG8_STAGE(PG8_SA(0, 1), a2 + hstepA, voffA);
;             PG8_WAIT_V(8); PG8_WAIT_L(0); PG8_BAR; PG8_MMA(0, 0, At, B0); PG8_MMA(0, 1, At, B1); PG8_BAR; PG8_SCHED;
;             PG8_LDA(At, 1, 1); PG8_STAGE(PG8_SB(1, 0), b3, voffB); PG8_STAGE(PG8_SB(1, 1), b3 + hstepB, voffB); PG8_STAGE(PG8_SA(1, 0), a3, voffA);
;             PG8_WAIT_V(8); PG8_WAIT_L(0); PG8_BAR; PG8_MMA(1, 0, At, B0); PG8_MMA(1, 1, At, B1); PG8_BAR; PG8_SCHED;
	s_setprio 1
	s_waitcnt lgkmcnt(0)
	v_mfma_f32_16x16x32_bf16 v[30:33], v[130:133], v[162:165], v[30:33]
	v_mfma_f32_16x16x32_bf16 v[22:25], v[138:141], v[162:165], v[22:25]
	v_mfma_f32_16x16x32_bf16 v[10:13], v[130:133], v[170:173], v[10:13]
	v_mfma_f32_16x16x32_bf16 v[6:9], v[138:141], v[170:173], v[6:9]
	v_mfma_f32_16x16x32_bf16 v[50:53], v[130:133], v[198:201], v[50:53]
	v_mfma_f32_16x16x32_bf16 v[54:57], v[138:141], v[198:201], v[54:57]
	v_mfma_f32_16x16x32_bf16 v[74:77], v[130:133], v[212:215], v[74:77]
	v_mfma_f32_16x16x32_bf16 v[78:81], v[138:141], v[212:215], v[78:81]
	v_mfma_f32_16x16x32_bf16 v[30:33], v[134:137], v[166:169], v[30:33]
	v_mfma_f32_16x16x32_bf16 v[22:25], v[142:145], v[166:169], v[22:25]
	v_mfma_f32_16x16x32_bf16 v[10:13], v[134:137], v[174:177], v[10:13]
	v_mfma_f32_16x16x32_bf16 v[6:9], v[142:145], v[174:177], v[6:9]
	v_mfma_f32_16x16x32_bf16 v[50:53], v[134:137], v[208:211], v[50:53]
	v_mfma_f32_16x16x32_bf16 v[54:57], v[142:145], v[208:211], v[54:57]
	v_mfma_f32_16x16x32_bf16 v[74:77], v[134:137], v[216:219], v[74:77]
	v_mfma_f32_16x16x32_bf16 v[78:81], v[142:145], v[216:219], v[78:81]
	s_setprio 0
	s_setprio 1
	v_mfma_f32_16x16x32_bf16 v[26:29], v[146:149], v[162:165], v[26:29]
	v_mfma_f32_16x16x32_bf16 v[18:21], v[154:157], v[162:165], v[18:21]
	v_mfma_f32_16x16x32_bf16 v[42:45], v[146:149], v[170:173], v[42:45]
	v_mfma_f32_16x16x32_bf16 v[46:49], v[154:157], v[170:173], v[46:49]
	v_mfma_f32_16x16x32_bf16 v[66:69], v[146:149], v[198:201], v[66:69]
	v_mfma_f32_16x16x32_bf16 v[70:73], v[154:157], v[198:201], v[70:73]
	v_mfma_f32_16x16x32_bf16 v[82:85], v[146:149], v[212:215], v[82:85]
	v_mfma_f32_16x16x32_bf16 v[86:89], v[154:157], v[212:215], v[86:89]
	v_mfma_f32_16x16x32_bf16 v[26:29], v[150:153], v[166:169], v[26:29]
	v_mfma_f32_16x16x32_bf16 v[18:21], v[158:161], v[166:169], v[18:21]
	v_mfma_f32_16x16x32_bf16 v[42:45], v[150:153], v[174:177], v[42:45]
	v_mfma_f32_16x16x32_bf16 v[46:49], v[158:161], v[174:177], v[46:49]
	v_mfma_f32_16x16x32_bf16 v[66:69], v[150:153], v[208:211], v[66:69]
	v_mfma_f32_16x16x32_bf16 v[70:73], v[158:161], v[208:211], v[70:73]
	v_mfma_f32_16x16x32_bf16 v[82:85], v[150:153], v[216:219], v[82:85]
	v_mfma_f32_16x16x32_bf16 v[86:89], v[158:161], v[216:219], v[86:89]
	s_setprio 0
	s_barrier
	s_add_u32 s36, s34, 0x8000
	s_addc_u32 s37, s35, 0
	s_add_i32 s40, s40, s2
	v_lshl_add_u64 v[202:203], s[36:37], 0, v[186:187]
	s_mov_b32 m0, s40
	ds_read_b128 v[162:165], v207 offset:49152
	ds_read_b128 v[166:169], v207 offset:50176
	ds_read_b128 v[170:173], v207 offset:51200
	ds_read_b128 v[174:177], v207 offset:52224
	ds_read_b128 v[198:201], v207 offset:53248
	ds_read_b128 v[208:211], v207 offset:54272
	ds_read_b128 v[212:215], v207 offset:55296
	ds_read_b128 v[216:219], v207 offset:56320
	global_load_lds_dwordx4 v[202:203], off
	s_add_i32 m0, s40, 0x2000
	s_add_u32 s34, s34, 0xc000
	v_lshl_add_u64 v[202:203], s[36:37], 0, v[182:183]
	s_addc_u32 s35, s35, 0
	s_add_i32 s36, s41, s2
	global_load_lds_dwordx4 v[202:203], off
	v_lshl_add_u64 v[202:203], s[34:35], 0, v[186:187]
	s_mov_b32 m0, s36
	s_nop 0
	global_load_lds_dwordx4 v[202:203], off
	v_lshl_add_u64 v[202:203], s[34:35], 0, v[182:183]
	s_add_i32 m0, s36, 0x2000
	s_nop 0
	global_load_lds_dwordx4 v[202:203], off
	v_lshl_add_u64 v[202:203], s[8:9], 0, v[178:179]
	s_mov_b32 m0, s92
	s_nop 0
	global_load_lds_dwordx4 v[202:203], off
	v_lshl_add_u64 v[202:203], s[8:9], 0, v[180:181]
	s_mov_b32 m0, s93
	s_nop 0
	global_load_lds_dwordx4 v[202:203], off
	s_waitcnt vmcnt(8)
	s_waitcnt lgkmcnt(0)
	s_barrier
	s_setprio 1
	s_waitcnt lgkmcnt(0)
	v_mfma_f32_16x16x32_bf16 v[106:109], v[130:133], v[162:165], v[106:109]
	v_mfma_f32_16x16x32_bf16 v[110:113], v[138:141], v[162:165], v[110:113]
	v_mfma_f32_16x16x32_bf16 v[122:125], v[130:133], v[170:173], v[122:125]
	v_mfma_f32_16x16x32_bf16 v[126:129], v[138:141], v[170:173], v[126:129]
	v_mfma_f32_16x16x32_bf16 v[94:97], v[130:133], v[198:201], v[94:97]
	v_mfma_f32_16x16x32_bf16 v[90:93], v[138:141], v[198:201], v[90:93]
	v_mfma_f32_16x16x32_bf16 v[38:41], v[130:133], v[212:215], v[38:41]
	v_mfma_f32_16x16x32_bf16 v[34:37], v[138:141], v[212:215], v[34:37]
	v_mfma_f32_16x16x32_bf16 v[106:109], v[134:137], v[166:169], v[106:109]
	v_mfma_f32_16x16x32_bf16 v[110:113], v[142:145], v[166:169], v[110:113]
	v_mfma_f32_16x16x32_bf16 v[122:125], v[134:137], v[174:177], v[122:125]
	v_mfma_f32_16x16x32_bf16 v[126:129], v[142:145], v[174:177], v[126:129]
	v_mfma_f32_16x16x32_bf16 v[94:97], v[134:137], v[208:211], v[94:97]
	v_mfma_f32_16x16x32_bf16 v[90:93], v[142:145], v[208:211], v[90:93]
	v_mfma_f32_16x16x32_bf16 v[38:41], v[134:137], v[216:219], v[38:41]
	v_mfma_f32_16x16x32_bf16 v[34:37], v[142:145], v[216:219], v[34:37]
	s_setprio 0
	s_setprio 1
	v_mfma_f32_16x16x32_bf16 v[114:117], v[146:149], v[162:165], v[114:117]
	v_mfma_f32_16x16x32_bf16 v[118:121], v[154:157], v[162:165], v[118:121]
	v_mfma_f32_16x16x32_bf16 v[102:105], v[146:149], v[170:173], v[102:105]
	v_mfma_f32_16x16x32_bf16 v[98:101], v[154:157], v[170:173], v[98:101]
	v_mfma_f32_16x16x32_bf16 v[62:65], v[146:149], v[198:201], v[62:65]
	v_mfma_f32_16x16x32_bf16 v[58:61], v[154:157], v[198:201], v[58:61]
	v_mfma_f32_16x16x32_bf16 v[14:17], v[146:149], v[212:215], v[14:17]
	v_mfma_f32_16x16x32_bf16 v[2:5], v[154:157], v[212:215], v[2:5]
	v_mfma_f32_16x16x32_bf16 v[114:117], v[150:153], v[166:169], v[114:117]
	v_mfma_f32_16x16x32_bf16 v[118:121], v[158:161], v[166:169], v[118:121]
	v_mfma_f32_16x16x32_bf16 v[102:105], v[150:153], v[174:177], v[102:105]
	v_mfma_f32_16x16x32_bf16 v[98:101], v[158:161], v[174:177], v[98:101]
	v_mfma_f32_16x16x32_bf16 v[62:65], v[150:153], v[208:211], v[62:65]
	v_mfma_f32_16x16x32_bf16 v[58:61], v[158:161], v[208:211], v[58:61]
	v_mfma_f32_16x16x32_bf16 v[14:17], v[150:153], v[216:219], v[14:17]
	v_mfma_f32_16x16x32_bf16 v[2:5], v[158:161], v[216:219], v[2:5]
	s_setprio 0
	s_barrier
	s_add_i32 s33, s33, 2
	s_add_u32 s0, s0, 0x10000
	s_addc_u32 s1, s1, 0
	s_add_u32 s29, s29, 0x10000
	s_addc_u32 s31, s31, 0
	s_cmpk_gt_u32 s33, 0x55
	s_cbranch_scc0 .LBB0_305
	s_and_b64 vcc, exec, s[18:19]
	s_cbranch_vccz .LBB0_308
	s_barrier

; #define PG8_STAGE(bufoff, gbase, voff) do { _Pragma("unroll") for (int _i = 0; _i < 2; ++_i) \
;         __builtin_amdgcn_global_load_lds((const unsigned*)((const char*)(gbase) + (voff)[_i]), (PG8_LAS unsigned*)(lds + (bufoff) + ldsw + _i * 8192), 16, 0, 0); } while (0)
; #define PG8_LDA(dst, b, h) do { _Pragma("unroll") for (int m = 0; m < 4; ++m) _Pragma("unroll") for (int k = 0; k < 2; ++k) dst[m][k] = *(const PG8_LAS bf16x8*)(lds + PG8_SA(b, h) + aoff + m * 2048 + k * 1024); } while (0)
; #define PG8_LDB(dst, b, h) do { _Pragma("unroll") for (int n = 0; n < 2; ++n) _Pragma("unroll") for (int k = 0; k < 2; ++k) dst[n][k] = *(const PG8_LAS bf16x8*)(lds + PG8_SB(b, h) + boff + n * 2048 + k * 1024); } while (0)
; #define PG8_WAIT_V(n) asm volatile("s_waitcnt vmcnt(" #n ")" ::: "memory")
; #define PG8_WAIT_L(n) asm volatile("s_waitcnt lgkmcnt(" #n ")" ::: "memory")
; #define PG8_BAR __builtin_amdgcn_s_barrier()
; template <class Epi, class Sched, bool ALIGN_EPI = false, bool SP2 = false, bool ABLK = false, bool BBLK = false>
; __device__ __forceinline__ void gemm_phase(PG8_LAS unsigned char* lds, const Gemm g, const Sched& S, const Epi& E) {
;     ...
;     for (;;) {
;         const bool has_next = S.next(ui + 1, nxt);
;         const char* nA = has_next ? (const char*)g.A + (size_t)nxt.pm * tstepA : cA; const char* nB = has_next ? (const char*)g.Bt + (size_t)nxt.pn * tstepB : cB;
;         for (int t = 0; t < nt; t += 2) {
;             const bool last = (t == nt - 2);
;             const char* a1 = cA + (size_t)(t + 1) * kstepA;
;             const char* a2 = last ? nA : cA + (size_t)(t + 2) * kstepA; const char* b2 = last ? nB : cB + (size_t)(t + 2) * kstepB;
;             const char* a3 = a2 + kstepA; const char* b3 = b2 + kstepB;
;             if (last && has_next) S.a_ready(nxt);
;             if constexpr (SP2) {
;             PG8_LDB(B0, 0, 0); PG8_LDB(B1, 0, 1); PG8_SCHED; PG8_LDA(At, 0, 0); PG8_STAGE(PG8_SA(1, 1), a1 + hstepA, voffA);
;             PG8_WAIT_V(8); PG8_WAIT_L(0); PG8_BAR; PG8_MMA(0, 0, At, B0); PG8_MMA(0, 1, At, B1); PG8_BAR; PG8_SCHED;
;             PG8_LDA(At, 0, 1); PG8_STAGE(PG8_SB(0, 0), b2, voffB); PG8_STAGE(PG8_SB(0, 1), b2 + hstepB, voffB); PG8_STAGE(PG8_SA(0, 0), a2, voffA);
;             PG8_WAIT_V(8); PG8_WAIT_L(0); PG8_BAR; PG8_MMA(1, 0, At, B0); PG8_MMA(1, 1, At, B1); PG8_BAR; PG8_SCHED;
.LBB0_593:
	s_ashr_i32 s21, s20, 31
	s_lshl_b64 s[24:25], s[20:21], 20
	s_add_u32 s24, s51, s24
	s_addc_u32 s25, s53, s25
	s_and_b64 s[26:27], s[6:7], exec
	s_cselect_b32 s9, s25, s1
	s_cselect_b32 s16, s24, s0
	s_ashr_i32 s23, s22, 31
	s_lshl_b64 s[26:27], s[22:23], 20
	s_add_u32 s26, s44, s26
	s_addc_u32 s27, s45, s27
	s_and_b64 s[34:35], s[6:7], exec
	s_cselect_b32 s21, s27, s31
	s_cselect_b32 s23, s26, s30
	s_add_u32 s0, s0, 0xc000
	s_addc_u32 s1, s1, 0
	s_add_u32 s29, s30, 0x10000
	v_mov_b32_e32 v2, 0
	s_addc_u32 s40, s31, 0
	s_mov_b32 s41, -2
	v_mov_b32_e32 v3, v2
	v_mov_b32_e32 v4, v2
	v_mov_b32_e32 v5, v2
	v_mov_b32_e32 v6, v2
	v_mov_b32_e32 v7, v2
	v_mov_b32_e32 v8, v2
	v_mov_b32_e32 v9, v2
	s_waitcnt vmcnt(0)
	s_add_u32 s30, s0, 0x4000
	s_addc_u32 s31, s1, 0
	s_cmp_eq_u32 s41, 28
	s_cselect_b32 s36, s16, s30
	s_cselect_b32 s37, s9, s31
	s_cselect_b32 s34, s23, s29
	s_cselect_b32 s35, s21, s40
	s_add_u32 s30, s36, 0x8000
	s_addc_u32 s31, s37, 0
	s_add_i32 s60, 0, 0x10000
	s_add_i32 s75, 0, 0x14000
	v_add_u32_e32 v142, s60, v169
	v_add_u32_e32 v171, s75, v169
	ds_read_b128 v[130:133], v142
	ds_read_b128 v[134:137], v142 offset:1024
	ds_read_b128 v[138:141], v142 offset:2048
	ds_read_b128 v[142:145], v142 offset:3072
	ds_read_b128 v[160:163], v171
	ds_read_b128 v[164:167], v171 offset:1024
	ds_read_b128 v[172:175], v171 offset:2048
	ds_read_b128 v[176:179], v171 offset:3072
	v_lshl_add_u64 v[184:185], s[0:1], 0, v[156:157]
	s_add_i32 m0, s83, 0xc000
	ds_read_b128 v[180:183], v170
	ds_read_b128 v[196:199], v170 offset:1024
	ds_read_b128 v[200:203], v170 offset:2048
	ds_read_b128 v[204:207], v170 offset:3072
	ds_read_b128 v[208:211], v170 offset:4096
	ds_read_b128 v[212:215], v170 offset:5120
	ds_read_b128 v[216:219], v170 offset:6144
	ds_read_b128 v[220:223], v170 offset:7168
	global_load_lds_dwordx4 v[184:185], off
	v_lshl_add_u64 v[184:185], s[0:1], 0, v[158:159]
	s_add_i32 m0, s83, 0xe000
	s_nop 0
	global_load_lds_dwordx4 v[184:185], off
	s_waitcnt vmcnt(8)
	s_waitcnt lgkmcnt(0)
	s_barrier
	s_setprio 1
	s_waitcnt lgkmcnt(0)
	v_mfma_f32_16x16x32_bf16 v[126:129], v[130:133], v[180:183], 0
	v_mfma_f32_16x16x32_bf16 v[122:125], v[138:141], v[180:183], 0
	v_mfma_f32_16x16x32_bf16 v[110:113], v[130:133], v[200:203], 0
	v_mfma_f32_16x16x32_bf16 v[106:109], v[138:141], v[200:203], 0
	v_mfma_f32_16x16x32_bf16 v[94:97], v[130:133], v[208:211], 0
	v_mfma_f32_16x16x32_bf16 v[90:93], v[138:141], v[208:211], 0
	v_mfma_f32_16x16x32_bf16 v[78:81], v[130:133], v[216:219], 0
	v_mfma_f32_16x16x32_bf16 v[74:77], v[138:141], v[216:219], 0
	v_mfma_f32_16x16x32_bf16 v[126:129], v[134:137], v[196:199], v[126:129]
	v_mfma_f32_16x16x32_bf16 v[122:125], v[142:145], v[196:199], v[122:125]
	v_mfma_f32_16x16x32_bf16 v[110:113], v[134:137], v[204:207], v[110:113]
	v_mfma_f32_16x16x32_bf16 v[106:109], v[142:145], v[204:207], v[106:109]
	v_mfma_f32_16x16x32_bf16 v[94:97], v[134:137], v[212:215], v[94:97]
	v_mfma_f32_16x16x32_bf16 v[90:93], v[142:145], v[212:215], v[90:93]
	v_mfma_f32_16x16x32_bf16 v[78:81], v[134:137], v[220:223], v[78:81]
	v_mfma_f32_16x16x32_bf16 v[74:77], v[142:145], v[220:223], v[74:77]
	s_setprio 0
	s_setprio 1
	v_mfma_f32_16x16x32_bf16 v[118:121], v[160:163], v[180:183], 0
	v_mfma_f32_16x16x32_bf16 v[114:117], v[172:175], v[180:183], 0
	v_mfma_f32_16x16x32_bf16 v[102:105], v[160:163], v[200:203], 0
	v_mfma_f32_16x16x32_bf16 v[98:101], v[172:175], v[200:203], 0
	v_mfma_f32_16x16x32_bf16 v[86:89], v[160:163], v[208:211], 0
	v_mfma_f32_16x16x32_bf16 v[82:85], v[172:175], v[208:211], 0
	v_mfma_f32_16x16x32_bf16 v[70:73], v[160:163], v[216:219], 0
	v_mfma_f32_16x16x32_bf16 v[66:69], v[172:175], v[216:219], 0
	v_mfma_f32_16x16x32_bf16 v[118:121], v[164:167], v[196:199], v[118:121]
	v_mfma_f32_16x16x32_bf16 v[114:117], v[176:179], v[196:199], v[114:117]
	v_mfma_f32_16x16x32_bf16 v[102:105], v[164:167], v[204:207], v[102:105]
	v_mfma_f32_16x16x32_bf16 v[98:101], v[176:179], v[204:207], v[98:101]
	v_mfma_f32_16x16x32_bf16 v[86:89], v[164:167], v[212:215], v[86:89]
	v_mfma_f32_16x16x32_bf16 v[82:85], v[176:179], v[212:215], v[82:85]
	v_mfma_f32_16x16x32_bf16 v[70:73], v[164:167], v[220:223], v[70:73]
	v_mfma_f32_16x16x32_bf16 v[66:69], v[176:179], v[220:223], v[66:69]
	s_setprio 0
	s_barrier
	s_add_i32 s60, s60, s81
	v_lshl_add_u64 v[184:185], s[34:35], 0, v[148:149]
	s_mov_b32 m0, s60
	ds_read_b128 v[180:183], v170 offset:16384
	ds_read_b128 v[196:199], v170 offset:17408
	ds_read_b128 v[200:203], v170 offset:18432
	ds_read_b128 v[204:207], v170 offset:19456
	ds_read_b128 v[208:211], v170 offset:20480
	ds_read_b128 v[212:215], v170 offset:21504
	ds_read_b128 v[216:219], v170 offset:22528
	ds_read_b128 v[220:223], v170 offset:23552
	global_load_lds_dwordx4 v[184:185], off
	s_add_i32 m0, s60, 0x2000
	s_add_u32 s60, s34, 0x4000
	v_lshl_add_u64 v[184:185], s[34:35], 0, v[152:153]
	s_addc_u32 s61, s35, 0
	s_add_i32 s75, s75, s81
	global_load_lds_dwordx4 v[184:185], off
	v_lshl_add_u64 v[184:185], s[60:61], 0, v[148:149]
	s_mov_b32 m0, s75
	s_nop 0
	global_load_lds_dwordx4 v[184:185], off
	v_lshl_add_u64 v[184:185], s[60:61], 0, v[152:153]
	s_add_i32 m0, s75, 0x2000
	s_nop 0
	global_load_lds_dwordx4 v[184:185], off
	v_lshl_add_u64 v[184:185], s[36:37], 0, v[146:147]
	s_mov_b32 m0, s83
	s_nop 0
	global_load_lds_dwordx4 v[184:185], off
	v_lshl_add_u64 v[184:185], s[36:37], 0, v[150:151]
	s_mov_b32 m0, s84
	s_nop 0
	global_load_lds_dwordx4 v[184:185], off
	s_waitcnt vmcnt(8)
	s_waitcnt lgkmcnt(0)
	s_barrier
; #define PG8_STAGE(bufoff, gbase, voff) do { _Pragma("unroll") for (int _i = 0; _i < 2; ++_i) \
;         __builtin_amdgcn_global_load_lds((const unsigned*)((const char*)(gbase) + (voff)[_i]), (PG8_LAS unsigned*)(lds + (bufoff) + ldsw + _i * 8192), 16, 0, 0); } while (0)
; #define PG8_LDA(dst, b, h) do { _Pragma("unroll") for (int m = 0; m < 4; ++m) _Pragma("unroll") for (int k = 0; k < 2; ++k) dst[m][k] = *(const PG8_LAS bf16x8*)(lds + PG8_SA(b, h) + aoff + m * 2048 + k * 1024); } while (0)
; #define PG8_LDB(dst, b, h) do { _Pragma("unroll") for (int n = 0; n < 2; ++n) _Pragma("unroll") for (int k = 0; k < 2; ++k) dst[n][k] = *(const PG8_LAS bf16x8*)(lds + PG8_SB(b, h) + boff + n * 2048 + k * 1024); } while (0)
; #define PG8_MMA(ai, bj, At, Bt) do { __builtin_amdgcn_s_setprio(1); _Pragma("unroll") for (int m = 0; m < 4; ++m) _Pragma("unroll") for (int n = 0; n < 2; ++n) _Pragma("unroll") for (int k = 0; k < 2; ++k) \
;         acc[ai][bj][m][n] = __builtin_amdgcn_mfma_f32_16x16x32_bf16(Bt[n][k], At[m][k], acc[ai][bj][m][n], 0, 0, 0); __builtin_amdgcn_s_setprio(0); } while (0)
; #define PG8_WAIT_V(n) asm volatile("s_waitcnt vmcnt(" #n ")" ::: "memory")
; template <class Epi, class Sched, bool ALIGN_EPI = false, bool SP2 = false, bool ABLK = false, bool BBLK = false>
; __device__ __forceinline__ void gemm_phase(PG8_LAS unsigned char* lds, const Gemm g, const Sched& S, const Epi& E) {
;     ...
;         for (int t = 0; t < nt; t += 2) {
;             const bool last = (t == nt - 2);
;             const char* a1 = cA + (size_t)(t + 1) * kstepA;
;             const char* a2 = last ? nA : cA + (size_t)(t + 2) * kstepA; const char* b2 = last ? nB : cB + (size_t)(t + 2) * kstepB;
;             const char* a3 = a2 + kstepA; const char* b3 = b2 + kstepB;
;             if (last && has_next) S.a_ready(nxt);
;             if constexpr (SP2) {
;             PG8_LDB(B0, 0, 0); PG8_LDB(B1, 0, 1); PG8_SCHED; PG8_LDA(At, 0, 0); PG8_STAGE(PG8_SA(1, 1), a1 + hstepA, voffA);
;             PG8_WAIT_V(8); PG8_WAIT_L(0); PG8_BAR; PG8_MMA(0, 0, At, B0); PG8_MMA(0, 1, At, B1); PG8_BAR; PG8_SCHED;
;             PG8_LDA(At, 0, 1); PG8_STAGE(PG8_SB(0, 0), b2, voffB); PG8_STAGE(PG8_SB(0, 1), b2 + hstepB, voffB); PG8_STAGE(PG8_SA(0, 0), a2, voffA);
;             PG8_WAIT_V(8); PG8_WAIT_L(0); PG8_BAR; PG8_MMA(1, 0, At, B0); PG8_MMA(1, 1, At, B1); PG8_BAR; PG8_SCHED;
	s_setprio 1
	s_waitcnt lgkmcnt(0)
	v_mfma_f32_16x16x32_bf16 v[62:65], v[130:133], v[180:183], 0
	v_mfma_f32_16x16x32_bf16 v[58:61], v[138:141], v[180:183], 0
	v_mfma_f32_16x16x32_bf16 v[46:49], v[130:133], v[200:203], 0
	v_mfma_f32_16x16x32_bf16 v[42:45], v[138:141], v[200:203], 0
	v_mfma_f32_16x16x32_bf16 v[30:33], v[130:133], v[208:211], 0
	v_mfma_f32_16x16x32_bf16 v[26:29], v[138:141], v[208:211], 0
	v_mfma_f32_16x16x32_bf16 v[14:17], v[130:133], v[216:219], 0
	v_mfma_f32_16x16x32_bf16 v[10:13], v[138:141], v[216:219], 0
	v_mfma_f32_16x16x32_bf16 v[62:65], v[134:137], v[196:199], v[62:65]
	v_mfma_f32_16x16x32_bf16 v[58:61], v[142:145], v[196:199], v[58:61]
	v_mfma_f32_16x16x32_bf16 v[46:49], v[134:137], v[204:207], v[46:49]
	v_mfma_f32_16x16x32_bf16 v[42:45], v[142:145], v[204:207], v[42:45]
	v_mfma_f32_16x16x32_bf16 v[30:33], v[134:137], v[212:215], v[30:33]
	v_mfma_f32_16x16x32_bf16 v[26:29], v[142:145], v[212:215], v[26:29]
	v_mfma_f32_16x16x32_bf16 v[14:17], v[134:137], v[220:223], v[14:17]
	v_mfma_f32_16x16x32_bf16 v[10:13], v[142:145], v[220:223], v[10:13]
	s_setprio 0
	s_setprio 1
	v_mfma_f32_16x16x32_bf16 v[54:57], v[160:163], v[180:183], 0
	v_mfma_f32_16x16x32_bf16 v[50:53], v[172:175], v[180:183], 0
	v_mfma_f32_16x16x32_bf16 v[38:41], v[160:163], v[200:203], 0
	v_mfma_f32_16x16x32_bf16 v[34:37], v[172:175], v[200:203], 0
	v_mfma_f32_16x16x32_bf16 v[22:25], v[160:163], v[208:211], 0
	v_mfma_f32_16x16x32_bf16 v[18:21], v[172:175], v[208:211], 0
	v_mfma_f32_16x16x32_bf16 v[6:9], v[160:163], v[216:219], 0
	v_mfma_f32_16x16x32_bf16 v[2:5], v[172:175], v[216:219], 0
	v_mfma_f32_16x16x32_bf16 v[54:57], v[164:167], v[196:199], v[54:57]
	v_mfma_f32_16x16x32_bf16 v[50:53], v[176:179], v[196:199], v[50:53]
	v_mfma_f32_16x16x32_bf16 v[38:41], v[164:167], v[204:207], v[38:41]
	v_mfma_f32_16x16x32_bf16 v[34:37], v[176:179], v[204:207], v[34:37]
	v_mfma_f32_16x16x32_bf16 v[22:25], v[164:167], v[212:215], v[22:25]
	v_mfma_f32_16x16x32_bf16 v[18:21], v[176:179], v[212:215], v[18:21]
	v_mfma_f32_16x16x32_bf16 v[6:9], v[164:167], v[220:223], v[6:9]
	v_mfma_f32_16x16x32_bf16 v[2:5], v[176:179], v[220:223], v[2:5]
	s_setprio 0
	s_barrier
	s_branch .Lmid_594
.LBB0_594:
	s_add_u32 s30, s0, 0x4000
	s_addc_u32 s31, s1, 0
	s_cmp_eq_u32 s41, 28
	s_cselect_b32 s36, s16, s30
	s_cselect_b32 s37, s9, s31
	s_cselect_b32 s34, s23, s29
	s_cselect_b32 s35, s21, s40
	s_add_u32 s30, s36, 0x8000
	s_addc_u32 s31, s37, 0
	s_add_i32 s60, 0, 0x10000
	s_add_i32 s75, 0, 0x14000
	v_add_u32_e32 v142, s60, v169
	v_add_u32_e32 v171, s75, v169
	ds_read_b128 v[130:133], v142
	ds_read_b128 v[134:137], v142 offset:1024
	ds_read_b128 v[138:141], v142 offset:2048
	ds_read_b128 v[142:145], v142 offset:3072
	ds_read_b128 v[160:163], v171
	ds_read_b128 v[164:167], v171 offset:1024
	ds_read_b128 v[172:175], v171 offset:2048
	ds_read_b128 v[176:179], v171 offset:3072
	v_lshl_add_u64 v[184:185], s[0:1], 0, v[156:157]
	s_add_i32 m0, s83, 0xc000
	ds_read_b128 v[180:183], v170
	ds_read_b128 v[196:199], v170 offset:1024
	ds_read_b128 v[200:203], v170 offset:2048
	ds_read_b128 v[204:207], v170 offset:3072
	ds_read_b128 v[208:211], v170 offset:4096
	ds_read_b128 v[212:215], v170 offset:5120
	ds_read_b128 v[216:219], v170 offset:6144
	ds_read_b128 v[220:223], v170 offset:7168
	global_load_lds_dwordx4 v[184:185], off
	v_lshl_add_u64 v[184:185], s[0:1], 0, v[158:159]
	s_add_i32 m0, s83, 0xe000
	s_nop 0
	global_load_lds_dwordx4 v[184:185], off
	s_waitcnt vmcnt(8)
	s_waitcnt lgkmcnt(0)
	s_barrier
	s_setprio 1
	s_waitcnt lgkmcnt(0)
	v_mfma_f32_16x16x32_bf16 v[126:129], v[130:133], v[180:183], v[126:129]
	v_mfma_f32_16x16x32_bf16 v[122:125], v[138:141], v[180:183], v[122:125]
	v_mfma_f32_16x16x32_bf16 v[110:113], v[130:133], v[200:203], v[110:113]
	v_mfma_f32_16x16x32_bf16 v[106:109], v[138:141], v[200:203], v[106:109]
	v_mfma_f32_16x16x32_bf16 v[94:97], v[130:133], v[208:211], v[94:97]
	v_mfma_f32_16x16x32_bf16 v[90:93], v[138:141], v[208:211], v[90:93]
	v_mfma_f32_16x16x32_bf16 v[78:81], v[130:133], v[216:219], v[78:81]
	v_mfma_f32_16x16x32_bf16 v[74:77], v[138:141], v[216:219], v[74:77]
	v_mfma_f32_16x16x32_bf16 v[126:129], v[134:137], v[196:199], v[126:129]
	v_mfma_f32_16x16x32_bf16 v[122:125], v[142:145], v[196:199], v[122:125]
	v_mfma_f32_16x16x32_bf16 v[110:113], v[134:137], v[204:207], v[110:113]
	v_mfma_f32_16x16x32_bf16 v[106:109], v[142:145], v[204:207], v[106:109]
	v_mfma_f32_16x16x32_bf16 v[94:97], v[134:137], v[212:215], v[94:97]
	v_mfma_f32_16x16x32_bf16 v[90:93], v[142:145], v[212:215], v[90:93]
	v_mfma_f32_16x16x32_bf16 v[78:81], v[134:137], v[220:223], v[78:81]
	v_mfma_f32_16x16x32_bf16 v[74:77], v[142:145], v[220:223], v[74:77]
	s_setprio 0
	s_setprio 1
	v_mfma_f32_16x16x32_bf16 v[118:121], v[160:163], v[180:183], v[118:121]
	v_mfma_f32_16x16x32_bf16 v[114:117], v[172:175], v[180:183], v[114:117]
	v_mfma_f32_16x16x32_bf16 v[102:105], v[160:163], v[200:203], v[102:105]
	v_mfma_f32_16x16x32_bf16 v[98:101], v[172:175], v[200:203], v[98:101]
	v_mfma_f32_16x16x32_bf16 v[86:89], v[160:163], v[208:211], v[86:89]
	v_mfma_f32_16x16x32_bf16 v[82:85], v[172:175], v[208:211], v[82:85]
	v_mfma_f32_16x16x32_bf16 v[70:73], v[160:163], v[216:219], v[70:73]
	v_mfma_f32_16x16x32_bf16 v[66:69], v[172:175], v[216:219], v[66:69]
	v_mfma_f32_16x16x32_bf16 v[118:121], v[164:167], v[196:199], v[118:121]
	v_mfma_f32_16x16x32_bf16 v[114:117], v[176:179], v[196:199], v[114:117]
	v_mfma_f32_16x16x32_bf16 v[102:105], v[164:167], v[204:207], v[102:105]
	v_mfma_f32_16x16x32_bf16 v[98:101], v[176:179], v[204:207], v[98:101]
	v_mfma_f32_16x16x32_bf16 v[86:89], v[164:167], v[212:215], v[86:89]
	v_mfma_f32_16x16x32_bf16 v[82:85], v[176:179], v[212:215], v[82:85]
	v_mfma_f32_16x16x32_bf16 v[70:73], v[164:167], v[220:223], v[70:73]
	v_mfma_f32_16x16x32_bf16 v[66:69], v[176:179], v[220:223], v[66:69]
	s_setprio 0
	s_barrier
; #define PG8_STAGE(bufoff, gbase, voff) do { _Pragma("unroll") for (int _i = 0; _i < 2; ++_i) \
;         __builtin_amdgcn_global_load_lds((const unsigned*)((const char*)(gbase) + (voff)[_i]), (PG8_LAS unsigned*)(lds + (bufoff) + ldsw + _i * 8192), 16, 0, 0); } while (0)
; #define PG8_LDA(dst, b, h) do { _Pragma("unroll") for (int m = 0; m < 4; ++m) _Pragma("unroll") for (int k = 0; k < 2; ++k) dst[m][k] = *(const PG8_LAS bf16x8*)(lds + PG8_SA(b, h) + aoff + m * 2048 + k * 1024); } while (0)
; #define PG8_LDB(dst, b, h) do { _Pragma("unroll") for (int n = 0; n < 2; ++n) _Pragma("unroll") for (int k = 0; k < 2; ++k) dst[n][k] = *(const PG8_LAS bf16x8*)(lds + PG8_SB(b, h) + boff + n * 2048 + k * 1024); } while (0)
; #define PG8_MMA(ai, bj, At, Bt) do { __builtin_amdgcn_s_setprio(1); _Pragma("unroll") for (int m = 0; m < 4; ++m) _Pragma("unroll") for (int n = 0; n < 2; ++n) _Pragma("unroll") for (int k = 0; k < 2; ++k) \
;         acc[ai][bj][m][n] = __builtin_amdgcn_mfma_f32_16x16x32_bf16(Bt[n][k], At[m][k], acc[ai][bj][m][n], 0, 0, 0); __builtin_amdgcn_s_setprio(0); } while (0)
; #define PG8_WAIT_V(n) asm volatile("s_waitcnt vmcnt(" #n ")" ::: "memory")
; #define PG8_WAIT_L(n) asm volatile("s_waitcnt lgkmcnt(" #n ")" ::: "memory")
; #define PG8_BAR __builtin_amdgcn_s_barrier()
; #define PG8_SCHED __builtin_amdgcn_sched_barrier(0)
; template <class Epi, class Sched, bool ALIGN_EPI = false, bool SP2 = false, bool ABLK = false, bool BBLK = false>
; __device__ __forceinline__ void gemm_phase(PG8_LAS unsigned char* lds, const Gemm g, const Sched& S, const Epi& E) {
;     ...
;             PG8_LDA(At, 0, 1); PG8_STAGE(PG8_SB(0, 0), b2, voffB); PG8_STAGE(PG8_SB(0, 1), b2 + hstepB, voffB); PG8_STAGE(PG8_SA(0, 0), a2, voffA);
;             PG8_WAIT_V(8); PG8_WAIT_L(0); PG8_BAR; PG8_MMA(1, 0, At, B0); PG8_MMA(1, 1, At, B1); PG8_BAR; PG8_SCHED;
;             PG8_LDB(B0, 1, 0); PG8_LDB(B1, 1, 1); PG8_SCHED; PG8_LDA(At, 1, 0); PG8_STAGE(PG8_SA(0, 1), a2 + hstepA, voffA);
;             PG8_WAIT_V(8); PG8_WAIT_L(0); PG8_BAR; PG8_MMA(0, 0, At, B0); PG8_MMA(0, 1, At, B1); PG8_BAR; PG8_SCHED;
	s_add_i32 s60, s60, s81
	v_lshl_add_u64 v[184:185], s[34:35], 0, v[148:149]
	s_mov_b32 m0, s60
	ds_read_b128 v[180:183], v170 offset:16384
	ds_read_b128 v[196:199], v170 offset:17408
	ds_read_b128 v[200:203], v170 offset:18432
	ds_read_b128 v[204:207], v170 offset:19456
	ds_read_b128 v[208:211], v170 offset:20480
	ds_read_b128 v[212:215], v170 offset:21504
	ds_read_b128 v[216:219], v170 offset:22528
	ds_read_b128 v[220:223], v170 offset:23552
	global_load_lds_dwordx4 v[184:185], off
	s_add_i32 m0, s60, 0x2000
	s_add_u32 s60, s34, 0x4000
	v_lshl_add_u64 v[184:185], s[34:35], 0, v[152:153]
	s_addc_u32 s61, s35, 0
	s_add_i32 s75, s75, s81
	global_load_lds_dwordx4 v[184:185], off
	v_lshl_add_u64 v[184:185], s[60:61], 0, v[148:149]
	s_mov_b32 m0, s75
	s_nop 0
	global_load_lds_dwordx4 v[184:185], off
	v_lshl_add_u64 v[184:185], s[60:61], 0, v[152:153]
	s_add_i32 m0, s75, 0x2000
	s_nop 0
	global_load_lds_dwordx4 v[184:185], off
	v_lshl_add_u64 v[184:185], s[36:37], 0, v[146:147]
	s_mov_b32 m0, s83
	s_nop 0
	global_load_lds_dwordx4 v[184:185], off
	v_lshl_add_u64 v[184:185], s[36:37], 0, v[150:151]
	s_mov_b32 m0, s84
	s_nop 0
	global_load_lds_dwordx4 v[184:185], off
	s_waitcnt vmcnt(8)
	s_waitcnt lgkmcnt(0)
	s_barrier
	s_setprio 1
	s_waitcnt lgkmcnt(0)
	v_mfma_f32_16x16x32_bf16 v[62:65], v[130:133], v[180:183], v[62:65]
	v_mfma_f32_16x16x32_bf16 v[58:61], v[138:141], v[180:183], v[58:61]
	v_mfma_f32_16x16x32_bf16 v[46:49], v[130:133], v[200:203], v[46:49]
	v_mfma_f32_16x16x32_bf16 v[42:45], v[138:141], v[200:203], v[42:45]
	v_mfma_f32_16x16x32_bf16 v[30:33], v[130:133], v[208:211], v[30:33]
	v_mfma_f32_16x16x32_bf16 v[26:29], v[138:141], v[208:211], v[26:29]
	v_mfma_f32_16x16x32_bf16 v[14:17], v[130:133], v[216:219], v[14:17]
	v_mfma_f32_16x16x32_bf16 v[10:13], v[138:141], v[216:219], v[10:13]
	v_mfma_f32_16x16x32_bf16 v[62:65], v[134:137], v[196:199], v[62:65]
	v_mfma_f32_16x16x32_bf16 v[58:61], v[142:145], v[196:199], v[58:61]
	v_mfma_f32_16x16x32_bf16 v[46:49], v[134:137], v[204:207], v[46:49]
	v_mfma_f32_16x16x32_bf16 v[42:45], v[142:145], v[204:207], v[42:45]
	v_mfma_f32_16x16x32_bf16 v[30:33], v[134:137], v[212:215], v[30:33]
	v_mfma_f32_16x16x32_bf16 v[26:29], v[142:145], v[212:215], v[26:29]
	v_mfma_f32_16x16x32_bf16 v[14:17], v[134:137], v[220:223], v[14:17]
	v_mfma_f32_16x16x32_bf16 v[10:13], v[142:145], v[220:223], v[10:13]
	s_setprio 0
	s_setprio 1
	v_mfma_f32_16x16x32_bf16 v[54:57], v[160:163], v[180:183], v[54:57]
	v_mfma_f32_16x16x32_bf16 v[50:53], v[172:175], v[180:183], v[50:53]
	v_mfma_f32_16x16x32_bf16 v[38:41], v[160:163], v[200:203], v[38:41]
	v_mfma_f32_16x16x32_bf16 v[34:37], v[172:175], v[200:203], v[34:37]
	v_mfma_f32_16x16x32_bf16 v[22:25], v[160:163], v[208:211], v[22:25]
	v_mfma_f32_16x16x32_bf16 v[18:21], v[172:175], v[208:211], v[18:21]
	v_mfma_f32_16x16x32_bf16 v[6:9], v[160:163], v[216:219], v[6:9]
	v_mfma_f32_16x16x32_bf16 v[2:5], v[172:175], v[216:219], v[2:5]
	v_mfma_f32_16x16x32_bf16 v[54:57], v[164:167], v[196:199], v[54:57]
	v_mfma_f32_16x16x32_bf16 v[50:53], v[176:179], v[196:199], v[50:53]
	v_mfma_f32_16x16x32_bf16 v[38:41], v[164:167], v[204:207], v[38:41]
	v_mfma_f32_16x16x32_bf16 v[34:37], v[176:179], v[204:207], v[34:37]
	v_mfma_f32_16x16x32_bf16 v[22:25], v[164:167], v[212:215], v[22:25]
	v_mfma_f32_16x16x32_bf16 v[18:21], v[176:179], v[212:215], v[18:21]
	v_mfma_f32_16x16x32_bf16 v[6:9], v[164:167], v[220:223], v[6:9]
	v_mfma_f32_16x16x32_bf16 v[2:5], v[176:179], v[220:223], v[2:5]
	s_setprio 0
	s_barrier
.Lmid_594:
	s_add_i32 s60, 0, 0x18000
	s_add_i32 s61, 0, 0x1c000
	v_add_u32_e32 v142, s60, v169
	v_add_u32_e32 v171, s61, v169
	ds_read_b128 v[130:133], v142
	ds_read_b128 v[134:137], v142 offset:1024
	ds_read_b128 v[138:141], v142 offset:2048
	ds_read_b128 v[142:145], v142 offset:3072
	ds_read_b128 v[160:163], v171
	ds_read_b128 v[164:167], v171 offset:1024
	ds_read_b128 v[172:175], v171 offset:2048
	ds_read_b128 v[176:179], v171 offset:3072
	s_add_u32 s36, s36, 0x4000
	s_addc_u32 s37, s37, 0
	s_mov_b32 m0, s86
	v_lshl_add_u64 v[184:185], s[36:37], 0, v[146:147]
	ds_read_b128 v[180:183], v170 offset:32768
	ds_read_b128 v[196:199], v170 offset:33792
	ds_read_b128 v[200:203], v170 offset:34816
	ds_read_b128 v[204:207], v170 offset:35840
	ds_read_b128 v[208:211], v170 offset:36864
	ds_read_b128 v[212:215], v170 offset:37888
	ds_read_b128 v[216:219], v170 offset:38912
	ds_read_b128 v[220:223], v170 offset:39936
	global_load_lds_dwordx4 v[184:185], off
	v_lshl_add_u64 v[184:185], s[36:37], 0, v[150:151]
	s_mov_b32 m0, s88
	s_nop 0
	global_load_lds_dwordx4 v[184:185], off
	s_waitcnt vmcnt(8)
	s_waitcnt lgkmcnt(0)
	s_barrier
; #define PG8_STAGE(bufoff, gbase, voff) do { _Pragma("unroll") for (int _i = 0; _i < 2; ++_i) \
;         __builtin_amdgcn_global_load_lds((const unsigned*)((const char*)(gbase) + (voff)[_i]), (PG8_LAS unsigned*)(lds + (bufoff) + ldsw + _i * 8192), 16, 0, 0); } while (0)
; #define PG8_LDA(dst, b, h) do { _Pragma("unroll") for (int m = 0; m < 4; ++m) _Pragma("unroll") for (int k = 0; k < 2; ++k) dst[m][k] = *(const PG8_LAS bf16x8*)(lds + PG8_SA(b, h) + aoff + m * 2048 + k * 1024); } while (0)
; #define PG8_MMA(ai, bj, At, Bt) do { __builtin_amdgcn_s_setprio(1); _Pragma("unroll") for (int m = 0; m < 4; ++m) _Pragma("unroll") for (int n = 0; n < 2; ++n) _Pragma("unroll") for (int k = 0; k < 2; ++k) \
;         acc[ai][bj][m][n] = __builtin_amdgcn_mfma_f32_16x16x32_bf16(Bt[n][k], At[m][k], acc[ai][bj][m][n], 0, 0, 0); __builtin_amdgcn_s_setprio(0); } while (0)
; #define PG8_WAIT_V(n) asm volatile("s_waitcnt vmcnt(" #n ")" ::: "memory")
; #define PG8_WAIT_L(n) asm volatile("s_waitcnt lgkmcnt(" #n ")" ::: "memory")
; #define PG8_BAR __builtin_amdgcn_s_barrier()
; #define PG8_SCHED __builtin_amdgcn_sched_barrier(0)
; template <class Epi, class Sched, bool ALIGN_EPI = false, bool SP2 = false, bool ABLK = false, bool BBLK = false>
; __device__ __forceinline__ void gemm_phase(PG8_LAS unsigned char* lds, const Gemm g, const Sched& S, const Epi& E) {
;     ...
;             PG8_WAIT_V(8); PG8_WAIT_L(0); PG8_BAR; PG8_MMA(0, 0, At, B0); PG8_MMA(0, 1, At, B1); PG8_BAR; PG8_SCHED;
;             PG8_LDA(At, 1, 1); PG8_STAGE(PG8_SB(1, 0), b3, voffB); PG8_STAGE(PG8_SB(1, 1), b3 + hstepB, voffB); PG8_STAGE(PG8_SA(1, 0), a3, voffA);
;             PG8_WAIT_V(8); PG8_WAIT_L(0); PG8_BAR; PG8_MMA(1, 0, At, B0); PG8_MMA(1, 1, At, B1); PG8_BAR; PG8_SCHED;
;     ...
;         if constexpr (ALIGN_EPI) { if (wr == 0) PG8_BAR; }
	s_setprio 1
	s_waitcnt lgkmcnt(0)
	v_mfma_f32_16x16x32_bf16 v[126:129], v[130:133], v[180:183], v[126:129]
	v_mfma_f32_16x16x32_bf16 v[122:125], v[138:141], v[180:183], v[122:125]
	v_mfma_f32_16x16x32_bf16 v[110:113], v[130:133], v[200:203], v[110:113]
	v_mfma_f32_16x16x32_bf16 v[106:109], v[138:141], v[200:203], v[106:109]
	v_mfma_f32_16x16x32_bf16 v[94:97], v[130:133], v[208:211], v[94:97]
	v_mfma_f32_16x16x32_bf16 v[90:93], v[138:141], v[208:211], v[90:93]
	v_mfma_f32_16x16x32_bf16 v[78:81], v[130:133], v[216:219], v[78:81]
	v_mfma_f32_16x16x32_bf16 v[74:77], v[138:141], v[216:219], v[74:77]
	v_mfma_f32_16x16x32_bf16 v[126:129], v[134:137], v[196:199], v[126:129]
	v_mfma_f32_16x16x32_bf16 v[122:125], v[142:145], v[196:199], v[122:125]
	v_mfma_f32_16x16x32_bf16 v[110:113], v[134:137], v[204:207], v[110:113]
	v_mfma_f32_16x16x32_bf16 v[106:109], v[142:145], v[204:207], v[106:109]
	v_mfma_f32_16x16x32_bf16 v[94:97], v[134:137], v[212:215], v[94:97]
	v_mfma_f32_16x16x32_bf16 v[90:93], v[142:145], v[212:215], v[90:93]
	v_mfma_f32_16x16x32_bf16 v[78:81], v[134:137], v[220:223], v[78:81]
	v_mfma_f32_16x16x32_bf16 v[74:77], v[142:145], v[220:223], v[74:77]
	s_setprio 0
	s_setprio 1
	v_mfma_f32_16x16x32_bf16 v[118:121], v[160:163], v[180:183], v[118:121]
	v_mfma_f32_16x16x32_bf16 v[114:117], v[172:175], v[180:183], v[114:117]
	v_mfma_f32_16x16x32_bf16 v[102:105], v[160:163], v[200:203], v[102:105]
	v_mfma_f32_16x16x32_bf16 v[98:101], v[172:175], v[200:203], v[98:101]
	v_mfma_f32_16x16x32_bf16 v[86:89], v[160:163], v[208:211], v[86:89]
	v_mfma_f32_16x16x32_bf16 v[82:85], v[172:175], v[208:211], v[82:85]
	v_mfma_f32_16x16x32_bf16 v[70:73], v[160:163], v[216:219], v[70:73]
	v_mfma_f32_16x16x32_bf16 v[66:69], v[172:175], v[216:219], v[66:69]
	v_mfma_f32_16x16x32_bf16 v[118:121], v[164:167], v[196:199], v[118:121]
	v_mfma_f32_16x16x32_bf16 v[114:117], v[176:179], v[196:199], v[114:117]
	v_mfma_f32_16x16x32_bf16 v[102:105], v[164:167], v[204:207], v[102:105]
	v_mfma_f32_16x16x32_bf16 v[98:101], v[176:179], v[204:207], v[98:101]
	v_mfma_f32_16x16x32_bf16 v[86:89], v[164:167], v[212:215], v[86:89]
	v_mfma_f32_16x16x32_bf16 v[82:85], v[176:179], v[212:215], v[82:85]
	v_mfma_f32_16x16x32_bf16 v[70:73], v[164:167], v[220:223], v[70:73]
	v_mfma_f32_16x16x32_bf16 v[66:69], v[176:179], v[220:223], v[66:69]
	s_setprio 0
	s_barrier
	s_add_u32 s36, s34, 0x8000
	s_addc_u32 s37, s35, 0
	s_add_i32 s60, s60, s81
	v_lshl_add_u64 v[184:185], s[36:37], 0, v[148:149]
	s_mov_b32 m0, s60
	ds_read_b128 v[180:183], v170 offset:49152
	ds_read_b128 v[196:199], v170 offset:50176
	ds_read_b128 v[200:203], v170 offset:51200
	ds_read_b128 v[204:207], v170 offset:52224
	ds_read_b128 v[208:211], v170 offset:53248
	ds_read_b128 v[212:215], v170 offset:54272
	ds_read_b128 v[216:219], v170 offset:55296
	ds_read_b128 v[220:223], v170 offset:56320
	global_load_lds_dwordx4 v[184:185], off
	s_add_i32 m0, s60, 0x2000
	s_add_u32 s34, s34, 0xc000
	v_lshl_add_u64 v[184:185], s[36:37], 0, v[152:153]
	s_addc_u32 s35, s35, 0
	s_add_i32 s36, s61, s81
	global_load_lds_dwordx4 v[184:185], off
	v_lshl_add_u64 v[184:185], s[34:35], 0, v[148:149]
	s_mov_b32 m0, s36
	s_nop 0
	global_load_lds_dwordx4 v[184:185], off
	v_lshl_add_u64 v[184:185], s[34:35], 0, v[152:153]
	s_add_i32 m0, s36, 0x2000
	s_nop 0
	global_load_lds_dwordx4 v[184:185], off
	v_lshl_add_u64 v[184:185], s[30:31], 0, v[146:147]
	s_mov_b32 m0, s90
	s_nop 0
	global_load_lds_dwordx4 v[184:185], off
	v_lshl_add_u64 v[184:185], s[30:31], 0, v[150:151]
	s_mov_b32 m0, s91
	s_nop 0
	global_load_lds_dwordx4 v[184:185], off
	s_waitcnt vmcnt(8)
	s_waitcnt lgkmcnt(0)
	s_barrier
	s_setprio 1
	s_waitcnt lgkmcnt(0)
	v_mfma_f32_16x16x32_bf16 v[62:65], v[130:133], v[180:183], v[62:65]
	v_mfma_f32_16x16x32_bf16 v[58:61], v[138:141], v[180:183], v[58:61]
	v_mfma_f32_16x16x32_bf16 v[46:49], v[130:133], v[200:203], v[46:49]
	v_mfma_f32_16x16x32_bf16 v[42:45], v[138:141], v[200:203], v[42:45]
	v_mfma_f32_16x16x32_bf16 v[30:33], v[130:133], v[208:211], v[30:33]
	v_mfma_f32_16x16x32_bf16 v[26:29], v[138:141], v[208:211], v[26:29]
	v_mfma_f32_16x16x32_bf16 v[14:17], v[130:133], v[216:219], v[14:17]
	v_mfma_f32_16x16x32_bf16 v[10:13], v[138:141], v[216:219], v[10:13]
	v_mfma_f32_16x16x32_bf16 v[62:65], v[134:137], v[196:199], v[62:65]
	v_mfma_f32_16x16x32_bf16 v[58:61], v[142:145], v[196:199], v[58:61]
	v_mfma_f32_16x16x32_bf16 v[46:49], v[134:137], v[204:207], v[46:49]
	v_mfma_f32_16x16x32_bf16 v[42:45], v[142:145], v[204:207], v[42:45]
	v_mfma_f32_16x16x32_bf16 v[30:33], v[134:137], v[212:215], v[30:33]
	v_mfma_f32_16x16x32_bf16 v[26:29], v[142:145], v[212:215], v[26:29]
	v_mfma_f32_16x16x32_bf16 v[14:17], v[134:137], v[220:223], v[14:17]
	v_mfma_f32_16x16x32_bf16 v[10:13], v[142:145], v[220:223], v[10:13]
	s_setprio 0
	s_setprio 1
	v_mfma_f32_16x16x32_bf16 v[54:57], v[160:163], v[180:183], v[54:57]
	v_mfma_f32_16x16x32_bf16 v[50:53], v[172:175], v[180:183], v[50:53]
	v_mfma_f32_16x16x32_bf16 v[38:41], v[160:163], v[200:203], v[38:41]
	v_mfma_f32_16x16x32_bf16 v[34:37], v[172:175], v[200:203], v[34:37]
	v_mfma_f32_16x16x32_bf16 v[22:25], v[160:163], v[208:211], v[22:25]
	v_mfma_f32_16x16x32_bf16 v[18:21], v[172:175], v[208:211], v[18:21]
	v_mfma_f32_16x16x32_bf16 v[6:9], v[160:163], v[216:219], v[6:9]
	v_mfma_f32_16x16x32_bf16 v[2:5], v[172:175], v[216:219], v[2:5]
	v_mfma_f32_16x16x32_bf16 v[54:57], v[164:167], v[196:199], v[54:57]
	v_mfma_f32_16x16x32_bf16 v[50:53], v[176:179], v[196:199], v[50:53]
	v_mfma_f32_16x16x32_bf16 v[38:41], v[164:167], v[204:207], v[38:41]
	v_mfma_f32_16x16x32_bf16 v[34:37], v[176:179], v[204:207], v[34:37]
	v_mfma_f32_16x16x32_bf16 v[22:25], v[164:167], v[212:215], v[22:25]
	v_mfma_f32_16x16x32_bf16 v[18:21], v[176:179], v[212:215], v[18:21]
	v_mfma_f32_16x16x32_bf16 v[6:9], v[164:167], v[220:223], v[6:9]
	v_mfma_f32_16x16x32_bf16 v[2:5], v[176:179], v[220:223], v[2:5]
	s_setprio 0
	s_barrier
	s_add_i32 s41, s41, 2
	s_add_u32 s0, s0, 0x10000
	s_addc_u32 s1, s1, 0
	s_add_u32 s29, s29, 0x10000
	s_addc_u32 s40, s40, 0
	s_cmp_gt_u32 s41, 29
	s_cbranch_scc0 .LBB0_594
	s_and_b64 vcc, exec, s[18:19]
	s_cbranch_vccz .LBB0_597
	s_barrier

; #define PG8_STAGE(bufoff, gbase, voff) do { _Pragma("unroll") for (int _i = 0; _i < 2; ++_i) \
;         __builtin_amdgcn_global_load_lds((const unsigned*)((const char*)(gbase) + (voff)[_i]), (PG8_LAS unsigned*)(lds + (bufoff) + ldsw + _i * 8192), 16, 0, 0); } while (0)
; #define PG8_LDA(dst, b, h) do { _Pragma("unroll") for (int m = 0; m < 4; ++m) _Pragma("unroll") for (int k = 0; k < 2; ++k) dst[m][k] = *(const PG8_LAS bf16x8*)(lds + PG8_SA(b, h) + aoff + m * 2048 + k * 1024); } while (0)
; #define PG8_LDB(dst, b, h) do { _Pragma("unroll") for (int n = 0; n < 2; ++n) _Pragma("unroll") for (int k = 0; k < 2; ++k) dst[n][k] = *(const PG8_LAS bf16x8*)(lds + PG8_SB(b, h) + boff + n * 2048 + k * 1024); } while (0)
; #define PG8_WAIT_V(n) asm volatile("s_waitcnt vmcnt(" #n ")" ::: "memory")
; #define PG8_WAIT_L(n) asm volatile("s_waitcnt lgkmcnt(" #n ")" ::: "memory")
; #define PG8_BAR __builtin_amdgcn_s_barrier()
; template <class Epi, class Sched, bool ALIGN_EPI = false, bool SP2 = false, bool ABLK = false, bool BBLK = false>
; __device__ __forceinline__ void gemm_phase(PG8_LAS unsigned char* lds, const Gemm g, const Sched& S, const Epi& E) {
;     ...
;     for (;;) {
;         const bool has_next = S.next(ui + 1, nxt);
;         const char* nA = has_next ? (const char*)g.A + (size_t)nxt.pm * tstepA : cA; const char* nB = has_next ? (const char*)g.Bt + (size_t)nxt.pn * tstepB : cB;
;         for (int t = 0; t < nt; t += 2) {
;             const bool last = (t == nt - 2);
;             const char* a1 = cA + (size_t)(t + 1) * kstepA;
;             const char* a2 = last ? nA : cA + (size_t)(t + 2) * kstepA; const char* b2 = last ? nB : cB + (size_t)(t + 2) * kstepB;
;             const char* a3 = a2 + kstepA; const char* b3 = b2 + kstepB;
;             if (last && has_next) S.a_ready(nxt);
;             if constexpr (SP2) {
;             PG8_LDB(B0, 0, 0); PG8_LDB(B1, 0, 1); PG8_SCHED; PG8_LDA(At, 0, 0); PG8_STAGE(PG8_SA(1, 1), a1 + hstepA, voffA);
;             PG8_WAIT_V(8); PG8_WAIT_L(0); PG8_BAR; PG8_MMA(0, 0, At, B0); PG8_MMA(0, 1, At, B1); PG8_BAR; PG8_SCHED;
;             PG8_LDA(At, 0, 1); PG8_STAGE(PG8_SB(0, 0), b2, voffB); PG8_STAGE(PG8_SB(0, 1), b2 + hstepB, voffB); PG8_STAGE(PG8_SA(0, 0), a2, voffA);
;             PG8_WAIT_V(8); PG8_WAIT_L(0); PG8_BAR; PG8_MMA(1, 0, At, B0); PG8_MMA(1, 1, At, B1); PG8_BAR; PG8_SCHED;
.LBB0_657:
	s_ashr_i32 s13, s12, 31
	s_lshl_b64 s[14:15], s[12:13], 20
	s_add_u32 s14, s31, s14
	s_addc_u32 s15, s33, s15
	s_and_b64 s[18:19], s[6:7], exec
	s_cselect_b32 s13, s15, s23
	s_cselect_b32 s61, s14, s22
	s_ashr_i32 s1, s0, 31
	s_lshl_b64 s[18:19], s[0:1], 20
	s_add_u32 s18, s51, s18
	s_addc_u32 s19, s53, s19
	s_and_b64 s[26:27], s[6:7], exec
	s_cselect_b32 s1, s19, s25
	s_cselect_b32 s65, s18, s24
	s_add_u32 s22, s22, 0xc000
	s_addc_u32 s23, s23, 0
	s_add_u32 s68, s24, 0x10000
	v_mov_b32_e32 v2, 0
	s_addc_u32 s72, s25, 0
	s_mov_b32 s73, -2
	s_add_u32 s24, s22, 0x4000
	s_addc_u32 s25, s23, 0
	s_cmp_eq_u32 s73, 28
	s_cselect_b32 s28, s61, s24
	s_cselect_b32 s29, s13, s25
	s_cselect_b32 s26, s65, s68
	s_cselect_b32 s27, s1, s72
	s_add_u32 s24, s28, 0x8000
	s_addc_u32 s25, s29, 0
	s_add_i32 s75, 0, 0x10000
	s_add_i32 s82, 0, 0x14000
	v_add_u32_e32 v158, s75, v147
	v_add_u32_e32 v174, s82, v147
	ds_read_b128 v[142:145], v158
	ds_read_b128 v[150:153], v158 offset:1024
	ds_read_b128 v[154:157], v158 offset:2048
	ds_read_b128 v[158:161], v158 offset:3072
	ds_read_b128 v[162:165], v174
	ds_read_b128 v[166:169], v174 offset:1024
	ds_read_b128 v[170:173], v174 offset:2048
	ds_read_b128 v[174:177], v174 offset:3072
	v_lshl_add_u64 v[220:221], s[22:23], 0, v[138:139]
	s_add_i32 m0, s40, 0xc000
	ds_read_b128 v[178:181], v149
	ds_read_b128 v[182:185], v149 offset:1024
	ds_read_b128 v[196:199], v149 offset:2048
	ds_read_b128 v[200:203], v149 offset:3072
	ds_read_b128 v[204:207], v149 offset:4096
	ds_read_b128 v[208:211], v149 offset:5120
	ds_read_b128 v[212:215], v149 offset:6144
	ds_read_b128 v[216:219], v149 offset:7168
	global_load_lds_dwordx4 v[220:221], off
	v_lshl_add_u64 v[220:221], s[22:23], 0, v[140:141]
	s_add_i32 m0, s40, 0xe000
	s_nop 0
	global_load_lds_dwordx4 v[220:221], off
	s_waitcnt vmcnt(8)
	s_waitcnt lgkmcnt(0)
	s_barrier
	s_setprio 1
	s_waitcnt lgkmcnt(0)
	v_mfma_f32_16x16x32_bf16 v[126:129], v[142:145], v[178:181], 0
	v_mfma_f32_16x16x32_bf16 v[122:125], v[154:157], v[178:181], 0
	v_mfma_f32_16x16x32_bf16 v[114:117], v[142:145], v[196:199], 0
	v_mfma_f32_16x16x32_bf16 v[106:109], v[154:157], v[196:199], 0
	v_mfma_f32_16x16x32_bf16 v[102:105], v[142:145], v[204:207], 0
	v_mfma_f32_16x16x32_bf16 v[94:97], v[154:157], v[204:207], 0
	v_mfma_f32_16x16x32_bf16 v[86:89], v[142:145], v[212:215], 0
	v_mfma_f32_16x16x32_bf16 v[78:81], v[154:157], v[212:215], 0
	v_mfma_f32_16x16x32_bf16 v[126:129], v[150:153], v[182:185], v[126:129]
	v_mfma_f32_16x16x32_bf16 v[122:125], v[158:161], v[182:185], v[122:125]
	v_mfma_f32_16x16x32_bf16 v[114:117], v[150:153], v[200:203], v[114:117]
	v_mfma_f32_16x16x32_bf16 v[106:109], v[158:161], v[200:203], v[106:109]
	v_mfma_f32_16x16x32_bf16 v[102:105], v[150:153], v[208:211], v[102:105]
	v_mfma_f32_16x16x32_bf16 v[94:97], v[158:161], v[208:211], v[94:97]
	v_mfma_f32_16x16x32_bf16 v[86:89], v[150:153], v[216:219], v[86:89]
	v_mfma_f32_16x16x32_bf16 v[78:81], v[158:161], v[216:219], v[78:81]
	s_setprio 0
	s_setprio 1
	v_mfma_f32_16x16x32_bf16 v[118:121], v[162:165], v[178:181], 0
	v_mfma_f32_16x16x32_bf16 v[110:113], v[170:173], v[178:181], 0
	v_mfma_f32_16x16x32_bf16 v[98:101], v[162:165], v[196:199], 0
	v_mfma_f32_16x16x32_bf16 v[90:93], v[170:173], v[196:199], 0
	v_mfma_f32_16x16x32_bf16 v[82:85], v[162:165], v[204:207], 0
	v_mfma_f32_16x16x32_bf16 v[74:77], v[170:173], v[204:207], 0
	v_mfma_f32_16x16x32_bf16 v[70:73], v[162:165], v[212:215], 0
	v_mfma_f32_16x16x32_bf16 v[66:69], v[170:173], v[212:215], 0
	v_mfma_f32_16x16x32_bf16 v[118:121], v[166:169], v[182:185], v[118:121]
	v_mfma_f32_16x16x32_bf16 v[110:113], v[174:177], v[182:185], v[110:113]
	v_mfma_f32_16x16x32_bf16 v[98:101], v[166:169], v[200:203], v[98:101]
	v_mfma_f32_16x16x32_bf16 v[90:93], v[174:177], v[200:203], v[90:93]
	v_mfma_f32_16x16x32_bf16 v[82:85], v[166:169], v[208:211], v[82:85]
	v_mfma_f32_16x16x32_bf16 v[74:77], v[174:177], v[208:211], v[74:77]
	v_mfma_f32_16x16x32_bf16 v[70:73], v[166:169], v[216:219], v[70:73]
	v_mfma_f32_16x16x32_bf16 v[66:69], v[174:177], v[216:219], v[66:69]
	s_setprio 0
	s_barrier
	s_add_i32 s75, s75, s37
	v_lshl_add_u64 v[220:221], s[26:27], 0, v[134:135]
	s_mov_b32 m0, s75
	ds_read_b128 v[178:181], v149 offset:16384
	ds_read_b128 v[182:185], v149 offset:17408
	ds_read_b128 v[196:199], v149 offset:18432
	ds_read_b128 v[200:203], v149 offset:19456
	ds_read_b128 v[204:207], v149 offset:20480
	ds_read_b128 v[208:211], v149 offset:21504
	ds_read_b128 v[212:215], v149 offset:22528
	ds_read_b128 v[216:219], v149 offset:23552
	global_load_lds_dwordx4 v[220:221], off
	s_add_i32 m0, s75, 0x2000
	s_add_u32 s80, s26, 0x4000
	v_lshl_add_u64 v[220:221], s[26:27], 0, v[130:131]
	s_addc_u32 s81, s27, 0
	s_add_i32 s75, s82, s37
	global_load_lds_dwordx4 v[220:221], off
	v_lshl_add_u64 v[220:221], s[80:81], 0, v[134:135]
	s_mov_b32 m0, s75
	s_nop 0
	global_load_lds_dwordx4 v[220:221], off
	v_lshl_add_u64 v[220:221], s[80:81], 0, v[130:131]
	s_add_i32 m0, s75, 0x2000
	s_nop 0
	global_load_lds_dwordx4 v[220:221], off
	v_lshl_add_u64 v[220:221], s[28:29], 0, v[136:137]
	s_mov_b32 m0, s40
	s_nop 0
	global_load_lds_dwordx4 v[220:221], off
	v_lshl_add_u64 v[220:221], s[28:29], 0, v[132:133]
	s_mov_b32 m0, s41
	s_nop 0
	global_load_lds_dwordx4 v[220:221], off
	s_waitcnt vmcnt(8)
	s_waitcnt lgkmcnt(0)
	s_barrier
; #define PG8_STAGE(bufoff, gbase, voff) do { _Pragma("unroll") for (int _i = 0; _i < 2; ++_i) \
;         __builtin_amdgcn_global_load_lds((const unsigned*)((const char*)(gbase) + (voff)[_i]), (PG8_LAS unsigned*)(lds + (bufoff) + ldsw + _i * 8192), 16, 0, 0); } while (0)
; #define PG8_LDA(dst, b, h) do { _Pragma("unroll") for (int m = 0; m < 4; ++m) _Pragma("unroll") for (int k = 0; k < 2; ++k) dst[m][k] = *(const PG8_LAS bf16x8*)(lds + PG8_SA(b, h) + aoff + m * 2048 + k * 1024); } while (0)
; #define PG8_LDB(dst, b, h) do { _Pragma("unroll") for (int n = 0; n < 2; ++n) _Pragma("unroll") for (int k = 0; k < 2; ++k) dst[n][k] = *(const PG8_LAS bf16x8*)(lds + PG8_SB(b, h) + boff + n * 2048 + k * 1024); } while (0)
; #define PG8_MMA(ai, bj, At, Bt) do { __builtin_amdgcn_s_setprio(1); _Pragma("unroll") for (int m = 0; m < 4; ++m) _Pragma("unroll") for (int n = 0; n < 2; ++n) _Pragma("unroll") for (int k = 0; k < 2; ++k) \
;         acc[ai][bj][m][n] = __builtin_amdgcn_mfma_f32_16x16x32_bf16(Bt[n][k], At[m][k], acc[ai][bj][m][n], 0, 0, 0); __builtin_amdgcn_s_setprio(0); } while (0)
; #define PG8_WAIT_V(n) asm volatile("s_waitcnt vmcnt(" #n ")" ::: "memory")
; template <class Epi, class Sched, bool ALIGN_EPI = false, bool SP2 = false, bool ABLK = false, bool BBLK = false>
; __device__ __forceinline__ void gemm_phase(PG8_LAS unsigned char* lds, const Gemm g, const Sched& S, const Epi& E) {
;     ...
;         for (int t = 0; t < nt; t += 2) {
;             const bool last = (t == nt - 2);
;             const char* a1 = cA + (size_t)(t + 1) * kstepA;
;             const char* a2 = last ? nA : cA + (size_t)(t + 2) * kstepA; const char* b2 = last ? nB : cB + (size_t)(t + 2) * kstepB;
;             const char* a3 = a2 + kstepA; const char* b3 = b2 + kstepB;
;             if (last && has_next) S.a_ready(nxt);
;             if constexpr (SP2) {
;             PG8_LDB(B0, 0, 0); PG8_LDB(B1, 0, 1); PG8_SCHED; PG8_LDA(At, 0, 0); PG8_STAGE(PG8_SA(1, 1), a1 + hstepA, voffA);
;             PG8_WAIT_V(8); PG8_WAIT_L(0); PG8_BAR; PG8_MMA(0, 0, At, B0); PG8_MMA(0, 1, At, B1); PG8_BAR; PG8_SCHED;
;             PG8_LDA(At, 0, 1); PG8_STAGE(PG8_SB(0, 0), b2, voffB); PG8_STAGE(PG8_SB(0, 1), b2 + hstepB, voffB); PG8_STAGE(PG8_SA(0, 0), a2, voffA);
;             PG8_WAIT_V(8); PG8_WAIT_L(0); PG8_BAR; PG8_MMA(1, 0, At, B0); PG8_MMA(1, 1, At, B1); PG8_BAR; PG8_SCHED;
	s_setprio 1
	s_waitcnt lgkmcnt(0)
	v_mfma_f32_16x16x32_bf16 v[62:65], v[142:145], v[178:181], 0
	v_mfma_f32_16x16x32_bf16 v[58:61], v[154:157], v[178:181], 0
	v_mfma_f32_16x16x32_bf16 v[50:53], v[142:145], v[196:199], 0
	v_mfma_f32_16x16x32_bf16 v[42:45], v[154:157], v[196:199], 0
	v_mfma_f32_16x16x32_bf16 v[38:41], v[142:145], v[204:207], 0
	v_mfma_f32_16x16x32_bf16 v[30:33], v[154:157], v[204:207], 0
	v_mfma_f32_16x16x32_bf16 v[22:25], v[142:145], v[212:215], 0
	v_mfma_f32_16x16x32_bf16 v[14:17], v[154:157], v[212:215], 0
	v_mfma_f32_16x16x32_bf16 v[62:65], v[150:153], v[182:185], v[62:65]
	v_mfma_f32_16x16x32_bf16 v[58:61], v[158:161], v[182:185], v[58:61]
	v_mfma_f32_16x16x32_bf16 v[50:53], v[150:153], v[200:203], v[50:53]
	v_mfma_f32_16x16x32_bf16 v[42:45], v[158:161], v[200:203], v[42:45]
	v_mfma_f32_16x16x32_bf16 v[38:41], v[150:153], v[208:211], v[38:41]
	v_mfma_f32_16x16x32_bf16 v[30:33], v[158:161], v[208:211], v[30:33]
	v_mfma_f32_16x16x32_bf16 v[22:25], v[150:153], v[216:219], v[22:25]
	v_mfma_f32_16x16x32_bf16 v[14:17], v[158:161], v[216:219], v[14:17]
	s_setprio 0
	s_setprio 1
	v_mfma_f32_16x16x32_bf16 v[54:57], v[162:165], v[178:181], 0
	v_mfma_f32_16x16x32_bf16 v[46:49], v[170:173], v[178:181], 0
	v_mfma_f32_16x16x32_bf16 v[34:37], v[162:165], v[196:199], 0
	v_mfma_f32_16x16x32_bf16 v[26:29], v[170:173], v[196:199], 0
	v_mfma_f32_16x16x32_bf16 v[18:21], v[162:165], v[204:207], 0
	v_mfma_f32_16x16x32_bf16 v[10:13], v[170:173], v[204:207], 0
	v_mfma_f32_16x16x32_bf16 v[6:9], v[162:165], v[212:215], 0
	v_mfma_f32_16x16x32_bf16 v[2:5], v[170:173], v[212:215], 0
	v_mfma_f32_16x16x32_bf16 v[54:57], v[166:169], v[182:185], v[54:57]
	v_mfma_f32_16x16x32_bf16 v[46:49], v[174:177], v[182:185], v[46:49]
	v_mfma_f32_16x16x32_bf16 v[34:37], v[166:169], v[200:203], v[34:37]
	v_mfma_f32_16x16x32_bf16 v[26:29], v[174:177], v[200:203], v[26:29]
	v_mfma_f32_16x16x32_bf16 v[18:21], v[166:169], v[208:211], v[18:21]
	v_mfma_f32_16x16x32_bf16 v[10:13], v[174:177], v[208:211], v[10:13]
	v_mfma_f32_16x16x32_bf16 v[6:9], v[166:169], v[216:219], v[6:9]
	v_mfma_f32_16x16x32_bf16 v[2:5], v[174:177], v[216:219], v[2:5]
	s_setprio 0
	s_barrier
	s_branch .Lmid_658
.LBB0_658:
	s_add_u32 s24, s22, 0x4000
	s_addc_u32 s25, s23, 0
	s_cmp_eq_u32 s73, 28
	s_cselect_b32 s28, s61, s24
	s_cselect_b32 s29, s13, s25
	s_cselect_b32 s26, s65, s68
	s_cselect_b32 s27, s1, s72
	s_add_u32 s24, s28, 0x8000
	s_addc_u32 s25, s29, 0
	s_add_i32 s75, 0, 0x10000
	s_add_i32 s82, 0, 0x14000
	v_add_u32_e32 v158, s75, v147
	v_add_u32_e32 v174, s82, v147
	ds_read_b128 v[142:145], v158
	ds_read_b128 v[150:153], v158 offset:1024
	ds_read_b128 v[154:157], v158 offset:2048
	ds_read_b128 v[158:161], v158 offset:3072
	ds_read_b128 v[162:165], v174
	ds_read_b128 v[166:169], v174 offset:1024
	ds_read_b128 v[170:173], v174 offset:2048
	ds_read_b128 v[174:177], v174 offset:3072
	v_lshl_add_u64 v[220:221], s[22:23], 0, v[138:139]
	s_add_i32 m0, s40, 0xc000
	ds_read_b128 v[178:181], v149
	ds_read_b128 v[182:185], v149 offset:1024
	ds_read_b128 v[196:199], v149 offset:2048
	ds_read_b128 v[200:203], v149 offset:3072
	ds_read_b128 v[204:207], v149 offset:4096
	ds_read_b128 v[208:211], v149 offset:5120
	ds_read_b128 v[212:215], v149 offset:6144
	ds_read_b128 v[216:219], v149 offset:7168
	global_load_lds_dwordx4 v[220:221], off
	v_lshl_add_u64 v[220:221], s[22:23], 0, v[140:141]
	s_add_i32 m0, s40, 0xe000
	s_nop 0
	global_load_lds_dwordx4 v[220:221], off
	s_waitcnt vmcnt(8)
	s_waitcnt lgkmcnt(0)
	s_barrier
	s_setprio 1
	s_waitcnt lgkmcnt(0)
	v_mfma_f32_16x16x32_bf16 v[126:129], v[142:145], v[178:181], v[126:129]
	v_mfma_f32_16x16x32_bf16 v[122:125], v[154:157], v[178:181], v[122:125]
	v_mfma_f32_16x16x32_bf16 v[114:117], v[142:145], v[196:199], v[114:117]
	v_mfma_f32_16x16x32_bf16 v[106:109], v[154:157], v[196:199], v[106:109]
	v_mfma_f32_16x16x32_bf16 v[102:105], v[142:145], v[204:207], v[102:105]
	v_mfma_f32_16x16x32_bf16 v[94:97], v[154:157], v[204:207], v[94:97]
	v_mfma_f32_16x16x32_bf16 v[86:89], v[142:145], v[212:215], v[86:89]
	v_mfma_f32_16x16x32_bf16 v[78:81], v[154:157], v[212:215], v[78:81]
	v_mfma_f32_16x16x32_bf16 v[126:129], v[150:153], v[182:185], v[126:129]
	v_mfma_f32_16x16x32_bf16 v[122:125], v[158:161], v[182:185], v[122:125]
	v_mfma_f32_16x16x32_bf16 v[114:117], v[150:153], v[200:203], v[114:117]
	v_mfma_f32_16x16x32_bf16 v[106:109], v[158:161], v[200:203], v[106:109]
	v_mfma_f32_16x16x32_bf16 v[102:105], v[150:153], v[208:211], v[102:105]
	v_mfma_f32_16x16x32_bf16 v[94:97], v[158:161], v[208:211], v[94:97]
	v_mfma_f32_16x16x32_bf16 v[86:89], v[150:153], v[216:219], v[86:89]
	v_mfma_f32_16x16x32_bf16 v[78:81], v[158:161], v[216:219], v[78:81]
	s_setprio 0
	s_setprio 1
	v_mfma_f32_16x16x32_bf16 v[118:121], v[162:165], v[178:181], v[118:121]
	v_mfma_f32_16x16x32_bf16 v[110:113], v[170:173], v[178:181], v[110:113]
	v_mfma_f32_16x16x32_bf16 v[98:101], v[162:165], v[196:199], v[98:101]
	v_mfma_f32_16x16x32_bf16 v[90:93], v[170:173], v[196:199], v[90:93]
	v_mfma_f32_16x16x32_bf16 v[82:85], v[162:165], v[204:207], v[82:85]
	v_mfma_f32_16x16x32_bf16 v[74:77], v[170:173], v[204:207], v[74:77]
	v_mfma_f32_16x16x32_bf16 v[70:73], v[162:165], v[212:215], v[70:73]
	v_mfma_f32_16x16x32_bf16 v[66:69], v[170:173], v[212:215], v[66:69]
	v_mfma_f32_16x16x32_bf16 v[118:121], v[166:169], v[182:185], v[118:121]
	v_mfma_f32_16x16x32_bf16 v[110:113], v[174:177], v[182:185], v[110:113]
	v_mfma_f32_16x16x32_bf16 v[98:101], v[166:169], v[200:203], v[98:101]
	v_mfma_f32_16x16x32_bf16 v[90:93], v[174:177], v[200:203], v[90:93]
	v_mfma_f32_16x16x32_bf16 v[82:85], v[166:169], v[208:211], v[82:85]
	v_mfma_f32_16x16x32_bf16 v[74:77], v[174:177], v[208:211], v[74:77]
	v_mfma_f32_16x16x32_bf16 v[70:73], v[166:169], v[216:219], v[70:73]
	v_mfma_f32_16x16x32_bf16 v[66:69], v[174:177], v[216:219], v[66:69]
	s_setprio 0
	s_barrier
; #define PG8_STAGE(bufoff, gbase, voff) do { _Pragma("unroll") for (int _i = 0; _i < 2; ++_i) \
;         __builtin_amdgcn_global_load_lds((const unsigned*)((const char*)(gbase) + (voff)[_i]), (PG8_LAS unsigned*)(lds + (bufoff) + ldsw + _i * 8192), 16, 0, 0); } while (0)
; #define PG8_LDA(dst, b, h) do { _Pragma("unroll") for (int m = 0; m < 4; ++m) _Pragma("unroll") for (int k = 0; k < 2; ++k) dst[m][k] = *(const PG8_LAS bf16x8*)(lds + PG8_SA(b, h) + aoff + m * 2048 + k * 1024); } while (0)
; #define PG8_LDB(dst, b, h) do { _Pragma("unroll") for (int n = 0; n < 2; ++n) _Pragma("unroll") for (int k = 0; k < 2; ++k) dst[n][k] = *(const PG8_LAS bf16x8*)(lds + PG8_SB(b, h) + boff + n * 2048 + k * 1024); } while (0)
; #define PG8_MMA(ai, bj, At, Bt) do { __builtin_amdgcn_s_setprio(1); _Pragma("unroll") for (int m = 0; m < 4; ++m) _Pragma("unroll") for (int n = 0; n < 2; ++n) _Pragma("unroll") for (int k = 0; k < 2; ++k) \
;         acc[ai][bj][m][n] = __builtin_amdgcn_mfma_f32_16x16x32_bf16(Bt[n][k], At[m][k], acc[ai][bj][m][n], 0, 0, 0); __builtin_amdgcn_s_setprio(0); } while (0)
; #define PG8_WAIT_V(n) asm volatile("s_waitcnt vmcnt(" #n ")" ::: "memory")
; #define PG8_WAIT_L(n) asm volatile("s_waitcnt lgkmcnt(" #n ")" ::: "memory")
; #define PG8_BAR __builtin_amdgcn_s_barrier()
; #define PG8_SCHED __builtin_amdgcn_sched_barrier(0)
; template <class Epi, class Sched, bool ALIGN_EPI = false, bool SP2 = false, bool ABLK = false, bool BBLK = false>
; __device__ __forceinline__ void gemm_phase(PG8_LAS unsigned char* lds, const Gemm g, const Sched& S, const Epi& E) {
;     ...
;             PG8_LDA(At, 0, 1); PG8_STAGE(PG8_SB(0, 0), b2, voffB); PG8_STAGE(PG8_SB(0, 1), b2 + hstepB, voffB); PG8_STAGE(PG8_SA(0, 0), a2, voffA);
;             PG8_WAIT_V(8); PG8_WAIT_L(0); PG8_BAR; PG8_MMA(1, 0, At, B0); PG8_MMA(1, 1, At, B1); PG8_BAR; PG8_SCHED;
;             PG8_LDB(B0, 1, 0); PG8_LDB(B1, 1, 1); PG8_SCHED; PG8_LDA(At, 1, 0); PG8_STAGE(PG8_SA(0, 1), a2 + hstepA, voffA);
;             PG8_WAIT_V(8); PG8_WAIT_L(0); PG8_BAR; PG8_MMA(0, 0, At, B0); PG8_MMA(0, 1, At, B1); PG8_BAR; PG8_SCHED;
	s_add_i32 s75, s75, s37
	v_lshl_add_u64 v[220:221], s[26:27], 0, v[134:135]
	s_mov_b32 m0, s75
	ds_read_b128 v[178:181], v149 offset:16384
	ds_read_b128 v[182:185], v149 offset:17408
	ds_read_b128 v[196:199], v149 offset:18432
	ds_read_b128 v[200:203], v149 offset:19456
	ds_read_b128 v[204:207], v149 offset:20480
	ds_read_b128 v[208:211], v149 offset:21504
	ds_read_b128 v[212:215], v149 offset:22528
	ds_read_b128 v[216:219], v149 offset:23552
	global_load_lds_dwordx4 v[220:221], off
	s_add_i32 m0, s75, 0x2000
	s_add_u32 s80, s26, 0x4000
	v_lshl_add_u64 v[220:221], s[26:27], 0, v[130:131]
	s_addc_u32 s81, s27, 0
	s_add_i32 s75, s82, s37
	global_load_lds_dwordx4 v[220:221], off
	v_lshl_add_u64 v[220:221], s[80:81], 0, v[134:135]
	s_mov_b32 m0, s75
	s_nop 0
	global_load_lds_dwordx4 v[220:221], off
	v_lshl_add_u64 v[220:221], s[80:81], 0, v[130:131]
	s_add_i32 m0, s75, 0x2000
	s_nop 0
	global_load_lds_dwordx4 v[220:221], off
	v_lshl_add_u64 v[220:221], s[28:29], 0, v[136:137]
	s_mov_b32 m0, s40
	s_nop 0
	global_load_lds_dwordx4 v[220:221], off
	v_lshl_add_u64 v[220:221], s[28:29], 0, v[132:133]
	s_mov_b32 m0, s41
	s_nop 0
	global_load_lds_dwordx4 v[220:221], off
	s_waitcnt vmcnt(8)
	s_waitcnt lgkmcnt(0)
	s_barrier
	s_setprio 1
	s_waitcnt lgkmcnt(0)
	v_mfma_f32_16x16x32_bf16 v[62:65], v[142:145], v[178:181], v[62:65]
	v_mfma_f32_16x16x32_bf16 v[58:61], v[154:157], v[178:181], v[58:61]
	v_mfma_f32_16x16x32_bf16 v[50:53], v[142:145], v[196:199], v[50:53]
	v_mfma_f32_16x16x32_bf16 v[42:45], v[154:157], v[196:199], v[42:45]
	v_mfma_f32_16x16x32_bf16 v[38:41], v[142:145], v[204:207], v[38:41]
	v_mfma_f32_16x16x32_bf16 v[30:33], v[154:157], v[204:207], v[30:33]
	v_mfma_f32_16x16x32_bf16 v[22:25], v[142:145], v[212:215], v[22:25]
	v_mfma_f32_16x16x32_bf16 v[14:17], v[154:157], v[212:215], v[14:17]
	v_mfma_f32_16x16x32_bf16 v[62:65], v[150:153], v[182:185], v[62:65]
	v_mfma_f32_16x16x32_bf16 v[58:61], v[158:161], v[182:185], v[58:61]
	v_mfma_f32_16x16x32_bf16 v[50:53], v[150:153], v[200:203], v[50:53]
	v_mfma_f32_16x16x32_bf16 v[42:45], v[158:161], v[200:203], v[42:45]
	v_mfma_f32_16x16x32_bf16 v[38:41], v[150:153], v[208:211], v[38:41]
	v_mfma_f32_16x16x32_bf16 v[30:33], v[158:161], v[208:211], v[30:33]
	v_mfma_f32_16x16x32_bf16 v[22:25], v[150:153], v[216:219], v[22:25]
	v_mfma_f32_16x16x32_bf16 v[14:17], v[158:161], v[216:219], v[14:17]
	s_setprio 0
	s_setprio 1
	v_mfma_f32_16x16x32_bf16 v[54:57], v[162:165], v[178:181], v[54:57]
	v_mfma_f32_16x16x32_bf16 v[46:49], v[170:173], v[178:181], v[46:49]
	v_mfma_f32_16x16x32_bf16 v[34:37], v[162:165], v[196:199], v[34:37]
	v_mfma_f32_16x16x32_bf16 v[26:29], v[170:173], v[196:199], v[26:29]
	v_mfma_f32_16x16x32_bf16 v[18:21], v[162:165], v[204:207], v[18:21]
	v_mfma_f32_16x16x32_bf16 v[10:13], v[170:173], v[204:207], v[10:13]
	v_mfma_f32_16x16x32_bf16 v[6:9], v[162:165], v[212:215], v[6:9]
	v_mfma_f32_16x16x32_bf16 v[2:5], v[170:173], v[212:215], v[2:5]
	v_mfma_f32_16x16x32_bf16 v[54:57], v[166:169], v[182:185], v[54:57]
	v_mfma_f32_16x16x32_bf16 v[46:49], v[174:177], v[182:185], v[46:49]
	v_mfma_f32_16x16x32_bf16 v[34:37], v[166:169], v[200:203], v[34:37]
	v_mfma_f32_16x16x32_bf16 v[26:29], v[174:177], v[200:203], v[26:29]
	v_mfma_f32_16x16x32_bf16 v[18:21], v[166:169], v[208:211], v[18:21]
	v_mfma_f32_16x16x32_bf16 v[10:13], v[174:177], v[208:211], v[10:13]
	v_mfma_f32_16x16x32_bf16 v[6:9], v[166:169], v[216:219], v[6:9]
	v_mfma_f32_16x16x32_bf16 v[2:5], v[174:177], v[216:219], v[2:5]
	s_setprio 0
	s_barrier
.Lmid_658:
	s_add_i32 s75, 0, 0x18000
	s_add_i32 s80, 0, 0x1c000
	v_add_u32_e32 v158, s75, v147
	v_add_u32_e32 v174, s80, v147
	ds_read_b128 v[142:145], v158
	ds_read_b128 v[150:153], v158 offset:1024
	ds_read_b128 v[154:157], v158 offset:2048
	ds_read_b128 v[158:161], v158 offset:3072
	ds_read_b128 v[162:165], v174
	ds_read_b128 v[166:169], v174 offset:1024
	ds_read_b128 v[170:173], v174 offset:2048
	ds_read_b128 v[174:177], v174 offset:3072
	s_add_u32 s28, s28, 0x4000
	s_addc_u32 s29, s29, 0
	s_mov_b32 m0, s44
	v_lshl_add_u64 v[220:221], s[28:29], 0, v[136:137]
	ds_read_b128 v[178:181], v149 offset:32768
	ds_read_b128 v[182:185], v149 offset:33792
	ds_read_b128 v[196:199], v149 offset:34816
	ds_read_b128 v[200:203], v149 offset:35840
	ds_read_b128 v[204:207], v149 offset:36864
	ds_read_b128 v[208:211], v149 offset:37888
	ds_read_b128 v[212:215], v149 offset:38912
	ds_read_b128 v[216:219], v149 offset:39936
	global_load_lds_dwordx4 v[220:221], off
	v_lshl_add_u64 v[220:221], s[28:29], 0, v[132:133]
	s_mov_b32 m0, s45
	s_nop 0
	global_load_lds_dwordx4 v[220:221], off
	s_waitcnt vmcnt(8)
	s_waitcnt lgkmcnt(0)
	s_barrier
; #define PG8_STAGE(bufoff, gbase, voff) do { _Pragma("unroll") for (int _i = 0; _i < 2; ++_i) \
;         __builtin_amdgcn_global_load_lds((const unsigned*)((const char*)(gbase) + (voff)[_i]), (PG8_LAS unsigned*)(lds + (bufoff) + ldsw + _i * 8192), 16, 0, 0); } while (0)
; #define PG8_LDA(dst, b, h) do { _Pragma("unroll") for (int m = 0; m < 4; ++m) _Pragma("unroll") for (int k = 0; k < 2; ++k) dst[m][k] = *(const PG8_LAS bf16x8*)(lds + PG8_SA(b, h) + aoff + m * 2048 + k * 1024); } while (0)
; #define PG8_MMA(ai, bj, At, Bt) do { __builtin_amdgcn_s_setprio(1); _Pragma("unroll") for (int m = 0; m < 4; ++m) _Pragma("unroll") for (int n = 0; n < 2; ++n) _Pragma("unroll") for (int k = 0; k < 2; ++k) \
;         acc[ai][bj][m][n] = __builtin_amdgcn_mfma_f32_16x16x32_bf16(Bt[n][k], At[m][k], acc[ai][bj][m][n], 0, 0, 0); __builtin_amdgcn_s_setprio(0); } while (0)
; #define PG8_WAIT_V(n) asm volatile("s_waitcnt vmcnt(" #n ")" ::: "memory")
; #define PG8_WAIT_L(n) asm volatile("s_waitcnt lgkmcnt(" #n ")" ::: "memory")
; #define PG8_BAR __builtin_amdgcn_s_barrier()
; #define PG8_SCHED __builtin_amdgcn_sched_barrier(0)
; template <class Epi, class Sched, bool ALIGN_EPI = false, bool SP2 = false, bool ABLK = false, bool BBLK = false>
; __device__ __forceinline__ void gemm_phase(PG8_LAS unsigned char* lds, const Gemm g, const Sched& S, const Epi& E) {
;     ...
;             PG8_WAIT_V(8); PG8_WAIT_L(0); PG8_BAR; PG8_MMA(0, 0, At, B0); PG8_MMA(0, 1, At, B1); PG8_BAR; PG8_SCHED;
;             PG8_LDA(At, 1, 1); PG8_STAGE(PG8_SB(1, 0), b3, voffB); PG8_STAGE(PG8_SB(1, 1), b3 + hstepB, voffB); PG8_STAGE(PG8_SA(1, 0), a3, voffA);
;             PG8_WAIT_V(8); PG8_WAIT_L(0); PG8_BAR; PG8_MMA(1, 0, At, B0); PG8_MMA(1, 1, At, B1); PG8_BAR; PG8_SCHED;
;     ...
;         if constexpr (ALIGN_EPI) { if (wr == 0) PG8_BAR; }
	s_setprio 1
	s_waitcnt lgkmcnt(0)
	v_mfma_f32_16x16x32_bf16 v[126:129], v[142:145], v[178:181], v[126:129]
	v_mfma_f32_16x16x32_bf16 v[122:125], v[154:157], v[178:181], v[122:125]
	v_mfma_f32_16x16x32_bf16 v[114:117], v[142:145], v[196:199], v[114:117]
	v_mfma_f32_16x16x32_bf16 v[106:109], v[154:157], v[196:199], v[106:109]
	v_mfma_f32_16x16x32_bf16 v[102:105], v[142:145], v[204:207], v[102:105]
	v_mfma_f32_16x16x32_bf16 v[94:97], v[154:157], v[204:207], v[94:97]
	v_mfma_f32_16x16x32_bf16 v[86:89], v[142:145], v[212:215], v[86:89]
	v_mfma_f32_16x16x32_bf16 v[78:81], v[154:157], v[212:215], v[78:81]
	v_mfma_f32_16x16x32_bf16 v[126:129], v[150:153], v[182:185], v[126:129]
	v_mfma_f32_16x16x32_bf16 v[122:125], v[158:161], v[182:185], v[122:125]
	v_mfma_f32_16x16x32_bf16 v[114:117], v[150:153], v[200:203], v[114:117]
	v_mfma_f32_16x16x32_bf16 v[106:109], v[158:161], v[200:203], v[106:109]
	v_mfma_f32_16x16x32_bf16 v[102:105], v[150:153], v[208:211], v[102:105]
	v_mfma_f32_16x16x32_bf16 v[94:97], v[158:161], v[208:211], v[94:97]
	v_mfma_f32_16x16x32_bf16 v[86:89], v[150:153], v[216:219], v[86:89]
	v_mfma_f32_16x16x32_bf16 v[78:81], v[158:161], v[216:219], v[78:81]
	s_setprio 0
	s_setprio 1
	v_mfma_f32_16x16x32_bf16 v[118:121], v[162:165], v[178:181], v[118:121]
	v_mfma_f32_16x16x32_bf16 v[110:113], v[170:173], v[178:181], v[110:113]
	v_mfma_f32_16x16x32_bf16 v[98:101], v[162:165], v[196:199], v[98:101]
	v_mfma_f32_16x16x32_bf16 v[90:93], v[170:173], v[196:199], v[90:93]
	v_mfma_f32_16x16x32_bf16 v[82:85], v[162:165], v[204:207], v[82:85]
	v_mfma_f32_16x16x32_bf16 v[74:77], v[170:173], v[204:207], v[74:77]
	v_mfma_f32_16x16x32_bf16 v[70:73], v[162:165], v[212:215], v[70:73]
	v_mfma_f32_16x16x32_bf16 v[66:69], v[170:173], v[212:215], v[66:69]
	v_mfma_f32_16x16x32_bf16 v[118:121], v[166:169], v[182:185], v[118:121]
	v_mfma_f32_16x16x32_bf16 v[110:113], v[174:177], v[182:185], v[110:113]
	v_mfma_f32_16x16x32_bf16 v[98:101], v[166:169], v[200:203], v[98:101]
	v_mfma_f32_16x16x32_bf16 v[90:93], v[174:177], v[200:203], v[90:93]
	v_mfma_f32_16x16x32_bf16 v[82:85], v[166:169], v[208:211], v[82:85]
	v_mfma_f32_16x16x32_bf16 v[74:77], v[174:177], v[208:211], v[74:77]
	v_mfma_f32_16x16x32_bf16 v[70:73], v[166:169], v[216:219], v[70:73]
	v_mfma_f32_16x16x32_bf16 v[66:69], v[174:177], v[216:219], v[66:69]
	s_setprio 0
	s_barrier
	s_add_u32 s28, s26, 0x8000
	s_addc_u32 s29, s27, 0
	s_add_i32 s75, s75, s37
	v_lshl_add_u64 v[220:221], s[28:29], 0, v[134:135]
	s_mov_b32 m0, s75
	ds_read_b128 v[178:181], v149 offset:49152
	ds_read_b128 v[182:185], v149 offset:50176
	ds_read_b128 v[196:199], v149 offset:51200
	ds_read_b128 v[200:203], v149 offset:52224
	ds_read_b128 v[204:207], v149 offset:53248
	ds_read_b128 v[208:211], v149 offset:54272
	ds_read_b128 v[212:215], v149 offset:55296
	ds_read_b128 v[216:219], v149 offset:56320
	global_load_lds_dwordx4 v[220:221], off
	s_add_i32 m0, s75, 0x2000
	s_add_u32 s26, s26, 0xc000
	v_lshl_add_u64 v[220:221], s[28:29], 0, v[130:131]
	s_addc_u32 s27, s27, 0
	s_add_i32 s28, s80, s37
	global_load_lds_dwordx4 v[220:221], off
	v_lshl_add_u64 v[220:221], s[26:27], 0, v[134:135]
	s_mov_b32 m0, s28
	s_nop 0
	global_load_lds_dwordx4 v[220:221], off
	v_lshl_add_u64 v[220:221], s[26:27], 0, v[130:131]
	s_add_i32 m0, s28, 0x2000
	s_nop 0
	global_load_lds_dwordx4 v[220:221], off
	v_lshl_add_u64 v[220:221], s[24:25], 0, v[136:137]
	s_mov_b32 m0, s46
	s_nop 0
	global_load_lds_dwordx4 v[220:221], off
	v_lshl_add_u64 v[220:221], s[24:25], 0, v[132:133]
	s_mov_b32 m0, s47
	s_nop 0
	global_load_lds_dwordx4 v[220:221], off
	s_waitcnt vmcnt(8)
	s_waitcnt lgkmcnt(0)
	s_barrier
	s_setprio 1
	s_waitcnt lgkmcnt(0)
	v_mfma_f32_16x16x32_bf16 v[62:65], v[142:145], v[178:181], v[62:65]
	v_mfma_f32_16x16x32_bf16 v[58:61], v[154:157], v[178:181], v[58:61]
	v_mfma_f32_16x16x32_bf16 v[50:53], v[142:145], v[196:199], v[50:53]
	v_mfma_f32_16x16x32_bf16 v[42:45], v[154:157], v[196:199], v[42:45]
	v_mfma_f32_16x16x32_bf16 v[38:41], v[142:145], v[204:207], v[38:41]
	v_mfma_f32_16x16x32_bf16 v[30:33], v[154:157], v[204:207], v[30:33]
	v_mfma_f32_16x16x32_bf16 v[22:25], v[142:145], v[212:215], v[22:25]
	v_mfma_f32_16x16x32_bf16 v[14:17], v[154:157], v[212:215], v[14:17]
	v_mfma_f32_16x16x32_bf16 v[62:65], v[150:153], v[182:185], v[62:65]
	v_mfma_f32_16x16x32_bf16 v[58:61], v[158:161], v[182:185], v[58:61]
	v_mfma_f32_16x16x32_bf16 v[50:53], v[150:153], v[200:203], v[50:53]
	v_mfma_f32_16x16x32_bf16 v[42:45], v[158:161], v[200:203], v[42:45]
	v_mfma_f32_16x16x32_bf16 v[38:41], v[150:153], v[208:211], v[38:41]
	v_mfma_f32_16x16x32_bf16 v[30:33], v[158:161], v[208:211], v[30:33]
	v_mfma_f32_16x16x32_bf16 v[22:25], v[150:153], v[216:219], v[22:25]
	v_mfma_f32_16x16x32_bf16 v[14:17], v[158:161], v[216:219], v[14:17]
	s_setprio 0
	s_setprio 1
	v_mfma_f32_16x16x32_bf16 v[54:57], v[162:165], v[178:181], v[54:57]
	v_mfma_f32_16x16x32_bf16 v[46:49], v[170:173], v[178:181], v[46:49]
	v_mfma_f32_16x16x32_bf16 v[34:37], v[162:165], v[196:199], v[34:37]
	v_mfma_f32_16x16x32_bf16 v[26:29], v[170:173], v[196:199], v[26:29]
	v_mfma_f32_16x16x32_bf16 v[18:21], v[162:165], v[204:207], v[18:21]
	v_mfma_f32_16x16x32_bf16 v[10:13], v[170:173], v[204:207], v[10:13]
	v_mfma_f32_16x16x32_bf16 v[6:9], v[162:165], v[212:215], v[6:9]
	v_mfma_f32_16x16x32_bf16 v[2:5], v[170:173], v[212:215], v[2:5]
	v_mfma_f32_16x16x32_bf16 v[54:57], v[166:169], v[182:185], v[54:57]
	v_mfma_f32_16x16x32_bf16 v[46:49], v[174:177], v[182:185], v[46:49]
	v_mfma_f32_16x16x32_bf16 v[34:37], v[166:169], v[200:203], v[34:37]
	v_mfma_f32_16x16x32_bf16 v[26:29], v[174:177], v[200:203], v[26:29]
	v_mfma_f32_16x16x32_bf16 v[18:21], v[166:169], v[208:211], v[18:21]
	v_mfma_f32_16x16x32_bf16 v[10:13], v[174:177], v[208:211], v[10:13]
	v_mfma_f32_16x16x32_bf16 v[6:9], v[166:169], v[216:219], v[6:9]
	v_mfma_f32_16x16x32_bf16 v[2:5], v[174:177], v[216:219], v[2:5]
	s_setprio 0
	s_barrier
	s_add_i32 s73, s73, 2
	s_add_u32 s22, s22, 0x10000
	s_addc_u32 s23, s23, 0
	s_add_u32 s68, s68, 0x10000
	s_addc_u32 s72, s72, 0
	s_cmp_gt_u32 s73, 29
	s_cbranch_scc0 .LBB0_658
	s_and_b64 vcc, exec, s[8:9]
	s_cbranch_vccz .LBB0_661
	s_barrier

; #define PG8_STAGE(bufoff, gbase, voff) do { _Pragma("unroll") for (int _i = 0; _i < 2; ++_i) \
;         __builtin_amdgcn_global_load_lds((const unsigned*)((const char*)(gbase) + (voff)[_i]), (PG8_LAS unsigned*)(lds + (bufoff) + ldsw + _i * 8192), 16, 0, 0); } while (0)
; #define PG8_LDA(dst, b, h) do { _Pragma("unroll") for (int m = 0; m < 4; ++m) _Pragma("unroll") for (int k = 0; k < 2; ++k) dst[m][k] = *(const PG8_LAS bf16x8*)(lds + PG8_SA(b, h) + aoff + m * 2048 + k * 1024); } while (0)
; #define PG8_LDB(dst, b, h) do { _Pragma("unroll") for (int n = 0; n < 2; ++n) _Pragma("unroll") for (int k = 0; k < 2; ++k) dst[n][k] = *(const PG8_LAS bf16x8*)(lds + PG8_SB(b, h) + boff + n * 2048 + k * 1024); } while (0)
; #define PG8_WAIT_V(n) asm volatile("s_waitcnt vmcnt(" #n ")" ::: "memory")
; #define PG8_WAIT_L(n) asm volatile("s_waitcnt lgkmcnt(" #n ")" ::: "memory")
; #define PG8_BAR __builtin_amdgcn_s_barrier()
; template <class Epi, class Sched, bool ALIGN_EPI = false, bool SP2 = false, bool ABLK = false, bool BBLK = false>
; __device__ __forceinline__ void gemm_phase(PG8_LAS unsigned char* lds, const Gemm g, const Sched& S, const Epi& E) {
;     ...
;     for (;;) {
;         const bool has_next = S.next(ui + 1, nxt);
;         const char* nA = has_next ? (const char*)g.A + (size_t)nxt.pm * tstepA : cA; const char* nB = has_next ? (const char*)g.Bt + (size_t)nxt.pn * tstepB : cB;
;         for (int t = 0; t < nt; t += 2) {
;             const bool last = (t == nt - 2);
;             const char* a1 = cA + (size_t)(t + 1) * kstepA;
;             const char* a2 = last ? nA : cA + (size_t)(t + 2) * kstepA; const char* b2 = last ? nB : cB + (size_t)(t + 2) * kstepB;
;             const char* a3 = a2 + kstepA; const char* b3 = b2 + kstepB;
;             if (last && has_next) S.a_ready(nxt);
;             if constexpr (SP2) {
;             PG8_LDB(B0, 0, 0); PG8_LDB(B1, 0, 1); PG8_SCHED; PG8_LDA(At, 0, 0); PG8_STAGE(PG8_SA(1, 1), a1 + hstepA, voffA);
;             PG8_WAIT_V(8); PG8_WAIT_L(0); PG8_BAR; PG8_MMA(0, 0, At, B0); PG8_MMA(0, 1, At, B1); PG8_BAR; PG8_SCHED;
;             PG8_LDA(At, 0, 1); PG8_STAGE(PG8_SB(0, 0), b2, voffB); PG8_STAGE(PG8_SB(0, 1), b2 + hstepB, voffB); PG8_STAGE(PG8_SA(0, 0), a2, voffA);
;             PG8_WAIT_V(8); PG8_WAIT_L(0); PG8_BAR; PG8_MMA(1, 0, At, B0); PG8_MMA(1, 1, At, B1); PG8_BAR; PG8_SCHED;
.LBB0_765:
	s_ashr_i32 s15, s14, 31
	s_lshl_b64 s[18:19], s[14:15], 20
	s_add_u32 s18, s33, s18
	s_addc_u32 s19, s34, s19
	s_and_b64 s[20:21], s[6:7], exec
	s_cselect_b32 s1, s19, s25
	s_cselect_b32 s11, s18, s24
	s_ashr_i32 s13, s12, 31
	s_lshl_b64 s[20:21], s[12:13], 20
	s_add_u32 s20, s35, s20
	s_addc_u32 s21, s36, s21
	s_and_b64 s[28:29], s[6:7], exec
	s_cselect_b32 s13, s21, s27
	s_cselect_b32 s15, s20, s26
	s_add_u32 s24, s24, 0x80080
	s_addc_u32 s25, s25, 0
	s_add_u32 s23, s26, 0x100
	v_mov_b32_e32 v2, 0
	s_addc_u32 s65, s27, 0
	s_mov_b32 s68, -2
	s_add_u32 s26, s24, 0xfff80080
	s_addc_u32 s27, s25, -1
	s_add_i32 s72, 0, 0x10000
	s_cmp_eq_u32 s68, 28
	s_cselect_b32 s29, s1, s27
	s_cselect_b32 s28, s11, s26
	v_add_u32_e32 v142, s72, v145
	s_cselect_b32 s27, s13, s65
	s_cselect_b32 s26, s15, s23
	s_add_i32 s75, 0, 0x14000
	ds_read_b128 v[148:151], v142
	ds_read_b128 v[152:155], v142 offset:1024
	ds_read_b128 v[156:159], v142 offset:2048
	ds_read_b128 v[160:163], v142 offset:3072
	v_add_u32_e32 v142, s75, v145
	ds_read_b128 v[164:167], v142
	ds_read_b128 v[168:171], v142 offset:1024
	ds_read_b128 v[172:175], v142 offset:2048
	ds_read_b128 v[176:179], v142 offset:3072
	v_lshl_add_u64 v[142:143], s[24:25], 0, v[138:139]
	s_add_i32 m0, s45, 0xc000
	ds_read_b128 v[180:183], v146
	ds_read_b128 v[196:199], v146 offset:1024
	ds_read_b128 v[200:203], v146 offset:2048
	ds_read_b128 v[204:207], v146 offset:3072
	ds_read_b128 v[208:211], v146 offset:4096
	ds_read_b128 v[212:215], v146 offset:5120
	ds_read_b128 v[216:219], v146 offset:6144
	ds_read_b128 v[220:223], v146 offset:7168
	global_load_lds_dwordx4 v[142:143], off
	v_lshl_add_u64 v[142:143], s[24:25], 0, v[140:141]
	s_add_i32 m0, s45, 0xe000
	s_nop 0
	global_load_lds_dwordx4 v[142:143], off
	s_waitcnt vmcnt(8)
	s_waitcnt lgkmcnt(0)
	s_barrier
	s_setprio 1
	s_waitcnt lgkmcnt(0)
	v_mfma_f32_16x16x32_bf16 v[126:129], v[148:151], v[180:183], 0
	v_mfma_f32_16x16x32_bf16 v[122:125], v[156:159], v[180:183], 0
	v_mfma_f32_16x16x32_bf16 v[114:117], v[148:151], v[200:203], 0
	v_mfma_f32_16x16x32_bf16 v[106:109], v[156:159], v[200:203], 0
	v_mfma_f32_16x16x32_bf16 v[98:101], v[148:151], v[208:211], 0
	v_mfma_f32_16x16x32_bf16 v[90:93], v[156:159], v[208:211], 0
	v_mfma_f32_16x16x32_bf16 v[82:85], v[148:151], v[216:219], 0
	v_mfma_f32_16x16x32_bf16 v[74:77], v[156:159], v[216:219], 0
	v_mfma_f32_16x16x32_bf16 v[126:129], v[152:155], v[196:199], v[126:129]
	v_mfma_f32_16x16x32_bf16 v[122:125], v[160:163], v[196:199], v[122:125]
	v_mfma_f32_16x16x32_bf16 v[114:117], v[152:155], v[204:207], v[114:117]
	v_mfma_f32_16x16x32_bf16 v[106:109], v[160:163], v[204:207], v[106:109]
	v_mfma_f32_16x16x32_bf16 v[98:101], v[152:155], v[212:215], v[98:101]
	v_mfma_f32_16x16x32_bf16 v[90:93], v[160:163], v[212:215], v[90:93]
	v_mfma_f32_16x16x32_bf16 v[82:85], v[152:155], v[220:223], v[82:85]
	v_mfma_f32_16x16x32_bf16 v[74:77], v[160:163], v[220:223], v[74:77]
	s_setprio 0
	s_setprio 1
	v_mfma_f32_16x16x32_bf16 v[118:121], v[164:167], v[180:183], 0
	v_mfma_f32_16x16x32_bf16 v[110:113], v[172:175], v[180:183], 0
	v_mfma_f32_16x16x32_bf16 v[102:105], v[164:167], v[200:203], 0
	v_mfma_f32_16x16x32_bf16 v[94:97], v[172:175], v[200:203], 0
	v_mfma_f32_16x16x32_bf16 v[86:89], v[164:167], v[208:211], 0
	v_mfma_f32_16x16x32_bf16 v[78:81], v[172:175], v[208:211], 0
	v_mfma_f32_16x16x32_bf16 v[70:73], v[164:167], v[216:219], 0
	v_mfma_f32_16x16x32_bf16 v[66:69], v[172:175], v[216:219], 0
	v_mfma_f32_16x16x32_bf16 v[118:121], v[168:171], v[196:199], v[118:121]
	v_mfma_f32_16x16x32_bf16 v[110:113], v[176:179], v[196:199], v[110:113]
	v_mfma_f32_16x16x32_bf16 v[102:105], v[168:171], v[204:207], v[102:105]
	v_mfma_f32_16x16x32_bf16 v[94:97], v[176:179], v[204:207], v[94:97]
	v_mfma_f32_16x16x32_bf16 v[86:89], v[168:171], v[212:215], v[86:89]
	v_mfma_f32_16x16x32_bf16 v[78:81], v[176:179], v[212:215], v[78:81]
	v_mfma_f32_16x16x32_bf16 v[70:73], v[168:171], v[220:223], v[70:73]
	v_mfma_f32_16x16x32_bf16 v[66:69], v[176:179], v[220:223], v[66:69]
	s_setprio 0
	s_barrier
	s_add_i32 s72, s72, s37
	v_lshl_add_u64 v[142:143], s[26:27], 0, v[134:135]
	s_mov_b32 m0, s72
	ds_read_b128 v[180:183], v146 offset:16384
	ds_read_b128 v[196:199], v146 offset:17408
	ds_read_b128 v[200:203], v146 offset:18432
	ds_read_b128 v[204:207], v146 offset:19456
	ds_read_b128 v[208:211], v146 offset:20480
	ds_read_b128 v[212:215], v146 offset:21504
	ds_read_b128 v[216:219], v146 offset:22528
	ds_read_b128 v[220:223], v146 offset:23552
	global_load_lds_dwordx4 v[142:143], off
	s_add_i32 m0, s72, 0x2000
	s_add_u32 s72, s26, 0x80000
	v_lshl_add_u64 v[184:185], s[26:27], 0, v[130:131]
	s_addc_u32 s73, s27, 0
	s_add_i32 s75, s75, s37
	global_load_lds_dwordx4 v[184:185], off
	v_lshl_add_u64 v[224:225], s[72:73], 0, v[134:135]
	s_mov_b32 m0, s75
	v_lshl_add_u64 v[226:227], s[28:29], 0, v[132:133]
	global_load_lds_dwordx4 v[224:225], off
	v_lshl_add_u64 v[224:225], s[72:73], 0, v[130:131]
	s_add_i32 m0, s75, 0x2000
	s_nop 0
	global_load_lds_dwordx4 v[224:225], off
	v_lshl_add_u64 v[224:225], s[28:29], 0, v[136:137]
	s_mov_b32 m0, s45
	s_nop 0
	global_load_lds_dwordx4 v[224:225], off
	s_mov_b32 m0, s46
	s_nop 0
	global_load_lds_dwordx4 v[226:227], off
	s_waitcnt vmcnt(8)
	s_waitcnt lgkmcnt(0)
	s_barrier
; #define PG8_STAGE(bufoff, gbase, voff) do { _Pragma("unroll") for (int _i = 0; _i < 2; ++_i) \
;         __builtin_amdgcn_global_load_lds((const unsigned*)((const char*)(gbase) + (voff)[_i]), (PG8_LAS unsigned*)(lds + (bufoff) + ldsw + _i * 8192), 16, 0, 0); } while (0)
; #define PG8_LDA(dst, b, h) do { _Pragma("unroll") for (int m = 0; m < 4; ++m) _Pragma("unroll") for (int k = 0; k < 2; ++k) dst[m][k] = *(const PG8_LAS bf16x8*)(lds + PG8_SA(b, h) + aoff + m * 2048 + k * 1024); } while (0)
; #define PG8_LDB(dst, b, h) do { _Pragma("unroll") for (int n = 0; n < 2; ++n) _Pragma("unroll") for (int k = 0; k < 2; ++k) dst[n][k] = *(const PG8_LAS bf16x8*)(lds + PG8_SB(b, h) + boff + n * 2048 + k * 1024); } while (0)
; #define PG8_MMA(ai, bj, At, Bt) do { __builtin_amdgcn_s_setprio(1); _Pragma("unroll") for (int m = 0; m < 4; ++m) _Pragma("unroll") for (int n = 0; n < 2; ++n) _Pragma("unroll") for (int k = 0; k < 2; ++k) \
;         acc[ai][bj][m][n] = __builtin_amdgcn_mfma_f32_16x16x32_bf16(Bt[n][k], At[m][k], acc[ai][bj][m][n], 0, 0, 0); __builtin_amdgcn_s_setprio(0); } while (0)
; #define PG8_WAIT_V(n) asm volatile("s_waitcnt vmcnt(" #n ")" ::: "memory")
; template <class Epi, class Sched, bool ALIGN_EPI = false, bool SP2 = false, bool ABLK = false, bool BBLK = false>
; __device__ __forceinline__ void gemm_phase(PG8_LAS unsigned char* lds, const Gemm g, const Sched& S, const Epi& E) {
;     ...
;         for (int t = 0; t < nt; t += 2) {
;             const bool last = (t == nt - 2);
;             const char* a1 = cA + (size_t)(t + 1) * kstepA;
;             const char* a2 = last ? nA : cA + (size_t)(t + 2) * kstepA; const char* b2 = last ? nB : cB + (size_t)(t + 2) * kstepB;
;             const char* a3 = a2 + kstepA; const char* b3 = b2 + kstepB;
;             if (last && has_next) S.a_ready(nxt);
;             if constexpr (SP2) {
;             PG8_LDB(B0, 0, 0); PG8_LDB(B1, 0, 1); PG8_SCHED; PG8_LDA(At, 0, 0); PG8_STAGE(PG8_SA(1, 1), a1 + hstepA, voffA);
;             PG8_WAIT_V(8); PG8_WAIT_L(0); PG8_BAR; PG8_MMA(0, 0, At, B0); PG8_MMA(0, 1, At, B1); PG8_BAR; PG8_SCHED;
;             PG8_LDA(At, 0, 1); PG8_STAGE(PG8_SB(0, 0), b2, voffB); PG8_STAGE(PG8_SB(0, 1), b2 + hstepB, voffB); PG8_STAGE(PG8_SA(0, 0), a2, voffA);
;             PG8_WAIT_V(8); PG8_WAIT_L(0); PG8_BAR; PG8_MMA(1, 0, At, B0); PG8_MMA(1, 1, At, B1); PG8_BAR; PG8_SCHED;
	s_setprio 1
	s_waitcnt lgkmcnt(0)
	v_mfma_f32_16x16x32_bf16 v[62:65], v[148:151], v[180:183], 0
	v_mfma_f32_16x16x32_bf16 v[58:61], v[156:159], v[180:183], 0
	v_mfma_f32_16x16x32_bf16 v[50:53], v[148:151], v[200:203], 0
	v_mfma_f32_16x16x32_bf16 v[42:45], v[156:159], v[200:203], 0
	v_mfma_f32_16x16x32_bf16 v[34:37], v[148:151], v[208:211], 0
	v_mfma_f32_16x16x32_bf16 v[26:29], v[156:159], v[208:211], 0
	v_mfma_f32_16x16x32_bf16 v[18:21], v[148:151], v[216:219], 0
	v_mfma_f32_16x16x32_bf16 v[10:13], v[156:159], v[216:219], 0
	v_mfma_f32_16x16x32_bf16 v[62:65], v[152:155], v[196:199], v[62:65]
	v_mfma_f32_16x16x32_bf16 v[58:61], v[160:163], v[196:199], v[58:61]
	v_mfma_f32_16x16x32_bf16 v[50:53], v[152:155], v[204:207], v[50:53]
	v_mfma_f32_16x16x32_bf16 v[42:45], v[160:163], v[204:207], v[42:45]
	v_mfma_f32_16x16x32_bf16 v[34:37], v[152:155], v[212:215], v[34:37]
	v_mfma_f32_16x16x32_bf16 v[26:29], v[160:163], v[212:215], v[26:29]
	v_mfma_f32_16x16x32_bf16 v[18:21], v[152:155], v[220:223], v[18:21]
	v_mfma_f32_16x16x32_bf16 v[10:13], v[160:163], v[220:223], v[10:13]
	s_setprio 0
	s_setprio 1
	v_mfma_f32_16x16x32_bf16 v[54:57], v[164:167], v[180:183], 0
	v_mfma_f32_16x16x32_bf16 v[46:49], v[172:175], v[180:183], 0
	v_mfma_f32_16x16x32_bf16 v[38:41], v[164:167], v[200:203], 0
	v_mfma_f32_16x16x32_bf16 v[30:33], v[172:175], v[200:203], 0
	v_mfma_f32_16x16x32_bf16 v[22:25], v[164:167], v[208:211], 0
	v_mfma_f32_16x16x32_bf16 v[14:17], v[172:175], v[208:211], 0
	v_mfma_f32_16x16x32_bf16 v[6:9], v[164:167], v[216:219], 0
	v_mfma_f32_16x16x32_bf16 v[2:5], v[172:175], v[216:219], 0
	v_mfma_f32_16x16x32_bf16 v[54:57], v[168:171], v[196:199], v[54:57]
	v_mfma_f32_16x16x32_bf16 v[46:49], v[176:179], v[196:199], v[46:49]
	v_mfma_f32_16x16x32_bf16 v[38:41], v[168:171], v[204:207], v[38:41]
	v_mfma_f32_16x16x32_bf16 v[30:33], v[176:179], v[204:207], v[30:33]
	v_mfma_f32_16x16x32_bf16 v[22:25], v[168:171], v[212:215], v[22:25]
	v_mfma_f32_16x16x32_bf16 v[14:17], v[176:179], v[212:215], v[14:17]
	v_mfma_f32_16x16x32_bf16 v[6:9], v[168:171], v[220:223], v[6:9]
	v_mfma_f32_16x16x32_bf16 v[2:5], v[176:179], v[220:223], v[2:5]
	s_setprio 0
	s_barrier
	s_branch .Lmid_766
.LBB0_766:
	s_add_u32 s26, s24, 0xfff80080
	s_addc_u32 s27, s25, -1
	s_add_i32 s72, 0, 0x10000
	s_cmp_eq_u32 s68, 28
	s_cselect_b32 s29, s1, s27
	s_cselect_b32 s28, s11, s26
	v_add_u32_e32 v142, s72, v145
	s_cselect_b32 s27, s13, s65
	s_cselect_b32 s26, s15, s23
	s_add_i32 s75, 0, 0x14000
	ds_read_b128 v[148:151], v142
	ds_read_b128 v[152:155], v142 offset:1024
	ds_read_b128 v[156:159], v142 offset:2048
	ds_read_b128 v[160:163], v142 offset:3072
	v_add_u32_e32 v142, s75, v145
	ds_read_b128 v[164:167], v142
	ds_read_b128 v[168:171], v142 offset:1024
	ds_read_b128 v[172:175], v142 offset:2048
	ds_read_b128 v[176:179], v142 offset:3072
	v_lshl_add_u64 v[142:143], s[24:25], 0, v[138:139]
	s_add_i32 m0, s45, 0xc000
	ds_read_b128 v[180:183], v146
	ds_read_b128 v[196:199], v146 offset:1024
	ds_read_b128 v[200:203], v146 offset:2048
	ds_read_b128 v[204:207], v146 offset:3072
	ds_read_b128 v[208:211], v146 offset:4096
	ds_read_b128 v[212:215], v146 offset:5120
	ds_read_b128 v[216:219], v146 offset:6144
	ds_read_b128 v[220:223], v146 offset:7168
	global_load_lds_dwordx4 v[142:143], off
	v_lshl_add_u64 v[142:143], s[24:25], 0, v[140:141]
	s_add_i32 m0, s45, 0xe000
	s_nop 0
	global_load_lds_dwordx4 v[142:143], off
	s_waitcnt vmcnt(8)
	s_waitcnt lgkmcnt(0)
	s_barrier
	s_setprio 1
	s_waitcnt lgkmcnt(0)
	v_mfma_f32_16x16x32_bf16 v[126:129], v[148:151], v[180:183], v[126:129]
	v_mfma_f32_16x16x32_bf16 v[122:125], v[156:159], v[180:183], v[122:125]
	v_mfma_f32_16x16x32_bf16 v[114:117], v[148:151], v[200:203], v[114:117]
	v_mfma_f32_16x16x32_bf16 v[106:109], v[156:159], v[200:203], v[106:109]
	v_mfma_f32_16x16x32_bf16 v[98:101], v[148:151], v[208:211], v[98:101]
	v_mfma_f32_16x16x32_bf16 v[90:93], v[156:159], v[208:211], v[90:93]
	v_mfma_f32_16x16x32_bf16 v[82:85], v[148:151], v[216:219], v[82:85]
	v_mfma_f32_16x16x32_bf16 v[74:77], v[156:159], v[216:219], v[74:77]
	v_mfma_f32_16x16x32_bf16 v[126:129], v[152:155], v[196:199], v[126:129]
	v_mfma_f32_16x16x32_bf16 v[122:125], v[160:163], v[196:199], v[122:125]
	v_mfma_f32_16x16x32_bf16 v[114:117], v[152:155], v[204:207], v[114:117]
	v_mfma_f32_16x16x32_bf16 v[106:109], v[160:163], v[204:207], v[106:109]
	v_mfma_f32_16x16x32_bf16 v[98:101], v[152:155], v[212:215], v[98:101]
	v_mfma_f32_16x16x32_bf16 v[90:93], v[160:163], v[212:215], v[90:93]
	v_mfma_f32_16x16x32_bf16 v[82:85], v[152:155], v[220:223], v[82:85]
	v_mfma_f32_16x16x32_bf16 v[74:77], v[160:163], v[220:223], v[74:77]
	s_setprio 0
	s_setprio 1
	v_mfma_f32_16x16x32_bf16 v[118:121], v[164:167], v[180:183], v[118:121]
	v_mfma_f32_16x16x32_bf16 v[110:113], v[172:175], v[180:183], v[110:113]
	v_mfma_f32_16x16x32_bf16 v[102:105], v[164:167], v[200:203], v[102:105]
	v_mfma_f32_16x16x32_bf16 v[94:97], v[172:175], v[200:203], v[94:97]
	v_mfma_f32_16x16x32_bf16 v[86:89], v[164:167], v[208:211], v[86:89]
	v_mfma_f32_16x16x32_bf16 v[78:81], v[172:175], v[208:211], v[78:81]
	v_mfma_f32_16x16x32_bf16 v[70:73], v[164:167], v[216:219], v[70:73]
	v_mfma_f32_16x16x32_bf16 v[66:69], v[172:175], v[216:219], v[66:69]
	v_mfma_f32_16x16x32_bf16 v[118:121], v[168:171], v[196:199], v[118:121]
	v_mfma_f32_16x16x32_bf16 v[110:113], v[176:179], v[196:199], v[110:113]
	v_mfma_f32_16x16x32_bf16 v[102:105], v[168:171], v[204:207], v[102:105]
	v_mfma_f32_16x16x32_bf16 v[94:97], v[176:179], v[204:207], v[94:97]
	v_mfma_f32_16x16x32_bf16 v[86:89], v[168:171], v[212:215], v[86:89]
	v_mfma_f32_16x16x32_bf16 v[78:81], v[176:179], v[212:215], v[78:81]
	v_mfma_f32_16x16x32_bf16 v[70:73], v[168:171], v[220:223], v[70:73]
	v_mfma_f32_16x16x32_bf16 v[66:69], v[176:179], v[220:223], v[66:69]
	s_setprio 0
	s_barrier
; #define PG8_STAGE(bufoff, gbase, voff) do { _Pragma("unroll") for (int _i = 0; _i < 2; ++_i) \
;         __builtin_amdgcn_global_load_lds((const unsigned*)((const char*)(gbase) + (voff)[_i]), (PG8_LAS unsigned*)(lds + (bufoff) + ldsw + _i * 8192), 16, 0, 0); } while (0)
; #define PG8_LDA(dst, b, h) do { _Pragma("unroll") for (int m = 0; m < 4; ++m) _Pragma("unroll") for (int k = 0; k < 2; ++k) dst[m][k] = *(const PG8_LAS bf16x8*)(lds + PG8_SA(b, h) + aoff + m * 2048 + k * 1024); } while (0)
; #define PG8_LDB(dst, b, h) do { _Pragma("unroll") for (int n = 0; n < 2; ++n) _Pragma("unroll") for (int k = 0; k < 2; ++k) dst[n][k] = *(const PG8_LAS bf16x8*)(lds + PG8_SB(b, h) + boff + n * 2048 + k * 1024); } while (0)
; #define PG8_MMA(ai, bj, At, Bt) do { __builtin_amdgcn_s_setprio(1); _Pragma("unroll") for (int m = 0; m < 4; ++m) _Pragma("unroll") for (int n = 0; n < 2; ++n) _Pragma("unroll") for (int k = 0; k < 2; ++k) \
;         acc[ai][bj][m][n] = __builtin_amdgcn_mfma_f32_16x16x32_bf16(Bt[n][k], At[m][k], acc[ai][bj][m][n], 0, 0, 0); __builtin_amdgcn_s_setprio(0); } while (0)
; #define PG8_WAIT_V(n) asm volatile("s_waitcnt vmcnt(" #n ")" ::: "memory")
; #define PG8_WAIT_L(n) asm volatile("s_waitcnt lgkmcnt(" #n ")" ::: "memory")
; #define PG8_BAR __builtin_amdgcn_s_barrier()
; #define PG8_SCHED __builtin_amdgcn_sched_barrier(0)
; template <class Epi, class Sched, bool ALIGN_EPI = false, bool SP2 = false, bool ABLK = false, bool BBLK = false>
; __device__ __forceinline__ void gemm_phase(PG8_LAS unsigned char* lds, const Gemm g, const Sched& S, const Epi& E) {
;     ...
;             PG8_LDA(At, 0, 1); PG8_STAGE(PG8_SB(0, 0), b2, voffB); PG8_STAGE(PG8_SB(0, 1), b2 + hstepB, voffB); PG8_STAGE(PG8_SA(0, 0), a2, voffA);
;             PG8_WAIT_V(8); PG8_WAIT_L(0); PG8_BAR; PG8_MMA(1, 0, At, B0); PG8_MMA(1, 1, At, B1); PG8_BAR; PG8_SCHED;
;             PG8_LDB(B0, 1, 0); PG8_LDB(B1, 1, 1); PG8_SCHED; PG8_LDA(At, 1, 0); PG8_STAGE(PG8_SA(0, 1), a2 + hstepA, voffA);
;             PG8_WAIT_V(8); PG8_WAIT_L(0); PG8_BAR; PG8_MMA(0, 0, At, B0); PG8_MMA(0, 1, At, B1); PG8_BAR; PG8_SCHED;
	s_add_i32 s72, s72, s37
	v_lshl_add_u64 v[142:143], s[26:27], 0, v[134:135]
	s_mov_b32 m0, s72
	ds_read_b128 v[180:183], v146 offset:16384
	ds_read_b128 v[196:199], v146 offset:17408
	ds_read_b128 v[200:203], v146 offset:18432
	ds_read_b128 v[204:207], v146 offset:19456
	ds_read_b128 v[208:211], v146 offset:20480
	ds_read_b128 v[212:215], v146 offset:21504
	ds_read_b128 v[216:219], v146 offset:22528
	ds_read_b128 v[220:223], v146 offset:23552
	global_load_lds_dwordx4 v[142:143], off
	s_add_i32 m0, s72, 0x2000
	s_add_u32 s72, s26, 0x80000
	v_lshl_add_u64 v[184:185], s[26:27], 0, v[130:131]
	s_addc_u32 s73, s27, 0
	s_add_i32 s75, s75, s37
	global_load_lds_dwordx4 v[184:185], off
	v_lshl_add_u64 v[224:225], s[72:73], 0, v[134:135]
	s_mov_b32 m0, s75
	v_lshl_add_u64 v[226:227], s[28:29], 0, v[132:133]
	global_load_lds_dwordx4 v[224:225], off
	v_lshl_add_u64 v[224:225], s[72:73], 0, v[130:131]
	s_add_i32 m0, s75, 0x2000
	s_nop 0
	global_load_lds_dwordx4 v[224:225], off
	v_lshl_add_u64 v[224:225], s[28:29], 0, v[136:137]
	s_mov_b32 m0, s45
	s_nop 0
	global_load_lds_dwordx4 v[224:225], off
	s_mov_b32 m0, s46
	s_nop 0
	global_load_lds_dwordx4 v[226:227], off
	s_waitcnt vmcnt(8)
	s_waitcnt lgkmcnt(0)
	s_barrier
	s_setprio 1
	s_waitcnt lgkmcnt(0)
	v_mfma_f32_16x16x32_bf16 v[62:65], v[148:151], v[180:183], v[62:65]
	v_mfma_f32_16x16x32_bf16 v[58:61], v[156:159], v[180:183], v[58:61]
	v_mfma_f32_16x16x32_bf16 v[50:53], v[148:151], v[200:203], v[50:53]
	v_mfma_f32_16x16x32_bf16 v[42:45], v[156:159], v[200:203], v[42:45]
	v_mfma_f32_16x16x32_bf16 v[34:37], v[148:151], v[208:211], v[34:37]
	v_mfma_f32_16x16x32_bf16 v[26:29], v[156:159], v[208:211], v[26:29]
	v_mfma_f32_16x16x32_bf16 v[18:21], v[148:151], v[216:219], v[18:21]
	v_mfma_f32_16x16x32_bf16 v[10:13], v[156:159], v[216:219], v[10:13]
	v_mfma_f32_16x16x32_bf16 v[62:65], v[152:155], v[196:199], v[62:65]
	v_mfma_f32_16x16x32_bf16 v[58:61], v[160:163], v[196:199], v[58:61]
	v_mfma_f32_16x16x32_bf16 v[50:53], v[152:155], v[204:207], v[50:53]
	v_mfma_f32_16x16x32_bf16 v[42:45], v[160:163], v[204:207], v[42:45]
	v_mfma_f32_16x16x32_bf16 v[34:37], v[152:155], v[212:215], v[34:37]
	v_mfma_f32_16x16x32_bf16 v[26:29], v[160:163], v[212:215], v[26:29]
	v_mfma_f32_16x16x32_bf16 v[18:21], v[152:155], v[220:223], v[18:21]
	v_mfma_f32_16x16x32_bf16 v[10:13], v[160:163], v[220:223], v[10:13]
	s_setprio 0
	s_setprio 1
	v_mfma_f32_16x16x32_bf16 v[54:57], v[164:167], v[180:183], v[54:57]
	v_mfma_f32_16x16x32_bf16 v[46:49], v[172:175], v[180:183], v[46:49]
	v_mfma_f32_16x16x32_bf16 v[38:41], v[164:167], v[200:203], v[38:41]
	v_mfma_f32_16x16x32_bf16 v[30:33], v[172:175], v[200:203], v[30:33]
	v_mfma_f32_16x16x32_bf16 v[22:25], v[164:167], v[208:211], v[22:25]
	v_mfma_f32_16x16x32_bf16 v[14:17], v[172:175], v[208:211], v[14:17]
	v_mfma_f32_16x16x32_bf16 v[6:9], v[164:167], v[216:219], v[6:9]
	v_mfma_f32_16x16x32_bf16 v[2:5], v[172:175], v[216:219], v[2:5]
	v_mfma_f32_16x16x32_bf16 v[54:57], v[168:171], v[196:199], v[54:57]
	v_mfma_f32_16x16x32_bf16 v[46:49], v[176:179], v[196:199], v[46:49]
	v_mfma_f32_16x16x32_bf16 v[38:41], v[168:171], v[204:207], v[38:41]
	v_mfma_f32_16x16x32_bf16 v[30:33], v[176:179], v[204:207], v[30:33]
	v_mfma_f32_16x16x32_bf16 v[22:25], v[168:171], v[212:215], v[22:25]
	v_mfma_f32_16x16x32_bf16 v[14:17], v[176:179], v[212:215], v[14:17]
	v_mfma_f32_16x16x32_bf16 v[6:9], v[168:171], v[220:223], v[6:9]
	v_mfma_f32_16x16x32_bf16 v[2:5], v[176:179], v[220:223], v[2:5]
	s_setprio 0
	s_barrier
.Lmid_766:
	s_add_i32 s72, 0, 0x18000
	v_add_u32_e32 v147, s72, v145
	s_add_i32 s73, 0, 0x1c000
	ds_read_b128 v[148:151], v147
	ds_read_b128 v[152:155], v147 offset:1024
	ds_read_b128 v[156:159], v147 offset:2048
	ds_read_b128 v[160:163], v147 offset:3072
	v_add_u32_e32 v147, s73, v145
	ds_read_b128 v[164:167], v147
	ds_read_b128 v[168:171], v147 offset:1024
	ds_read_b128 v[172:175], v147 offset:2048
	ds_read_b128 v[176:179], v147 offset:3072
	s_add_u32 s28, s28, 0x80000
	s_addc_u32 s29, s29, 0
	s_mov_b32 m0, s47
	v_lshl_add_u64 v[228:229], s[28:29], 0, v[136:137]
	ds_read_b128 v[180:183], v146 offset:32768
	ds_read_b128 v[196:199], v146 offset:33792
	ds_read_b128 v[200:203], v146 offset:34816
	ds_read_b128 v[204:207], v146 offset:35840
	ds_read_b128 v[208:211], v146 offset:36864
	ds_read_b128 v[212:215], v146 offset:37888
	ds_read_b128 v[216:219], v146 offset:38912
	ds_read_b128 v[220:223], v146 offset:39936
	global_load_lds_dwordx4 v[228:229], off
	v_lshl_add_u64 v[228:229], s[28:29], 0, v[132:133]
	s_mov_b32 m0, s50
	s_nop 0
	global_load_lds_dwordx4 v[228:229], off
	s_waitcnt vmcnt(8)
	s_waitcnt lgkmcnt(0)
	s_barrier
; #define PG8_STAGE(bufoff, gbase, voff) do { _Pragma("unroll") for (int _i = 0; _i < 2; ++_i) \
;         __builtin_amdgcn_global_load_lds((const unsigned*)((const char*)(gbase) + (voff)[_i]), (PG8_LAS unsigned*)(lds + (bufoff) + ldsw + _i * 8192), 16, 0, 0); } while (0)
; #define PG8_LDA(dst, b, h) do { _Pragma("unroll") for (int m = 0; m < 4; ++m) _Pragma("unroll") for (int k = 0; k < 2; ++k) dst[m][k] = *(const PG8_LAS bf16x8*)(lds + PG8_SA(b, h) + aoff + m * 2048 + k * 1024); } while (0)
; #define PG8_MMA(ai, bj, At, Bt) do { __builtin_amdgcn_s_setprio(1); _Pragma("unroll") for (int m = 0; m < 4; ++m) _Pragma("unroll") for (int n = 0; n < 2; ++n) _Pragma("unroll") for (int k = 0; k < 2; ++k) \
;         acc[ai][bj][m][n] = __builtin_amdgcn_mfma_f32_16x16x32_bf16(Bt[n][k], At[m][k], acc[ai][bj][m][n], 0, 0, 0); __builtin_amdgcn_s_setprio(0); } while (0)
; #define PG8_WAIT_V(n) asm volatile("s_waitcnt vmcnt(" #n ")" ::: "memory")
; #define PG8_WAIT_L(n) asm volatile("s_waitcnt lgkmcnt(" #n ")" ::: "memory")
; #define PG8_BAR __builtin_amdgcn_s_barrier()
; #define PG8_SCHED __builtin_amdgcn_sched_barrier(0)
; template <class Epi, class Sched, bool ALIGN_EPI = false, bool SP2 = false, bool ABLK = false, bool BBLK = false>
; __device__ __forceinline__ void gemm_phase(PG8_LAS unsigned char* lds, const Gemm g, const Sched& S, const Epi& E) {
;     ...
;             PG8_WAIT_V(8); PG8_WAIT_L(0); PG8_BAR; PG8_MMA(0, 0, At, B0); PG8_MMA(0, 1, At, B1); PG8_BAR; PG8_SCHED;
;             PG8_LDA(At, 1, 1); PG8_STAGE(PG8_SB(1, 0), b3, voffB); PG8_STAGE(PG8_SB(1, 1), b3 + hstepB, voffB); PG8_STAGE(PG8_SA(1, 0), a3, voffA);
;             PG8_WAIT_V(8); PG8_WAIT_L(0); PG8_BAR; PG8_MMA(1, 0, At, B0); PG8_MMA(1, 1, At, B1); PG8_BAR; PG8_SCHED;
;     ...
;         if constexpr (ALIGN_EPI) { if (wr == 0) PG8_BAR; }
	s_setprio 1
	s_waitcnt lgkmcnt(0)
	v_mfma_f32_16x16x32_bf16 v[126:129], v[148:151], v[180:183], v[126:129]
	v_mfma_f32_16x16x32_bf16 v[122:125], v[156:159], v[180:183], v[122:125]
	v_mfma_f32_16x16x32_bf16 v[114:117], v[148:151], v[200:203], v[114:117]
	v_mfma_f32_16x16x32_bf16 v[106:109], v[156:159], v[200:203], v[106:109]
	v_mfma_f32_16x16x32_bf16 v[98:101], v[148:151], v[208:211], v[98:101]
	v_mfma_f32_16x16x32_bf16 v[90:93], v[156:159], v[208:211], v[90:93]
	v_mfma_f32_16x16x32_bf16 v[82:85], v[148:151], v[216:219], v[82:85]
	v_mfma_f32_16x16x32_bf16 v[74:77], v[156:159], v[216:219], v[74:77]
	v_mfma_f32_16x16x32_bf16 v[126:129], v[152:155], v[196:199], v[126:129]
	v_mfma_f32_16x16x32_bf16 v[122:125], v[160:163], v[196:199], v[122:125]
	v_mfma_f32_16x16x32_bf16 v[114:117], v[152:155], v[204:207], v[114:117]
	v_mfma_f32_16x16x32_bf16 v[106:109], v[160:163], v[204:207], v[106:109]
	v_mfma_f32_16x16x32_bf16 v[98:101], v[152:155], v[212:215], v[98:101]
	v_mfma_f32_16x16x32_bf16 v[90:93], v[160:163], v[212:215], v[90:93]
	v_mfma_f32_16x16x32_bf16 v[82:85], v[152:155], v[220:223], v[82:85]
	v_mfma_f32_16x16x32_bf16 v[74:77], v[160:163], v[220:223], v[74:77]
	s_setprio 0
	s_setprio 1
	v_mfma_f32_16x16x32_bf16 v[118:121], v[164:167], v[180:183], v[118:121]
	v_mfma_f32_16x16x32_bf16 v[110:113], v[172:175], v[180:183], v[110:113]
	v_mfma_f32_16x16x32_bf16 v[102:105], v[164:167], v[200:203], v[102:105]
	v_mfma_f32_16x16x32_bf16 v[94:97], v[172:175], v[200:203], v[94:97]
	v_mfma_f32_16x16x32_bf16 v[86:89], v[164:167], v[208:211], v[86:89]
	v_mfma_f32_16x16x32_bf16 v[78:81], v[172:175], v[208:211], v[78:81]
	v_mfma_f32_16x16x32_bf16 v[70:73], v[164:167], v[216:219], v[70:73]
	v_mfma_f32_16x16x32_bf16 v[66:69], v[172:175], v[216:219], v[66:69]
	v_mfma_f32_16x16x32_bf16 v[118:121], v[168:171], v[196:199], v[118:121]
	v_mfma_f32_16x16x32_bf16 v[110:113], v[176:179], v[196:199], v[110:113]
	v_mfma_f32_16x16x32_bf16 v[102:105], v[168:171], v[204:207], v[102:105]
	v_mfma_f32_16x16x32_bf16 v[94:97], v[176:179], v[204:207], v[94:97]
	v_mfma_f32_16x16x32_bf16 v[86:89], v[168:171], v[212:215], v[86:89]
	v_mfma_f32_16x16x32_bf16 v[78:81], v[176:179], v[212:215], v[78:81]
	v_mfma_f32_16x16x32_bf16 v[70:73], v[168:171], v[220:223], v[70:73]
	v_mfma_f32_16x16x32_bf16 v[66:69], v[176:179], v[220:223], v[66:69]
	s_setprio 0
	s_barrier
	s_add_i32 s28, s72, s37
	v_lshl_add_u64 v[142:143], v[142:143], 0, s[62:63]
	s_mov_b32 m0, s28
	ds_read_b128 v[180:183], v146 offset:49152
	ds_read_b128 v[196:199], v146 offset:50176
	ds_read_b128 v[200:203], v146 offset:51200
	ds_read_b128 v[204:207], v146 offset:52224
	ds_read_b128 v[208:211], v146 offset:53248
	ds_read_b128 v[212:215], v146 offset:54272
	ds_read_b128 v[216:219], v146 offset:55296
	ds_read_b128 v[220:223], v146 offset:56320
	global_load_lds_dwordx4 v[142:143], off
	s_add_i32 m0, s28, 0x2000
	s_add_u32 s26, s26, 0x80080
	v_lshl_add_u64 v[142:143], v[184:185], 0, s[62:63]
	s_addc_u32 s27, s27, 0
	s_add_i32 s28, s73, s37
	global_load_lds_dwordx4 v[142:143], off
	v_lshl_add_u64 v[142:143], s[26:27], 0, v[134:135]
	s_mov_b32 m0, s28
	s_nop 0
	global_load_lds_dwordx4 v[142:143], off
	v_lshl_add_u64 v[142:143], s[26:27], 0, v[130:131]
	s_add_i32 m0, s28, 0x2000
	s_nop 0
	global_load_lds_dwordx4 v[142:143], off
	v_lshl_add_u64 v[142:143], v[224:225], 0, s[62:63]
	s_mov_b32 m0, s53
	s_nop 0
	global_load_lds_dwordx4 v[142:143], off
	v_lshl_add_u64 v[142:143], v[226:227], 0, s[62:63]
	s_mov_b32 m0, s56
	s_nop 0
	global_load_lds_dwordx4 v[142:143], off
	s_waitcnt vmcnt(8)
	s_waitcnt lgkmcnt(0)
	s_barrier
	s_setprio 1
	s_waitcnt lgkmcnt(0)
	v_mfma_f32_16x16x32_bf16 v[62:65], v[148:151], v[180:183], v[62:65]
	v_mfma_f32_16x16x32_bf16 v[58:61], v[156:159], v[180:183], v[58:61]
	v_mfma_f32_16x16x32_bf16 v[50:53], v[148:151], v[200:203], v[50:53]
	v_mfma_f32_16x16x32_bf16 v[42:45], v[156:159], v[200:203], v[42:45]
	v_mfma_f32_16x16x32_bf16 v[34:37], v[148:151], v[208:211], v[34:37]
	v_mfma_f32_16x16x32_bf16 v[26:29], v[156:159], v[208:211], v[26:29]
	v_mfma_f32_16x16x32_bf16 v[18:21], v[148:151], v[216:219], v[18:21]
	v_mfma_f32_16x16x32_bf16 v[10:13], v[156:159], v[216:219], v[10:13]
	v_mfma_f32_16x16x32_bf16 v[62:65], v[152:155], v[196:199], v[62:65]
	v_mfma_f32_16x16x32_bf16 v[58:61], v[160:163], v[196:199], v[58:61]
	v_mfma_f32_16x16x32_bf16 v[50:53], v[152:155], v[204:207], v[50:53]
	v_mfma_f32_16x16x32_bf16 v[42:45], v[160:163], v[204:207], v[42:45]
	v_mfma_f32_16x16x32_bf16 v[34:37], v[152:155], v[212:215], v[34:37]
	v_mfma_f32_16x16x32_bf16 v[26:29], v[160:163], v[212:215], v[26:29]
	v_mfma_f32_16x16x32_bf16 v[18:21], v[152:155], v[220:223], v[18:21]
	v_mfma_f32_16x16x32_bf16 v[10:13], v[160:163], v[220:223], v[10:13]
	s_setprio 0
	s_setprio 1
	v_mfma_f32_16x16x32_bf16 v[54:57], v[164:167], v[180:183], v[54:57]
	v_mfma_f32_16x16x32_bf16 v[46:49], v[172:175], v[180:183], v[46:49]
	v_mfma_f32_16x16x32_bf16 v[38:41], v[164:167], v[200:203], v[38:41]
	v_mfma_f32_16x16x32_bf16 v[30:33], v[172:175], v[200:203], v[30:33]
	v_mfma_f32_16x16x32_bf16 v[22:25], v[164:167], v[208:211], v[22:25]
	v_mfma_f32_16x16x32_bf16 v[14:17], v[172:175], v[208:211], v[14:17]
	v_mfma_f32_16x16x32_bf16 v[6:9], v[164:167], v[216:219], v[6:9]
	v_mfma_f32_16x16x32_bf16 v[2:5], v[172:175], v[216:219], v[2:5]
	v_mfma_f32_16x16x32_bf16 v[54:57], v[168:171], v[196:199], v[54:57]
	v_mfma_f32_16x16x32_bf16 v[46:49], v[176:179], v[196:199], v[46:49]
	v_mfma_f32_16x16x32_bf16 v[38:41], v[168:171], v[204:207], v[38:41]
	v_mfma_f32_16x16x32_bf16 v[30:33], v[176:179], v[204:207], v[30:33]
	v_mfma_f32_16x16x32_bf16 v[22:25], v[168:171], v[212:215], v[22:25]
	v_mfma_f32_16x16x32_bf16 v[14:17], v[176:179], v[212:215], v[14:17]
	v_mfma_f32_16x16x32_bf16 v[6:9], v[168:171], v[220:223], v[6:9]
	v_mfma_f32_16x16x32_bf16 v[2:5], v[176:179], v[220:223], v[2:5]
	s_setprio 0
	s_barrier
	s_add_i32 s68, s68, 2
	s_add_u32 s24, s24, 0x100
	s_addc_u32 s25, s25, 0
	s_add_u32 s23, s23, 0x100
	s_addc_u32 s65, s65, 0
	s_cmp_gt_u32 s68, 29
	s_cbranch_scc0 .LBB0_766
	s_and_b64 vcc, exec, s[8:9]
	s_cbranch_vccz .LBB0_769
	s_barrier

; #define PG8_STAGE(bufoff, gbase, voff) do { _Pragma("unroll") for (int _i = 0; _i < 2; ++_i) \
;         __builtin_amdgcn_global_load_lds((const unsigned*)((const char*)(gbase) + (voff)[_i]), (PG8_LAS unsigned*)(lds + (bufoff) + ldsw + _i * 8192), 16, 0, 0); } while (0)
; #define PG8_LDA(dst, b, h) do { _Pragma("unroll") for (int m = 0; m < 4; ++m) _Pragma("unroll") for (int k = 0; k < 2; ++k) dst[m][k] = *(const PG8_LAS bf16x8*)(lds + PG8_SA(b, h) + aoff + m * 2048 + k * 1024); } while (0)
; #define PG8_LDB(dst, b, h) do { _Pragma("unroll") for (int n = 0; n < 2; ++n) _Pragma("unroll") for (int k = 0; k < 2; ++k) dst[n][k] = *(const PG8_LAS bf16x8*)(lds + PG8_SB(b, h) + boff + n * 2048 + k * 1024); } while (0)
; #define PG8_WAIT_V(n) asm volatile("s_waitcnt vmcnt(" #n ")" ::: "memory")
; #define PG8_WAIT_L(n) asm volatile("s_waitcnt lgkmcnt(" #n ")" ::: "memory")
; #define PG8_BAR __builtin_amdgcn_s_barrier()
; template <class Epi, class Sched, bool ALIGN_EPI = false, bool SP2 = false, bool ABLK = false, bool BBLK = false>
; __device__ __forceinline__ void gemm_phase(PG8_LAS unsigned char* lds, const Gemm g, const Sched& S, const Epi& E) {
;     ...
;     for (;;) {
;         const bool has_next = S.next(ui + 1, nxt);
;         const char* nA = has_next ? (const char*)g.A + (size_t)nxt.pm * tstepA : cA; const char* nB = has_next ? (const char*)g.Bt + (size_t)nxt.pn * tstepB : cB;
;         for (int t = 0; t < nt; t += 2) {
;             const bool last = (t == nt - 2);
;             const char* a1 = cA + (size_t)(t + 1) * kstepA;
;             const char* a2 = last ? nA : cA + (size_t)(t + 2) * kstepA; const char* b2 = last ? nB : cB + (size_t)(t + 2) * kstepB;
;             const char* a3 = a2 + kstepA; const char* b3 = b2 + kstepB;
;             if (last && has_next) S.a_ready(nxt);
;             if constexpr (SP2) {
;             PG8_LDB(B0, 0, 0); PG8_LDB(B1, 0, 1); PG8_SCHED; PG8_LDA(At, 0, 0); PG8_STAGE(PG8_SA(1, 1), a1 + hstepA, voffA);
;             PG8_WAIT_V(8); PG8_WAIT_L(0); PG8_BAR; PG8_MMA(0, 0, At, B0); PG8_MMA(0, 1, At, B1); PG8_BAR; PG8_SCHED;
;             PG8_LDA(At, 0, 1); PG8_STAGE(PG8_SB(0, 0), b2, voffB); PG8_STAGE(PG8_SB(0, 1), b2 + hstepB, voffB); PG8_STAGE(PG8_SA(0, 0), a2, voffA);
;             PG8_WAIT_V(8); PG8_WAIT_L(0); PG8_BAR; PG8_MMA(1, 0, At, B0); PG8_MMA(1, 1, At, B1); PG8_BAR; PG8_SCHED;
.LBB0_789:
	s_ashr_i32 s15, s14, 31
	s_lshl_b64 s[18:19], s[14:15], 20
	s_add_u32 s18, s36, s18
	s_addc_u32 s19, s37, s19
	s_and_b64 s[20:21], s[6:7], exec
	s_cselect_b32 s1, s19, s25
	s_cselect_b32 s11, s18, s24
	s_ashr_i32 s13, s12, 31
	s_lshl_b64 s[20:21], s[12:13], 20
	s_add_u32 s20, s44, s20
	s_addc_u32 s21, s45, s21
	s_and_b64 s[28:29], s[6:7], exec
	s_cselect_b32 s13, s21, s27
	s_cselect_b32 s15, s20, s26
	s_add_u32 s24, s24, 0x80080
	s_addc_u32 s25, s25, 0
	s_add_u32 s23, s26, 0x100
	v_mov_b32_e32 v2, 0
	s_addc_u32 s73, s27, 0
	s_mov_b32 s81, -2
	s_add_u32 s26, s24, 0xfff80080
	s_addc_u32 s27, s25, -1
	s_add_i32 s51, 0, 0x10000
	s_cmp_eq_u32 s81, 28
	s_cselect_b32 s29, s1, s27
	s_cselect_b32 s28, s11, s26
	v_add_u32_e32 v142, s51, v145
	s_cselect_b32 s27, s13, s73
	s_cselect_b32 s26, s15, s23
	s_add_i32 s75, 0, 0x14000
	ds_read_b128 v[148:151], v142
	ds_read_b128 v[152:155], v142 offset:1024
	ds_read_b128 v[156:159], v142 offset:2048
	ds_read_b128 v[160:163], v142 offset:3072
	v_add_u32_e32 v142, s75, v145
	ds_read_b128 v[164:167], v142
	ds_read_b128 v[168:171], v142 offset:1024
	ds_read_b128 v[172:175], v142 offset:2048
	ds_read_b128 v[176:179], v142 offset:3072
	v_lshl_add_u64 v[142:143], s[24:25], 0, v[138:139]
	s_add_i32 m0, s46, 0xc000
	ds_read_b128 v[180:183], v146
	ds_read_b128 v[196:199], v146 offset:1024
	ds_read_b128 v[200:203], v146 offset:2048
	ds_read_b128 v[204:207], v146 offset:3072
	ds_read_b128 v[208:211], v146 offset:4096
	ds_read_b128 v[212:215], v146 offset:5120
	ds_read_b128 v[216:219], v146 offset:6144
	ds_read_b128 v[220:223], v146 offset:7168
	global_load_lds_dwordx4 v[142:143], off
	v_lshl_add_u64 v[142:143], s[24:25], 0, v[140:141]
	s_add_i32 m0, s46, 0xe000
	s_nop 0
	global_load_lds_dwordx4 v[142:143], off
	s_waitcnt vmcnt(8)
	s_waitcnt lgkmcnt(0)
	s_barrier
	s_setprio 1
	s_waitcnt lgkmcnt(0)
	v_mfma_f32_16x16x32_bf16 v[126:129], v[148:151], v[180:183], 0
	v_mfma_f32_16x16x32_bf16 v[122:125], v[156:159], v[180:183], 0
	v_mfma_f32_16x16x32_bf16 v[114:117], v[148:151], v[200:203], 0
	v_mfma_f32_16x16x32_bf16 v[106:109], v[156:159], v[200:203], 0
	v_mfma_f32_16x16x32_bf16 v[98:101], v[148:151], v[208:211], 0
	v_mfma_f32_16x16x32_bf16 v[90:93], v[156:159], v[208:211], 0
	v_mfma_f32_16x16x32_bf16 v[82:85], v[148:151], v[216:219], 0
	v_mfma_f32_16x16x32_bf16 v[74:77], v[156:159], v[216:219], 0
	v_mfma_f32_16x16x32_bf16 v[126:129], v[152:155], v[196:199], v[126:129]
	v_mfma_f32_16x16x32_bf16 v[122:125], v[160:163], v[196:199], v[122:125]
	v_mfma_f32_16x16x32_bf16 v[114:117], v[152:155], v[204:207], v[114:117]
	v_mfma_f32_16x16x32_bf16 v[106:109], v[160:163], v[204:207], v[106:109]
	v_mfma_f32_16x16x32_bf16 v[98:101], v[152:155], v[212:215], v[98:101]
	v_mfma_f32_16x16x32_bf16 v[90:93], v[160:163], v[212:215], v[90:93]
	v_mfma_f32_16x16x32_bf16 v[82:85], v[152:155], v[220:223], v[82:85]
	v_mfma_f32_16x16x32_bf16 v[74:77], v[160:163], v[220:223], v[74:77]
	s_setprio 0
	s_setprio 1
	v_mfma_f32_16x16x32_bf16 v[118:121], v[164:167], v[180:183], 0
	v_mfma_f32_16x16x32_bf16 v[110:113], v[172:175], v[180:183], 0
	v_mfma_f32_16x16x32_bf16 v[102:105], v[164:167], v[200:203], 0
	v_mfma_f32_16x16x32_bf16 v[94:97], v[172:175], v[200:203], 0
	v_mfma_f32_16x16x32_bf16 v[86:89], v[164:167], v[208:211], 0
	v_mfma_f32_16x16x32_bf16 v[78:81], v[172:175], v[208:211], 0
	v_mfma_f32_16x16x32_bf16 v[70:73], v[164:167], v[216:219], 0
	v_mfma_f32_16x16x32_bf16 v[66:69], v[172:175], v[216:219], 0
	v_mfma_f32_16x16x32_bf16 v[118:121], v[168:171], v[196:199], v[118:121]
	v_mfma_f32_16x16x32_bf16 v[110:113], v[176:179], v[196:199], v[110:113]
	v_mfma_f32_16x16x32_bf16 v[102:105], v[168:171], v[204:207], v[102:105]
	v_mfma_f32_16x16x32_bf16 v[94:97], v[176:179], v[204:207], v[94:97]
	v_mfma_f32_16x16x32_bf16 v[86:89], v[168:171], v[212:215], v[86:89]
	v_mfma_f32_16x16x32_bf16 v[78:81], v[176:179], v[212:215], v[78:81]
	v_mfma_f32_16x16x32_bf16 v[70:73], v[168:171], v[220:223], v[70:73]
	v_mfma_f32_16x16x32_bf16 v[66:69], v[176:179], v[220:223], v[66:69]
	s_setprio 0
	s_barrier
	s_add_i32 s51, s51, s35
	v_lshl_add_u64 v[142:143], s[26:27], 0, v[132:133]
	s_mov_b32 m0, s51
	ds_read_b128 v[180:183], v146 offset:16384
	ds_read_b128 v[196:199], v146 offset:17408
	ds_read_b128 v[200:203], v146 offset:18432
	ds_read_b128 v[204:207], v146 offset:19456
	ds_read_b128 v[208:211], v146 offset:20480
	ds_read_b128 v[212:215], v146 offset:21504
	ds_read_b128 v[216:219], v146 offset:22528
	ds_read_b128 v[220:223], v146 offset:23552
	global_load_lds_dwordx4 v[142:143], off
	s_add_i32 m0, s51, 0x2000
	s_add_u32 s82, s26, 0x80000
	v_lshl_add_u64 v[184:185], s[26:27], 0, v[136:137]
	s_addc_u32 s83, s27, 0
	s_add_i32 s51, s75, s35
	global_load_lds_dwordx4 v[184:185], off
	v_lshl_add_u64 v[224:225], s[82:83], 0, v[132:133]
	s_mov_b32 m0, s51
	v_lshl_add_u64 v[226:227], s[28:29], 0, v[134:135]
	global_load_lds_dwordx4 v[224:225], off
	v_lshl_add_u64 v[224:225], s[82:83], 0, v[136:137]
	s_add_i32 m0, s51, 0x2000
	s_nop 0
	global_load_lds_dwordx4 v[224:225], off
	v_lshl_add_u64 v[224:225], s[28:29], 0, v[130:131]
	s_mov_b32 m0, s46
	s_nop 0
	global_load_lds_dwordx4 v[224:225], off
	s_mov_b32 m0, s47
	s_nop 0
	global_load_lds_dwordx4 v[226:227], off
	s_waitcnt vmcnt(8)
	s_waitcnt lgkmcnt(0)
	s_barrier
; #define PG8_STAGE(bufoff, gbase, voff) do { _Pragma("unroll") for (int _i = 0; _i < 2; ++_i) \
;         __builtin_amdgcn_global_load_lds((const unsigned*)((const char*)(gbase) + (voff)[_i]), (PG8_LAS unsigned*)(lds + (bufoff) + ldsw + _i * 8192), 16, 0, 0); } while (0)
; #define PG8_LDA(dst, b, h) do { _Pragma("unroll") for (int m = 0; m < 4; ++m) _Pragma("unroll") for (int k = 0; k < 2; ++k) dst[m][k] = *(const PG8_LAS bf16x8*)(lds + PG8_SA(b, h) + aoff + m * 2048 + k * 1024); } while (0)
; #define PG8_LDB(dst, b, h) do { _Pragma("unroll") for (int n = 0; n < 2; ++n) _Pragma("unroll") for (int k = 0; k < 2; ++k) dst[n][k] = *(const PG8_LAS bf16x8*)(lds + PG8_SB(b, h) + boff + n * 2048 + k * 1024); } while (0)
; #define PG8_MMA(ai, bj, At, Bt) do { __builtin_amdgcn_s_setprio(1); _Pragma("unroll") for (int m = 0; m < 4; ++m) _Pragma("unroll") for (int n = 0; n < 2; ++n) _Pragma("unroll") for (int k = 0; k < 2; ++k) \
;         acc[ai][bj][m][n] = __builtin_amdgcn_mfma_f32_16x16x32_bf16(Bt[n][k], At[m][k], acc[ai][bj][m][n], 0, 0, 0); __builtin_amdgcn_s_setprio(0); } while (0)
; #define PG8_WAIT_V(n) asm volatile("s_waitcnt vmcnt(" #n ")" ::: "memory")
; template <class Epi, class Sched, bool ALIGN_EPI = false, bool SP2 = false, bool ABLK = false, bool BBLK = false>
; __device__ __forceinline__ void gemm_phase(PG8_LAS unsigned char* lds, const Gemm g, const Sched& S, const Epi& E) {
;     ...
;         for (int t = 0; t < nt; t += 2) {
;             const bool last = (t == nt - 2);
;             const char* a1 = cA + (size_t)(t + 1) * kstepA;
;             const char* a2 = last ? nA : cA + (size_t)(t + 2) * kstepA; const char* b2 = last ? nB : cB + (size_t)(t + 2) * kstepB;
;             const char* a3 = a2 + kstepA; const char* b3 = b2 + kstepB;
;             if (last && has_next) S.a_ready(nxt);
;             if constexpr (SP2) {
;             PG8_LDB(B0, 0, 0); PG8_LDB(B1, 0, 1); PG8_SCHED; PG8_LDA(At, 0, 0); PG8_STAGE(PG8_SA(1, 1), a1 + hstepA, voffA);
;             PG8_WAIT_V(8); PG8_WAIT_L(0); PG8_BAR; PG8_MMA(0, 0, At, B0); PG8_MMA(0, 1, At, B1); PG8_BAR; PG8_SCHED;
;             PG8_LDA(At, 0, 1); PG8_STAGE(PG8_SB(0, 0), b2, voffB); PG8_STAGE(PG8_SB(0, 1), b2 + hstepB, voffB); PG8_STAGE(PG8_SA(0, 0), a2, voffA);
;             PG8_WAIT_V(8); PG8_WAIT_L(0); PG8_BAR; PG8_MMA(1, 0, At, B0); PG8_MMA(1, 1, At, B1); PG8_BAR; PG8_SCHED;
	s_setprio 1
	s_waitcnt lgkmcnt(0)
	v_mfma_f32_16x16x32_bf16 v[62:65], v[148:151], v[180:183], 0
	v_mfma_f32_16x16x32_bf16 v[58:61], v[156:159], v[180:183], 0
	v_mfma_f32_16x16x32_bf16 v[50:53], v[148:151], v[200:203], 0
	v_mfma_f32_16x16x32_bf16 v[42:45], v[156:159], v[200:203], 0
	v_mfma_f32_16x16x32_bf16 v[34:37], v[148:151], v[208:211], 0
	v_mfma_f32_16x16x32_bf16 v[26:29], v[156:159], v[208:211], 0
	v_mfma_f32_16x16x32_bf16 v[18:21], v[148:151], v[216:219], 0
	v_mfma_f32_16x16x32_bf16 v[10:13], v[156:159], v[216:219], 0
	v_mfma_f32_16x16x32_bf16 v[62:65], v[152:155], v[196:199], v[62:65]
	v_mfma_f32_16x16x32_bf16 v[58:61], v[160:163], v[196:199], v[58:61]
	v_mfma_f32_16x16x32_bf16 v[50:53], v[152:155], v[204:207], v[50:53]
	v_mfma_f32_16x16x32_bf16 v[42:45], v[160:163], v[204:207], v[42:45]
	v_mfma_f32_16x16x32_bf16 v[34:37], v[152:155], v[212:215], v[34:37]
	v_mfma_f32_16x16x32_bf16 v[26:29], v[160:163], v[212:215], v[26:29]
	v_mfma_f32_16x16x32_bf16 v[18:21], v[152:155], v[220:223], v[18:21]
	v_mfma_f32_16x16x32_bf16 v[10:13], v[160:163], v[220:223], v[10:13]
	s_setprio 0
	s_setprio 1
	v_mfma_f32_16x16x32_bf16 v[54:57], v[164:167], v[180:183], 0
	v_mfma_f32_16x16x32_bf16 v[46:49], v[172:175], v[180:183], 0
	v_mfma_f32_16x16x32_bf16 v[38:41], v[164:167], v[200:203], 0
	v_mfma_f32_16x16x32_bf16 v[30:33], v[172:175], v[200:203], 0
	v_mfma_f32_16x16x32_bf16 v[22:25], v[164:167], v[208:211], 0
	v_mfma_f32_16x16x32_bf16 v[14:17], v[172:175], v[208:211], 0
	v_mfma_f32_16x16x32_bf16 v[6:9], v[164:167], v[216:219], 0
	v_mfma_f32_16x16x32_bf16 v[2:5], v[172:175], v[216:219], 0
	v_mfma_f32_16x16x32_bf16 v[54:57], v[168:171], v[196:199], v[54:57]
	v_mfma_f32_16x16x32_bf16 v[46:49], v[176:179], v[196:199], v[46:49]
	v_mfma_f32_16x16x32_bf16 v[38:41], v[168:171], v[204:207], v[38:41]
	v_mfma_f32_16x16x32_bf16 v[30:33], v[176:179], v[204:207], v[30:33]
	v_mfma_f32_16x16x32_bf16 v[22:25], v[168:171], v[212:215], v[22:25]
	v_mfma_f32_16x16x32_bf16 v[14:17], v[176:179], v[212:215], v[14:17]
	v_mfma_f32_16x16x32_bf16 v[6:9], v[168:171], v[220:223], v[6:9]
	v_mfma_f32_16x16x32_bf16 v[2:5], v[176:179], v[220:223], v[2:5]
	s_setprio 0
	s_barrier
	s_branch .Lmid_790
.LBB0_790:
	s_add_u32 s26, s24, 0xfff80080
	s_addc_u32 s27, s25, -1
	s_add_i32 s51, 0, 0x10000
	s_cmp_eq_u32 s81, 28
	s_cselect_b32 s29, s1, s27
	s_cselect_b32 s28, s11, s26
	v_add_u32_e32 v142, s51, v145
	s_cselect_b32 s27, s13, s73
	s_cselect_b32 s26, s15, s23
	s_add_i32 s75, 0, 0x14000
	ds_read_b128 v[148:151], v142
	ds_read_b128 v[152:155], v142 offset:1024
	ds_read_b128 v[156:159], v142 offset:2048
	ds_read_b128 v[160:163], v142 offset:3072
	v_add_u32_e32 v142, s75, v145
	ds_read_b128 v[164:167], v142
	ds_read_b128 v[168:171], v142 offset:1024
	ds_read_b128 v[172:175], v142 offset:2048
	ds_read_b128 v[176:179], v142 offset:3072
	v_lshl_add_u64 v[142:143], s[24:25], 0, v[138:139]
	s_add_i32 m0, s46, 0xc000
	ds_read_b128 v[180:183], v146
	ds_read_b128 v[196:199], v146 offset:1024
	ds_read_b128 v[200:203], v146 offset:2048
	ds_read_b128 v[204:207], v146 offset:3072
	ds_read_b128 v[208:211], v146 offset:4096
	ds_read_b128 v[212:215], v146 offset:5120
	ds_read_b128 v[216:219], v146 offset:6144
	ds_read_b128 v[220:223], v146 offset:7168
	global_load_lds_dwordx4 v[142:143], off
	v_lshl_add_u64 v[142:143], s[24:25], 0, v[140:141]
	s_add_i32 m0, s46, 0xe000
	s_nop 0
	global_load_lds_dwordx4 v[142:143], off
	s_waitcnt vmcnt(8)
	s_waitcnt lgkmcnt(0)
	s_barrier
	s_setprio 1
	s_waitcnt lgkmcnt(0)
	v_mfma_f32_16x16x32_bf16 v[126:129], v[148:151], v[180:183], v[126:129]
	v_mfma_f32_16x16x32_bf16 v[122:125], v[156:159], v[180:183], v[122:125]
	v_mfma_f32_16x16x32_bf16 v[114:117], v[148:151], v[200:203], v[114:117]
	v_mfma_f32_16x16x32_bf16 v[106:109], v[156:159], v[200:203], v[106:109]
	v_mfma_f32_16x16x32_bf16 v[98:101], v[148:151], v[208:211], v[98:101]
	v_mfma_f32_16x16x32_bf16 v[90:93], v[156:159], v[208:211], v[90:93]
	v_mfma_f32_16x16x32_bf16 v[82:85], v[148:151], v[216:219], v[82:85]
	v_mfma_f32_16x16x32_bf16 v[74:77], v[156:159], v[216:219], v[74:77]
	v_mfma_f32_16x16x32_bf16 v[126:129], v[152:155], v[196:199], v[126:129]
	v_mfma_f32_16x16x32_bf16 v[122:125], v[160:163], v[196:199], v[122:125]
	v_mfma_f32_16x16x32_bf16 v[114:117], v[152:155], v[204:207], v[114:117]
	v_mfma_f32_16x16x32_bf16 v[106:109], v[160:163], v[204:207], v[106:109]
	v_mfma_f32_16x16x32_bf16 v[98:101], v[152:155], v[212:215], v[98:101]
	v_mfma_f32_16x16x32_bf16 v[90:93], v[160:163], v[212:215], v[90:93]
	v_mfma_f32_16x16x32_bf16 v[82:85], v[152:155], v[220:223], v[82:85]
	v_mfma_f32_16x16x32_bf16 v[74:77], v[160:163], v[220:223], v[74:77]
	s_setprio 0
	s_setprio 1
	v_mfma_f32_16x16x32_bf16 v[118:121], v[164:167], v[180:183], v[118:121]
	v_mfma_f32_16x16x32_bf16 v[110:113], v[172:175], v[180:183], v[110:113]
	v_mfma_f32_16x16x32_bf16 v[102:105], v[164:167], v[200:203], v[102:105]
	v_mfma_f32_16x16x32_bf16 v[94:97], v[172:175], v[200:203], v[94:97]
	v_mfma_f32_16x16x32_bf16 v[86:89], v[164:167], v[208:211], v[86:89]
	v_mfma_f32_16x16x32_bf16 v[78:81], v[172:175], v[208:211], v[78:81]
	v_mfma_f32_16x16x32_bf16 v[70:73], v[164:167], v[216:219], v[70:73]
	v_mfma_f32_16x16x32_bf16 v[66:69], v[172:175], v[216:219], v[66:69]
	v_mfma_f32_16x16x32_bf16 v[118:121], v[168:171], v[196:199], v[118:121]
	v_mfma_f32_16x16x32_bf16 v[110:113], v[176:179], v[196:199], v[110:113]
	v_mfma_f32_16x16x32_bf16 v[102:105], v[168:171], v[204:207], v[102:105]
	v_mfma_f32_16x16x32_bf16 v[94:97], v[176:179], v[204:207], v[94:97]
	v_mfma_f32_16x16x32_bf16 v[86:89], v[168:171], v[212:215], v[86:89]
	v_mfma_f32_16x16x32_bf16 v[78:81], v[176:179], v[212:215], v[78:81]
	v_mfma_f32_16x16x32_bf16 v[70:73], v[168:171], v[220:223], v[70:73]
	v_mfma_f32_16x16x32_bf16 v[66:69], v[176:179], v[220:223], v[66:69]
	s_setprio 0
	s_barrier
; #define PG8_STAGE(bufoff, gbase, voff) do { _Pragma("unroll") for (int _i = 0; _i < 2; ++_i) \
;         __builtin_amdgcn_global_load_lds((const unsigned*)((const char*)(gbase) + (voff)[_i]), (PG8_LAS unsigned*)(lds + (bufoff) + ldsw + _i * 8192), 16, 0, 0); } while (0)
; #define PG8_LDA(dst, b, h) do { _Pragma("unroll") for (int m = 0; m < 4; ++m) _Pragma("unroll") for (int k = 0; k < 2; ++k) dst[m][k] = *(const PG8_LAS bf16x8*)(lds + PG8_SA(b, h) + aoff + m * 2048 + k * 1024); } while (0)
; #define PG8_LDB(dst, b, h) do { _Pragma("unroll") for (int n = 0; n < 2; ++n) _Pragma("unroll") for (int k = 0; k < 2; ++k) dst[n][k] = *(const PG8_LAS bf16x8*)(lds + PG8_SB(b, h) + boff + n * 2048 + k * 1024); } while (0)
; #define PG8_MMA(ai, bj, At, Bt) do { __builtin_amdgcn_s_setprio(1); _Pragma("unroll") for (int m = 0; m < 4; ++m) _Pragma("unroll") for (int n = 0; n < 2; ++n) _Pragma("unroll") for (int k = 0; k < 2; ++k) \
;         acc[ai][bj][m][n] = __builtin_amdgcn_mfma_f32_16x16x32_bf16(Bt[n][k], At[m][k], acc[ai][bj][m][n], 0, 0, 0); __builtin_amdgcn_s_setprio(0); } while (0)
; #define PG8_WAIT_V(n) asm volatile("s_waitcnt vmcnt(" #n ")" ::: "memory")
; #define PG8_WAIT_L(n) asm volatile("s_waitcnt lgkmcnt(" #n ")" ::: "memory")
; #define PG8_BAR __builtin_amdgcn_s_barrier()
; #define PG8_SCHED __builtin_amdgcn_sched_barrier(0)
; template <class Epi, class Sched, bool ALIGN_EPI = false, bool SP2 = false, bool ABLK = false, bool BBLK = false>
; __device__ __forceinline__ void gemm_phase(PG8_LAS unsigned char* lds, const Gemm g, const Sched& S, const Epi& E) {
;     ...
;             PG8_LDA(At, 0, 1); PG8_STAGE(PG8_SB(0, 0), b2, voffB); PG8_STAGE(PG8_SB(0, 1), b2 + hstepB, voffB); PG8_STAGE(PG8_SA(0, 0), a2, voffA);
;             PG8_WAIT_V(8); PG8_WAIT_L(0); PG8_BAR; PG8_MMA(1, 0, At, B0); PG8_MMA(1, 1, At, B1); PG8_BAR; PG8_SCHED;
;             PG8_LDB(B0, 1, 0); PG8_LDB(B1, 1, 1); PG8_SCHED; PG8_LDA(At, 1, 0); PG8_STAGE(PG8_SA(0, 1), a2 + hstepA, voffA);
;             PG8_WAIT_V(8); PG8_WAIT_L(0); PG8_BAR; PG8_MMA(0, 0, At, B0); PG8_MMA(0, 1, At, B1); PG8_BAR; PG8_SCHED;
	s_add_i32 s51, s51, s35
	v_lshl_add_u64 v[142:143], s[26:27], 0, v[132:133]
	s_mov_b32 m0, s51
	ds_read_b128 v[180:183], v146 offset:16384
	ds_read_b128 v[196:199], v146 offset:17408
	ds_read_b128 v[200:203], v146 offset:18432
	ds_read_b128 v[204:207], v146 offset:19456
	ds_read_b128 v[208:211], v146 offset:20480
	ds_read_b128 v[212:215], v146 offset:21504
	ds_read_b128 v[216:219], v146 offset:22528
	ds_read_b128 v[220:223], v146 offset:23552
	global_load_lds_dwordx4 v[142:143], off
	s_add_i32 m0, s51, 0x2000
	s_add_u32 s82, s26, 0x80000
	v_lshl_add_u64 v[184:185], s[26:27], 0, v[136:137]
	s_addc_u32 s83, s27, 0
	s_add_i32 s51, s75, s35
	global_load_lds_dwordx4 v[184:185], off
	v_lshl_add_u64 v[224:225], s[82:83], 0, v[132:133]
	s_mov_b32 m0, s51
	v_lshl_add_u64 v[226:227], s[28:29], 0, v[134:135]
	global_load_lds_dwordx4 v[224:225], off
	v_lshl_add_u64 v[224:225], s[82:83], 0, v[136:137]
	s_add_i32 m0, s51, 0x2000
	s_nop 0
	global_load_lds_dwordx4 v[224:225], off
	v_lshl_add_u64 v[224:225], s[28:29], 0, v[130:131]
	s_mov_b32 m0, s46
	s_nop 0
	global_load_lds_dwordx4 v[224:225], off
	s_mov_b32 m0, s47
	s_nop 0
	global_load_lds_dwordx4 v[226:227], off
	s_waitcnt vmcnt(8)
	s_waitcnt lgkmcnt(0)
	s_barrier
	s_setprio 1
	s_waitcnt lgkmcnt(0)
	v_mfma_f32_16x16x32_bf16 v[62:65], v[148:151], v[180:183], v[62:65]
	v_mfma_f32_16x16x32_bf16 v[58:61], v[156:159], v[180:183], v[58:61]
	v_mfma_f32_16x16x32_bf16 v[50:53], v[148:151], v[200:203], v[50:53]
	v_mfma_f32_16x16x32_bf16 v[42:45], v[156:159], v[200:203], v[42:45]
	v_mfma_f32_16x16x32_bf16 v[34:37], v[148:151], v[208:211], v[34:37]
	v_mfma_f32_16x16x32_bf16 v[26:29], v[156:159], v[208:211], v[26:29]
	v_mfma_f32_16x16x32_bf16 v[18:21], v[148:151], v[216:219], v[18:21]
	v_mfma_f32_16x16x32_bf16 v[10:13], v[156:159], v[216:219], v[10:13]
	v_mfma_f32_16x16x32_bf16 v[62:65], v[152:155], v[196:199], v[62:65]
	v_mfma_f32_16x16x32_bf16 v[58:61], v[160:163], v[196:199], v[58:61]
	v_mfma_f32_16x16x32_bf16 v[50:53], v[152:155], v[204:207], v[50:53]
	v_mfma_f32_16x16x32_bf16 v[42:45], v[160:163], v[204:207], v[42:45]
	v_mfma_f32_16x16x32_bf16 v[34:37], v[152:155], v[212:215], v[34:37]
	v_mfma_f32_16x16x32_bf16 v[26:29], v[160:163], v[212:215], v[26:29]
	v_mfma_f32_16x16x32_bf16 v[18:21], v[152:155], v[220:223], v[18:21]
	v_mfma_f32_16x16x32_bf16 v[10:13], v[160:163], v[220:223], v[10:13]
	s_setprio 0
	s_setprio 1
	v_mfma_f32_16x16x32_bf16 v[54:57], v[164:167], v[180:183], v[54:57]
	v_mfma_f32_16x16x32_bf16 v[46:49], v[172:175], v[180:183], v[46:49]
	v_mfma_f32_16x16x32_bf16 v[38:41], v[164:167], v[200:203], v[38:41]
	v_mfma_f32_16x16x32_bf16 v[30:33], v[172:175], v[200:203], v[30:33]
	v_mfma_f32_16x16x32_bf16 v[22:25], v[164:167], v[208:211], v[22:25]
	v_mfma_f32_16x16x32_bf16 v[14:17], v[172:175], v[208:211], v[14:17]
	v_mfma_f32_16x16x32_bf16 v[6:9], v[164:167], v[216:219], v[6:9]
	v_mfma_f32_16x16x32_bf16 v[2:5], v[172:175], v[216:219], v[2:5]
	v_mfma_f32_16x16x32_bf16 v[54:57], v[168:171], v[196:199], v[54:57]
	v_mfma_f32_16x16x32_bf16 v[46:49], v[176:179], v[196:199], v[46:49]
	v_mfma_f32_16x16x32_bf16 v[38:41], v[168:171], v[204:207], v[38:41]
	v_mfma_f32_16x16x32_bf16 v[30:33], v[176:179], v[204:207], v[30:33]
	v_mfma_f32_16x16x32_bf16 v[22:25], v[168:171], v[212:215], v[22:25]
	v_mfma_f32_16x16x32_bf16 v[14:17], v[176:179], v[212:215], v[14:17]
	v_mfma_f32_16x16x32_bf16 v[6:9], v[168:171], v[220:223], v[6:9]
	v_mfma_f32_16x16x32_bf16 v[2:5], v[176:179], v[220:223], v[2:5]
	s_setprio 0
	s_barrier
.Lmid_790:
	s_add_i32 s51, 0, 0x18000
	v_add_u32_e32 v147, s51, v145
	s_add_i32 s75, 0, 0x1c000
	ds_read_b128 v[148:151], v147
	ds_read_b128 v[152:155], v147 offset:1024
	ds_read_b128 v[156:159], v147 offset:2048
	ds_read_b128 v[160:163], v147 offset:3072
	v_add_u32_e32 v147, s75, v145
	ds_read_b128 v[164:167], v147
	ds_read_b128 v[168:171], v147 offset:1024
	ds_read_b128 v[172:175], v147 offset:2048
	ds_read_b128 v[176:179], v147 offset:3072
	s_add_u32 s28, s28, 0x80000
	s_addc_u32 s29, s29, 0
	s_mov_b32 m0, s53
	v_lshl_add_u64 v[228:229], s[28:29], 0, v[130:131]
	ds_read_b128 v[180:183], v146 offset:32768
	ds_read_b128 v[196:199], v146 offset:33792
	ds_read_b128 v[200:203], v146 offset:34816
	ds_read_b128 v[204:207], v146 offset:35840
	ds_read_b128 v[208:211], v146 offset:36864
	ds_read_b128 v[212:215], v146 offset:37888
	ds_read_b128 v[216:219], v146 offset:38912
	ds_read_b128 v[220:223], v146 offset:39936
	global_load_lds_dwordx4 v[228:229], off
	v_lshl_add_u64 v[228:229], s[28:29], 0, v[134:135]
	s_mov_b32 m0, s56
	s_nop 0
	global_load_lds_dwordx4 v[228:229], off
	s_waitcnt vmcnt(8)
	s_waitcnt lgkmcnt(0)
	s_barrier
; #define PG8_STAGE(bufoff, gbase, voff) do { _Pragma("unroll") for (int _i = 0; _i < 2; ++_i) \
;         __builtin_amdgcn_global_load_lds((const unsigned*)((const char*)(gbase) + (voff)[_i]), (PG8_LAS unsigned*)(lds + (bufoff) + ldsw + _i * 8192), 16, 0, 0); } while (0)
; #define PG8_LDA(dst, b, h) do { _Pragma("unroll") for (int m = 0; m < 4; ++m) _Pragma("unroll") for (int k = 0; k < 2; ++k) dst[m][k] = *(const PG8_LAS bf16x8*)(lds + PG8_SA(b, h) + aoff + m * 2048 + k * 1024); } while (0)
; #define PG8_MMA(ai, bj, At, Bt) do { __builtin_amdgcn_s_setprio(1); _Pragma("unroll") for (int m = 0; m < 4; ++m) _Pragma("unroll") for (int n = 0; n < 2; ++n) _Pragma("unroll") for (int k = 0; k < 2; ++k) \
;         acc[ai][bj][m][n] = __builtin_amdgcn_mfma_f32_16x16x32_bf16(Bt[n][k], At[m][k], acc[ai][bj][m][n], 0, 0, 0); __builtin_amdgcn_s_setprio(0); } while (0)
; #define PG8_WAIT_V(n) asm volatile("s_waitcnt vmcnt(" #n ")" ::: "memory")
; #define PG8_WAIT_L(n) asm volatile("s_waitcnt lgkmcnt(" #n ")" ::: "memory")
; #define PG8_BAR __builtin_amdgcn_s_barrier()
; #define PG8_SCHED __builtin_amdgcn_sched_barrier(0)
; template <class Epi, class Sched, bool ALIGN_EPI = false, bool SP2 = false, bool ABLK = false, bool BBLK = false>
; __device__ __forceinline__ void gemm_phase(PG8_LAS unsigned char* lds, const Gemm g, const Sched& S, const Epi& E) {
;     ...
;             PG8_WAIT_V(8); PG8_WAIT_L(0); PG8_BAR; PG8_MMA(0, 0, At, B0); PG8_MMA(0, 1, At, B1); PG8_BAR; PG8_SCHED;
;             PG8_LDA(At, 1, 1); PG8_STAGE(PG8_SB(1, 0), b3, voffB); PG8_STAGE(PG8_SB(1, 1), b3 + hstepB, voffB); PG8_STAGE(PG8_SA(1, 0), a3, voffA);
;             PG8_WAIT_V(8); PG8_WAIT_L(0); PG8_BAR; PG8_MMA(1, 0, At, B0); PG8_MMA(1, 1, At, B1); PG8_BAR; PG8_SCHED;
;     ...
;         if constexpr (ALIGN_EPI) { if (wr == 0) PG8_BAR; }
	s_setprio 1
	s_waitcnt lgkmcnt(0)
	v_mfma_f32_16x16x32_bf16 v[126:129], v[148:151], v[180:183], v[126:129]
	v_mfma_f32_16x16x32_bf16 v[122:125], v[156:159], v[180:183], v[122:125]
	v_mfma_f32_16x16x32_bf16 v[114:117], v[148:151], v[200:203], v[114:117]
	v_mfma_f32_16x16x32_bf16 v[106:109], v[156:159], v[200:203], v[106:109]
	v_mfma_f32_16x16x32_bf16 v[98:101], v[148:151], v[208:211], v[98:101]
	v_mfma_f32_16x16x32_bf16 v[90:93], v[156:159], v[208:211], v[90:93]
	v_mfma_f32_16x16x32_bf16 v[82:85], v[148:151], v[216:219], v[82:85]
	v_mfma_f32_16x16x32_bf16 v[74:77], v[156:159], v[216:219], v[74:77]
	v_mfma_f32_16x16x32_bf16 v[126:129], v[152:155], v[196:199], v[126:129]
	v_mfma_f32_16x16x32_bf16 v[122:125], v[160:163], v[196:199], v[122:125]
	v_mfma_f32_16x16x32_bf16 v[114:117], v[152:155], v[204:207], v[114:117]
	v_mfma_f32_16x16x32_bf16 v[106:109], v[160:163], v[204:207], v[106:109]
	v_mfma_f32_16x16x32_bf16 v[98:101], v[152:155], v[212:215], v[98:101]
	v_mfma_f32_16x16x32_bf16 v[90:93], v[160:163], v[212:215], v[90:93]
	v_mfma_f32_16x16x32_bf16 v[82:85], v[152:155], v[220:223], v[82:85]
	v_mfma_f32_16x16x32_bf16 v[74:77], v[160:163], v[220:223], v[74:77]
	s_setprio 0
	s_setprio 1
	v_mfma_f32_16x16x32_bf16 v[118:121], v[164:167], v[180:183], v[118:121]
	v_mfma_f32_16x16x32_bf16 v[110:113], v[172:175], v[180:183], v[110:113]
	v_mfma_f32_16x16x32_bf16 v[102:105], v[164:167], v[200:203], v[102:105]
	v_mfma_f32_16x16x32_bf16 v[94:97], v[172:175], v[200:203], v[94:97]
	v_mfma_f32_16x16x32_bf16 v[86:89], v[164:167], v[208:211], v[86:89]
	v_mfma_f32_16x16x32_bf16 v[78:81], v[172:175], v[208:211], v[78:81]
	v_mfma_f32_16x16x32_bf16 v[70:73], v[164:167], v[216:219], v[70:73]
	v_mfma_f32_16x16x32_bf16 v[66:69], v[172:175], v[216:219], v[66:69]
	v_mfma_f32_16x16x32_bf16 v[118:121], v[168:171], v[196:199], v[118:121]
	v_mfma_f32_16x16x32_bf16 v[110:113], v[176:179], v[196:199], v[110:113]
	v_mfma_f32_16x16x32_bf16 v[102:105], v[168:171], v[204:207], v[102:105]
	v_mfma_f32_16x16x32_bf16 v[94:97], v[176:179], v[204:207], v[94:97]
	v_mfma_f32_16x16x32_bf16 v[86:89], v[168:171], v[212:215], v[86:89]
	v_mfma_f32_16x16x32_bf16 v[78:81], v[176:179], v[212:215], v[78:81]
	v_mfma_f32_16x16x32_bf16 v[70:73], v[168:171], v[220:223], v[70:73]
	v_mfma_f32_16x16x32_bf16 v[66:69], v[176:179], v[220:223], v[66:69]
	s_setprio 0
	s_barrier
	s_add_i32 s28, s51, s35
	v_lshl_add_u64 v[142:143], v[142:143], 0, s[62:63]
	s_mov_b32 m0, s28
	ds_read_b128 v[180:183], v146 offset:49152
	ds_read_b128 v[196:199], v146 offset:50176
	ds_read_b128 v[200:203], v146 offset:51200
	ds_read_b128 v[204:207], v146 offset:52224
	ds_read_b128 v[208:211], v146 offset:53248
	ds_read_b128 v[212:215], v146 offset:54272
	ds_read_b128 v[216:219], v146 offset:55296
	ds_read_b128 v[220:223], v146 offset:56320
	global_load_lds_dwordx4 v[142:143], off
	s_add_i32 m0, s28, 0x2000
	s_add_u32 s26, s26, 0x80080
	v_lshl_add_u64 v[142:143], v[184:185], 0, s[62:63]
	s_addc_u32 s27, s27, 0
	s_add_i32 s28, s75, s35
	global_load_lds_dwordx4 v[142:143], off
	v_lshl_add_u64 v[142:143], s[26:27], 0, v[132:133]
	s_mov_b32 m0, s28
	s_nop 0
	global_load_lds_dwordx4 v[142:143], off
	v_lshl_add_u64 v[142:143], s[26:27], 0, v[136:137]
	s_add_i32 m0, s28, 0x2000
	s_nop 0
	global_load_lds_dwordx4 v[142:143], off
	v_lshl_add_u64 v[142:143], v[224:225], 0, s[62:63]
	s_mov_b32 m0, s61
	s_nop 0
	global_load_lds_dwordx4 v[142:143], off
	v_lshl_add_u64 v[142:143], v[226:227], 0, s[62:63]
	s_mov_b32 m0, s65
	s_nop 0
	global_load_lds_dwordx4 v[142:143], off
	s_waitcnt vmcnt(8)
	s_waitcnt lgkmcnt(0)
	s_barrier
	s_setprio 1
	s_waitcnt lgkmcnt(0)
	v_mfma_f32_16x16x32_bf16 v[62:65], v[148:151], v[180:183], v[62:65]
	v_mfma_f32_16x16x32_bf16 v[58:61], v[156:159], v[180:183], v[58:61]
	v_mfma_f32_16x16x32_bf16 v[50:53], v[148:151], v[200:203], v[50:53]
	v_mfma_f32_16x16x32_bf16 v[42:45], v[156:159], v[200:203], v[42:45]
	v_mfma_f32_16x16x32_bf16 v[34:37], v[148:151], v[208:211], v[34:37]
	v_mfma_f32_16x16x32_bf16 v[26:29], v[156:159], v[208:211], v[26:29]
	v_mfma_f32_16x16x32_bf16 v[18:21], v[148:151], v[216:219], v[18:21]
	v_mfma_f32_16x16x32_bf16 v[10:13], v[156:159], v[216:219], v[10:13]
	v_mfma_f32_16x16x32_bf16 v[62:65], v[152:155], v[196:199], v[62:65]
	v_mfma_f32_16x16x32_bf16 v[58:61], v[160:163], v[196:199], v[58:61]
	v_mfma_f32_16x16x32_bf16 v[50:53], v[152:155], v[204:207], v[50:53]
	v_mfma_f32_16x16x32_bf16 v[42:45], v[160:163], v[204:207], v[42:45]
	v_mfma_f32_16x16x32_bf16 v[34:37], v[152:155], v[212:215], v[34:37]
	v_mfma_f32_16x16x32_bf16 v[26:29], v[160:163], v[212:215], v[26:29]
	v_mfma_f32_16x16x32_bf16 v[18:21], v[152:155], v[220:223], v[18:21]
	v_mfma_f32_16x16x32_bf16 v[10:13], v[160:163], v[220:223], v[10:13]
	s_setprio 0
	s_setprio 1
	v_mfma_f32_16x16x32_bf16 v[54:57], v[164:167], v[180:183], v[54:57]
	v_mfma_f32_16x16x32_bf16 v[46:49], v[172:175], v[180:183], v[46:49]
	v_mfma_f32_16x16x32_bf16 v[38:41], v[164:167], v[200:203], v[38:41]
	v_mfma_f32_16x16x32_bf16 v[30:33], v[172:175], v[200:203], v[30:33]
	v_mfma_f32_16x16x32_bf16 v[22:25], v[164:167], v[208:211], v[22:25]
	v_mfma_f32_16x16x32_bf16 v[14:17], v[172:175], v[208:211], v[14:17]
	v_mfma_f32_16x16x32_bf16 v[6:9], v[164:167], v[216:219], v[6:9]
	v_mfma_f32_16x16x32_bf16 v[2:5], v[172:175], v[216:219], v[2:5]
	v_mfma_f32_16x16x32_bf16 v[54:57], v[168:171], v[196:199], v[54:57]
	v_mfma_f32_16x16x32_bf16 v[46:49], v[176:179], v[196:199], v[46:49]
	v_mfma_f32_16x16x32_bf16 v[38:41], v[168:171], v[204:207], v[38:41]
	v_mfma_f32_16x16x32_bf16 v[30:33], v[176:179], v[204:207], v[30:33]
	v_mfma_f32_16x16x32_bf16 v[22:25], v[168:171], v[212:215], v[22:25]
	v_mfma_f32_16x16x32_bf16 v[14:17], v[176:179], v[212:215], v[14:17]
	v_mfma_f32_16x16x32_bf16 v[6:9], v[168:171], v[220:223], v[6:9]
	v_mfma_f32_16x16x32_bf16 v[2:5], v[176:179], v[220:223], v[2:5]
	s_setprio 0
	s_barrier
	s_add_i32 s81, s81, 2
	s_add_u32 s24, s24, 0x100
	s_addc_u32 s25, s25, 0
	s_add_u32 s23, s23, 0x100
	s_addc_u32 s73, s73, 0
	s_cmp_gt_u32 s81, 29
	s_cbranch_scc0 .LBB0_790
	s_and_b64 vcc, exec, s[8:9]
	s_cbranch_vccz .LBB0_793
	s_barrier

; #define PG8_STAGE(bufoff, gbase, voff) do { _Pragma("unroll") for (int _i = 0; _i < 2; ++_i) \
;         __builtin_amdgcn_global_load_lds((const unsigned*)((const char*)(gbase) + (voff)[_i]), (PG8_LAS unsigned*)(lds + (bufoff) + ldsw + _i * 8192), 16, 0, 0); } while (0)
; #define PG8_LDA(dst, b, h) do { _Pragma("unroll") for (int m = 0; m < 4; ++m) _Pragma("unroll") for (int k = 0; k < 2; ++k) dst[m][k] = *(const PG8_LAS bf16x8*)(lds + PG8_SA(b, h) + aoff + m * 2048 + k * 1024); } while (0)
; #define PG8_LDB(dst, b, h) do { _Pragma("unroll") for (int n = 0; n < 2; ++n) _Pragma("unroll") for (int k = 0; k < 2; ++k) dst[n][k] = *(const PG8_LAS bf16x8*)(lds + PG8_SB(b, h) + boff + n * 2048 + k * 1024); } while (0)
; #define PG8_WAIT_V(n) asm volatile("s_waitcnt vmcnt(" #n ")" ::: "memory")
; #define PG8_WAIT_L(n) asm volatile("s_waitcnt lgkmcnt(" #n ")" ::: "memory")
; #define PG8_BAR __builtin_amdgcn_s_barrier()
; template <class Epi, class Sched, bool ALIGN_EPI = false, bool SP2 = false, bool ABLK = false, bool BBLK = false>
; __device__ __forceinline__ void gemm_phase(PG8_LAS unsigned char* lds, const Gemm g, const Sched& S, const Epi& E) {
;     ...
;     for (;;) {
;         const bool has_next = S.next(ui + 1, nxt);
;         const char* nA = has_next ? (const char*)g.A + (size_t)nxt.pm * tstepA : cA; const char* nB = has_next ? (const char*)g.Bt + (size_t)nxt.pn * tstepB : cB;
;         for (int t = 0; t < nt; t += 2) {
;             const bool last = (t == nt - 2);
;             const char* a1 = cA + (size_t)(t + 1) * kstepA;
;             const char* a2 = last ? nA : cA + (size_t)(t + 2) * kstepA; const char* b2 = last ? nB : cB + (size_t)(t + 2) * kstepB;
;             const char* a3 = a2 + kstepA; const char* b3 = b2 + kstepB;
;             if (last && has_next) S.a_ready(nxt);
;             if constexpr (SP2) {
;             PG8_LDB(B0, 0, 0); PG8_LDB(B1, 0, 1); PG8_SCHED; PG8_LDA(At, 0, 0); PG8_STAGE(PG8_SA(1, 1), a1 + hstepA, voffA);
;             PG8_WAIT_V(8); PG8_WAIT_L(0); PG8_BAR; PG8_MMA(0, 0, At, B0); PG8_MMA(0, 1, At, B1); PG8_BAR; PG8_SCHED;
;             PG8_LDA(At, 0, 1); PG8_STAGE(PG8_SB(0, 0), b2, voffB); PG8_STAGE(PG8_SB(0, 1), b2 + hstepB, voffB); PG8_STAGE(PG8_SA(0, 0), a2, voffA);
;             PG8_WAIT_V(8); PG8_WAIT_L(0); PG8_BAR; PG8_MMA(1, 0, At, B0); PG8_MMA(1, 1, At, B1); PG8_BAR; PG8_SCHED;
.LBB0_1116:
	s_ashr_i32 s23, s22, 31
	s_lshl_b64 s[24:25], s[22:23], 18
	s_add_u32 s24, s33, s24
	s_addc_u32 s25, s44, s25
	s_and_b64 s[26:27], s[6:7], exec
	s_cselect_b32 s23, s25, s35
	s_cselect_b32 s31, s24, s34
	s_ashr_i32 s21, s20, 31
	s_lshl_b64 s[26:27], s[20:21], 18
	s_add_u32 s26, s45, s26
	s_addc_u32 s27, s46, s27
	s_and_b64 s[36:37], s[6:7], exec
	s_cselect_b32 s21, s27, s1
	s_cselect_b32 s91, s26, s0
	s_add_u32 s92, s0, 0x10000
	s_addc_u32 s93, s1, 0
	s_add_u32 s0, s34, 0x20080
	v_mov_b32_e32 v2, 0
	s_addc_u32 s1, s35, 0
	s_mov_b32 s94, -2
	s_add_u32 s34, s0, 0xfffe0080
	s_addc_u32 s35, s1, -1
	s_add_i32 s52, 0, 0x10000
	s_cmp_eq_u32 s94, 4
	s_cselect_b32 s37, s23, s35
	s_cselect_b32 s36, s31, s34
	s_cselect_b32 s35, s21, s93
	s_cselect_b32 s34, s91, s92
	s_add_i32 s75, 0, 0x14000
	v_add_u32_e32 v142, s52, v163
	v_add_u32_e32 v160, s75, v163
	ds_read_b128 v[130:133], v142
	ds_read_b128 v[134:137], v142 offset:1024
	ds_read_b128 v[138:141], v142 offset:2048
	ds_read_b128 v[142:145], v142 offset:3072
	ds_read_b128 v[146:149], v160
	ds_read_b128 v[166:169], v160 offset:1024
	ds_read_b128 v[170:173], v160 offset:2048
	ds_read_b128 v[174:177], v160 offset:3072
	v_lshl_add_u64 v[160:161], s[0:1], 0, v[156:157]
	s_add_i32 m0, s29, 0xc000
	ds_read_b128 v[178:181], v165
	ds_read_b128 v[182:185], v165 offset:1024
	ds_read_b128 v[196:199], v165 offset:2048
	ds_read_b128 v[200:203], v165 offset:3072
	ds_read_b128 v[204:207], v165 offset:4096
	ds_read_b128 v[208:211], v165 offset:5120
	ds_read_b128 v[212:215], v165 offset:6144
	ds_read_b128 v[216:219], v165 offset:7168
	global_load_lds_dwordx4 v[160:161], off
	v_lshl_add_u64 v[160:161], s[0:1], 0, v[158:159]
	s_add_i32 m0, s29, 0xe000
	s_nop 0
	global_load_lds_dwordx4 v[160:161], off
	s_waitcnt vmcnt(8)
	s_waitcnt lgkmcnt(0)
	s_barrier
	s_setprio 1
	s_waitcnt lgkmcnt(0)
	v_mfma_f32_16x16x32_bf16 v[126:129], v[130:133], v[178:181], 0
	v_mfma_f32_16x16x32_bf16 v[122:125], v[138:141], v[178:181], 0
	v_mfma_f32_16x16x32_bf16 v[118:121], v[130:133], v[196:199], 0
	v_mfma_f32_16x16x32_bf16 v[114:117], v[138:141], v[196:199], 0
	v_mfma_f32_16x16x32_bf16 v[94:97], v[130:133], v[204:207], 0
	v_mfma_f32_16x16x32_bf16 v[90:93], v[138:141], v[204:207], 0
	v_mfma_f32_16x16x32_bf16 v[78:81], v[130:133], v[212:215], 0
	v_mfma_f32_16x16x32_bf16 v[74:77], v[138:141], v[212:215], 0
	v_mfma_f32_16x16x32_bf16 v[126:129], v[134:137], v[182:185], v[126:129]
	v_mfma_f32_16x16x32_bf16 v[122:125], v[142:145], v[182:185], v[122:125]
	v_mfma_f32_16x16x32_bf16 v[118:121], v[134:137], v[200:203], v[118:121]
	v_mfma_f32_16x16x32_bf16 v[114:117], v[142:145], v[200:203], v[114:117]
	v_mfma_f32_16x16x32_bf16 v[94:97], v[134:137], v[208:211], v[94:97]
	v_mfma_f32_16x16x32_bf16 v[90:93], v[142:145], v[208:211], v[90:93]
	v_mfma_f32_16x16x32_bf16 v[78:81], v[134:137], v[216:219], v[78:81]
	v_mfma_f32_16x16x32_bf16 v[74:77], v[142:145], v[216:219], v[74:77]
	s_setprio 0
	s_setprio 1
	v_mfma_f32_16x16x32_bf16 v[110:113], v[146:149], v[178:181], 0
	v_mfma_f32_16x16x32_bf16 v[106:109], v[170:173], v[178:181], 0
	v_mfma_f32_16x16x32_bf16 v[102:105], v[146:149], v[196:199], 0
	v_mfma_f32_16x16x32_bf16 v[98:101], v[170:173], v[196:199], 0
	v_mfma_f32_16x16x32_bf16 v[86:89], v[146:149], v[204:207], 0
	v_mfma_f32_16x16x32_bf16 v[82:85], v[170:173], v[204:207], 0
	v_mfma_f32_16x16x32_bf16 v[70:73], v[146:149], v[212:215], 0
	v_mfma_f32_16x16x32_bf16 v[66:69], v[170:173], v[212:215], 0
	v_mfma_f32_16x16x32_bf16 v[110:113], v[166:169], v[182:185], v[110:113]
	v_mfma_f32_16x16x32_bf16 v[106:109], v[174:177], v[182:185], v[106:109]
	v_mfma_f32_16x16x32_bf16 v[102:105], v[166:169], v[200:203], v[102:105]
	v_mfma_f32_16x16x32_bf16 v[98:101], v[174:177], v[200:203], v[98:101]
	v_mfma_f32_16x16x32_bf16 v[86:89], v[166:169], v[208:211], v[86:89]
	v_mfma_f32_16x16x32_bf16 v[82:85], v[174:177], v[208:211], v[82:85]
	v_mfma_f32_16x16x32_bf16 v[70:73], v[166:169], v[216:219], v[70:73]
	v_mfma_f32_16x16x32_bf16 v[66:69], v[174:177], v[216:219], v[66:69]
	s_setprio 0
	s_barrier
	s_add_i32 s52, s52, s47
	v_lshl_add_u64 v[160:161], s[34:35], 0, v[150:151]
	s_mov_b32 m0, s52
	ds_read_b128 v[178:181], v165 offset:16384
	ds_read_b128 v[182:185], v165 offset:17408
	ds_read_b128 v[196:199], v165 offset:18432
	ds_read_b128 v[200:203], v165 offset:19456
	ds_read_b128 v[204:207], v165 offset:20480
	ds_read_b128 v[208:211], v165 offset:21504
	ds_read_b128 v[212:215], v165 offset:22528
	ds_read_b128 v[216:219], v165 offset:23552
	global_load_lds_dwordx4 v[160:161], off
	s_add_i32 m0, s52, 0x2000
	s_add_u32 s96, s34, 0x4000
	v_lshl_add_u64 v[160:161], s[34:35], 0, v[154:155]
	s_addc_u32 s97, s35, 0
	s_add_i32 s52, s75, s47
	global_load_lds_dwordx4 v[160:161], off
	v_lshl_add_u64 v[160:161], s[96:97], 0, v[150:151]
	s_mov_b32 m0, s52
	v_lshl_add_u64 v[188:189], s[36:37], 0, v[152:153]
	global_load_lds_dwordx4 v[160:161], off
	v_lshl_add_u64 v[160:161], s[96:97], 0, v[154:155]
	s_add_i32 m0, s52, 0x2000
	s_nop 0
	global_load_lds_dwordx4 v[160:161], off
	v_lshl_add_u64 v[160:161], s[36:37], 0, v[186:187]
	s_mov_b32 m0, s29
	s_nop 0
	global_load_lds_dwordx4 v[160:161], off
	s_mov_b32 m0, s65
	s_nop 0
	global_load_lds_dwordx4 v[188:189], off
	s_waitcnt vmcnt(8)
	s_waitcnt lgkmcnt(0)
	s_barrier
; #define PG8_STAGE(bufoff, gbase, voff) do { _Pragma("unroll") for (int _i = 0; _i < 2; ++_i) \
;         __builtin_amdgcn_global_load_lds((const unsigned*)((const char*)(gbase) + (voff)[_i]), (PG8_LAS unsigned*)(lds + (bufoff) + ldsw + _i * 8192), 16, 0, 0); } while (0)
; #define PG8_LDA(dst, b, h) do { _Pragma("unroll") for (int m = 0; m < 4; ++m) _Pragma("unroll") for (int k = 0; k < 2; ++k) dst[m][k] = *(const PG8_LAS bf16x8*)(lds + PG8_SA(b, h) + aoff + m * 2048 + k * 1024); } while (0)
; #define PG8_LDB(dst, b, h) do { _Pragma("unroll") for (int n = 0; n < 2; ++n) _Pragma("unroll") for (int k = 0; k < 2; ++k) dst[n][k] = *(const PG8_LAS bf16x8*)(lds + PG8_SB(b, h) + boff + n * 2048 + k * 1024); } while (0)
; #define PG8_MMA(ai, bj, At, Bt) do { __builtin_amdgcn_s_setprio(1); _Pragma("unroll") for (int m = 0; m < 4; ++m) _Pragma("unroll") for (int n = 0; n < 2; ++n) _Pragma("unroll") for (int k = 0; k < 2; ++k) \
;         acc[ai][bj][m][n] = __builtin_amdgcn_mfma_f32_16x16x32_bf16(Bt[n][k], At[m][k], acc[ai][bj][m][n], 0, 0, 0); __builtin_amdgcn_s_setprio(0); } while (0)
; #define PG8_WAIT_V(n) asm volatile("s_waitcnt vmcnt(" #n ")" ::: "memory")
; template <class Epi, class Sched, bool ALIGN_EPI = false, bool SP2 = false, bool ABLK = false, bool BBLK = false>
; __device__ __forceinline__ void gemm_phase(PG8_LAS unsigned char* lds, const Gemm g, const Sched& S, const Epi& E) {
;     ...
;         for (int t = 0; t < nt; t += 2) {
;             const bool last = (t == nt - 2);
;             const char* a1 = cA + (size_t)(t + 1) * kstepA;
;             const char* a2 = last ? nA : cA + (size_t)(t + 2) * kstepA; const char* b2 = last ? nB : cB + (size_t)(t + 2) * kstepB;
;             const char* a3 = a2 + kstepA; const char* b3 = b2 + kstepB;
;             if (last && has_next) S.a_ready(nxt);
;             if constexpr (SP2) {
;             PG8_LDB(B0, 0, 0); PG8_LDB(B1, 0, 1); PG8_SCHED; PG8_LDA(At, 0, 0); PG8_STAGE(PG8_SA(1, 1), a1 + hstepA, voffA);
;             PG8_WAIT_V(8); PG8_WAIT_L(0); PG8_BAR; PG8_MMA(0, 0, At, B0); PG8_MMA(0, 1, At, B1); PG8_BAR; PG8_SCHED;
;             PG8_LDA(At, 0, 1); PG8_STAGE(PG8_SB(0, 0), b2, voffB); PG8_STAGE(PG8_SB(0, 1), b2 + hstepB, voffB); PG8_STAGE(PG8_SA(0, 0), a2, voffA);
;             PG8_WAIT_V(8); PG8_WAIT_L(0); PG8_BAR; PG8_MMA(1, 0, At, B0); PG8_MMA(1, 1, At, B1); PG8_BAR; PG8_SCHED;
	s_setprio 1
	s_waitcnt lgkmcnt(0)
	v_mfma_f32_16x16x32_bf16 v[62:65], v[130:133], v[178:181], 0
	v_mfma_f32_16x16x32_bf16 v[58:61], v[138:141], v[178:181], 0
	v_mfma_f32_16x16x32_bf16 v[46:49], v[130:133], v[196:199], 0
	v_mfma_f32_16x16x32_bf16 v[42:45], v[138:141], v[196:199], 0
	v_mfma_f32_16x16x32_bf16 v[30:33], v[130:133], v[204:207], 0
	v_mfma_f32_16x16x32_bf16 v[26:29], v[138:141], v[204:207], 0
	v_mfma_f32_16x16x32_bf16 v[14:17], v[130:133], v[212:215], 0
	v_mfma_f32_16x16x32_bf16 v[10:13], v[138:141], v[212:215], 0
	v_mfma_f32_16x16x32_bf16 v[62:65], v[134:137], v[182:185], v[62:65]
	v_mfma_f32_16x16x32_bf16 v[58:61], v[142:145], v[182:185], v[58:61]
	v_mfma_f32_16x16x32_bf16 v[46:49], v[134:137], v[200:203], v[46:49]
	v_mfma_f32_16x16x32_bf16 v[42:45], v[142:145], v[200:203], v[42:45]
	v_mfma_f32_16x16x32_bf16 v[30:33], v[134:137], v[208:211], v[30:33]
	v_mfma_f32_16x16x32_bf16 v[26:29], v[142:145], v[208:211], v[26:29]
	v_mfma_f32_16x16x32_bf16 v[14:17], v[134:137], v[216:219], v[14:17]
	v_mfma_f32_16x16x32_bf16 v[10:13], v[142:145], v[216:219], v[10:13]
	s_setprio 0
	s_setprio 1
	v_mfma_f32_16x16x32_bf16 v[54:57], v[146:149], v[178:181], 0
	v_mfma_f32_16x16x32_bf16 v[50:53], v[170:173], v[178:181], 0
	v_mfma_f32_16x16x32_bf16 v[38:41], v[146:149], v[196:199], 0
	v_mfma_f32_16x16x32_bf16 v[34:37], v[170:173], v[196:199], 0
	v_mfma_f32_16x16x32_bf16 v[22:25], v[146:149], v[204:207], 0
	v_mfma_f32_16x16x32_bf16 v[18:21], v[170:173], v[204:207], 0
	v_mfma_f32_16x16x32_bf16 v[6:9], v[146:149], v[212:215], 0
	v_mfma_f32_16x16x32_bf16 v[2:5], v[170:173], v[212:215], 0
	v_mfma_f32_16x16x32_bf16 v[54:57], v[166:169], v[182:185], v[54:57]
	v_mfma_f32_16x16x32_bf16 v[50:53], v[174:177], v[182:185], v[50:53]
	v_mfma_f32_16x16x32_bf16 v[38:41], v[166:169], v[200:203], v[38:41]
	v_mfma_f32_16x16x32_bf16 v[34:37], v[174:177], v[200:203], v[34:37]
	v_mfma_f32_16x16x32_bf16 v[22:25], v[166:169], v[208:211], v[22:25]
	v_mfma_f32_16x16x32_bf16 v[18:21], v[174:177], v[208:211], v[18:21]
	v_mfma_f32_16x16x32_bf16 v[6:9], v[166:169], v[216:219], v[6:9]
	v_mfma_f32_16x16x32_bf16 v[2:5], v[174:177], v[216:219], v[2:5]
	s_setprio 0
	s_barrier
	s_branch .Lmid_1117
.LBB0_1117:
	s_add_u32 s34, s0, 0xfffe0080
	s_addc_u32 s35, s1, -1
	s_add_i32 s52, 0, 0x10000
	s_cmp_eq_u32 s94, 4
	s_cselect_b32 s37, s23, s35
	s_cselect_b32 s36, s31, s34
	s_cselect_b32 s35, s21, s93
	s_cselect_b32 s34, s91, s92
	s_add_i32 s75, 0, 0x14000
	v_add_u32_e32 v142, s52, v163
	v_add_u32_e32 v160, s75, v163
	ds_read_b128 v[130:133], v142
	ds_read_b128 v[134:137], v142 offset:1024
	ds_read_b128 v[138:141], v142 offset:2048
	ds_read_b128 v[142:145], v142 offset:3072
	ds_read_b128 v[146:149], v160
	ds_read_b128 v[166:169], v160 offset:1024
	ds_read_b128 v[170:173], v160 offset:2048
	ds_read_b128 v[174:177], v160 offset:3072
	v_lshl_add_u64 v[160:161], s[0:1], 0, v[156:157]
	s_add_i32 m0, s29, 0xc000
	ds_read_b128 v[178:181], v165
	ds_read_b128 v[182:185], v165 offset:1024
	ds_read_b128 v[196:199], v165 offset:2048
	ds_read_b128 v[200:203], v165 offset:3072
	ds_read_b128 v[204:207], v165 offset:4096
	ds_read_b128 v[208:211], v165 offset:5120
	ds_read_b128 v[212:215], v165 offset:6144
	ds_read_b128 v[216:219], v165 offset:7168
	global_load_lds_dwordx4 v[160:161], off
	v_lshl_add_u64 v[160:161], s[0:1], 0, v[158:159]
	s_add_i32 m0, s29, 0xe000
	s_nop 0
	global_load_lds_dwordx4 v[160:161], off
	s_waitcnt vmcnt(8)
	s_waitcnt lgkmcnt(0)
	s_barrier
	s_setprio 1
	s_waitcnt lgkmcnt(0)
	v_mfma_f32_16x16x32_bf16 v[126:129], v[130:133], v[178:181], v[126:129]
	v_mfma_f32_16x16x32_bf16 v[122:125], v[138:141], v[178:181], v[122:125]
	v_mfma_f32_16x16x32_bf16 v[118:121], v[130:133], v[196:199], v[118:121]
	v_mfma_f32_16x16x32_bf16 v[114:117], v[138:141], v[196:199], v[114:117]
	v_mfma_f32_16x16x32_bf16 v[94:97], v[130:133], v[204:207], v[94:97]
	v_mfma_f32_16x16x32_bf16 v[90:93], v[138:141], v[204:207], v[90:93]
	v_mfma_f32_16x16x32_bf16 v[78:81], v[130:133], v[212:215], v[78:81]
	v_mfma_f32_16x16x32_bf16 v[74:77], v[138:141], v[212:215], v[74:77]
	v_mfma_f32_16x16x32_bf16 v[126:129], v[134:137], v[182:185], v[126:129]
	v_mfma_f32_16x16x32_bf16 v[122:125], v[142:145], v[182:185], v[122:125]
	v_mfma_f32_16x16x32_bf16 v[118:121], v[134:137], v[200:203], v[118:121]
	v_mfma_f32_16x16x32_bf16 v[114:117], v[142:145], v[200:203], v[114:117]
	v_mfma_f32_16x16x32_bf16 v[94:97], v[134:137], v[208:211], v[94:97]
	v_mfma_f32_16x16x32_bf16 v[90:93], v[142:145], v[208:211], v[90:93]
	v_mfma_f32_16x16x32_bf16 v[78:81], v[134:137], v[216:219], v[78:81]
	v_mfma_f32_16x16x32_bf16 v[74:77], v[142:145], v[216:219], v[74:77]
	s_setprio 0
	s_setprio 1
	v_mfma_f32_16x16x32_bf16 v[110:113], v[146:149], v[178:181], v[110:113]
	v_mfma_f32_16x16x32_bf16 v[106:109], v[170:173], v[178:181], v[106:109]
	v_mfma_f32_16x16x32_bf16 v[102:105], v[146:149], v[196:199], v[102:105]
	v_mfma_f32_16x16x32_bf16 v[98:101], v[170:173], v[196:199], v[98:101]
	v_mfma_f32_16x16x32_bf16 v[86:89], v[146:149], v[204:207], v[86:89]
	v_mfma_f32_16x16x32_bf16 v[82:85], v[170:173], v[204:207], v[82:85]
	v_mfma_f32_16x16x32_bf16 v[70:73], v[146:149], v[212:215], v[70:73]
	v_mfma_f32_16x16x32_bf16 v[66:69], v[170:173], v[212:215], v[66:69]
	v_mfma_f32_16x16x32_bf16 v[110:113], v[166:169], v[182:185], v[110:113]
	v_mfma_f32_16x16x32_bf16 v[106:109], v[174:177], v[182:185], v[106:109]
	v_mfma_f32_16x16x32_bf16 v[102:105], v[166:169], v[200:203], v[102:105]
	v_mfma_f32_16x16x32_bf16 v[98:101], v[174:177], v[200:203], v[98:101]
	v_mfma_f32_16x16x32_bf16 v[86:89], v[166:169], v[208:211], v[86:89]
	v_mfma_f32_16x16x32_bf16 v[82:85], v[174:177], v[208:211], v[82:85]
	v_mfma_f32_16x16x32_bf16 v[70:73], v[166:169], v[216:219], v[70:73]
	v_mfma_f32_16x16x32_bf16 v[66:69], v[174:177], v[216:219], v[66:69]
	s_setprio 0
	s_barrier
; #define PG8_STAGE(bufoff, gbase, voff) do { _Pragma("unroll") for (int _i = 0; _i < 2; ++_i) \
;         __builtin_amdgcn_global_load_lds((const unsigned*)((const char*)(gbase) + (voff)[_i]), (PG8_LAS unsigned*)(lds + (bufoff) + ldsw + _i * 8192), 16, 0, 0); } while (0)
; #define PG8_LDA(dst, b, h) do { _Pragma("unroll") for (int m = 0; m < 4; ++m) _Pragma("unroll") for (int k = 0; k < 2; ++k) dst[m][k] = *(const PG8_LAS bf16x8*)(lds + PG8_SA(b, h) + aoff + m * 2048 + k * 1024); } while (0)
; #define PG8_LDB(dst, b, h) do { _Pragma("unroll") for (int n = 0; n < 2; ++n) _Pragma("unroll") for (int k = 0; k < 2; ++k) dst[n][k] = *(const PG8_LAS bf16x8*)(lds + PG8_SB(b, h) + boff + n * 2048 + k * 1024); } while (0)
; #define PG8_MMA(ai, bj, At, Bt) do { __builtin_amdgcn_s_setprio(1); _Pragma("unroll") for (int m = 0; m < 4; ++m) _Pragma("unroll") for (int n = 0; n < 2; ++n) _Pragma("unroll") for (int k = 0; k < 2; ++k) \
;         acc[ai][bj][m][n] = __builtin_amdgcn_mfma_f32_16x16x32_bf16(Bt[n][k], At[m][k], acc[ai][bj][m][n], 0, 0, 0); __builtin_amdgcn_s_setprio(0); } while (0)
; #define PG8_WAIT_V(n) asm volatile("s_waitcnt vmcnt(" #n ")" ::: "memory")
; #define PG8_WAIT_L(n) asm volatile("s_waitcnt lgkmcnt(" #n ")" ::: "memory")
; #define PG8_BAR __builtin_amdgcn_s_barrier()
; #define PG8_SCHED __builtin_amdgcn_sched_barrier(0)
; template <class Epi, class Sched, bool ALIGN_EPI = false, bool SP2 = false, bool ABLK = false, bool BBLK = false>
; __device__ __forceinline__ void gemm_phase(PG8_LAS unsigned char* lds, const Gemm g, const Sched& S, const Epi& E) {
;     ...
;             PG8_LDA(At, 0, 1); PG8_STAGE(PG8_SB(0, 0), b2, voffB); PG8_STAGE(PG8_SB(0, 1), b2 + hstepB, voffB); PG8_STAGE(PG8_SA(0, 0), a2, voffA);
;             PG8_WAIT_V(8); PG8_WAIT_L(0); PG8_BAR; PG8_MMA(1, 0, At, B0); PG8_MMA(1, 1, At, B1); PG8_BAR; PG8_SCHED;
;             PG8_LDB(B0, 1, 0); PG8_LDB(B1, 1, 1); PG8_SCHED; PG8_LDA(At, 1, 0); PG8_STAGE(PG8_SA(0, 1), a2 + hstepA, voffA);
;             PG8_WAIT_V(8); PG8_WAIT_L(0); PG8_BAR; PG8_MMA(0, 0, At, B0); PG8_MMA(0, 1, At, B1); PG8_BAR; PG8_SCHED;
	s_add_i32 s52, s52, s47
	v_lshl_add_u64 v[160:161], s[34:35], 0, v[150:151]
	s_mov_b32 m0, s52
	ds_read_b128 v[178:181], v165 offset:16384
	ds_read_b128 v[182:185], v165 offset:17408
	ds_read_b128 v[196:199], v165 offset:18432
	ds_read_b128 v[200:203], v165 offset:19456
	ds_read_b128 v[204:207], v165 offset:20480
	ds_read_b128 v[208:211], v165 offset:21504
	ds_read_b128 v[212:215], v165 offset:22528
	ds_read_b128 v[216:219], v165 offset:23552
	global_load_lds_dwordx4 v[160:161], off
	s_add_i32 m0, s52, 0x2000
	s_add_u32 s96, s34, 0x4000
	v_lshl_add_u64 v[160:161], s[34:35], 0, v[154:155]
	s_addc_u32 s97, s35, 0
	s_add_i32 s52, s75, s47
	global_load_lds_dwordx4 v[160:161], off
	v_lshl_add_u64 v[160:161], s[96:97], 0, v[150:151]
	s_mov_b32 m0, s52
	v_lshl_add_u64 v[188:189], s[36:37], 0, v[152:153]
	global_load_lds_dwordx4 v[160:161], off
	v_lshl_add_u64 v[160:161], s[96:97], 0, v[154:155]
	s_add_i32 m0, s52, 0x2000
	s_nop 0
	global_load_lds_dwordx4 v[160:161], off
	v_lshl_add_u64 v[160:161], s[36:37], 0, v[186:187]
	s_mov_b32 m0, s29
	s_nop 0
	global_load_lds_dwordx4 v[160:161], off
	s_mov_b32 m0, s65
	s_nop 0
	global_load_lds_dwordx4 v[188:189], off
	s_waitcnt vmcnt(8)
	s_waitcnt lgkmcnt(0)
	s_barrier
	s_setprio 1
	s_waitcnt lgkmcnt(0)
	v_mfma_f32_16x16x32_bf16 v[62:65], v[130:133], v[178:181], v[62:65]
	v_mfma_f32_16x16x32_bf16 v[58:61], v[138:141], v[178:181], v[58:61]
	v_mfma_f32_16x16x32_bf16 v[46:49], v[130:133], v[196:199], v[46:49]
	v_mfma_f32_16x16x32_bf16 v[42:45], v[138:141], v[196:199], v[42:45]
	v_mfma_f32_16x16x32_bf16 v[30:33], v[130:133], v[204:207], v[30:33]
	v_mfma_f32_16x16x32_bf16 v[26:29], v[138:141], v[204:207], v[26:29]
	v_mfma_f32_16x16x32_bf16 v[14:17], v[130:133], v[212:215], v[14:17]
	v_mfma_f32_16x16x32_bf16 v[10:13], v[138:141], v[212:215], v[10:13]
	v_mfma_f32_16x16x32_bf16 v[62:65], v[134:137], v[182:185], v[62:65]
	v_mfma_f32_16x16x32_bf16 v[58:61], v[142:145], v[182:185], v[58:61]
	v_mfma_f32_16x16x32_bf16 v[46:49], v[134:137], v[200:203], v[46:49]
	v_mfma_f32_16x16x32_bf16 v[42:45], v[142:145], v[200:203], v[42:45]
	v_mfma_f32_16x16x32_bf16 v[30:33], v[134:137], v[208:211], v[30:33]
	v_mfma_f32_16x16x32_bf16 v[26:29], v[142:145], v[208:211], v[26:29]
	v_mfma_f32_16x16x32_bf16 v[14:17], v[134:137], v[216:219], v[14:17]
	v_mfma_f32_16x16x32_bf16 v[10:13], v[142:145], v[216:219], v[10:13]
	s_setprio 0
	s_setprio 1
	v_mfma_f32_16x16x32_bf16 v[54:57], v[146:149], v[178:181], v[54:57]
	v_mfma_f32_16x16x32_bf16 v[50:53], v[170:173], v[178:181], v[50:53]
	v_mfma_f32_16x16x32_bf16 v[38:41], v[146:149], v[196:199], v[38:41]
	v_mfma_f32_16x16x32_bf16 v[34:37], v[170:173], v[196:199], v[34:37]
	v_mfma_f32_16x16x32_bf16 v[22:25], v[146:149], v[204:207], v[22:25]
	v_mfma_f32_16x16x32_bf16 v[18:21], v[170:173], v[204:207], v[18:21]
	v_mfma_f32_16x16x32_bf16 v[6:9], v[146:149], v[212:215], v[6:9]
	v_mfma_f32_16x16x32_bf16 v[2:5], v[170:173], v[212:215], v[2:5]
	v_mfma_f32_16x16x32_bf16 v[54:57], v[166:169], v[182:185], v[54:57]
	v_mfma_f32_16x16x32_bf16 v[50:53], v[174:177], v[182:185], v[50:53]
	v_mfma_f32_16x16x32_bf16 v[38:41], v[166:169], v[200:203], v[38:41]
	v_mfma_f32_16x16x32_bf16 v[34:37], v[174:177], v[200:203], v[34:37]
	v_mfma_f32_16x16x32_bf16 v[22:25], v[166:169], v[208:211], v[22:25]
	v_mfma_f32_16x16x32_bf16 v[18:21], v[174:177], v[208:211], v[18:21]
	v_mfma_f32_16x16x32_bf16 v[6:9], v[166:169], v[216:219], v[6:9]
	v_mfma_f32_16x16x32_bf16 v[2:5], v[174:177], v[216:219], v[2:5]
	s_setprio 0
	s_barrier
.Lmid_1117:
	s_add_i32 s52, 0, 0x18000
	s_add_i32 s75, 0, 0x1c000
	v_add_u32_e32 v142, s52, v163
	v_add_u32_e32 v174, s75, v163
	ds_read_b128 v[130:133], v142
	ds_read_b128 v[134:137], v142 offset:1024
	ds_read_b128 v[138:141], v142 offset:2048
	ds_read_b128 v[142:145], v142 offset:3072
	ds_read_b128 v[146:149], v174
	ds_read_b128 v[166:169], v174 offset:1024
	ds_read_b128 v[170:173], v174 offset:2048
	ds_read_b128 v[174:177], v174 offset:3072
	s_add_u32 s36, s36, 0x20000
	s_addc_u32 s37, s37, 0
	s_mov_b32 m0, s68
	v_lshl_add_u64 v[190:191], s[36:37], 0, v[186:187]
	ds_read_b128 v[178:181], v165 offset:32768
	ds_read_b128 v[182:185], v165 offset:33792
	ds_read_b128 v[196:199], v165 offset:34816
	ds_read_b128 v[200:203], v165 offset:35840
	ds_read_b128 v[204:207], v165 offset:36864
	ds_read_b128 v[208:211], v165 offset:37888
	ds_read_b128 v[212:215], v165 offset:38912
	ds_read_b128 v[216:219], v165 offset:39936
	global_load_lds_dwordx4 v[190:191], off
	v_lshl_add_u64 v[190:191], s[36:37], 0, v[152:153]
	s_mov_b32 m0, s72
	s_nop 0
	global_load_lds_dwordx4 v[190:191], off
	s_waitcnt vmcnt(8)
	s_waitcnt lgkmcnt(0)
	s_barrier
; #define PG8_STAGE(bufoff, gbase, voff) do { _Pragma("unroll") for (int _i = 0; _i < 2; ++_i) \
;         __builtin_amdgcn_global_load_lds((const unsigned*)((const char*)(gbase) + (voff)[_i]), (PG8_LAS unsigned*)(lds + (bufoff) + ldsw + _i * 8192), 16, 0, 0); } while (0)
; #define PG8_LDA(dst, b, h) do { _Pragma("unroll") for (int m = 0; m < 4; ++m) _Pragma("unroll") for (int k = 0; k < 2; ++k) dst[m][k] = *(const PG8_LAS bf16x8*)(lds + PG8_SA(b, h) + aoff + m * 2048 + k * 1024); } while (0)
; #define PG8_MMA(ai, bj, At, Bt) do { __builtin_amdgcn_s_setprio(1); _Pragma("unroll") for (int m = 0; m < 4; ++m) _Pragma("unroll") for (int n = 0; n < 2; ++n) _Pragma("unroll") for (int k = 0; k < 2; ++k) \
;         acc[ai][bj][m][n] = __builtin_amdgcn_mfma_f32_16x16x32_bf16(Bt[n][k], At[m][k], acc[ai][bj][m][n], 0, 0, 0); __builtin_amdgcn_s_setprio(0); } while (0)
; #define PG8_WAIT_V(n) asm volatile("s_waitcnt vmcnt(" #n ")" ::: "memory")
; #define PG8_WAIT_L(n) asm volatile("s_waitcnt lgkmcnt(" #n ")" ::: "memory")
; #define PG8_BAR __builtin_amdgcn_s_barrier()
; #define PG8_SCHED __builtin_amdgcn_sched_barrier(0)
; template <class Epi, class Sched, bool ALIGN_EPI = false, bool SP2 = false, bool ABLK = false, bool BBLK = false>
; __device__ __forceinline__ void gemm_phase(PG8_LAS unsigned char* lds, const Gemm g, const Sched& S, const Epi& E) {
;     ...
;             PG8_WAIT_V(8); PG8_WAIT_L(0); PG8_BAR; PG8_MMA(0, 0, At, B0); PG8_MMA(0, 1, At, B1); PG8_BAR; PG8_SCHED;
;             PG8_LDA(At, 1, 1); PG8_STAGE(PG8_SB(1, 0), b3, voffB); PG8_STAGE(PG8_SB(1, 1), b3 + hstepB, voffB); PG8_STAGE(PG8_SA(1, 0), a3, voffA);
;             PG8_WAIT_V(8); PG8_WAIT_L(0); PG8_BAR; PG8_MMA(1, 0, At, B0); PG8_MMA(1, 1, At, B1); PG8_BAR; PG8_SCHED;
;     ...
;         if constexpr (ALIGN_EPI) { if (wr == 0) PG8_BAR; }
	s_setprio 1
	s_waitcnt lgkmcnt(0)
	v_mfma_f32_16x16x32_bf16 v[126:129], v[130:133], v[178:181], v[126:129]
	v_mfma_f32_16x16x32_bf16 v[122:125], v[138:141], v[178:181], v[122:125]
	v_mfma_f32_16x16x32_bf16 v[118:121], v[130:133], v[196:199], v[118:121]
	v_mfma_f32_16x16x32_bf16 v[114:117], v[138:141], v[196:199], v[114:117]
	v_mfma_f32_16x16x32_bf16 v[94:97], v[130:133], v[204:207], v[94:97]
	v_mfma_f32_16x16x32_bf16 v[90:93], v[138:141], v[204:207], v[90:93]
	v_mfma_f32_16x16x32_bf16 v[78:81], v[130:133], v[212:215], v[78:81]
	v_mfma_f32_16x16x32_bf16 v[74:77], v[138:141], v[212:215], v[74:77]
	v_mfma_f32_16x16x32_bf16 v[126:129], v[134:137], v[182:185], v[126:129]
	v_mfma_f32_16x16x32_bf16 v[122:125], v[142:145], v[182:185], v[122:125]
	v_mfma_f32_16x16x32_bf16 v[118:121], v[134:137], v[200:203], v[118:121]
	v_mfma_f32_16x16x32_bf16 v[114:117], v[142:145], v[200:203], v[114:117]
	v_mfma_f32_16x16x32_bf16 v[94:97], v[134:137], v[208:211], v[94:97]
	v_mfma_f32_16x16x32_bf16 v[90:93], v[142:145], v[208:211], v[90:93]
	v_mfma_f32_16x16x32_bf16 v[78:81], v[134:137], v[216:219], v[78:81]
	v_mfma_f32_16x16x32_bf16 v[74:77], v[142:145], v[216:219], v[74:77]
	s_setprio 0
	s_setprio 1
	v_mfma_f32_16x16x32_bf16 v[110:113], v[146:149], v[178:181], v[110:113]
	v_mfma_f32_16x16x32_bf16 v[106:109], v[170:173], v[178:181], v[106:109]
	v_mfma_f32_16x16x32_bf16 v[102:105], v[146:149], v[196:199], v[102:105]
	v_mfma_f32_16x16x32_bf16 v[98:101], v[170:173], v[196:199], v[98:101]
	v_mfma_f32_16x16x32_bf16 v[86:89], v[146:149], v[204:207], v[86:89]
	v_mfma_f32_16x16x32_bf16 v[82:85], v[170:173], v[204:207], v[82:85]
	v_mfma_f32_16x16x32_bf16 v[70:73], v[146:149], v[212:215], v[70:73]
	v_mfma_f32_16x16x32_bf16 v[66:69], v[170:173], v[212:215], v[66:69]
	v_mfma_f32_16x16x32_bf16 v[110:113], v[166:169], v[182:185], v[110:113]
	v_mfma_f32_16x16x32_bf16 v[106:109], v[174:177], v[182:185], v[106:109]
	v_mfma_f32_16x16x32_bf16 v[102:105], v[166:169], v[200:203], v[102:105]
	v_mfma_f32_16x16x32_bf16 v[98:101], v[174:177], v[200:203], v[98:101]
	v_mfma_f32_16x16x32_bf16 v[86:89], v[166:169], v[208:211], v[86:89]
	v_mfma_f32_16x16x32_bf16 v[82:85], v[174:177], v[208:211], v[82:85]
	v_mfma_f32_16x16x32_bf16 v[70:73], v[166:169], v[216:219], v[70:73]
	v_mfma_f32_16x16x32_bf16 v[66:69], v[174:177], v[216:219], v[66:69]
	s_setprio 0
	s_barrier
	s_add_u32 s36, s34, 0x8000
	s_addc_u32 s37, s35, 0
	s_add_i32 s52, s52, s47
	v_lshl_add_u64 v[190:191], s[36:37], 0, v[150:151]
	s_mov_b32 m0, s52
	ds_read_b128 v[178:181], v165 offset:49152
	ds_read_b128 v[182:185], v165 offset:50176
	ds_read_b128 v[196:199], v165 offset:51200
	ds_read_b128 v[200:203], v165 offset:52224
	ds_read_b128 v[204:207], v165 offset:53248
	ds_read_b128 v[208:211], v165 offset:54272
	ds_read_b128 v[212:215], v165 offset:55296
	ds_read_b128 v[216:219], v165 offset:56320
	global_load_lds_dwordx4 v[190:191], off
	s_add_i32 m0, s52, 0x2000
	s_add_u32 s34, s34, 0xc000
	v_lshl_add_u64 v[190:191], s[36:37], 0, v[154:155]
	s_addc_u32 s35, s35, 0
	s_add_i32 s36, s75, s47
	global_load_lds_dwordx4 v[190:191], off
	v_lshl_add_u64 v[190:191], s[34:35], 0, v[150:151]
	s_mov_b32 m0, s36
	v_lshl_add_u64 v[160:161], v[160:161], 0, s[62:63]
	global_load_lds_dwordx4 v[190:191], off
	v_lshl_add_u64 v[190:191], s[34:35], 0, v[154:155]
	s_add_i32 m0, s36, 0x2000
	s_nop 0
	global_load_lds_dwordx4 v[190:191], off
	s_mov_b32 m0, s86
	s_nop 0
	global_load_lds_dwordx4 v[160:161], off
	v_lshl_add_u64 v[160:161], v[188:189], 0, s[62:63]
	s_mov_b32 m0, s88
	s_nop 0
	global_load_lds_dwordx4 v[160:161], off
	s_waitcnt vmcnt(8)
	s_waitcnt lgkmcnt(0)
	s_barrier
	s_setprio 1
	s_waitcnt lgkmcnt(0)
	v_mfma_f32_16x16x32_bf16 v[62:65], v[130:133], v[178:181], v[62:65]
	v_mfma_f32_16x16x32_bf16 v[58:61], v[138:141], v[178:181], v[58:61]
	v_mfma_f32_16x16x32_bf16 v[46:49], v[130:133], v[196:199], v[46:49]
	v_mfma_f32_16x16x32_bf16 v[42:45], v[138:141], v[196:199], v[42:45]
	v_mfma_f32_16x16x32_bf16 v[30:33], v[130:133], v[204:207], v[30:33]
	v_mfma_f32_16x16x32_bf16 v[26:29], v[138:141], v[204:207], v[26:29]
	v_mfma_f32_16x16x32_bf16 v[14:17], v[130:133], v[212:215], v[14:17]
	v_mfma_f32_16x16x32_bf16 v[10:13], v[138:141], v[212:215], v[10:13]
	v_mfma_f32_16x16x32_bf16 v[62:65], v[134:137], v[182:185], v[62:65]
	v_mfma_f32_16x16x32_bf16 v[58:61], v[142:145], v[182:185], v[58:61]
	v_mfma_f32_16x16x32_bf16 v[46:49], v[134:137], v[200:203], v[46:49]
	v_mfma_f32_16x16x32_bf16 v[42:45], v[142:145], v[200:203], v[42:45]
	v_mfma_f32_16x16x32_bf16 v[30:33], v[134:137], v[208:211], v[30:33]
	v_mfma_f32_16x16x32_bf16 v[26:29], v[142:145], v[208:211], v[26:29]
	v_mfma_f32_16x16x32_bf16 v[14:17], v[134:137], v[216:219], v[14:17]
	v_mfma_f32_16x16x32_bf16 v[10:13], v[142:145], v[216:219], v[10:13]
	s_setprio 0
	s_setprio 1
	v_mfma_f32_16x16x32_bf16 v[54:57], v[146:149], v[178:181], v[54:57]
	v_mfma_f32_16x16x32_bf16 v[50:53], v[170:173], v[178:181], v[50:53]
	v_mfma_f32_16x16x32_bf16 v[38:41], v[146:149], v[196:199], v[38:41]
	v_mfma_f32_16x16x32_bf16 v[34:37], v[170:173], v[196:199], v[34:37]
	v_mfma_f32_16x16x32_bf16 v[22:25], v[146:149], v[204:207], v[22:25]
	v_mfma_f32_16x16x32_bf16 v[18:21], v[170:173], v[204:207], v[18:21]
	v_mfma_f32_16x16x32_bf16 v[6:9], v[146:149], v[212:215], v[6:9]
	v_mfma_f32_16x16x32_bf16 v[2:5], v[170:173], v[212:215], v[2:5]
	v_mfma_f32_16x16x32_bf16 v[54:57], v[166:169], v[182:185], v[54:57]
	v_mfma_f32_16x16x32_bf16 v[50:53], v[174:177], v[182:185], v[50:53]
	v_mfma_f32_16x16x32_bf16 v[38:41], v[166:169], v[200:203], v[38:41]
	v_mfma_f32_16x16x32_bf16 v[34:37], v[174:177], v[200:203], v[34:37]
	v_mfma_f32_16x16x32_bf16 v[22:25], v[166:169], v[208:211], v[22:25]
	v_mfma_f32_16x16x32_bf16 v[18:21], v[174:177], v[208:211], v[18:21]
	v_mfma_f32_16x16x32_bf16 v[6:9], v[166:169], v[216:219], v[6:9]
	v_mfma_f32_16x16x32_bf16 v[2:5], v[174:177], v[216:219], v[2:5]
	s_setprio 0
	s_barrier
	s_add_i32 s94, s94, 2
	s_add_u32 s92, s92, 0x10000
	s_addc_u32 s93, s93, 0
	s_add_u32 s0, s0, 0x100
	s_addc_u32 s1, s1, 0
	s_cmp_gt_u32 s94, 5
	s_cbranch_scc0 .LBB0_1117
	s_and_b64 vcc, exec, s[18:19]
	s_cbranch_vccz .LBB0_1120
	s_barrier

; #define PG8_STAGE(bufoff, gbase, voff) do { _Pragma("unroll") for (int _i = 0; _i < 2; ++_i) \
;         __builtin_amdgcn_global_load_lds((const unsigned*)((const char*)(gbase) + (voff)[_i]), (PG8_LAS unsigned*)(lds + (bufoff) + ldsw + _i * 8192), 16, 0, 0); } while (0)
; #define PG8_LDA(dst, b, h) do { _Pragma("unroll") for (int m = 0; m < 4; ++m) _Pragma("unroll") for (int k = 0; k < 2; ++k) dst[m][k] = *(const PG8_LAS bf16x8*)(lds + PG8_SA(b, h) + aoff + m * 2048 + k * 1024); } while (0)
; #define PG8_LDB(dst, b, h) do { _Pragma("unroll") for (int n = 0; n < 2; ++n) _Pragma("unroll") for (int k = 0; k < 2; ++k) dst[n][k] = *(const PG8_LAS bf16x8*)(lds + PG8_SB(b, h) + boff + n * 2048 + k * 1024); } while (0)
; #define PG8_WAIT_V(n) asm volatile("s_waitcnt vmcnt(" #n ")" ::: "memory")
; #define PG8_WAIT_L(n) asm volatile("s_waitcnt lgkmcnt(" #n ")" ::: "memory")
; #define PG8_BAR __builtin_amdgcn_s_barrier()
; template <class Epi, class Sched, bool ALIGN_EPI = false, bool SP2 = false, bool ABLK = false, bool BBLK = false>
; __device__ __forceinline__ void gemm_phase(PG8_LAS unsigned char* lds, const Gemm g, const Sched& S, const Epi& E) {
;     ...
;     for (;;) {
;         const bool has_next = S.next(ui + 1, nxt);
;         const char* nA = has_next ? (const char*)g.A + (size_t)nxt.pm * tstepA : cA; const char* nB = has_next ? (const char*)g.Bt + (size_t)nxt.pn * tstepB : cB;
;         for (int t = 0; t < nt; t += 2) {
;             const bool last = (t == nt - 2);
;             const char* a1 = cA + (size_t)(t + 1) * kstepA;
;             const char* a2 = last ? nA : cA + (size_t)(t + 2) * kstepA; const char* b2 = last ? nB : cB + (size_t)(t + 2) * kstepB;
;             const char* a3 = a2 + kstepA; const char* b3 = b2 + kstepB;
;             if (last && has_next) S.a_ready(nxt);
;             if constexpr (SP2) {
;             PG8_LDB(B0, 0, 0); PG8_LDB(B1, 0, 1); PG8_SCHED; PG8_LDA(At, 0, 0); PG8_STAGE(PG8_SA(1, 1), a1 + hstepA, voffA);
;             PG8_WAIT_V(8); PG8_WAIT_L(0); PG8_BAR; PG8_MMA(0, 0, At, B0); PG8_MMA(0, 1, At, B1); PG8_BAR; PG8_SCHED;
;             PG8_LDA(At, 0, 1); PG8_STAGE(PG8_SB(0, 0), b2, voffB); PG8_STAGE(PG8_SB(0, 1), b2 + hstepB, voffB); PG8_STAGE(PG8_SA(0, 0), a2, voffA);
;             PG8_WAIT_V(8); PG8_WAIT_L(0); PG8_BAR; PG8_MMA(1, 0, At, B0); PG8_MMA(1, 1, At, B1); PG8_BAR; PG8_SCHED;
.LBB0_1139:
	s_ashr_i32 s23, s22, 31
	s_lshl_b64 s[24:25], s[22:23], 19
	s_add_u32 s24, s46, s24
	s_addc_u32 s25, s47, s25
	s_and_b64 s[26:27], s[6:7], exec
	s_cselect_b32 s23, s25, s35
	s_cselect_b32 s31, s24, s34
	s_ashr_i32 s21, s20, 31
	s_lshl_b64 s[26:27], s[20:21], 19
	s_add_u32 s26, s33, s26
	s_addc_u32 s27, s44, s27
	s_and_b64 s[36:37], s[6:7], exec
	s_cselect_b32 s21, s27, s1
	s_cselect_b32 s91, s26, s0
	s_add_u32 s92, s0, 0x10000
	s_addc_u32 s93, s1, 0
	s_add_u32 s0, s34, 0x40080
	v_mov_b32_e32 v2, 0
	s_addc_u32 s1, s35, 0
	s_mov_b32 s94, -2
	s_add_u32 s34, s0, 0xfffc0080
	s_addc_u32 s35, s1, -1
	s_add_i32 s52, 0, 0x10000
	s_cmp_eq_u32 s94, 12
	s_cselect_b32 s37, s23, s35
	s_cselect_b32 s36, s31, s34
	s_cselect_b32 s35, s21, s93
	s_cselect_b32 s34, s91, s92
	s_add_i32 s75, 0, 0x14000
	v_add_u32_e32 v142, s52, v223
	v_add_u32_e32 v158, s75, v223
	ds_read_b128 v[130:133], v142
	ds_read_b128 v[134:137], v142 offset:1024
	ds_read_b128 v[138:141], v142 offset:2048
	ds_read_b128 v[142:145], v142 offset:3072
	ds_read_b128 v[146:149], v158
	ds_read_b128 v[150:153], v158 offset:1024
	ds_read_b128 v[154:157], v158 offset:2048
	ds_read_b128 v[158:161], v158 offset:3072
	v_lshl_add_u64 v[188:189], s[0:1], 0, v[202:203]
	s_add_i32 m0, s29, 0xc000
	ds_read_b128 v[162:165], v225
	ds_read_b128 v[166:169], v225 offset:1024
	ds_read_b128 v[170:173], v225 offset:2048
	ds_read_b128 v[174:177], v225 offset:3072
	ds_read_b128 v[178:181], v225 offset:4096
	ds_read_b128 v[182:185], v225 offset:5120
	ds_read_b128 v[206:209], v225 offset:6144
	ds_read_b128 v[210:213], v225 offset:7168
	global_load_lds_dwordx4 v[188:189], off
	v_lshl_add_u64 v[188:189], s[0:1], 0, v[204:205]
	s_add_i32 m0, s29, 0xe000
	s_nop 0
	global_load_lds_dwordx4 v[188:189], off
	s_waitcnt vmcnt(8)
	s_waitcnt lgkmcnt(0)
	s_barrier
	s_setprio 1
	s_waitcnt lgkmcnt(0)
	v_mfma_f32_16x16x32_bf16 v[126:129], v[130:133], v[162:165], 0
	v_mfma_f32_16x16x32_bf16 v[122:125], v[138:141], v[162:165], 0
	v_mfma_f32_16x16x32_bf16 v[110:113], v[130:133], v[170:173], 0
	v_mfma_f32_16x16x32_bf16 v[106:109], v[138:141], v[170:173], 0
	v_mfma_f32_16x16x32_bf16 v[94:97], v[130:133], v[178:181], 0
	v_mfma_f32_16x16x32_bf16 v[90:93], v[138:141], v[178:181], 0
	v_mfma_f32_16x16x32_bf16 v[78:81], v[130:133], v[206:209], 0
	v_mfma_f32_16x16x32_bf16 v[74:77], v[138:141], v[206:209], 0
	v_mfma_f32_16x16x32_bf16 v[126:129], v[134:137], v[166:169], v[126:129]
	v_mfma_f32_16x16x32_bf16 v[122:125], v[142:145], v[166:169], v[122:125]
	v_mfma_f32_16x16x32_bf16 v[110:113], v[134:137], v[174:177], v[110:113]
	v_mfma_f32_16x16x32_bf16 v[106:109], v[142:145], v[174:177], v[106:109]
	v_mfma_f32_16x16x32_bf16 v[94:97], v[134:137], v[182:185], v[94:97]
	v_mfma_f32_16x16x32_bf16 v[90:93], v[142:145], v[182:185], v[90:93]
	v_mfma_f32_16x16x32_bf16 v[78:81], v[134:137], v[210:213], v[78:81]
	v_mfma_f32_16x16x32_bf16 v[74:77], v[142:145], v[210:213], v[74:77]
	s_setprio 0
	s_setprio 1
	v_mfma_f32_16x16x32_bf16 v[118:121], v[146:149], v[162:165], 0
	v_mfma_f32_16x16x32_bf16 v[114:117], v[154:157], v[162:165], 0
	v_mfma_f32_16x16x32_bf16 v[102:105], v[146:149], v[170:173], 0
	v_mfma_f32_16x16x32_bf16 v[98:101], v[154:157], v[170:173], 0
	v_mfma_f32_16x16x32_bf16 v[86:89], v[146:149], v[178:181], 0
	v_mfma_f32_16x16x32_bf16 v[82:85], v[154:157], v[178:181], 0
	v_mfma_f32_16x16x32_bf16 v[70:73], v[146:149], v[206:209], 0
	v_mfma_f32_16x16x32_bf16 v[66:69], v[154:157], v[206:209], 0
	v_mfma_f32_16x16x32_bf16 v[118:121], v[150:153], v[166:169], v[118:121]
	v_mfma_f32_16x16x32_bf16 v[114:117], v[158:161], v[166:169], v[114:117]
	v_mfma_f32_16x16x32_bf16 v[102:105], v[150:153], v[174:177], v[102:105]
	v_mfma_f32_16x16x32_bf16 v[98:101], v[158:161], v[174:177], v[98:101]
	v_mfma_f32_16x16x32_bf16 v[86:89], v[150:153], v[182:185], v[86:89]
	v_mfma_f32_16x16x32_bf16 v[82:85], v[158:161], v[182:185], v[82:85]
	v_mfma_f32_16x16x32_bf16 v[70:73], v[150:153], v[210:213], v[70:73]
	v_mfma_f32_16x16x32_bf16 v[66:69], v[158:161], v[210:213], v[66:69]
	s_setprio 0
	s_barrier
	s_add_i32 s52, s52, s45
	v_lshl_add_u64 v[188:189], s[34:35], 0, v[196:197]
	s_mov_b32 m0, s52
	ds_read_b128 v[162:165], v225 offset:16384
	ds_read_b128 v[166:169], v225 offset:17408
	ds_read_b128 v[170:173], v225 offset:18432
	ds_read_b128 v[174:177], v225 offset:19456
	ds_read_b128 v[178:181], v225 offset:20480
	ds_read_b128 v[182:185], v225 offset:21504
	ds_read_b128 v[206:209], v225 offset:22528
	ds_read_b128 v[210:213], v225 offset:23552
	global_load_lds_dwordx4 v[188:189], off
	s_add_i32 m0, s52, 0x2000
	s_add_u32 s96, s34, 0x4000
	v_lshl_add_u64 v[188:189], s[34:35], 0, v[200:201]
	s_addc_u32 s97, s35, 0
	s_add_i32 s52, s75, s45
	global_load_lds_dwordx4 v[188:189], off
	v_lshl_add_u64 v[188:189], s[96:97], 0, v[196:197]
	s_mov_b32 m0, s52
	v_lshl_add_u64 v[190:191], s[36:37], 0, v[198:199]
	global_load_lds_dwordx4 v[188:189], off
	v_lshl_add_u64 v[188:189], s[96:97], 0, v[200:201]
	s_add_i32 m0, s52, 0x2000
	s_nop 0
	global_load_lds_dwordx4 v[188:189], off
	v_lshl_add_u64 v[188:189], s[36:37], 0, v[186:187]
	s_mov_b32 m0, s29
	s_nop 0
	global_load_lds_dwordx4 v[188:189], off
	s_mov_b32 m0, s65
	s_nop 0
	global_load_lds_dwordx4 v[190:191], off
	s_waitcnt vmcnt(8)
	s_waitcnt lgkmcnt(0)
	s_barrier
; #define PG8_STAGE(bufoff, gbase, voff) do { _Pragma("unroll") for (int _i = 0; _i < 2; ++_i) \
;         __builtin_amdgcn_global_load_lds((const unsigned*)((const char*)(gbase) + (voff)[_i]), (PG8_LAS unsigned*)(lds + (bufoff) + ldsw + _i * 8192), 16, 0, 0); } while (0)
; #define PG8_LDA(dst, b, h) do { _Pragma("unroll") for (int m = 0; m < 4; ++m) _Pragma("unroll") for (int k = 0; k < 2; ++k) dst[m][k] = *(const PG8_LAS bf16x8*)(lds + PG8_SA(b, h) + aoff + m * 2048 + k * 1024); } while (0)
; #define PG8_LDB(dst, b, h) do { _Pragma("unroll") for (int n = 0; n < 2; ++n) _Pragma("unroll") for (int k = 0; k < 2; ++k) dst[n][k] = *(const PG8_LAS bf16x8*)(lds + PG8_SB(b, h) + boff + n * 2048 + k * 1024); } while (0)
; #define PG8_MMA(ai, bj, At, Bt) do { __builtin_amdgcn_s_setprio(1); _Pragma("unroll") for (int m = 0; m < 4; ++m) _Pragma("unroll") for (int n = 0; n < 2; ++n) _Pragma("unroll") for (int k = 0; k < 2; ++k) \
;         acc[ai][bj][m][n] = __builtin_amdgcn_mfma_f32_16x16x32_bf16(Bt[n][k], At[m][k], acc[ai][bj][m][n], 0, 0, 0); __builtin_amdgcn_s_setprio(0); } while (0)
; #define PG8_WAIT_V(n) asm volatile("s_waitcnt vmcnt(" #n ")" ::: "memory")
; template <class Epi, class Sched, bool ALIGN_EPI = false, bool SP2 = false, bool ABLK = false, bool BBLK = false>
; __device__ __forceinline__ void gemm_phase(PG8_LAS unsigned char* lds, const Gemm g, const Sched& S, const Epi& E) {
;     ...
;         for (int t = 0; t < nt; t += 2) {
;             const bool last = (t == nt - 2);
;             const char* a1 = cA + (size_t)(t + 1) * kstepA;
;             const char* a2 = last ? nA : cA + (size_t)(t + 2) * kstepA; const char* b2 = last ? nB : cB + (size_t)(t + 2) * kstepB;
;             const char* a3 = a2 + kstepA; const char* b3 = b2 + kstepB;
;             if (last && has_next) S.a_ready(nxt);
;             if constexpr (SP2) {
;             PG8_LDB(B0, 0, 0); PG8_LDB(B1, 0, 1); PG8_SCHED; PG8_LDA(At, 0, 0); PG8_STAGE(PG8_SA(1, 1), a1 + hstepA, voffA);
;             PG8_WAIT_V(8); PG8_WAIT_L(0); PG8_BAR; PG8_MMA(0, 0, At, B0); PG8_MMA(0, 1, At, B1); PG8_BAR; PG8_SCHED;
;             PG8_LDA(At, 0, 1); PG8_STAGE(PG8_SB(0, 0), b2, voffB); PG8_STAGE(PG8_SB(0, 1), b2 + hstepB, voffB); PG8_STAGE(PG8_SA(0, 0), a2, voffA);
;             PG8_WAIT_V(8); PG8_WAIT_L(0); PG8_BAR; PG8_MMA(1, 0, At, B0); PG8_MMA(1, 1, At, B1); PG8_BAR; PG8_SCHED;
	s_setprio 1
	s_waitcnt lgkmcnt(0)
	v_mfma_f32_16x16x32_bf16 v[62:65], v[130:133], v[162:165], 0
	v_mfma_f32_16x16x32_bf16 v[58:61], v[138:141], v[162:165], 0
	v_mfma_f32_16x16x32_bf16 v[46:49], v[130:133], v[170:173], 0
	v_mfma_f32_16x16x32_bf16 v[42:45], v[138:141], v[170:173], 0
	v_mfma_f32_16x16x32_bf16 v[30:33], v[130:133], v[178:181], 0
	v_mfma_f32_16x16x32_bf16 v[26:29], v[138:141], v[178:181], 0
	v_mfma_f32_16x16x32_bf16 v[14:17], v[130:133], v[206:209], 0
	v_mfma_f32_16x16x32_bf16 v[10:13], v[138:141], v[206:209], 0
	v_mfma_f32_16x16x32_bf16 v[62:65], v[134:137], v[166:169], v[62:65]
	v_mfma_f32_16x16x32_bf16 v[58:61], v[142:145], v[166:169], v[58:61]
	v_mfma_f32_16x16x32_bf16 v[46:49], v[134:137], v[174:177], v[46:49]
	v_mfma_f32_16x16x32_bf16 v[42:45], v[142:145], v[174:177], v[42:45]
	v_mfma_f32_16x16x32_bf16 v[30:33], v[134:137], v[182:185], v[30:33]
	v_mfma_f32_16x16x32_bf16 v[26:29], v[142:145], v[182:185], v[26:29]
	v_mfma_f32_16x16x32_bf16 v[14:17], v[134:137], v[210:213], v[14:17]
	v_mfma_f32_16x16x32_bf16 v[10:13], v[142:145], v[210:213], v[10:13]
	s_setprio 0
	s_setprio 1
	v_mfma_f32_16x16x32_bf16 v[54:57], v[146:149], v[162:165], 0
	v_mfma_f32_16x16x32_bf16 v[50:53], v[154:157], v[162:165], 0
	v_mfma_f32_16x16x32_bf16 v[38:41], v[146:149], v[170:173], 0
	v_mfma_f32_16x16x32_bf16 v[34:37], v[154:157], v[170:173], 0
	v_mfma_f32_16x16x32_bf16 v[22:25], v[146:149], v[178:181], 0
	v_mfma_f32_16x16x32_bf16 v[18:21], v[154:157], v[178:181], 0
	v_mfma_f32_16x16x32_bf16 v[6:9], v[146:149], v[206:209], 0
	v_mfma_f32_16x16x32_bf16 v[2:5], v[154:157], v[206:209], 0
	v_mfma_f32_16x16x32_bf16 v[54:57], v[150:153], v[166:169], v[54:57]
	v_mfma_f32_16x16x32_bf16 v[50:53], v[158:161], v[166:169], v[50:53]
	v_mfma_f32_16x16x32_bf16 v[38:41], v[150:153], v[174:177], v[38:41]
	v_mfma_f32_16x16x32_bf16 v[34:37], v[158:161], v[174:177], v[34:37]
	v_mfma_f32_16x16x32_bf16 v[22:25], v[150:153], v[182:185], v[22:25]
	v_mfma_f32_16x16x32_bf16 v[18:21], v[158:161], v[182:185], v[18:21]
	v_mfma_f32_16x16x32_bf16 v[6:9], v[150:153], v[210:213], v[6:9]
	v_mfma_f32_16x16x32_bf16 v[2:5], v[158:161], v[210:213], v[2:5]
	s_setprio 0
	s_barrier
	s_branch .Lmid_1140
.LBB0_1140:
	s_add_u32 s34, s0, 0xfffc0080
	s_addc_u32 s35, s1, -1
	s_add_i32 s52, 0, 0x10000
	s_cmp_eq_u32 s94, 12
	s_cselect_b32 s37, s23, s35
	s_cselect_b32 s36, s31, s34
	s_cselect_b32 s35, s21, s93
	s_cselect_b32 s34, s91, s92
	s_add_i32 s75, 0, 0x14000
	v_add_u32_e32 v142, s52, v223
	v_add_u32_e32 v158, s75, v223
	ds_read_b128 v[130:133], v142
	ds_read_b128 v[134:137], v142 offset:1024
	ds_read_b128 v[138:141], v142 offset:2048
	ds_read_b128 v[142:145], v142 offset:3072
	ds_read_b128 v[146:149], v158
	ds_read_b128 v[150:153], v158 offset:1024
	ds_read_b128 v[154:157], v158 offset:2048
	ds_read_b128 v[158:161], v158 offset:3072
	v_lshl_add_u64 v[188:189], s[0:1], 0, v[202:203]
	s_add_i32 m0, s29, 0xc000
	ds_read_b128 v[162:165], v225
	ds_read_b128 v[166:169], v225 offset:1024
	ds_read_b128 v[170:173], v225 offset:2048
	ds_read_b128 v[174:177], v225 offset:3072
	ds_read_b128 v[178:181], v225 offset:4096
	ds_read_b128 v[182:185], v225 offset:5120
	ds_read_b128 v[206:209], v225 offset:6144
	ds_read_b128 v[210:213], v225 offset:7168
	global_load_lds_dwordx4 v[188:189], off
	v_lshl_add_u64 v[188:189], s[0:1], 0, v[204:205]
	s_add_i32 m0, s29, 0xe000
	s_nop 0
	global_load_lds_dwordx4 v[188:189], off
	s_waitcnt vmcnt(8)
	s_waitcnt lgkmcnt(0)
	s_barrier
	s_setprio 1
	s_waitcnt lgkmcnt(0)
	v_mfma_f32_16x16x32_bf16 v[126:129], v[130:133], v[162:165], v[126:129]
	v_mfma_f32_16x16x32_bf16 v[122:125], v[138:141], v[162:165], v[122:125]
	v_mfma_f32_16x16x32_bf16 v[110:113], v[130:133], v[170:173], v[110:113]
	v_mfma_f32_16x16x32_bf16 v[106:109], v[138:141], v[170:173], v[106:109]
	v_mfma_f32_16x16x32_bf16 v[94:97], v[130:133], v[178:181], v[94:97]
	v_mfma_f32_16x16x32_bf16 v[90:93], v[138:141], v[178:181], v[90:93]
	v_mfma_f32_16x16x32_bf16 v[78:81], v[130:133], v[206:209], v[78:81]
	v_mfma_f32_16x16x32_bf16 v[74:77], v[138:141], v[206:209], v[74:77]
	v_mfma_f32_16x16x32_bf16 v[126:129], v[134:137], v[166:169], v[126:129]
	v_mfma_f32_16x16x32_bf16 v[122:125], v[142:145], v[166:169], v[122:125]
	v_mfma_f32_16x16x32_bf16 v[110:113], v[134:137], v[174:177], v[110:113]
	v_mfma_f32_16x16x32_bf16 v[106:109], v[142:145], v[174:177], v[106:109]
	v_mfma_f32_16x16x32_bf16 v[94:97], v[134:137], v[182:185], v[94:97]
	v_mfma_f32_16x16x32_bf16 v[90:93], v[142:145], v[182:185], v[90:93]
	v_mfma_f32_16x16x32_bf16 v[78:81], v[134:137], v[210:213], v[78:81]
	v_mfma_f32_16x16x32_bf16 v[74:77], v[142:145], v[210:213], v[74:77]
	s_setprio 0
	s_setprio 1
	v_mfma_f32_16x16x32_bf16 v[118:121], v[146:149], v[162:165], v[118:121]
	v_mfma_f32_16x16x32_bf16 v[114:117], v[154:157], v[162:165], v[114:117]
	v_mfma_f32_16x16x32_bf16 v[102:105], v[146:149], v[170:173], v[102:105]
	v_mfma_f32_16x16x32_bf16 v[98:101], v[154:157], v[170:173], v[98:101]
	v_mfma_f32_16x16x32_bf16 v[86:89], v[146:149], v[178:181], v[86:89]
	v_mfma_f32_16x16x32_bf16 v[82:85], v[154:157], v[178:181], v[82:85]
	v_mfma_f32_16x16x32_bf16 v[70:73], v[146:149], v[206:209], v[70:73]
	v_mfma_f32_16x16x32_bf16 v[66:69], v[154:157], v[206:209], v[66:69]
	v_mfma_f32_16x16x32_bf16 v[118:121], v[150:153], v[166:169], v[118:121]
	v_mfma_f32_16x16x32_bf16 v[114:117], v[158:161], v[166:169], v[114:117]
	v_mfma_f32_16x16x32_bf16 v[102:105], v[150:153], v[174:177], v[102:105]
	v_mfma_f32_16x16x32_bf16 v[98:101], v[158:161], v[174:177], v[98:101]
	v_mfma_f32_16x16x32_bf16 v[86:89], v[150:153], v[182:185], v[86:89]
	v_mfma_f32_16x16x32_bf16 v[82:85], v[158:161], v[182:185], v[82:85]
	v_mfma_f32_16x16x32_bf16 v[70:73], v[150:153], v[210:213], v[70:73]
	v_mfma_f32_16x16x32_bf16 v[66:69], v[158:161], v[210:213], v[66:69]
	s_setprio 0
	s_barrier
; #define PG8_STAGE(bufoff, gbase, voff) do { _Pragma("unroll") for (int _i = 0; _i < 2; ++_i) \
;         __builtin_amdgcn_global_load_lds((const unsigned*)((const char*)(gbase) + (voff)[_i]), (PG8_LAS unsigned*)(lds + (bufoff) + ldsw + _i * 8192), 16, 0, 0); } while (0)
; #define PG8_LDA(dst, b, h) do { _Pragma("unroll") for (int m = 0; m < 4; ++m) _Pragma("unroll") for (int k = 0; k < 2; ++k) dst[m][k] = *(const PG8_LAS bf16x8*)(lds + PG8_SA(b, h) + aoff + m * 2048 + k * 1024); } while (0)
; #define PG8_LDB(dst, b, h) do { _Pragma("unroll") for (int n = 0; n < 2; ++n) _Pragma("unroll") for (int k = 0; k < 2; ++k) dst[n][k] = *(const PG8_LAS bf16x8*)(lds + PG8_SB(b, h) + boff + n * 2048 + k * 1024); } while (0)
; #define PG8_MMA(ai, bj, At, Bt) do { __builtin_amdgcn_s_setprio(1); _Pragma("unroll") for (int m = 0; m < 4; ++m) _Pragma("unroll") for (int n = 0; n < 2; ++n) _Pragma("unroll") for (int k = 0; k < 2; ++k) \
;         acc[ai][bj][m][n] = __builtin_amdgcn_mfma_f32_16x16x32_bf16(Bt[n][k], At[m][k], acc[ai][bj][m][n], 0, 0, 0); __builtin_amdgcn_s_setprio(0); } while (0)
; #define PG8_WAIT_V(n) asm volatile("s_waitcnt vmcnt(" #n ")" ::: "memory")
; #define PG8_WAIT_L(n) asm volatile("s_waitcnt lgkmcnt(" #n ")" ::: "memory")
; #define PG8_BAR __builtin_amdgcn_s_barrier()
; #define PG8_SCHED __builtin_amdgcn_sched_barrier(0)
; template <class Epi, class Sched, bool ALIGN_EPI = false, bool SP2 = false, bool ABLK = false, bool BBLK = false>
; __device__ __forceinline__ void gemm_phase(PG8_LAS unsigned char* lds, const Gemm g, const Sched& S, const Epi& E) {
;     ...
;             PG8_LDA(At, 0, 1); PG8_STAGE(PG8_SB(0, 0), b2, voffB); PG8_STAGE(PG8_SB(0, 1), b2 + hstepB, voffB); PG8_STAGE(PG8_SA(0, 0), a2, voffA);
;             PG8_WAIT_V(8); PG8_WAIT_L(0); PG8_BAR; PG8_MMA(1, 0, At, B0); PG8_MMA(1, 1, At, B1); PG8_BAR; PG8_SCHED;
;             PG8_LDB(B0, 1, 0); PG8_LDB(B1, 1, 1); PG8_SCHED; PG8_LDA(At, 1, 0); PG8_STAGE(PG8_SA(0, 1), a2 + hstepA, voffA);
;             PG8_WAIT_V(8); PG8_WAIT_L(0); PG8_BAR; PG8_MMA(0, 0, At, B0); PG8_MMA(0, 1, At, B1); PG8_BAR; PG8_SCHED;
	s_add_i32 s52, s52, s45
	v_lshl_add_u64 v[188:189], s[34:35], 0, v[196:197]
	s_mov_b32 m0, s52
	ds_read_b128 v[162:165], v225 offset:16384
	ds_read_b128 v[166:169], v225 offset:17408
	ds_read_b128 v[170:173], v225 offset:18432
	ds_read_b128 v[174:177], v225 offset:19456
	ds_read_b128 v[178:181], v225 offset:20480
	ds_read_b128 v[182:185], v225 offset:21504
	ds_read_b128 v[206:209], v225 offset:22528
	ds_read_b128 v[210:213], v225 offset:23552
	global_load_lds_dwordx4 v[188:189], off
	s_add_i32 m0, s52, 0x2000
	s_add_u32 s96, s34, 0x4000
	v_lshl_add_u64 v[188:189], s[34:35], 0, v[200:201]
	s_addc_u32 s97, s35, 0
	s_add_i32 s52, s75, s45
	global_load_lds_dwordx4 v[188:189], off
	v_lshl_add_u64 v[188:189], s[96:97], 0, v[196:197]
	s_mov_b32 m0, s52
	v_lshl_add_u64 v[190:191], s[36:37], 0, v[198:199]
	global_load_lds_dwordx4 v[188:189], off
	v_lshl_add_u64 v[188:189], s[96:97], 0, v[200:201]
	s_add_i32 m0, s52, 0x2000
	s_nop 0
	global_load_lds_dwordx4 v[188:189], off
	v_lshl_add_u64 v[188:189], s[36:37], 0, v[186:187]
	s_mov_b32 m0, s29
	s_nop 0
	global_load_lds_dwordx4 v[188:189], off
	s_mov_b32 m0, s65
	s_nop 0
	global_load_lds_dwordx4 v[190:191], off
	s_waitcnt vmcnt(8)
	s_waitcnt lgkmcnt(0)
	s_barrier
	s_setprio 1
	s_waitcnt lgkmcnt(0)
	v_mfma_f32_16x16x32_bf16 v[62:65], v[130:133], v[162:165], v[62:65]
	v_mfma_f32_16x16x32_bf16 v[58:61], v[138:141], v[162:165], v[58:61]
	v_mfma_f32_16x16x32_bf16 v[46:49], v[130:133], v[170:173], v[46:49]
	v_mfma_f32_16x16x32_bf16 v[42:45], v[138:141], v[170:173], v[42:45]
	v_mfma_f32_16x16x32_bf16 v[30:33], v[130:133], v[178:181], v[30:33]
	v_mfma_f32_16x16x32_bf16 v[26:29], v[138:141], v[178:181], v[26:29]
	v_mfma_f32_16x16x32_bf16 v[14:17], v[130:133], v[206:209], v[14:17]
	v_mfma_f32_16x16x32_bf16 v[10:13], v[138:141], v[206:209], v[10:13]
	v_mfma_f32_16x16x32_bf16 v[62:65], v[134:137], v[166:169], v[62:65]
	v_mfma_f32_16x16x32_bf16 v[58:61], v[142:145], v[166:169], v[58:61]
	v_mfma_f32_16x16x32_bf16 v[46:49], v[134:137], v[174:177], v[46:49]
	v_mfma_f32_16x16x32_bf16 v[42:45], v[142:145], v[174:177], v[42:45]
	v_mfma_f32_16x16x32_bf16 v[30:33], v[134:137], v[182:185], v[30:33]
	v_mfma_f32_16x16x32_bf16 v[26:29], v[142:145], v[182:185], v[26:29]
	v_mfma_f32_16x16x32_bf16 v[14:17], v[134:137], v[210:213], v[14:17]
	v_mfma_f32_16x16x32_bf16 v[10:13], v[142:145], v[210:213], v[10:13]
	s_setprio 0
	s_setprio 1
	v_mfma_f32_16x16x32_bf16 v[54:57], v[146:149], v[162:165], v[54:57]
	v_mfma_f32_16x16x32_bf16 v[50:53], v[154:157], v[162:165], v[50:53]
	v_mfma_f32_16x16x32_bf16 v[38:41], v[146:149], v[170:173], v[38:41]
	v_mfma_f32_16x16x32_bf16 v[34:37], v[154:157], v[170:173], v[34:37]
	v_mfma_f32_16x16x32_bf16 v[22:25], v[146:149], v[178:181], v[22:25]
	v_mfma_f32_16x16x32_bf16 v[18:21], v[154:157], v[178:181], v[18:21]
	v_mfma_f32_16x16x32_bf16 v[6:9], v[146:149], v[206:209], v[6:9]
	v_mfma_f32_16x16x32_bf16 v[2:5], v[154:157], v[206:209], v[2:5]
	v_mfma_f32_16x16x32_bf16 v[54:57], v[150:153], v[166:169], v[54:57]
	v_mfma_f32_16x16x32_bf16 v[50:53], v[158:161], v[166:169], v[50:53]
	v_mfma_f32_16x16x32_bf16 v[38:41], v[150:153], v[174:177], v[38:41]
	v_mfma_f32_16x16x32_bf16 v[34:37], v[158:161], v[174:177], v[34:37]
	v_mfma_f32_16x16x32_bf16 v[22:25], v[150:153], v[182:185], v[22:25]
	v_mfma_f32_16x16x32_bf16 v[18:21], v[158:161], v[182:185], v[18:21]
	v_mfma_f32_16x16x32_bf16 v[6:9], v[150:153], v[210:213], v[6:9]
	v_mfma_f32_16x16x32_bf16 v[2:5], v[158:161], v[210:213], v[2:5]
	s_setprio 0
	s_barrier
.Lmid_1140:
	s_add_i32 s52, 0, 0x18000
	s_add_i32 s75, 0, 0x1c000
	v_add_u32_e32 v142, s52, v223
	v_add_u32_e32 v158, s75, v223
	ds_read_b128 v[130:133], v142
	ds_read_b128 v[134:137], v142 offset:1024
	ds_read_b128 v[138:141], v142 offset:2048
	ds_read_b128 v[142:145], v142 offset:3072
	ds_read_b128 v[146:149], v158
	ds_read_b128 v[150:153], v158 offset:1024
	ds_read_b128 v[154:157], v158 offset:2048
	ds_read_b128 v[158:161], v158 offset:3072
	s_add_u32 s36, s36, 0x40000
	s_addc_u32 s37, s37, 0
	s_mov_b32 m0, s68
	v_lshl_add_u64 v[192:193], s[36:37], 0, v[186:187]
	ds_read_b128 v[162:165], v225 offset:32768
	ds_read_b128 v[166:169], v225 offset:33792
	ds_read_b128 v[170:173], v225 offset:34816
	ds_read_b128 v[174:177], v225 offset:35840
	ds_read_b128 v[178:181], v225 offset:36864
	ds_read_b128 v[182:185], v225 offset:37888
	ds_read_b128 v[206:209], v225 offset:38912
	ds_read_b128 v[210:213], v225 offset:39936
	global_load_lds_dwordx4 v[192:193], off
	v_lshl_add_u64 v[192:193], s[36:37], 0, v[198:199]
	s_mov_b32 m0, s72
	s_nop 0
	global_load_lds_dwordx4 v[192:193], off
	s_waitcnt vmcnt(8)
	s_waitcnt lgkmcnt(0)
	s_barrier
; #define PG8_STAGE(bufoff, gbase, voff) do { _Pragma("unroll") for (int _i = 0; _i < 2; ++_i) \
;         __builtin_amdgcn_global_load_lds((const unsigned*)((const char*)(gbase) + (voff)[_i]), (PG8_LAS unsigned*)(lds + (bufoff) + ldsw + _i * 8192), 16, 0, 0); } while (0)
; template <class Epi, class Sched, bool ALIGN_EPI = false, bool SP2 = false, bool ABLK = false, bool BBLK = false>
; __device__ __forceinline__ void gemm_phase(PG8_LAS unsigned char* lds, const Gemm g, const Sched& S, const Epi& E) {
;     ...
;             PG8_LDB(B0, 1, 0); PG8_LDB(B1, 1, 1); PG8_SCHED; PG8_LDA(At, 1, 0); PG8_STAGE(PG8_SA(0, 1), a2 + hstepA, voffA);
;             PG8_WAIT_V(8); PG8_WAIT_L(0); PG8_BAR; PG8_MMA(0, 0, At, B0); PG8_MMA(0, 1, At, B1); PG8_BAR; PG8_SCHED;
;             PG8_LDA(At, 1, 1); PG8_STAGE(PG8_SB(1, 0), b3, voffB); PG8_STAGE(PG8_SB(1, 1), b3 + hstepB, voffB); PG8_STAGE(PG8_SA(1, 0), a3, voffA);
;             PG8_WAIT_V(8); PG8_WAIT_L(0); PG8_BAR; PG8_MMA(1, 0, At, B0); PG8_MMA(1, 1, At, B1); PG8_BAR; PG8_SCHED;
;             } else {
;             PG8_LDB(B0, 0, 0); PG8_SCHED; PG8_LDA(At, 0, 0); PG8_STAGE(PG8_SA(1, 1), a1 + hstepA, voffA);
;             PG8_WAIT_L(8); PG8_BAR; PG8_WAIT_L(0); PG8_MMA(0, 0, At, B0); PG8_BAR; PG8_SCHED;
;             PG8_LDB(B1, 0, 1); PG8_STAGE(PG8_SB(0, 0), b2, voffB);
;             PG8_BAR; PG8_WAIT_L(0); PG8_MMA(0, 1, At, B1); PG8_BAR;
;             PG8_LDA(At, 0, 1); PG8_STAGE(PG8_SA(0, 0), a2, voffA);
;             PG8_BAR; PG8_WAIT_L(0); PG8_MMA(1, 0, At, B0); PG8_BAR; PG8_SCHED;
;             PG8_STAGE(PG8_SB(0, 1), b2 + hstepB, voffB);
;             PG8_WAIT_V(6); PG8_BAR; PG8_MMA(1, 1, At, B1); PG8_BAR;
;             PG8_LDB(B0, 1, 0); PG8_SCHED; PG8_LDA(At, 1, 0); PG8_STAGE(PG8_SA(0, 1), a2 + hstepA, voffA);
;             PG8_WAIT_L(8); PG8_BAR; PG8_WAIT_L(0); PG8_MMA(0, 0, At, B0); PG8_BAR; PG8_SCHED;
;             PG8_LDB(B1, 1, 1); PG8_STAGE(PG8_SB(1, 0), b3, voffB);
;             PG8_BAR; PG8_WAIT_L(0); PG8_MMA(0, 1, At, B1); PG8_BAR;
;             PG8_LDA(At, 1, 1); PG8_STAGE(PG8_SA(1, 0), a3, voffA);
;             PG8_BAR; PG8_WAIT_L(0); PG8_MMA(1, 0, At, B0); PG8_BAR; PG8_SCHED;
;             PG8_STAGE(PG8_SB(1, 1), b3 + hstepB, voffB);
;             PG8_WAIT_V(6); PG8_BAR; PG8_MMA(1, 1, At, B1); PG8_BAR;
;             }
;         }
;         if constexpr (ALIGN_EPI) { if (wr == 0) PG8_BAR; }
	s_setprio 1
	s_waitcnt lgkmcnt(0)
	v_mfma_f32_16x16x32_bf16 v[126:129], v[130:133], v[162:165], v[126:129]
	v_mfma_f32_16x16x32_bf16 v[122:125], v[138:141], v[162:165], v[122:125]
	v_mfma_f32_16x16x32_bf16 v[110:113], v[130:133], v[170:173], v[110:113]
	v_mfma_f32_16x16x32_bf16 v[106:109], v[138:141], v[170:173], v[106:109]
	v_mfma_f32_16x16x32_bf16 v[94:97], v[130:133], v[178:181], v[94:97]
	v_mfma_f32_16x16x32_bf16 v[90:93], v[138:141], v[178:181], v[90:93]
	v_mfma_f32_16x16x32_bf16 v[78:81], v[130:133], v[206:209], v[78:81]
	v_mfma_f32_16x16x32_bf16 v[74:77], v[138:141], v[206:209], v[74:77]
	v_mfma_f32_16x16x32_bf16 v[126:129], v[134:137], v[166:169], v[126:129]
	v_mfma_f32_16x16x32_bf16 v[122:125], v[142:145], v[166:169], v[122:125]
	v_mfma_f32_16x16x32_bf16 v[110:113], v[134:137], v[174:177], v[110:113]
	v_mfma_f32_16x16x32_bf16 v[106:109], v[142:145], v[174:177], v[106:109]
	v_mfma_f32_16x16x32_bf16 v[94:97], v[134:137], v[182:185], v[94:97]
	v_mfma_f32_16x16x32_bf16 v[90:93], v[142:145], v[182:185], v[90:93]
	v_mfma_f32_16x16x32_bf16 v[78:81], v[134:137], v[210:213], v[78:81]
	v_mfma_f32_16x16x32_bf16 v[74:77], v[142:145], v[210:213], v[74:77]
	s_setprio 0
	s_setprio 1
	v_mfma_f32_16x16x32_bf16 v[118:121], v[146:149], v[162:165], v[118:121]
	v_mfma_f32_16x16x32_bf16 v[114:117], v[154:157], v[162:165], v[114:117]
	v_mfma_f32_16x16x32_bf16 v[102:105], v[146:149], v[170:173], v[102:105]
	v_mfma_f32_16x16x32_bf16 v[98:101], v[154:157], v[170:173], v[98:101]
	v_mfma_f32_16x16x32_bf16 v[86:89], v[146:149], v[178:181], v[86:89]
	v_mfma_f32_16x16x32_bf16 v[82:85], v[154:157], v[178:181], v[82:85]
	v_mfma_f32_16x16x32_bf16 v[70:73], v[146:149], v[206:209], v[70:73]
	v_mfma_f32_16x16x32_bf16 v[66:69], v[154:157], v[206:209], v[66:69]
	v_mfma_f32_16x16x32_bf16 v[118:121], v[150:153], v[166:169], v[118:121]
	v_mfma_f32_16x16x32_bf16 v[114:117], v[158:161], v[166:169], v[114:117]
	v_mfma_f32_16x16x32_bf16 v[102:105], v[150:153], v[174:177], v[102:105]
	v_mfma_f32_16x16x32_bf16 v[98:101], v[158:161], v[174:177], v[98:101]
	v_mfma_f32_16x16x32_bf16 v[86:89], v[150:153], v[182:185], v[86:89]
	v_mfma_f32_16x16x32_bf16 v[82:85], v[158:161], v[182:185], v[82:85]
	v_mfma_f32_16x16x32_bf16 v[70:73], v[150:153], v[210:213], v[70:73]
	v_mfma_f32_16x16x32_bf16 v[66:69], v[158:161], v[210:213], v[66:69]
	s_setprio 0
	s_barrier
	s_add_u32 s36, s34, 0x8000
	s_addc_u32 s37, s35, 0
	s_add_i32 s52, s52, s45
	v_lshl_add_u64 v[192:193], s[36:37], 0, v[196:197]
	s_mov_b32 m0, s52
	ds_read_b128 v[162:165], v225 offset:49152
	ds_read_b128 v[166:169], v225 offset:50176
	ds_read_b128 v[170:173], v225 offset:51200
	ds_read_b128 v[174:177], v225 offset:52224
	ds_read_b128 v[178:181], v225 offset:53248
	ds_read_b128 v[182:185], v225 offset:54272
	ds_read_b128 v[206:209], v225 offset:55296
	ds_read_b128 v[210:213], v225 offset:56320
	global_load_lds_dwordx4 v[192:193], off
	s_add_i32 m0, s52, 0x2000
	s_add_u32 s34, s34, 0xc000
	v_lshl_add_u64 v[192:193], s[36:37], 0, v[200:201]
	s_addc_u32 s35, s35, 0
	s_add_i32 s36, s75, s45
	global_load_lds_dwordx4 v[192:193], off
	v_lshl_add_u64 v[192:193], s[34:35], 0, v[196:197]
	s_mov_b32 m0, s36
	v_lshl_add_u64 v[188:189], v[188:189], 0, s[62:63]
	global_load_lds_dwordx4 v[192:193], off
	v_lshl_add_u64 v[192:193], s[34:35], 0, v[200:201]
	s_add_i32 m0, s36, 0x2000
	s_nop 0
	global_load_lds_dwordx4 v[192:193], off
	s_mov_b32 m0, s86
	s_nop 0
	global_load_lds_dwordx4 v[188:189], off
	v_lshl_add_u64 v[188:189], v[190:191], 0, s[62:63]
	s_mov_b32 m0, s88
	s_nop 0
	global_load_lds_dwordx4 v[188:189], off
	s_waitcnt vmcnt(8)
	s_waitcnt lgkmcnt(0)
	s_barrier
	s_setprio 1
	s_waitcnt lgkmcnt(0)
	v_mfma_f32_16x16x32_bf16 v[62:65], v[130:133], v[162:165], v[62:65]
	v_mfma_f32_16x16x32_bf16 v[58:61], v[138:141], v[162:165], v[58:61]
	v_mfma_f32_16x16x32_bf16 v[46:49], v[130:133], v[170:173], v[46:49]
	v_mfma_f32_16x16x32_bf16 v[42:45], v[138:141], v[170:173], v[42:45]
	v_mfma_f32_16x16x32_bf16 v[30:33], v[130:133], v[178:181], v[30:33]
	v_mfma_f32_16x16x32_bf16 v[26:29], v[138:141], v[178:181], v[26:29]
	v_mfma_f32_16x16x32_bf16 v[14:17], v[130:133], v[206:209], v[14:17]
	v_mfma_f32_16x16x32_bf16 v[10:13], v[138:141], v[206:209], v[10:13]
	v_mfma_f32_16x16x32_bf16 v[62:65], v[134:137], v[166:169], v[62:65]
	v_mfma_f32_16x16x32_bf16 v[58:61], v[142:145], v[166:169], v[58:61]
	v_mfma_f32_16x16x32_bf16 v[46:49], v[134:137], v[174:177], v[46:49]
	v_mfma_f32_16x16x32_bf16 v[42:45], v[142:145], v[174:177], v[42:45]
	v_mfma_f32_16x16x32_bf16 v[30:33], v[134:137], v[182:185], v[30:33]
	v_mfma_f32_16x16x32_bf16 v[26:29], v[142:145], v[182:185], v[26:29]
	v_mfma_f32_16x16x32_bf16 v[14:17], v[134:137], v[210:213], v[14:17]
	v_mfma_f32_16x16x32_bf16 v[10:13], v[142:145], v[210:213], v[10:13]
	s_setprio 0
	s_setprio 1
	v_mfma_f32_16x16x32_bf16 v[54:57], v[146:149], v[162:165], v[54:57]
	v_mfma_f32_16x16x32_bf16 v[50:53], v[154:157], v[162:165], v[50:53]
	v_mfma_f32_16x16x32_bf16 v[38:41], v[146:149], v[170:173], v[38:41]
	v_mfma_f32_16x16x32_bf16 v[34:37], v[154:157], v[170:173], v[34:37]
	v_mfma_f32_16x16x32_bf16 v[22:25], v[146:149], v[178:181], v[22:25]
	v_mfma_f32_16x16x32_bf16 v[18:21], v[154:157], v[178:181], v[18:21]
	v_mfma_f32_16x16x32_bf16 v[6:9], v[146:149], v[206:209], v[6:9]
	v_mfma_f32_16x16x32_bf16 v[2:5], v[154:157], v[206:209], v[2:5]
	v_mfma_f32_16x16x32_bf16 v[54:57], v[150:153], v[166:169], v[54:57]
	v_mfma_f32_16x16x32_bf16 v[50:53], v[158:161], v[166:169], v[50:53]
	v_mfma_f32_16x16x32_bf16 v[38:41], v[150:153], v[174:177], v[38:41]
	v_mfma_f32_16x16x32_bf16 v[34:37], v[158:161], v[174:177], v[34:37]
	v_mfma_f32_16x16x32_bf16 v[22:25], v[150:153], v[182:185], v[22:25]
	v_mfma_f32_16x16x32_bf16 v[18:21], v[158:161], v[182:185], v[18:21]
	v_mfma_f32_16x16x32_bf16 v[6:9], v[150:153], v[210:213], v[6:9]
	v_mfma_f32_16x16x32_bf16 v[2:5], v[158:161], v[210:213], v[2:5]
	s_setprio 0
	s_barrier
	s_add_i32 s94, s94, 2
	s_add_u32 s92, s92, 0x10000
	s_addc_u32 s93, s93, 0
	s_add_u32 s0, s0, 0x100
	s_addc_u32 s1, s1, 0
	s_cmp_gt_u32 s94, 13
	s_cbranch_scc0 .LBB0_1140
	s_and_b64 vcc, exec, s[14:15]
	s_cbranch_vccz .LBB0_1143
	s_barrier

; #define PG8_STAGE(bufoff, gbase, voff) do { _Pragma("unroll") for (int _i = 0; _i < 2; ++_i) \
;         __builtin_amdgcn_global_load_lds((const unsigned*)((const char*)(gbase) + (voff)[_i]), (PG8_LAS unsigned*)(lds + (bufoff) + ldsw + _i * 8192), 16, 0, 0); } while (0)
; #define PG8_LDA(dst, b, h) do { _Pragma("unroll") for (int m = 0; m < 4; ++m) _Pragma("unroll") for (int k = 0; k < 2; ++k) dst[m][k] = *(const PG8_LAS bf16x8*)(lds + PG8_SA(b, h) + aoff + m * 2048 + k * 1024); } while (0)
; #define PG8_LDB(dst, b, h) do { _Pragma("unroll") for (int n = 0; n < 2; ++n) _Pragma("unroll") for (int k = 0; k < 2; ++k) dst[n][k] = *(const PG8_LAS bf16x8*)(lds + PG8_SB(b, h) + boff + n * 2048 + k * 1024); } while (0)
; #define PG8_WAIT_V(n) asm volatile("s_waitcnt vmcnt(" #n ")" ::: "memory")
; #define PG8_WAIT_L(n) asm volatile("s_waitcnt lgkmcnt(" #n ")" ::: "memory")
; #define PG8_BAR __builtin_amdgcn_s_barrier()
; #define PG8_SCHED __builtin_amdgcn_sched_barrier(0)
; template <class Epi, class Sched, bool ALIGN_EPI = false, bool SP2 = false, bool ABLK = false, bool BBLK = false>
; __device__ __forceinline__ void gemm_phase(PG8_LAS unsigned char* lds, const Gemm g, const Sched& S, const Epi& E) {
;     ...
;         const bool has_next = S.next(ui + 1, nxt);
;         const char* nA = has_next ? (const char*)g.A + (size_t)nxt.pm * tstepA : cA; const char* nB = has_next ? (const char*)g.Bt + (size_t)nxt.pn * tstepB : cB;
;         for (int t = 0; t < nt; t += 2) {
;             const bool last = (t == nt - 2);
;             const char* a1 = cA + (size_t)(t + 1) * kstepA;
;             const char* a2 = last ? nA : cA + (size_t)(t + 2) * kstepA; const char* b2 = last ? nB : cB + (size_t)(t + 2) * kstepB;
;             const char* a3 = a2 + kstepA; const char* b3 = b2 + kstepB;
;             if (last && has_next) S.a_ready(nxt);
;             if constexpr (SP2) {
;             PG8_LDB(B0, 0, 0); PG8_LDB(B1, 0, 1); PG8_SCHED; PG8_LDA(At, 0, 0); PG8_STAGE(PG8_SA(1, 1), a1 + hstepA, voffA);
;             PG8_WAIT_V(8); PG8_WAIT_L(0); PG8_BAR; PG8_MMA(0, 0, At, B0); PG8_MMA(0, 1, At, B1); PG8_BAR; PG8_SCHED;
;             PG8_LDA(At, 0, 1); PG8_STAGE(PG8_SB(0, 0), b2, voffB); PG8_STAGE(PG8_SB(0, 1), b2 + hstepB, voffB); PG8_STAGE(PG8_SA(0, 0), a2, voffA);
;             PG8_WAIT_V(8); PG8_WAIT_L(0); PG8_BAR; PG8_MMA(1, 0, At, B0); PG8_MMA(1, 1, At, B1); PG8_BAR; PG8_SCHED;
.LBB0_1162:
	s_ashr_i32 s21, s20, 31
	s_lshl_b64 s[22:23], s[20:21], 18
	s_add_u32 s22, s33, s22
	s_addc_u32 s23, s36, s23
	s_and_b64 s[24:25], s[6:7], exec
	s_cselect_b32 s21, s23, s31
	s_cselect_b32 s29, s22, s30
	s_ashr_i32 s19, s18, 31
	s_lshl_b64 s[24:25], s[18:19], 18
	s_add_u32 s24, s37, s24
	s_addc_u32 s25, s44, s25
	s_and_b64 s[34:35], s[6:7], exec
	s_cselect_b32 s19, s25, s1
	s_cselect_b32 s61, s24, s0
	s_add_u32 s83, s0, 0x10000
	s_addc_u32 s84, s1, 0
	s_add_u32 s0, s30, 0x20080
	v_mov_b32_e32 v2, 0
	s_addc_u32 s1, s31, 0
	s_mov_b32 s86, -2
	s_add_u32 s30, s0, 0xfffe0080
	s_addc_u32 s31, s1, -1
	s_add_i32 s52, 0, 0x10000
	s_cmp_eq_u32 s86, 4
	s_cselect_b32 s35, s21, s31
	s_cselect_b32 s34, s29, s30
	s_cselect_b32 s31, s19, s84
	s_cselect_b32 s30, s61, s83
	s_add_i32 s75, 0, 0x14000
	v_add_u32_e32 v142, s52, v223
	v_add_u32_e32 v158, s75, v223
	ds_read_b128 v[130:133], v142
	ds_read_b128 v[134:137], v142 offset:1024
	ds_read_b128 v[138:141], v142 offset:2048
	ds_read_b128 v[142:145], v142 offset:3072
	ds_read_b128 v[146:149], v158
	ds_read_b128 v[150:153], v158 offset:1024
	ds_read_b128 v[154:157], v158 offset:2048
	ds_read_b128 v[158:161], v158 offset:3072
	v_lshl_add_u64 v[188:189], s[0:1], 0, v[202:203]
	s_add_i32 m0, s27, 0xc000
	ds_read_b128 v[162:165], v225
	ds_read_b128 v[166:169], v225 offset:1024
	ds_read_b128 v[170:173], v225 offset:2048
	ds_read_b128 v[174:177], v225 offset:3072
	ds_read_b128 v[178:181], v225 offset:4096
	ds_read_b128 v[182:185], v225 offset:5120
	ds_read_b128 v[206:209], v225 offset:6144
	ds_read_b128 v[210:213], v225 offset:7168
	global_load_lds_dwordx4 v[188:189], off
	v_lshl_add_u64 v[188:189], s[0:1], 0, v[204:205]
	s_add_i32 m0, s27, 0xe000
	s_nop 0
	global_load_lds_dwordx4 v[188:189], off
	s_waitcnt vmcnt(8)
	s_waitcnt lgkmcnt(0)
	s_barrier
	s_setprio 1
	s_waitcnt lgkmcnt(0)
	v_mfma_f32_16x16x32_bf16 v[126:129], v[130:133], v[162:165], 0
	v_mfma_f32_16x16x32_bf16 v[122:125], v[138:141], v[162:165], 0
	v_mfma_f32_16x16x32_bf16 v[110:113], v[130:133], v[170:173], 0
	v_mfma_f32_16x16x32_bf16 v[106:109], v[138:141], v[170:173], 0
	v_mfma_f32_16x16x32_bf16 v[94:97], v[130:133], v[178:181], 0
	v_mfma_f32_16x16x32_bf16 v[90:93], v[138:141], v[178:181], 0
	v_mfma_f32_16x16x32_bf16 v[78:81], v[130:133], v[206:209], 0
	v_mfma_f32_16x16x32_bf16 v[74:77], v[138:141], v[206:209], 0
	v_mfma_f32_16x16x32_bf16 v[126:129], v[134:137], v[166:169], v[126:129]
	v_mfma_f32_16x16x32_bf16 v[122:125], v[142:145], v[166:169], v[122:125]
	v_mfma_f32_16x16x32_bf16 v[110:113], v[134:137], v[174:177], v[110:113]
	v_mfma_f32_16x16x32_bf16 v[106:109], v[142:145], v[174:177], v[106:109]
	v_mfma_f32_16x16x32_bf16 v[94:97], v[134:137], v[182:185], v[94:97]
	v_mfma_f32_16x16x32_bf16 v[90:93], v[142:145], v[182:185], v[90:93]
	v_mfma_f32_16x16x32_bf16 v[78:81], v[134:137], v[210:213], v[78:81]
	v_mfma_f32_16x16x32_bf16 v[74:77], v[142:145], v[210:213], v[74:77]
	s_setprio 0
	s_setprio 1
	v_mfma_f32_16x16x32_bf16 v[118:121], v[146:149], v[162:165], 0
	v_mfma_f32_16x16x32_bf16 v[114:117], v[154:157], v[162:165], 0
	v_mfma_f32_16x16x32_bf16 v[102:105], v[146:149], v[170:173], 0
	v_mfma_f32_16x16x32_bf16 v[98:101], v[154:157], v[170:173], 0
	v_mfma_f32_16x16x32_bf16 v[86:89], v[146:149], v[178:181], 0
	v_mfma_f32_16x16x32_bf16 v[82:85], v[154:157], v[178:181], 0
	v_mfma_f32_16x16x32_bf16 v[70:73], v[146:149], v[206:209], 0
	v_mfma_f32_16x16x32_bf16 v[66:69], v[154:157], v[206:209], 0
	v_mfma_f32_16x16x32_bf16 v[118:121], v[150:153], v[166:169], v[118:121]
	v_mfma_f32_16x16x32_bf16 v[114:117], v[158:161], v[166:169], v[114:117]
	v_mfma_f32_16x16x32_bf16 v[102:105], v[150:153], v[174:177], v[102:105]
	v_mfma_f32_16x16x32_bf16 v[98:101], v[158:161], v[174:177], v[98:101]
	v_mfma_f32_16x16x32_bf16 v[86:89], v[150:153], v[182:185], v[86:89]
	v_mfma_f32_16x16x32_bf16 v[82:85], v[158:161], v[182:185], v[82:85]
	v_mfma_f32_16x16x32_bf16 v[70:73], v[150:153], v[210:213], v[70:73]
	v_mfma_f32_16x16x32_bf16 v[66:69], v[158:161], v[210:213], v[66:69]
	s_setprio 0
	s_barrier
	s_add_i32 s52, s52, s45
	v_lshl_add_u64 v[188:189], s[30:31], 0, v[196:197]
	s_mov_b32 m0, s52
	ds_read_b128 v[162:165], v225 offset:16384
	ds_read_b128 v[166:169], v225 offset:17408
	ds_read_b128 v[170:173], v225 offset:18432
	ds_read_b128 v[174:177], v225 offset:19456
	ds_read_b128 v[178:181], v225 offset:20480
	ds_read_b128 v[182:185], v225 offset:21504
	ds_read_b128 v[206:209], v225 offset:22528
	ds_read_b128 v[210:213], v225 offset:23552
	global_load_lds_dwordx4 v[188:189], off
	s_add_i32 m0, s52, 0x2000
	s_add_u32 s88, s30, 0x4000
	v_lshl_add_u64 v[188:189], s[30:31], 0, v[200:201]
	s_addc_u32 s89, s31, 0
	s_add_i32 s52, s75, s45
	global_load_lds_dwordx4 v[188:189], off
	v_lshl_add_u64 v[188:189], s[88:89], 0, v[196:197]
	s_mov_b32 m0, s52
	v_lshl_add_u64 v[190:191], s[34:35], 0, v[198:199]
	global_load_lds_dwordx4 v[188:189], off
	v_lshl_add_u64 v[188:189], s[88:89], 0, v[200:201]
	s_add_i32 m0, s52, 0x2000
	s_nop 0
	global_load_lds_dwordx4 v[188:189], off
	v_lshl_add_u64 v[188:189], s[34:35], 0, v[186:187]
	s_mov_b32 m0, s27
	s_nop 0
	global_load_lds_dwordx4 v[188:189], off
	s_mov_b32 m0, s46
	s_nop 0
	global_load_lds_dwordx4 v[190:191], off
	s_waitcnt vmcnt(8)
	s_waitcnt lgkmcnt(0)
	s_barrier
; #define PG8_STAGE(bufoff, gbase, voff) do { _Pragma("unroll") for (int _i = 0; _i < 2; ++_i) \
;         __builtin_amdgcn_global_load_lds((const unsigned*)((const char*)(gbase) + (voff)[_i]), (PG8_LAS unsigned*)(lds + (bufoff) + ldsw + _i * 8192), 16, 0, 0); } while (0)
; #define PG8_LDA(dst, b, h) do { _Pragma("unroll") for (int m = 0; m < 4; ++m) _Pragma("unroll") for (int k = 0; k < 2; ++k) dst[m][k] = *(const PG8_LAS bf16x8*)(lds + PG8_SA(b, h) + aoff + m * 2048 + k * 1024); } while (0)
; #define PG8_LDB(dst, b, h) do { _Pragma("unroll") for (int n = 0; n < 2; ++n) _Pragma("unroll") for (int k = 0; k < 2; ++k) dst[n][k] = *(const PG8_LAS bf16x8*)(lds + PG8_SB(b, h) + boff + n * 2048 + k * 1024); } while (0)
; #define PG8_MMA(ai, bj, At, Bt) do { __builtin_amdgcn_s_setprio(1); _Pragma("unroll") for (int m = 0; m < 4; ++m) _Pragma("unroll") for (int n = 0; n < 2; ++n) _Pragma("unroll") for (int k = 0; k < 2; ++k) \
;         acc[ai][bj][m][n] = __builtin_amdgcn_mfma_f32_16x16x32_bf16(Bt[n][k], At[m][k], acc[ai][bj][m][n], 0, 0, 0); __builtin_amdgcn_s_setprio(0); } while (0)
; #define PG8_WAIT_V(n) asm volatile("s_waitcnt vmcnt(" #n ")" ::: "memory")
; template <class Epi, class Sched, bool ALIGN_EPI = false, bool SP2 = false, bool ABLK = false, bool BBLK = false>
; __device__ __forceinline__ void gemm_phase(PG8_LAS unsigned char* lds, const Gemm g, const Sched& S, const Epi& E) {
;     ...
;         for (int t = 0; t < nt; t += 2) {
;             const bool last = (t == nt - 2);
;             const char* a1 = cA + (size_t)(t + 1) * kstepA;
;             const char* a2 = last ? nA : cA + (size_t)(t + 2) * kstepA; const char* b2 = last ? nB : cB + (size_t)(t + 2) * kstepB;
;             const char* a3 = a2 + kstepA; const char* b3 = b2 + kstepB;
;             if (last && has_next) S.a_ready(nxt);
;             if constexpr (SP2) {
;             PG8_LDB(B0, 0, 0); PG8_LDB(B1, 0, 1); PG8_SCHED; PG8_LDA(At, 0, 0); PG8_STAGE(PG8_SA(1, 1), a1 + hstepA, voffA);
;             PG8_WAIT_V(8); PG8_WAIT_L(0); PG8_BAR; PG8_MMA(0, 0, At, B0); PG8_MMA(0, 1, At, B1); PG8_BAR; PG8_SCHED;
;             PG8_LDA(At, 0, 1); PG8_STAGE(PG8_SB(0, 0), b2, voffB); PG8_STAGE(PG8_SB(0, 1), b2 + hstepB, voffB); PG8_STAGE(PG8_SA(0, 0), a2, voffA);
;             PG8_WAIT_V(8); PG8_WAIT_L(0); PG8_BAR; PG8_MMA(1, 0, At, B0); PG8_MMA(1, 1, At, B1); PG8_BAR; PG8_SCHED;
	s_setprio 1
	s_waitcnt lgkmcnt(0)
	v_mfma_f32_16x16x32_bf16 v[62:65], v[130:133], v[162:165], 0
	v_mfma_f32_16x16x32_bf16 v[58:61], v[138:141], v[162:165], 0
	v_mfma_f32_16x16x32_bf16 v[46:49], v[130:133], v[170:173], 0
	v_mfma_f32_16x16x32_bf16 v[42:45], v[138:141], v[170:173], 0
	v_mfma_f32_16x16x32_bf16 v[30:33], v[130:133], v[178:181], 0
	v_mfma_f32_16x16x32_bf16 v[26:29], v[138:141], v[178:181], 0
	v_mfma_f32_16x16x32_bf16 v[14:17], v[130:133], v[206:209], 0
	v_mfma_f32_16x16x32_bf16 v[10:13], v[138:141], v[206:209], 0
	v_mfma_f32_16x16x32_bf16 v[62:65], v[134:137], v[166:169], v[62:65]
	v_mfma_f32_16x16x32_bf16 v[58:61], v[142:145], v[166:169], v[58:61]
	v_mfma_f32_16x16x32_bf16 v[46:49], v[134:137], v[174:177], v[46:49]
	v_mfma_f32_16x16x32_bf16 v[42:45], v[142:145], v[174:177], v[42:45]
	v_mfma_f32_16x16x32_bf16 v[30:33], v[134:137], v[182:185], v[30:33]
	v_mfma_f32_16x16x32_bf16 v[26:29], v[142:145], v[182:185], v[26:29]
	v_mfma_f32_16x16x32_bf16 v[14:17], v[134:137], v[210:213], v[14:17]
	v_mfma_f32_16x16x32_bf16 v[10:13], v[142:145], v[210:213], v[10:13]
	s_setprio 0
	s_setprio 1
	v_mfma_f32_16x16x32_bf16 v[54:57], v[146:149], v[162:165], 0
	v_mfma_f32_16x16x32_bf16 v[50:53], v[154:157], v[162:165], 0
	v_mfma_f32_16x16x32_bf16 v[38:41], v[146:149], v[170:173], 0
	v_mfma_f32_16x16x32_bf16 v[34:37], v[154:157], v[170:173], 0
	v_mfma_f32_16x16x32_bf16 v[22:25], v[146:149], v[178:181], 0
	v_mfma_f32_16x16x32_bf16 v[18:21], v[154:157], v[178:181], 0
	v_mfma_f32_16x16x32_bf16 v[6:9], v[146:149], v[206:209], 0
	v_mfma_f32_16x16x32_bf16 v[2:5], v[154:157], v[206:209], 0
	v_mfma_f32_16x16x32_bf16 v[54:57], v[150:153], v[166:169], v[54:57]
	v_mfma_f32_16x16x32_bf16 v[50:53], v[158:161], v[166:169], v[50:53]
	v_mfma_f32_16x16x32_bf16 v[38:41], v[150:153], v[174:177], v[38:41]
	v_mfma_f32_16x16x32_bf16 v[34:37], v[158:161], v[174:177], v[34:37]
	v_mfma_f32_16x16x32_bf16 v[22:25], v[150:153], v[182:185], v[22:25]
	v_mfma_f32_16x16x32_bf16 v[18:21], v[158:161], v[182:185], v[18:21]
	v_mfma_f32_16x16x32_bf16 v[6:9], v[150:153], v[210:213], v[6:9]
	v_mfma_f32_16x16x32_bf16 v[2:5], v[158:161], v[210:213], v[2:5]
	s_setprio 0
	s_barrier
	s_branch .Lmid_1163
.LBB0_1163:
	s_add_u32 s30, s0, 0xfffe0080
	s_addc_u32 s31, s1, -1
	s_add_i32 s52, 0, 0x10000
	s_cmp_eq_u32 s86, 4
	s_cselect_b32 s35, s21, s31
	s_cselect_b32 s34, s29, s30
	s_cselect_b32 s31, s19, s84
	s_cselect_b32 s30, s61, s83
	s_add_i32 s75, 0, 0x14000
	v_add_u32_e32 v142, s52, v223
	v_add_u32_e32 v158, s75, v223
	ds_read_b128 v[130:133], v142
	ds_read_b128 v[134:137], v142 offset:1024
	ds_read_b128 v[138:141], v142 offset:2048
	ds_read_b128 v[142:145], v142 offset:3072
	ds_read_b128 v[146:149], v158
	ds_read_b128 v[150:153], v158 offset:1024
	ds_read_b128 v[154:157], v158 offset:2048
	ds_read_b128 v[158:161], v158 offset:3072
	v_lshl_add_u64 v[188:189], s[0:1], 0, v[202:203]
	s_add_i32 m0, s27, 0xc000
	ds_read_b128 v[162:165], v225
	ds_read_b128 v[166:169], v225 offset:1024
	ds_read_b128 v[170:173], v225 offset:2048
	ds_read_b128 v[174:177], v225 offset:3072
	ds_read_b128 v[178:181], v225 offset:4096
	ds_read_b128 v[182:185], v225 offset:5120
	ds_read_b128 v[206:209], v225 offset:6144
	ds_read_b128 v[210:213], v225 offset:7168
	global_load_lds_dwordx4 v[188:189], off
	v_lshl_add_u64 v[188:189], s[0:1], 0, v[204:205]
	s_add_i32 m0, s27, 0xe000
	s_nop 0
	global_load_lds_dwordx4 v[188:189], off
	s_waitcnt vmcnt(8)
	s_waitcnt lgkmcnt(0)
	s_barrier
	s_setprio 1
	s_waitcnt lgkmcnt(0)
	v_mfma_f32_16x16x32_bf16 v[126:129], v[130:133], v[162:165], v[126:129]
	v_mfma_f32_16x16x32_bf16 v[122:125], v[138:141], v[162:165], v[122:125]
	v_mfma_f32_16x16x32_bf16 v[110:113], v[130:133], v[170:173], v[110:113]
	v_mfma_f32_16x16x32_bf16 v[106:109], v[138:141], v[170:173], v[106:109]
	v_mfma_f32_16x16x32_bf16 v[94:97], v[130:133], v[178:181], v[94:97]
	v_mfma_f32_16x16x32_bf16 v[90:93], v[138:141], v[178:181], v[90:93]
	v_mfma_f32_16x16x32_bf16 v[78:81], v[130:133], v[206:209], v[78:81]
	v_mfma_f32_16x16x32_bf16 v[74:77], v[138:141], v[206:209], v[74:77]
	v_mfma_f32_16x16x32_bf16 v[126:129], v[134:137], v[166:169], v[126:129]
	v_mfma_f32_16x16x32_bf16 v[122:125], v[142:145], v[166:169], v[122:125]
	v_mfma_f32_16x16x32_bf16 v[110:113], v[134:137], v[174:177], v[110:113]
	v_mfma_f32_16x16x32_bf16 v[106:109], v[142:145], v[174:177], v[106:109]
	v_mfma_f32_16x16x32_bf16 v[94:97], v[134:137], v[182:185], v[94:97]
	v_mfma_f32_16x16x32_bf16 v[90:93], v[142:145], v[182:185], v[90:93]
	v_mfma_f32_16x16x32_bf16 v[78:81], v[134:137], v[210:213], v[78:81]
	v_mfma_f32_16x16x32_bf16 v[74:77], v[142:145], v[210:213], v[74:77]
	s_setprio 0
	s_setprio 1
	v_mfma_f32_16x16x32_bf16 v[118:121], v[146:149], v[162:165], v[118:121]
	v_mfma_f32_16x16x32_bf16 v[114:117], v[154:157], v[162:165], v[114:117]
	v_mfma_f32_16x16x32_bf16 v[102:105], v[146:149], v[170:173], v[102:105]
	v_mfma_f32_16x16x32_bf16 v[98:101], v[154:157], v[170:173], v[98:101]
	v_mfma_f32_16x16x32_bf16 v[86:89], v[146:149], v[178:181], v[86:89]
	v_mfma_f32_16x16x32_bf16 v[82:85], v[154:157], v[178:181], v[82:85]
	v_mfma_f32_16x16x32_bf16 v[70:73], v[146:149], v[206:209], v[70:73]
	v_mfma_f32_16x16x32_bf16 v[66:69], v[154:157], v[206:209], v[66:69]
	v_mfma_f32_16x16x32_bf16 v[118:121], v[150:153], v[166:169], v[118:121]
	v_mfma_f32_16x16x32_bf16 v[114:117], v[158:161], v[166:169], v[114:117]
	v_mfma_f32_16x16x32_bf16 v[102:105], v[150:153], v[174:177], v[102:105]
	v_mfma_f32_16x16x32_bf16 v[98:101], v[158:161], v[174:177], v[98:101]
	v_mfma_f32_16x16x32_bf16 v[86:89], v[150:153], v[182:185], v[86:89]
	v_mfma_f32_16x16x32_bf16 v[82:85], v[158:161], v[182:185], v[82:85]
	v_mfma_f32_16x16x32_bf16 v[70:73], v[150:153], v[210:213], v[70:73]
	v_mfma_f32_16x16x32_bf16 v[66:69], v[158:161], v[210:213], v[66:69]
	s_setprio 0
	s_barrier
; #define PG8_STAGE(bufoff, gbase, voff) do { _Pragma("unroll") for (int _i = 0; _i < 2; ++_i) \
;         __builtin_amdgcn_global_load_lds((const unsigned*)((const char*)(gbase) + (voff)[_i]), (PG8_LAS unsigned*)(lds + (bufoff) + ldsw + _i * 8192), 16, 0, 0); } while (0)
; #define PG8_LDA(dst, b, h) do { _Pragma("unroll") for (int m = 0; m < 4; ++m) _Pragma("unroll") for (int k = 0; k < 2; ++k) dst[m][k] = *(const PG8_LAS bf16x8*)(lds + PG8_SA(b, h) + aoff + m * 2048 + k * 1024); } while (0)
; #define PG8_LDB(dst, b, h) do { _Pragma("unroll") for (int n = 0; n < 2; ++n) _Pragma("unroll") for (int k = 0; k < 2; ++k) dst[n][k] = *(const PG8_LAS bf16x8*)(lds + PG8_SB(b, h) + boff + n * 2048 + k * 1024); } while (0)
; #define PG8_MMA(ai, bj, At, Bt) do { __builtin_amdgcn_s_setprio(1); _Pragma("unroll") for (int m = 0; m < 4; ++m) _Pragma("unroll") for (int n = 0; n < 2; ++n) _Pragma("unroll") for (int k = 0; k < 2; ++k) \
;         acc[ai][bj][m][n] = __builtin_amdgcn_mfma_f32_16x16x32_bf16(Bt[n][k], At[m][k], acc[ai][bj][m][n], 0, 0, 0); __builtin_amdgcn_s_setprio(0); } while (0)
; #define PG8_WAIT_V(n) asm volatile("s_waitcnt vmcnt(" #n ")" ::: "memory")
; #define PG8_WAIT_L(n) asm volatile("s_waitcnt lgkmcnt(" #n ")" ::: "memory")
; #define PG8_BAR __builtin_amdgcn_s_barrier()
; #define PG8_SCHED __builtin_amdgcn_sched_barrier(0)
; template <class Epi, class Sched, bool ALIGN_EPI = false, bool SP2 = false, bool ABLK = false, bool BBLK = false>
; __device__ __forceinline__ void gemm_phase(PG8_LAS unsigned char* lds, const Gemm g, const Sched& S, const Epi& E) {
;     ...
;             PG8_LDA(At, 0, 1); PG8_STAGE(PG8_SB(0, 0), b2, voffB); PG8_STAGE(PG8_SB(0, 1), b2 + hstepB, voffB); PG8_STAGE(PG8_SA(0, 0), a2, voffA);
;             PG8_WAIT_V(8); PG8_WAIT_L(0); PG8_BAR; PG8_MMA(1, 0, At, B0); PG8_MMA(1, 1, At, B1); PG8_BAR; PG8_SCHED;
;             PG8_LDB(B0, 1, 0); PG8_LDB(B1, 1, 1); PG8_SCHED; PG8_LDA(At, 1, 0); PG8_STAGE(PG8_SA(0, 1), a2 + hstepA, voffA);
;             PG8_WAIT_V(8); PG8_WAIT_L(0); PG8_BAR; PG8_MMA(0, 0, At, B0); PG8_MMA(0, 1, At, B1); PG8_BAR; PG8_SCHED;
	s_add_i32 s52, s52, s45
	v_lshl_add_u64 v[188:189], s[30:31], 0, v[196:197]
	s_mov_b32 m0, s52
	ds_read_b128 v[162:165], v225 offset:16384
	ds_read_b128 v[166:169], v225 offset:17408
	ds_read_b128 v[170:173], v225 offset:18432
	ds_read_b128 v[174:177], v225 offset:19456
	ds_read_b128 v[178:181], v225 offset:20480
	ds_read_b128 v[182:185], v225 offset:21504
	ds_read_b128 v[206:209], v225 offset:22528
	ds_read_b128 v[210:213], v225 offset:23552
	global_load_lds_dwordx4 v[188:189], off
	s_add_i32 m0, s52, 0x2000
	s_add_u32 s88, s30, 0x4000
	v_lshl_add_u64 v[188:189], s[30:31], 0, v[200:201]
	s_addc_u32 s89, s31, 0
	s_add_i32 s52, s75, s45
	global_load_lds_dwordx4 v[188:189], off
	v_lshl_add_u64 v[188:189], s[88:89], 0, v[196:197]
	s_mov_b32 m0, s52
	v_lshl_add_u64 v[190:191], s[34:35], 0, v[198:199]
	global_load_lds_dwordx4 v[188:189], off
	v_lshl_add_u64 v[188:189], s[88:89], 0, v[200:201]
	s_add_i32 m0, s52, 0x2000
	s_nop 0
	global_load_lds_dwordx4 v[188:189], off
	v_lshl_add_u64 v[188:189], s[34:35], 0, v[186:187]
	s_mov_b32 m0, s27
	s_nop 0
	global_load_lds_dwordx4 v[188:189], off
	s_mov_b32 m0, s46
	s_nop 0
	global_load_lds_dwordx4 v[190:191], off
	s_waitcnt vmcnt(8)
	s_waitcnt lgkmcnt(0)
	s_barrier
	s_setprio 1
	s_waitcnt lgkmcnt(0)
	v_mfma_f32_16x16x32_bf16 v[62:65], v[130:133], v[162:165], v[62:65]
	v_mfma_f32_16x16x32_bf16 v[58:61], v[138:141], v[162:165], v[58:61]
	v_mfma_f32_16x16x32_bf16 v[46:49], v[130:133], v[170:173], v[46:49]
	v_mfma_f32_16x16x32_bf16 v[42:45], v[138:141], v[170:173], v[42:45]
	v_mfma_f32_16x16x32_bf16 v[30:33], v[130:133], v[178:181], v[30:33]
	v_mfma_f32_16x16x32_bf16 v[26:29], v[138:141], v[178:181], v[26:29]
	v_mfma_f32_16x16x32_bf16 v[14:17], v[130:133], v[206:209], v[14:17]
	v_mfma_f32_16x16x32_bf16 v[10:13], v[138:141], v[206:209], v[10:13]
	v_mfma_f32_16x16x32_bf16 v[62:65], v[134:137], v[166:169], v[62:65]
	v_mfma_f32_16x16x32_bf16 v[58:61], v[142:145], v[166:169], v[58:61]
	v_mfma_f32_16x16x32_bf16 v[46:49], v[134:137], v[174:177], v[46:49]
	v_mfma_f32_16x16x32_bf16 v[42:45], v[142:145], v[174:177], v[42:45]
	v_mfma_f32_16x16x32_bf16 v[30:33], v[134:137], v[182:185], v[30:33]
	v_mfma_f32_16x16x32_bf16 v[26:29], v[142:145], v[182:185], v[26:29]
	v_mfma_f32_16x16x32_bf16 v[14:17], v[134:137], v[210:213], v[14:17]
	v_mfma_f32_16x16x32_bf16 v[10:13], v[142:145], v[210:213], v[10:13]
	s_setprio 0
	s_setprio 1
	v_mfma_f32_16x16x32_bf16 v[54:57], v[146:149], v[162:165], v[54:57]
	v_mfma_f32_16x16x32_bf16 v[50:53], v[154:157], v[162:165], v[50:53]
	v_mfma_f32_16x16x32_bf16 v[38:41], v[146:149], v[170:173], v[38:41]
	v_mfma_f32_16x16x32_bf16 v[34:37], v[154:157], v[170:173], v[34:37]
	v_mfma_f32_16x16x32_bf16 v[22:25], v[146:149], v[178:181], v[22:25]
	v_mfma_f32_16x16x32_bf16 v[18:21], v[154:157], v[178:181], v[18:21]
	v_mfma_f32_16x16x32_bf16 v[6:9], v[146:149], v[206:209], v[6:9]
	v_mfma_f32_16x16x32_bf16 v[2:5], v[154:157], v[206:209], v[2:5]
	v_mfma_f32_16x16x32_bf16 v[54:57], v[150:153], v[166:169], v[54:57]
	v_mfma_f32_16x16x32_bf16 v[50:53], v[158:161], v[166:169], v[50:53]
	v_mfma_f32_16x16x32_bf16 v[38:41], v[150:153], v[174:177], v[38:41]
	v_mfma_f32_16x16x32_bf16 v[34:37], v[158:161], v[174:177], v[34:37]
	v_mfma_f32_16x16x32_bf16 v[22:25], v[150:153], v[182:185], v[22:25]
	v_mfma_f32_16x16x32_bf16 v[18:21], v[158:161], v[182:185], v[18:21]
	v_mfma_f32_16x16x32_bf16 v[6:9], v[150:153], v[210:213], v[6:9]
	v_mfma_f32_16x16x32_bf16 v[2:5], v[158:161], v[210:213], v[2:5]
	s_setprio 0
	s_barrier
.Lmid_1163:
	s_add_i32 s52, 0, 0x18000
	s_add_i32 s75, 0, 0x1c000
	v_add_u32_e32 v142, s52, v223
	v_add_u32_e32 v158, s75, v223
	ds_read_b128 v[130:133], v142
	ds_read_b128 v[134:137], v142 offset:1024
	ds_read_b128 v[138:141], v142 offset:2048
	ds_read_b128 v[142:145], v142 offset:3072
	ds_read_b128 v[146:149], v158
	ds_read_b128 v[150:153], v158 offset:1024
	ds_read_b128 v[154:157], v158 offset:2048
	ds_read_b128 v[158:161], v158 offset:3072
	s_add_u32 s34, s34, 0x20000
	s_addc_u32 s35, s35, 0
	s_mov_b32 m0, s47
	v_lshl_add_u64 v[192:193], s[34:35], 0, v[186:187]
	ds_read_b128 v[162:165], v225 offset:32768
	ds_read_b128 v[166:169], v225 offset:33792
	ds_read_b128 v[170:173], v225 offset:34816
	ds_read_b128 v[174:177], v225 offset:35840
	ds_read_b128 v[178:181], v225 offset:36864
	ds_read_b128 v[182:185], v225 offset:37888
	ds_read_b128 v[206:209], v225 offset:38912
	ds_read_b128 v[210:213], v225 offset:39936
	global_load_lds_dwordx4 v[192:193], off
	v_lshl_add_u64 v[192:193], s[34:35], 0, v[198:199]
	s_mov_b32 m0, s65
	s_nop 0
	global_load_lds_dwordx4 v[192:193], off
	s_waitcnt vmcnt(8)
	s_waitcnt lgkmcnt(0)
	s_barrier
; #define PG8_STAGE(bufoff, gbase, voff) do { _Pragma("unroll") for (int _i = 0; _i < 2; ++_i) \
;         __builtin_amdgcn_global_load_lds((const unsigned*)((const char*)(gbase) + (voff)[_i]), (PG8_LAS unsigned*)(lds + (bufoff) + ldsw + _i * 8192), 16, 0, 0); } while (0)
; #define PG8_WAIT_V(n) asm volatile("s_waitcnt vmcnt(" #n ")" ::: "memory")
; #define PG8_BAR __builtin_amdgcn_s_barrier()
; template <class Epi, class Sched, bool ALIGN_EPI = false, bool SP2 = false, bool ABLK = false, bool BBLK = false>
; __device__ __forceinline__ void gemm_phase(PG8_LAS unsigned char* lds, const Gemm g, const Sched& S, const Epi& E) {
;     ...
;             PG8_WAIT_V(8); PG8_WAIT_L(0); PG8_BAR; PG8_MMA(0, 0, At, B0); PG8_MMA(0, 1, At, B1); PG8_BAR; PG8_SCHED;
;             PG8_LDA(At, 1, 1); PG8_STAGE(PG8_SB(1, 0), b3, voffB); PG8_STAGE(PG8_SB(1, 1), b3 + hstepB, voffB); PG8_STAGE(PG8_SA(1, 0), a3, voffA);
;             PG8_WAIT_V(8); PG8_WAIT_L(0); PG8_BAR; PG8_MMA(1, 0, At, B0); PG8_MMA(1, 1, At, B1); PG8_BAR; PG8_SCHED;
;             } else {
;             PG8_LDB(B0, 0, 0); PG8_SCHED; PG8_LDA(At, 0, 0); PG8_STAGE(PG8_SA(1, 1), a1 + hstepA, voffA);
;             PG8_WAIT_L(8); PG8_BAR; PG8_WAIT_L(0); PG8_MMA(0, 0, At, B0); PG8_BAR; PG8_SCHED;
;             PG8_LDB(B1, 0, 1); PG8_STAGE(PG8_SB(0, 0), b2, voffB);
;             PG8_BAR; PG8_WAIT_L(0); PG8_MMA(0, 1, At, B1); PG8_BAR;
;             PG8_LDA(At, 0, 1); PG8_STAGE(PG8_SA(0, 0), a2, voffA);
;             PG8_BAR; PG8_WAIT_L(0); PG8_MMA(1, 0, At, B0); PG8_BAR; PG8_SCHED;
;             PG8_STAGE(PG8_SB(0, 1), b2 + hstepB, voffB);
;             PG8_WAIT_V(6); PG8_BAR; PG8_MMA(1, 1, At, B1); PG8_BAR;
;             PG8_LDB(B0, 1, 0); PG8_SCHED; PG8_LDA(At, 1, 0); PG8_STAGE(PG8_SA(0, 1), a2 + hstepA, voffA);
;             PG8_WAIT_L(8); PG8_BAR; PG8_WAIT_L(0); PG8_MMA(0, 0, At, B0); PG8_BAR; PG8_SCHED;
;             PG8_LDB(B1, 1, 1); PG8_STAGE(PG8_SB(1, 0), b3, voffB);
;             PG8_BAR; PG8_WAIT_L(0); PG8_MMA(0, 1, At, B1); PG8_BAR;
;             PG8_LDA(At, 1, 1); PG8_STAGE(PG8_SA(1, 0), a3, voffA);
;             PG8_BAR; PG8_WAIT_L(0); PG8_MMA(1, 0, At, B0); PG8_BAR; PG8_SCHED;
;             PG8_STAGE(PG8_SB(1, 1), b3 + hstepB, voffB);
;             PG8_WAIT_V(6); PG8_BAR; PG8_MMA(1, 1, At, B1); PG8_BAR;
;             }
;         }
;         if constexpr (ALIGN_EPI) { if (wr == 0) PG8_BAR; }
	s_setprio 1
	s_waitcnt lgkmcnt(0)
	v_mfma_f32_16x16x32_bf16 v[126:129], v[130:133], v[162:165], v[126:129]
	v_mfma_f32_16x16x32_bf16 v[122:125], v[138:141], v[162:165], v[122:125]
	v_mfma_f32_16x16x32_bf16 v[110:113], v[130:133], v[170:173], v[110:113]
	v_mfma_f32_16x16x32_bf16 v[106:109], v[138:141], v[170:173], v[106:109]
	v_mfma_f32_16x16x32_bf16 v[94:97], v[130:133], v[178:181], v[94:97]
	v_mfma_f32_16x16x32_bf16 v[90:93], v[138:141], v[178:181], v[90:93]
	v_mfma_f32_16x16x32_bf16 v[78:81], v[130:133], v[206:209], v[78:81]
	v_mfma_f32_16x16x32_bf16 v[74:77], v[138:141], v[206:209], v[74:77]
	v_mfma_f32_16x16x32_bf16 v[126:129], v[134:137], v[166:169], v[126:129]
	v_mfma_f32_16x16x32_bf16 v[122:125], v[142:145], v[166:169], v[122:125]
	v_mfma_f32_16x16x32_bf16 v[110:113], v[134:137], v[174:177], v[110:113]
	v_mfma_f32_16x16x32_bf16 v[106:109], v[142:145], v[174:177], v[106:109]
	v_mfma_f32_16x16x32_bf16 v[94:97], v[134:137], v[182:185], v[94:97]
	v_mfma_f32_16x16x32_bf16 v[90:93], v[142:145], v[182:185], v[90:93]
	v_mfma_f32_16x16x32_bf16 v[78:81], v[134:137], v[210:213], v[78:81]
	v_mfma_f32_16x16x32_bf16 v[74:77], v[142:145], v[210:213], v[74:77]
	s_setprio 0
	s_setprio 1
	v_mfma_f32_16x16x32_bf16 v[118:121], v[146:149], v[162:165], v[118:121]
	v_mfma_f32_16x16x32_bf16 v[114:117], v[154:157], v[162:165], v[114:117]
	v_mfma_f32_16x16x32_bf16 v[102:105], v[146:149], v[170:173], v[102:105]
	v_mfma_f32_16x16x32_bf16 v[98:101], v[154:157], v[170:173], v[98:101]
	v_mfma_f32_16x16x32_bf16 v[86:89], v[146:149], v[178:181], v[86:89]
	v_mfma_f32_16x16x32_bf16 v[82:85], v[154:157], v[178:181], v[82:85]
	v_mfma_f32_16x16x32_bf16 v[70:73], v[146:149], v[206:209], v[70:73]
	v_mfma_f32_16x16x32_bf16 v[66:69], v[154:157], v[206:209], v[66:69]
	v_mfma_f32_16x16x32_bf16 v[118:121], v[150:153], v[166:169], v[118:121]
	v_mfma_f32_16x16x32_bf16 v[114:117], v[158:161], v[166:169], v[114:117]
	v_mfma_f32_16x16x32_bf16 v[102:105], v[150:153], v[174:177], v[102:105]
	v_mfma_f32_16x16x32_bf16 v[98:101], v[158:161], v[174:177], v[98:101]
	v_mfma_f32_16x16x32_bf16 v[86:89], v[150:153], v[182:185], v[86:89]
	v_mfma_f32_16x16x32_bf16 v[82:85], v[158:161], v[182:185], v[82:85]
	v_mfma_f32_16x16x32_bf16 v[70:73], v[150:153], v[210:213], v[70:73]
	v_mfma_f32_16x16x32_bf16 v[66:69], v[158:161], v[210:213], v[66:69]
	s_setprio 0
	s_barrier
	s_add_u32 s34, s30, 0x8000
	s_addc_u32 s35, s31, 0
	s_add_i32 s52, s52, s45
	v_lshl_add_u64 v[192:193], s[34:35], 0, v[196:197]
	s_mov_b32 m0, s52
	ds_read_b128 v[162:165], v225 offset:49152
	ds_read_b128 v[166:169], v225 offset:50176
	ds_read_b128 v[170:173], v225 offset:51200
	ds_read_b128 v[174:177], v225 offset:52224
	ds_read_b128 v[178:181], v225 offset:53248
	ds_read_b128 v[182:185], v225 offset:54272
	ds_read_b128 v[206:209], v225 offset:55296
	ds_read_b128 v[210:213], v225 offset:56320
	global_load_lds_dwordx4 v[192:193], off
	s_add_i32 m0, s52, 0x2000
	s_add_u32 s30, s30, 0xc000
	v_lshl_add_u64 v[192:193], s[34:35], 0, v[200:201]
	s_addc_u32 s31, s31, 0
	s_add_i32 s34, s75, s45
	global_load_lds_dwordx4 v[192:193], off
	v_lshl_add_u64 v[192:193], s[30:31], 0, v[196:197]
	s_mov_b32 m0, s34
	v_lshl_add_u64 v[188:189], v[188:189], 0, s[62:63]
	global_load_lds_dwordx4 v[192:193], off
	v_lshl_add_u64 v[192:193], s[30:31], 0, v[200:201]
	s_add_i32 m0, s34, 0x2000
	s_nop 0
	global_load_lds_dwordx4 v[192:193], off
	s_mov_b32 m0, s72
	s_nop 0
	global_load_lds_dwordx4 v[188:189], off
	v_lshl_add_u64 v[188:189], v[190:191], 0, s[62:63]
	s_mov_b32 m0, s73
	s_nop 0
	global_load_lds_dwordx4 v[188:189], off
	s_waitcnt vmcnt(8)
	s_waitcnt lgkmcnt(0)
	s_barrier
	s_setprio 1
	s_waitcnt lgkmcnt(0)
	v_mfma_f32_16x16x32_bf16 v[62:65], v[130:133], v[162:165], v[62:65]
	v_mfma_f32_16x16x32_bf16 v[58:61], v[138:141], v[162:165], v[58:61]
	v_mfma_f32_16x16x32_bf16 v[46:49], v[130:133], v[170:173], v[46:49]
	v_mfma_f32_16x16x32_bf16 v[42:45], v[138:141], v[170:173], v[42:45]
	v_mfma_f32_16x16x32_bf16 v[30:33], v[130:133], v[178:181], v[30:33]
	v_mfma_f32_16x16x32_bf16 v[26:29], v[138:141], v[178:181], v[26:29]
	v_mfma_f32_16x16x32_bf16 v[14:17], v[130:133], v[206:209], v[14:17]
	v_mfma_f32_16x16x32_bf16 v[10:13], v[138:141], v[206:209], v[10:13]
	v_mfma_f32_16x16x32_bf16 v[62:65], v[134:137], v[166:169], v[62:65]
	v_mfma_f32_16x16x32_bf16 v[58:61], v[142:145], v[166:169], v[58:61]
	v_mfma_f32_16x16x32_bf16 v[46:49], v[134:137], v[174:177], v[46:49]
	v_mfma_f32_16x16x32_bf16 v[42:45], v[142:145], v[174:177], v[42:45]
	v_mfma_f32_16x16x32_bf16 v[30:33], v[134:137], v[182:185], v[30:33]
	v_mfma_f32_16x16x32_bf16 v[26:29], v[142:145], v[182:185], v[26:29]
	v_mfma_f32_16x16x32_bf16 v[14:17], v[134:137], v[210:213], v[14:17]
	v_mfma_f32_16x16x32_bf16 v[10:13], v[142:145], v[210:213], v[10:13]
	s_setprio 0
	s_setprio 1
	v_mfma_f32_16x16x32_bf16 v[54:57], v[146:149], v[162:165], v[54:57]
	v_mfma_f32_16x16x32_bf16 v[50:53], v[154:157], v[162:165], v[50:53]
	v_mfma_f32_16x16x32_bf16 v[38:41], v[146:149], v[170:173], v[38:41]
	v_mfma_f32_16x16x32_bf16 v[34:37], v[154:157], v[170:173], v[34:37]
	v_mfma_f32_16x16x32_bf16 v[22:25], v[146:149], v[178:181], v[22:25]
	v_mfma_f32_16x16x32_bf16 v[18:21], v[154:157], v[178:181], v[18:21]
	v_mfma_f32_16x16x32_bf16 v[6:9], v[146:149], v[206:209], v[6:9]
	v_mfma_f32_16x16x32_bf16 v[2:5], v[154:157], v[206:209], v[2:5]
	v_mfma_f32_16x16x32_bf16 v[54:57], v[150:153], v[166:169], v[54:57]
	v_mfma_f32_16x16x32_bf16 v[50:53], v[158:161], v[166:169], v[50:53]
	v_mfma_f32_16x16x32_bf16 v[38:41], v[150:153], v[174:177], v[38:41]
	v_mfma_f32_16x16x32_bf16 v[34:37], v[158:161], v[174:177], v[34:37]
	v_mfma_f32_16x16x32_bf16 v[22:25], v[150:153], v[182:185], v[22:25]
	v_mfma_f32_16x16x32_bf16 v[18:21], v[158:161], v[182:185], v[18:21]
	v_mfma_f32_16x16x32_bf16 v[6:9], v[150:153], v[210:213], v[6:9]
	v_mfma_f32_16x16x32_bf16 v[2:5], v[158:161], v[210:213], v[2:5]
	s_setprio 0
	s_barrier
	s_add_i32 s86, s86, 2
	s_add_u32 s83, s83, 0x10000
	s_addc_u32 s84, s84, 0
	s_add_u32 s0, s0, 0x100
	s_addc_u32 s1, s1, 0
	s_cmp_gt_u32 s86, 5
	s_cbranch_scc0 .LBB0_1163
	s_and_b64 vcc, exec, s[12:13]
	s_cbranch_vccz .LBB0_1166
	s_barrier

; #define PG8_STAGE(bufoff, gbase, voff) do { _Pragma("unroll") for (int _i = 0; _i < 2; ++_i) \
;         __builtin_amdgcn_global_load_lds((const unsigned*)((const char*)(gbase) + (voff)[_i]), (PG8_LAS unsigned*)(lds + (bufoff) + ldsw + _i * 8192), 16, 0, 0); } while (0)
; #define PG8_LDA(dst, b, h) do { _Pragma("unroll") for (int m = 0; m < 4; ++m) _Pragma("unroll") for (int k = 0; k < 2; ++k) dst[m][k] = *(const PG8_LAS bf16x8*)(lds + PG8_SA(b, h) + aoff + m * 2048 + k * 1024); } while (0)
; #define PG8_LDB(dst, b, h) do { _Pragma("unroll") for (int n = 0; n < 2; ++n) _Pragma("unroll") for (int k = 0; k < 2; ++k) dst[n][k] = *(const PG8_LAS bf16x8*)(lds + PG8_SB(b, h) + boff + n * 2048 + k * 1024); } while (0)
; #define PG8_WAIT_V(n) asm volatile("s_waitcnt vmcnt(" #n ")" ::: "memory")
; #define PG8_WAIT_L(n) asm volatile("s_waitcnt lgkmcnt(" #n ")" ::: "memory")
; #define PG8_BAR __builtin_amdgcn_s_barrier()
; #define PG8_SCHED __builtin_amdgcn_sched_barrier(0)
; template <class Epi, class Sched, bool ALIGN_EPI = false, bool SP2 = false, bool ABLK = false, bool BBLK = false>
; __device__ __forceinline__ void gemm_phase(PG8_LAS unsigned char* lds, const Gemm g, const Sched& S, const Epi& E) {
;     ...
;         const bool has_next = S.next(ui + 1, nxt);
;         const char* nA = has_next ? (const char*)g.A + (size_t)nxt.pm * tstepA : cA; const char* nB = has_next ? (const char*)g.Bt + (size_t)nxt.pn * tstepB : cB;
;         for (int t = 0; t < nt; t += 2) {
;             const bool last = (t == nt - 2);
;             const char* a1 = cA + (size_t)(t + 1) * kstepA;
;             const char* a2 = last ? nA : cA + (size_t)(t + 2) * kstepA; const char* b2 = last ? nB : cB + (size_t)(t + 2) * kstepB;
;             const char* a3 = a2 + kstepA; const char* b3 = b2 + kstepB;
;             if (last && has_next) S.a_ready(nxt);
;             if constexpr (SP2) {
;             PG8_LDB(B0, 0, 0); PG8_LDB(B1, 0, 1); PG8_SCHED; PG8_LDA(At, 0, 0); PG8_STAGE(PG8_SA(1, 1), a1 + hstepA, voffA);
;             PG8_WAIT_V(8); PG8_WAIT_L(0); PG8_BAR; PG8_MMA(0, 0, At, B0); PG8_MMA(0, 1, At, B1); PG8_BAR; PG8_SCHED;
;             PG8_LDA(At, 0, 1); PG8_STAGE(PG8_SB(0, 0), b2, voffB); PG8_STAGE(PG8_SB(0, 1), b2 + hstepB, voffB); PG8_STAGE(PG8_SA(0, 0), a2, voffA);
;             PG8_WAIT_V(8); PG8_WAIT_L(0); PG8_BAR; PG8_MMA(1, 0, At, B0); PG8_MMA(1, 1, At, B1); PG8_BAR; PG8_SCHED;
.LBB0_1339:
	s_ashr_i32 s19, s18, 31
	s_lshl_b64 s[20:21], s[18:19], 20
	s_add_u32 s20, s40, s20
	s_addc_u32 s21, s41, s21
	s_and_b64 s[22:23], s[6:7], exec
	s_cselect_b32 s1, s21, s27
	s_cselect_b32 s19, s20, s26
	s_ashr_i32 s15, s14, 31
	s_lshl_b64 s[22:23], s[14:15], 20
	s_add_u32 s22, s42, s22
	s_addc_u32 s23, s43, s23
	s_and_b64 s[30:31], s[6:7], exec
	s_cselect_b32 s15, s23, s29
	s_cselect_b32 s72, s22, s28
	s_add_u32 s26, s26, 0xc000
	s_addc_u32 s27, s27, 0
	s_add_u32 s73, s28, 0x10000
	v_mov_b32_e32 v2, 0
	s_addc_u32 s81, s29, 0
	s_mov_b32 s83, -2
	s_add_u32 s28, s26, 0x4000
	s_addc_u32 s29, s27, 0
	s_cmp_eq_u32 s83, 28
	s_cselect_b32 s34, s19, s28
	s_cselect_b32 s35, s1, s29
	s_cselect_b32 s30, s72, s73
	s_cselect_b32 s31, s15, s81
	s_add_u32 s28, s34, 0x8000
	s_addc_u32 s29, s35, 0
	s_add_i32 s52, 0, 0x10000
	v_add_u32_e32 v142, s52, v145
	s_add_i32 s75, 0, 0x14000
	ds_read_b128 v[148:151], v142
	ds_read_b128 v[152:155], v142 offset:1024
	ds_read_b128 v[156:159], v142 offset:2048
	ds_read_b128 v[160:163], v142 offset:3072
	v_add_u32_e32 v142, s75, v145
	ds_read_b128 v[164:167], v142
	ds_read_b128 v[168:171], v142 offset:1024
	ds_read_b128 v[172:175], v142 offset:2048
	ds_read_b128 v[176:179], v142 offset:3072
	v_lshl_add_u64 v[142:143], s[26:27], 0, v[138:139]
	s_add_i32 m0, s25, 0xc000
	ds_read_b128 v[180:183], v146
	ds_read_b128 v[196:199], v146 offset:1024
	ds_read_b128 v[200:203], v146 offset:2048
	ds_read_b128 v[204:207], v146 offset:3072
	ds_read_b128 v[208:211], v146 offset:4096
	ds_read_b128 v[212:215], v146 offset:5120
	ds_read_b128 v[216:219], v146 offset:6144
	ds_read_b128 v[220:223], v146 offset:7168
	global_load_lds_dwordx4 v[142:143], off
	v_lshl_add_u64 v[142:143], s[26:27], 0, v[140:141]
	s_add_i32 m0, s25, 0xe000
	s_nop 0
	global_load_lds_dwordx4 v[142:143], off
	s_waitcnt vmcnt(8)
	s_waitcnt lgkmcnt(0)
	s_barrier
	s_setprio 1
	s_waitcnt lgkmcnt(0)
	v_mfma_f32_16x16x32_bf16 v[126:129], v[148:151], v[180:183], 0
	v_mfma_f32_16x16x32_bf16 v[118:121], v[156:159], v[180:183], 0
	v_mfma_f32_16x16x32_bf16 v[110:113], v[148:151], v[200:203], 0
	v_mfma_f32_16x16x32_bf16 v[102:105], v[156:159], v[200:203], 0
	v_mfma_f32_16x16x32_bf16 v[94:97], v[148:151], v[208:211], 0
	v_mfma_f32_16x16x32_bf16 v[86:89], v[156:159], v[208:211], 0
	v_mfma_f32_16x16x32_bf16 v[78:81], v[148:151], v[216:219], 0
	v_mfma_f32_16x16x32_bf16 v[70:73], v[156:159], v[216:219], 0
	v_mfma_f32_16x16x32_bf16 v[126:129], v[152:155], v[196:199], v[126:129]
	v_mfma_f32_16x16x32_bf16 v[118:121], v[160:163], v[196:199], v[118:121]
	v_mfma_f32_16x16x32_bf16 v[110:113], v[152:155], v[204:207], v[110:113]
	v_mfma_f32_16x16x32_bf16 v[102:105], v[160:163], v[204:207], v[102:105]
	v_mfma_f32_16x16x32_bf16 v[94:97], v[152:155], v[212:215], v[94:97]
	v_mfma_f32_16x16x32_bf16 v[86:89], v[160:163], v[212:215], v[86:89]
	v_mfma_f32_16x16x32_bf16 v[78:81], v[152:155], v[220:223], v[78:81]
	v_mfma_f32_16x16x32_bf16 v[70:73], v[160:163], v[220:223], v[70:73]
	s_setprio 0
	s_setprio 1
	v_mfma_f32_16x16x32_bf16 v[122:125], v[164:167], v[180:183], 0
	v_mfma_f32_16x16x32_bf16 v[114:117], v[172:175], v[180:183], 0
	v_mfma_f32_16x16x32_bf16 v[106:109], v[164:167], v[200:203], 0
	v_mfma_f32_16x16x32_bf16 v[98:101], v[172:175], v[200:203], 0
	v_mfma_f32_16x16x32_bf16 v[90:93], v[164:167], v[208:211], 0
	v_mfma_f32_16x16x32_bf16 v[82:85], v[172:175], v[208:211], 0
	v_mfma_f32_16x16x32_bf16 v[74:77], v[164:167], v[216:219], 0
	v_mfma_f32_16x16x32_bf16 v[66:69], v[172:175], v[216:219], 0
	v_mfma_f32_16x16x32_bf16 v[122:125], v[168:171], v[196:199], v[122:125]
	v_mfma_f32_16x16x32_bf16 v[114:117], v[176:179], v[196:199], v[114:117]
	v_mfma_f32_16x16x32_bf16 v[106:109], v[168:171], v[204:207], v[106:109]
	v_mfma_f32_16x16x32_bf16 v[98:101], v[176:179], v[204:207], v[98:101]
	v_mfma_f32_16x16x32_bf16 v[90:93], v[168:171], v[212:215], v[90:93]
	v_mfma_f32_16x16x32_bf16 v[82:85], v[176:179], v[212:215], v[82:85]
	v_mfma_f32_16x16x32_bf16 v[74:77], v[168:171], v[220:223], v[74:77]
	v_mfma_f32_16x16x32_bf16 v[66:69], v[176:179], v[220:223], v[66:69]
	s_setprio 0
	s_barrier
	s_add_i32 s52, s52, s44
	v_lshl_add_u64 v[142:143], s[30:31], 0, v[134:135]
	s_mov_b32 m0, s52
	ds_read_b128 v[180:183], v146 offset:16384
	ds_read_b128 v[196:199], v146 offset:17408
	ds_read_b128 v[200:203], v146 offset:18432
	ds_read_b128 v[204:207], v146 offset:19456
	ds_read_b128 v[208:211], v146 offset:20480
	ds_read_b128 v[212:215], v146 offset:21504
	ds_read_b128 v[216:219], v146 offset:22528
	ds_read_b128 v[220:223], v146 offset:23552
	global_load_lds_dwordx4 v[142:143], off
	s_add_i32 m0, s52, 0x2000
	s_add_u32 s88, s30, 0x4000
	v_lshl_add_u64 v[142:143], s[30:31], 0, v[130:131]
	s_addc_u32 s89, s31, 0
	s_add_i32 s52, s75, s44
	global_load_lds_dwordx4 v[142:143], off
	v_lshl_add_u64 v[142:143], s[88:89], 0, v[134:135]
	s_mov_b32 m0, s52
	s_nop 0
	global_load_lds_dwordx4 v[142:143], off
	v_lshl_add_u64 v[142:143], s[88:89], 0, v[130:131]
	s_add_i32 m0, s52, 0x2000
	s_nop 0
	global_load_lds_dwordx4 v[142:143], off
	v_lshl_add_u64 v[142:143], s[34:35], 0, v[136:137]
	s_mov_b32 m0, s25
	s_nop 0
	global_load_lds_dwordx4 v[142:143], off
	v_lshl_add_u64 v[142:143], s[34:35], 0, v[132:133]
	s_mov_b32 m0, s46
	s_nop 0
	global_load_lds_dwordx4 v[142:143], off
	s_waitcnt vmcnt(8)
	s_waitcnt lgkmcnt(0)
	s_barrier
; #define PG8_STAGE(bufoff, gbase, voff) do { _Pragma("unroll") for (int _i = 0; _i < 2; ++_i) \
;         __builtin_amdgcn_global_load_lds((const unsigned*)((const char*)(gbase) + (voff)[_i]), (PG8_LAS unsigned*)(lds + (bufoff) + ldsw + _i * 8192), 16, 0, 0); } while (0)
; #define PG8_LDA(dst, b, h) do { _Pragma("unroll") for (int m = 0; m < 4; ++m) _Pragma("unroll") for (int k = 0; k < 2; ++k) dst[m][k] = *(const PG8_LAS bf16x8*)(lds + PG8_SA(b, h) + aoff + m * 2048 + k * 1024); } while (0)
; #define PG8_LDB(dst, b, h) do { _Pragma("unroll") for (int n = 0; n < 2; ++n) _Pragma("unroll") for (int k = 0; k < 2; ++k) dst[n][k] = *(const PG8_LAS bf16x8*)(lds + PG8_SB(b, h) + boff + n * 2048 + k * 1024); } while (0)
; #define PG8_MMA(ai, bj, At, Bt) do { __builtin_amdgcn_s_setprio(1); _Pragma("unroll") for (int m = 0; m < 4; ++m) _Pragma("unroll") for (int n = 0; n < 2; ++n) _Pragma("unroll") for (int k = 0; k < 2; ++k) \
;         acc[ai][bj][m][n] = __builtin_amdgcn_mfma_f32_16x16x32_bf16(Bt[n][k], At[m][k], acc[ai][bj][m][n], 0, 0, 0); __builtin_amdgcn_s_setprio(0); } while (0)
; #define PG8_WAIT_V(n) asm volatile("s_waitcnt vmcnt(" #n ")" ::: "memory")
; template <class Epi, class Sched, bool ALIGN_EPI = false, bool SP2 = false, bool ABLK = false, bool BBLK = false>
; __device__ __forceinline__ void gemm_phase(PG8_LAS unsigned char* lds, const Gemm g, const Sched& S, const Epi& E) {
;     ...
;         for (int t = 0; t < nt; t += 2) {
;             const bool last = (t == nt - 2);
;             const char* a1 = cA + (size_t)(t + 1) * kstepA;
;             const char* a2 = last ? nA : cA + (size_t)(t + 2) * kstepA; const char* b2 = last ? nB : cB + (size_t)(t + 2) * kstepB;
;             const char* a3 = a2 + kstepA; const char* b3 = b2 + kstepB;
;             if (last && has_next) S.a_ready(nxt);
;             if constexpr (SP2) {
;             PG8_LDB(B0, 0, 0); PG8_LDB(B1, 0, 1); PG8_SCHED; PG8_LDA(At, 0, 0); PG8_STAGE(PG8_SA(1, 1), a1 + hstepA, voffA);
;             PG8_WAIT_V(8); PG8_WAIT_L(0); PG8_BAR; PG8_MMA(0, 0, At, B0); PG8_MMA(0, 1, At, B1); PG8_BAR; PG8_SCHED;
;             PG8_LDA(At, 0, 1); PG8_STAGE(PG8_SB(0, 0), b2, voffB); PG8_STAGE(PG8_SB(0, 1), b2 + hstepB, voffB); PG8_STAGE(PG8_SA(0, 0), a2, voffA);
;             PG8_WAIT_V(8); PG8_WAIT_L(0); PG8_BAR; PG8_MMA(1, 0, At, B0); PG8_MMA(1, 1, At, B1); PG8_BAR; PG8_SCHED;
	s_setprio 1
	s_waitcnt lgkmcnt(0)
	v_mfma_f32_16x16x32_bf16 v[62:65], v[148:151], v[180:183], 0
	v_mfma_f32_16x16x32_bf16 v[54:57], v[156:159], v[180:183], 0
	v_mfma_f32_16x16x32_bf16 v[46:49], v[148:151], v[200:203], 0
	v_mfma_f32_16x16x32_bf16 v[38:41], v[156:159], v[200:203], 0
	v_mfma_f32_16x16x32_bf16 v[30:33], v[148:151], v[208:211], 0
	v_mfma_f32_16x16x32_bf16 v[22:25], v[156:159], v[208:211], 0
	v_mfma_f32_16x16x32_bf16 v[14:17], v[148:151], v[216:219], 0
	v_mfma_f32_16x16x32_bf16 v[6:9], v[156:159], v[216:219], 0
	v_mfma_f32_16x16x32_bf16 v[62:65], v[152:155], v[196:199], v[62:65]
	v_mfma_f32_16x16x32_bf16 v[54:57], v[160:163], v[196:199], v[54:57]
	v_mfma_f32_16x16x32_bf16 v[46:49], v[152:155], v[204:207], v[46:49]
	v_mfma_f32_16x16x32_bf16 v[38:41], v[160:163], v[204:207], v[38:41]
	v_mfma_f32_16x16x32_bf16 v[30:33], v[152:155], v[212:215], v[30:33]
	v_mfma_f32_16x16x32_bf16 v[22:25], v[160:163], v[212:215], v[22:25]
	v_mfma_f32_16x16x32_bf16 v[14:17], v[152:155], v[220:223], v[14:17]
	v_mfma_f32_16x16x32_bf16 v[6:9], v[160:163], v[220:223], v[6:9]
	s_setprio 0
	s_setprio 1
	v_mfma_f32_16x16x32_bf16 v[58:61], v[164:167], v[180:183], 0
	v_mfma_f32_16x16x32_bf16 v[50:53], v[172:175], v[180:183], 0
	v_mfma_f32_16x16x32_bf16 v[42:45], v[164:167], v[200:203], 0
	v_mfma_f32_16x16x32_bf16 v[34:37], v[172:175], v[200:203], 0
	v_mfma_f32_16x16x32_bf16 v[26:29], v[164:167], v[208:211], 0
	v_mfma_f32_16x16x32_bf16 v[18:21], v[172:175], v[208:211], 0
	v_mfma_f32_16x16x32_bf16 v[10:13], v[164:167], v[216:219], 0
	v_mfma_f32_16x16x32_bf16 v[2:5], v[172:175], v[216:219], 0
	v_mfma_f32_16x16x32_bf16 v[58:61], v[168:171], v[196:199], v[58:61]
	v_mfma_f32_16x16x32_bf16 v[50:53], v[176:179], v[196:199], v[50:53]
	v_mfma_f32_16x16x32_bf16 v[42:45], v[168:171], v[204:207], v[42:45]
	v_mfma_f32_16x16x32_bf16 v[34:37], v[176:179], v[204:207], v[34:37]
	v_mfma_f32_16x16x32_bf16 v[26:29], v[168:171], v[212:215], v[26:29]
	v_mfma_f32_16x16x32_bf16 v[18:21], v[176:179], v[212:215], v[18:21]
	v_mfma_f32_16x16x32_bf16 v[10:13], v[168:171], v[220:223], v[10:13]
	v_mfma_f32_16x16x32_bf16 v[2:5], v[176:179], v[220:223], v[2:5]
	s_setprio 0
	s_barrier
	s_branch .Lmid_1340
.LBB0_1340:
	s_add_u32 s28, s26, 0x4000
	s_addc_u32 s29, s27, 0
	s_cmp_eq_u32 s83, 28
	s_cselect_b32 s34, s19, s28
	s_cselect_b32 s35, s1, s29
	s_cselect_b32 s30, s72, s73
	s_cselect_b32 s31, s15, s81
	s_add_u32 s28, s34, 0x8000
	s_addc_u32 s29, s35, 0
	s_add_i32 s52, 0, 0x10000
	v_add_u32_e32 v142, s52, v145
	s_add_i32 s75, 0, 0x14000
	ds_read_b128 v[148:151], v142
	ds_read_b128 v[152:155], v142 offset:1024
	ds_read_b128 v[156:159], v142 offset:2048
	ds_read_b128 v[160:163], v142 offset:3072
	v_add_u32_e32 v142, s75, v145
	ds_read_b128 v[164:167], v142
	ds_read_b128 v[168:171], v142 offset:1024
	ds_read_b128 v[172:175], v142 offset:2048
	ds_read_b128 v[176:179], v142 offset:3072
	v_lshl_add_u64 v[142:143], s[26:27], 0, v[138:139]
	s_add_i32 m0, s25, 0xc000
	ds_read_b128 v[180:183], v146
	ds_read_b128 v[196:199], v146 offset:1024
	ds_read_b128 v[200:203], v146 offset:2048
	ds_read_b128 v[204:207], v146 offset:3072
	ds_read_b128 v[208:211], v146 offset:4096
	ds_read_b128 v[212:215], v146 offset:5120
	ds_read_b128 v[216:219], v146 offset:6144
	ds_read_b128 v[220:223], v146 offset:7168
	global_load_lds_dwordx4 v[142:143], off
	v_lshl_add_u64 v[142:143], s[26:27], 0, v[140:141]
	s_add_i32 m0, s25, 0xe000
	s_nop 0
	global_load_lds_dwordx4 v[142:143], off
	s_waitcnt vmcnt(8)
	s_waitcnt lgkmcnt(0)
	s_barrier
	s_setprio 1
	s_waitcnt lgkmcnt(0)
	v_mfma_f32_16x16x32_bf16 v[126:129], v[148:151], v[180:183], v[126:129]
	v_mfma_f32_16x16x32_bf16 v[118:121], v[156:159], v[180:183], v[118:121]
	v_mfma_f32_16x16x32_bf16 v[110:113], v[148:151], v[200:203], v[110:113]
	v_mfma_f32_16x16x32_bf16 v[102:105], v[156:159], v[200:203], v[102:105]
	v_mfma_f32_16x16x32_bf16 v[94:97], v[148:151], v[208:211], v[94:97]
	v_mfma_f32_16x16x32_bf16 v[86:89], v[156:159], v[208:211], v[86:89]
	v_mfma_f32_16x16x32_bf16 v[78:81], v[148:151], v[216:219], v[78:81]
	v_mfma_f32_16x16x32_bf16 v[70:73], v[156:159], v[216:219], v[70:73]
	v_mfma_f32_16x16x32_bf16 v[126:129], v[152:155], v[196:199], v[126:129]
	v_mfma_f32_16x16x32_bf16 v[118:121], v[160:163], v[196:199], v[118:121]
	v_mfma_f32_16x16x32_bf16 v[110:113], v[152:155], v[204:207], v[110:113]
	v_mfma_f32_16x16x32_bf16 v[102:105], v[160:163], v[204:207], v[102:105]
	v_mfma_f32_16x16x32_bf16 v[94:97], v[152:155], v[212:215], v[94:97]
	v_mfma_f32_16x16x32_bf16 v[86:89], v[160:163], v[212:215], v[86:89]
	v_mfma_f32_16x16x32_bf16 v[78:81], v[152:155], v[220:223], v[78:81]
	v_mfma_f32_16x16x32_bf16 v[70:73], v[160:163], v[220:223], v[70:73]
	s_setprio 0
	s_setprio 1
	v_mfma_f32_16x16x32_bf16 v[122:125], v[164:167], v[180:183], v[122:125]
	v_mfma_f32_16x16x32_bf16 v[114:117], v[172:175], v[180:183], v[114:117]
	v_mfma_f32_16x16x32_bf16 v[106:109], v[164:167], v[200:203], v[106:109]
	v_mfma_f32_16x16x32_bf16 v[98:101], v[172:175], v[200:203], v[98:101]
	v_mfma_f32_16x16x32_bf16 v[90:93], v[164:167], v[208:211], v[90:93]
	v_mfma_f32_16x16x32_bf16 v[82:85], v[172:175], v[208:211], v[82:85]
	v_mfma_f32_16x16x32_bf16 v[74:77], v[164:167], v[216:219], v[74:77]
	v_mfma_f32_16x16x32_bf16 v[66:69], v[172:175], v[216:219], v[66:69]
	v_mfma_f32_16x16x32_bf16 v[122:125], v[168:171], v[196:199], v[122:125]
	v_mfma_f32_16x16x32_bf16 v[114:117], v[176:179], v[196:199], v[114:117]
	v_mfma_f32_16x16x32_bf16 v[106:109], v[168:171], v[204:207], v[106:109]
	v_mfma_f32_16x16x32_bf16 v[98:101], v[176:179], v[204:207], v[98:101]
	v_mfma_f32_16x16x32_bf16 v[90:93], v[168:171], v[212:215], v[90:93]
	v_mfma_f32_16x16x32_bf16 v[82:85], v[176:179], v[212:215], v[82:85]
	v_mfma_f32_16x16x32_bf16 v[74:77], v[168:171], v[220:223], v[74:77]
	v_mfma_f32_16x16x32_bf16 v[66:69], v[176:179], v[220:223], v[66:69]
	s_setprio 0
	s_barrier
; #define PG8_STAGE(bufoff, gbase, voff) do { _Pragma("unroll") for (int _i = 0; _i < 2; ++_i) \
;         __builtin_amdgcn_global_load_lds((const unsigned*)((const char*)(gbase) + (voff)[_i]), (PG8_LAS unsigned*)(lds + (bufoff) + ldsw + _i * 8192), 16, 0, 0); } while (0)
; #define PG8_LDA(dst, b, h) do { _Pragma("unroll") for (int m = 0; m < 4; ++m) _Pragma("unroll") for (int k = 0; k < 2; ++k) dst[m][k] = *(const PG8_LAS bf16x8*)(lds + PG8_SA(b, h) + aoff + m * 2048 + k * 1024); } while (0)
; #define PG8_LDB(dst, b, h) do { _Pragma("unroll") for (int n = 0; n < 2; ++n) _Pragma("unroll") for (int k = 0; k < 2; ++k) dst[n][k] = *(const PG8_LAS bf16x8*)(lds + PG8_SB(b, h) + boff + n * 2048 + k * 1024); } while (0)
; #define PG8_MMA(ai, bj, At, Bt) do { __builtin_amdgcn_s_setprio(1); _Pragma("unroll") for (int m = 0; m < 4; ++m) _Pragma("unroll") for (int n = 0; n < 2; ++n) _Pragma("unroll") for (int k = 0; k < 2; ++k) \
;         acc[ai][bj][m][n] = __builtin_amdgcn_mfma_f32_16x16x32_bf16(Bt[n][k], At[m][k], acc[ai][bj][m][n], 0, 0, 0); __builtin_amdgcn_s_setprio(0); } while (0)
; #define PG8_WAIT_V(n) asm volatile("s_waitcnt vmcnt(" #n ")" ::: "memory")
; #define PG8_WAIT_L(n) asm volatile("s_waitcnt lgkmcnt(" #n ")" ::: "memory")
; #define PG8_BAR __builtin_amdgcn_s_barrier()
; #define PG8_SCHED __builtin_amdgcn_sched_barrier(0)
; template <class Epi, class Sched, bool ALIGN_EPI = false, bool SP2 = false, bool ABLK = false, bool BBLK = false>
; __device__ __forceinline__ void gemm_phase(PG8_LAS unsigned char* lds, const Gemm g, const Sched& S, const Epi& E) {
;     ...
;             PG8_LDA(At, 0, 1); PG8_STAGE(PG8_SB(0, 0), b2, voffB); PG8_STAGE(PG8_SB(0, 1), b2 + hstepB, voffB); PG8_STAGE(PG8_SA(0, 0), a2, voffA);
;             PG8_WAIT_V(8); PG8_WAIT_L(0); PG8_BAR; PG8_MMA(1, 0, At, B0); PG8_MMA(1, 1, At, B1); PG8_BAR; PG8_SCHED;
;             PG8_LDB(B0, 1, 0); PG8_LDB(B1, 1, 1); PG8_SCHED; PG8_LDA(At, 1, 0); PG8_STAGE(PG8_SA(0, 1), a2 + hstepA, voffA);
;             PG8_WAIT_V(8); PG8_WAIT_L(0); PG8_BAR; PG8_MMA(0, 0, At, B0); PG8_MMA(0, 1, At, B1); PG8_BAR; PG8_SCHED;
	s_add_i32 s52, s52, s44
	v_lshl_add_u64 v[142:143], s[30:31], 0, v[134:135]
	s_mov_b32 m0, s52
	ds_read_b128 v[180:183], v146 offset:16384
	ds_read_b128 v[196:199], v146 offset:17408
	ds_read_b128 v[200:203], v146 offset:18432
	ds_read_b128 v[204:207], v146 offset:19456
	ds_read_b128 v[208:211], v146 offset:20480
	ds_read_b128 v[212:215], v146 offset:21504
	ds_read_b128 v[216:219], v146 offset:22528
	ds_read_b128 v[220:223], v146 offset:23552
	global_load_lds_dwordx4 v[142:143], off
	s_add_i32 m0, s52, 0x2000
	s_add_u32 s88, s30, 0x4000
	v_lshl_add_u64 v[142:143], s[30:31], 0, v[130:131]
	s_addc_u32 s89, s31, 0
	s_add_i32 s52, s75, s44
	global_load_lds_dwordx4 v[142:143], off
	v_lshl_add_u64 v[142:143], s[88:89], 0, v[134:135]
	s_mov_b32 m0, s52
	s_nop 0
	global_load_lds_dwordx4 v[142:143], off
	v_lshl_add_u64 v[142:143], s[88:89], 0, v[130:131]
	s_add_i32 m0, s52, 0x2000
	s_nop 0
	global_load_lds_dwordx4 v[142:143], off
	v_lshl_add_u64 v[142:143], s[34:35], 0, v[136:137]
	s_mov_b32 m0, s25
	s_nop 0
	global_load_lds_dwordx4 v[142:143], off
	v_lshl_add_u64 v[142:143], s[34:35], 0, v[132:133]
	s_mov_b32 m0, s46
	s_nop 0
	global_load_lds_dwordx4 v[142:143], off
	s_waitcnt vmcnt(8)
	s_waitcnt lgkmcnt(0)
	s_barrier
	s_setprio 1
	s_waitcnt lgkmcnt(0)
	v_mfma_f32_16x16x32_bf16 v[62:65], v[148:151], v[180:183], v[62:65]
	v_mfma_f32_16x16x32_bf16 v[54:57], v[156:159], v[180:183], v[54:57]
	v_mfma_f32_16x16x32_bf16 v[46:49], v[148:151], v[200:203], v[46:49]
	v_mfma_f32_16x16x32_bf16 v[38:41], v[156:159], v[200:203], v[38:41]
	v_mfma_f32_16x16x32_bf16 v[30:33], v[148:151], v[208:211], v[30:33]
	v_mfma_f32_16x16x32_bf16 v[22:25], v[156:159], v[208:211], v[22:25]
	v_mfma_f32_16x16x32_bf16 v[14:17], v[148:151], v[216:219], v[14:17]
	v_mfma_f32_16x16x32_bf16 v[6:9], v[156:159], v[216:219], v[6:9]
	v_mfma_f32_16x16x32_bf16 v[62:65], v[152:155], v[196:199], v[62:65]
	v_mfma_f32_16x16x32_bf16 v[54:57], v[160:163], v[196:199], v[54:57]
	v_mfma_f32_16x16x32_bf16 v[46:49], v[152:155], v[204:207], v[46:49]
	v_mfma_f32_16x16x32_bf16 v[38:41], v[160:163], v[204:207], v[38:41]
	v_mfma_f32_16x16x32_bf16 v[30:33], v[152:155], v[212:215], v[30:33]
	v_mfma_f32_16x16x32_bf16 v[22:25], v[160:163], v[212:215], v[22:25]
	v_mfma_f32_16x16x32_bf16 v[14:17], v[152:155], v[220:223], v[14:17]
	v_mfma_f32_16x16x32_bf16 v[6:9], v[160:163], v[220:223], v[6:9]
	s_setprio 0
	s_setprio 1
	v_mfma_f32_16x16x32_bf16 v[58:61], v[164:167], v[180:183], v[58:61]
	v_mfma_f32_16x16x32_bf16 v[50:53], v[172:175], v[180:183], v[50:53]
	v_mfma_f32_16x16x32_bf16 v[42:45], v[164:167], v[200:203], v[42:45]
	v_mfma_f32_16x16x32_bf16 v[34:37], v[172:175], v[200:203], v[34:37]
	v_mfma_f32_16x16x32_bf16 v[26:29], v[164:167], v[208:211], v[26:29]
	v_mfma_f32_16x16x32_bf16 v[18:21], v[172:175], v[208:211], v[18:21]
	v_mfma_f32_16x16x32_bf16 v[10:13], v[164:167], v[216:219], v[10:13]
	v_mfma_f32_16x16x32_bf16 v[2:5], v[172:175], v[216:219], v[2:5]
	v_mfma_f32_16x16x32_bf16 v[58:61], v[168:171], v[196:199], v[58:61]
	v_mfma_f32_16x16x32_bf16 v[50:53], v[176:179], v[196:199], v[50:53]
	v_mfma_f32_16x16x32_bf16 v[42:45], v[168:171], v[204:207], v[42:45]
	v_mfma_f32_16x16x32_bf16 v[34:37], v[176:179], v[204:207], v[34:37]
	v_mfma_f32_16x16x32_bf16 v[26:29], v[168:171], v[212:215], v[26:29]
	v_mfma_f32_16x16x32_bf16 v[18:21], v[176:179], v[212:215], v[18:21]
	v_mfma_f32_16x16x32_bf16 v[10:13], v[168:171], v[220:223], v[10:13]
	v_mfma_f32_16x16x32_bf16 v[2:5], v[176:179], v[220:223], v[2:5]
	s_setprio 0
	s_barrier
.Lmid_1340:
	s_add_i32 s52, 0, 0x18000
	v_add_u32_e32 v142, s52, v145
	s_add_i32 s75, 0, 0x1c000
	ds_read_b128 v[148:151], v142
	ds_read_b128 v[152:155], v142 offset:1024
	ds_read_b128 v[156:159], v142 offset:2048
	ds_read_b128 v[160:163], v142 offset:3072
	v_add_u32_e32 v142, s75, v145
	ds_read_b128 v[164:167], v142
	ds_read_b128 v[168:171], v142 offset:1024
	ds_read_b128 v[172:175], v142 offset:2048
	ds_read_b128 v[176:179], v142 offset:3072
	s_add_u32 s34, s34, 0x4000
	s_addc_u32 s35, s35, 0
	s_mov_b32 m0, s47
	v_lshl_add_u64 v[142:143], s[34:35], 0, v[136:137]
	ds_read_b128 v[180:183], v146 offset:32768
	ds_read_b128 v[196:199], v146 offset:33792
	ds_read_b128 v[200:203], v146 offset:34816
	ds_read_b128 v[204:207], v146 offset:35840
	ds_read_b128 v[208:211], v146 offset:36864
	ds_read_b128 v[212:215], v146 offset:37888
	ds_read_b128 v[216:219], v146 offset:38912
	ds_read_b128 v[220:223], v146 offset:39936
	global_load_lds_dwordx4 v[142:143], off
	v_lshl_add_u64 v[142:143], s[34:35], 0, v[132:133]
	s_mov_b32 m0, s50
	s_nop 0
	global_load_lds_dwordx4 v[142:143], off
	s_waitcnt vmcnt(8)
	s_waitcnt lgkmcnt(0)
	s_barrier
; #define PG8_STAGE(bufoff, gbase, voff) do { _Pragma("unroll") for (int _i = 0; _i < 2; ++_i) \
;         __builtin_amdgcn_global_load_lds((const unsigned*)((const char*)(gbase) + (voff)[_i]), (PG8_LAS unsigned*)(lds + (bufoff) + ldsw + _i * 8192), 16, 0, 0); } while (0)
; #define PG8_WAIT_V(n) asm volatile("s_waitcnt vmcnt(" #n ")" ::: "memory")
; #define PG8_BAR __builtin_amdgcn_s_barrier()
; template <class Epi, class Sched, bool ALIGN_EPI = false, bool SP2 = false, bool ABLK = false, bool BBLK = false>
; __device__ __forceinline__ void gemm_phase(PG8_LAS unsigned char* lds, const Gemm g, const Sched& S, const Epi& E) {
;     ...
;             PG8_WAIT_V(8); PG8_WAIT_L(0); PG8_BAR; PG8_MMA(0, 0, At, B0); PG8_MMA(0, 1, At, B1); PG8_BAR; PG8_SCHED;
;             PG8_LDA(At, 1, 1); PG8_STAGE(PG8_SB(1, 0), b3, voffB); PG8_STAGE(PG8_SB(1, 1), b3 + hstepB, voffB); PG8_STAGE(PG8_SA(1, 0), a3, voffA);
;             PG8_WAIT_V(8); PG8_WAIT_L(0); PG8_BAR; PG8_MMA(1, 0, At, B0); PG8_MMA(1, 1, At, B1); PG8_BAR; PG8_SCHED;
;             } else {
;             PG8_LDB(B0, 0, 0); PG8_SCHED; PG8_LDA(At, 0, 0); PG8_STAGE(PG8_SA(1, 1), a1 + hstepA, voffA);
;             PG8_WAIT_L(8); PG8_BAR; PG8_WAIT_L(0); PG8_MMA(0, 0, At, B0); PG8_BAR; PG8_SCHED;
;             PG8_LDB(B1, 0, 1); PG8_STAGE(PG8_SB(0, 0), b2, voffB);
;             PG8_BAR; PG8_WAIT_L(0); PG8_MMA(0, 1, At, B1); PG8_BAR;
;             PG8_LDA(At, 0, 1); PG8_STAGE(PG8_SA(0, 0), a2, voffA);
;             PG8_BAR; PG8_WAIT_L(0); PG8_MMA(1, 0, At, B0); PG8_BAR; PG8_SCHED;
;             PG8_STAGE(PG8_SB(0, 1), b2 + hstepB, voffB);
;             PG8_WAIT_V(6); PG8_BAR; PG8_MMA(1, 1, At, B1); PG8_BAR;
;             PG8_LDB(B0, 1, 0); PG8_SCHED; PG8_LDA(At, 1, 0); PG8_STAGE(PG8_SA(0, 1), a2 + hstepA, voffA);
;             PG8_WAIT_L(8); PG8_BAR; PG8_WAIT_L(0); PG8_MMA(0, 0, At, B0); PG8_BAR; PG8_SCHED;
;             PG8_LDB(B1, 1, 1); PG8_STAGE(PG8_SB(1, 0), b3, voffB);
;             PG8_BAR; PG8_WAIT_L(0); PG8_MMA(0, 1, At, B1); PG8_BAR;
;             PG8_LDA(At, 1, 1); PG8_STAGE(PG8_SA(1, 0), a3, voffA);
;             PG8_BAR; PG8_WAIT_L(0); PG8_MMA(1, 0, At, B0); PG8_BAR; PG8_SCHED;
;             PG8_STAGE(PG8_SB(1, 1), b3 + hstepB, voffB);
;             PG8_WAIT_V(6); PG8_BAR; PG8_MMA(1, 1, At, B1); PG8_BAR;
;             }
;         }
;         if constexpr (ALIGN_EPI) { if (wr == 0) PG8_BAR; }
	s_setprio 1
	s_waitcnt lgkmcnt(0)
	v_mfma_f32_16x16x32_bf16 v[126:129], v[148:151], v[180:183], v[126:129]
	v_mfma_f32_16x16x32_bf16 v[118:121], v[156:159], v[180:183], v[118:121]
	v_mfma_f32_16x16x32_bf16 v[110:113], v[148:151], v[200:203], v[110:113]
	v_mfma_f32_16x16x32_bf16 v[102:105], v[156:159], v[200:203], v[102:105]
	v_mfma_f32_16x16x32_bf16 v[94:97], v[148:151], v[208:211], v[94:97]
	v_mfma_f32_16x16x32_bf16 v[86:89], v[156:159], v[208:211], v[86:89]
	v_mfma_f32_16x16x32_bf16 v[78:81], v[148:151], v[216:219], v[78:81]
	v_mfma_f32_16x16x32_bf16 v[70:73], v[156:159], v[216:219], v[70:73]
	v_mfma_f32_16x16x32_bf16 v[126:129], v[152:155], v[196:199], v[126:129]
	v_mfma_f32_16x16x32_bf16 v[118:121], v[160:163], v[196:199], v[118:121]
	v_mfma_f32_16x16x32_bf16 v[110:113], v[152:155], v[204:207], v[110:113]
	v_mfma_f32_16x16x32_bf16 v[102:105], v[160:163], v[204:207], v[102:105]
	v_mfma_f32_16x16x32_bf16 v[94:97], v[152:155], v[212:215], v[94:97]
	v_mfma_f32_16x16x32_bf16 v[86:89], v[160:163], v[212:215], v[86:89]
	v_mfma_f32_16x16x32_bf16 v[78:81], v[152:155], v[220:223], v[78:81]
	v_mfma_f32_16x16x32_bf16 v[70:73], v[160:163], v[220:223], v[70:73]
	s_setprio 0
	s_setprio 1
	v_mfma_f32_16x16x32_bf16 v[122:125], v[164:167], v[180:183], v[122:125]
	v_mfma_f32_16x16x32_bf16 v[114:117], v[172:175], v[180:183], v[114:117]
	v_mfma_f32_16x16x32_bf16 v[106:109], v[164:167], v[200:203], v[106:109]
	v_mfma_f32_16x16x32_bf16 v[98:101], v[172:175], v[200:203], v[98:101]
	v_mfma_f32_16x16x32_bf16 v[90:93], v[164:167], v[208:211], v[90:93]
	v_mfma_f32_16x16x32_bf16 v[82:85], v[172:175], v[208:211], v[82:85]
	v_mfma_f32_16x16x32_bf16 v[74:77], v[164:167], v[216:219], v[74:77]
	v_mfma_f32_16x16x32_bf16 v[66:69], v[172:175], v[216:219], v[66:69]
	v_mfma_f32_16x16x32_bf16 v[122:125], v[168:171], v[196:199], v[122:125]
	v_mfma_f32_16x16x32_bf16 v[114:117], v[176:179], v[196:199], v[114:117]
	v_mfma_f32_16x16x32_bf16 v[106:109], v[168:171], v[204:207], v[106:109]
	v_mfma_f32_16x16x32_bf16 v[98:101], v[176:179], v[204:207], v[98:101]
	v_mfma_f32_16x16x32_bf16 v[90:93], v[168:171], v[212:215], v[90:93]
	v_mfma_f32_16x16x32_bf16 v[82:85], v[176:179], v[212:215], v[82:85]
	v_mfma_f32_16x16x32_bf16 v[74:77], v[168:171], v[220:223], v[74:77]
	v_mfma_f32_16x16x32_bf16 v[66:69], v[176:179], v[220:223], v[66:69]
	s_setprio 0
	s_barrier
	s_add_u32 s34, s30, 0x8000
	s_addc_u32 s35, s31, 0
	s_add_i32 s52, s52, s44
	v_lshl_add_u64 v[142:143], s[34:35], 0, v[134:135]
	s_mov_b32 m0, s52
	ds_read_b128 v[180:183], v146 offset:49152
	ds_read_b128 v[196:199], v146 offset:50176
	ds_read_b128 v[200:203], v146 offset:51200
	ds_read_b128 v[204:207], v146 offset:52224
	ds_read_b128 v[208:211], v146 offset:53248
	ds_read_b128 v[212:215], v146 offset:54272
	ds_read_b128 v[216:219], v146 offset:55296
	ds_read_b128 v[220:223], v146 offset:56320
	global_load_lds_dwordx4 v[142:143], off
	s_add_i32 m0, s52, 0x2000
	s_add_u32 s30, s30, 0xc000
	v_lshl_add_u64 v[142:143], s[34:35], 0, v[130:131]
	s_addc_u32 s31, s31, 0
	s_add_i32 s34, s75, s44
	global_load_lds_dwordx4 v[142:143], off
	v_lshl_add_u64 v[142:143], s[30:31], 0, v[134:135]
	s_mov_b32 m0, s34
	s_nop 0
	global_load_lds_dwordx4 v[142:143], off
	v_lshl_add_u64 v[142:143], s[30:31], 0, v[130:131]
	s_add_i32 m0, s34, 0x2000
	s_nop 0
	global_load_lds_dwordx4 v[142:143], off
	v_lshl_add_u64 v[142:143], s[28:29], 0, v[136:137]
	s_mov_b32 m0, s56
	s_nop 0
	global_load_lds_dwordx4 v[142:143], off
	v_lshl_add_u64 v[142:143], s[28:29], 0, v[132:133]
	s_mov_b32 m0, s60
	s_nop 0
	global_load_lds_dwordx4 v[142:143], off
	s_waitcnt vmcnt(8)
	s_waitcnt lgkmcnt(0)
	s_barrier
	s_setprio 1
	s_waitcnt lgkmcnt(0)
	v_mfma_f32_16x16x32_bf16 v[62:65], v[148:151], v[180:183], v[62:65]
	v_mfma_f32_16x16x32_bf16 v[54:57], v[156:159], v[180:183], v[54:57]
	v_mfma_f32_16x16x32_bf16 v[46:49], v[148:151], v[200:203], v[46:49]
	v_mfma_f32_16x16x32_bf16 v[38:41], v[156:159], v[200:203], v[38:41]
	v_mfma_f32_16x16x32_bf16 v[30:33], v[148:151], v[208:211], v[30:33]
	v_mfma_f32_16x16x32_bf16 v[22:25], v[156:159], v[208:211], v[22:25]
	v_mfma_f32_16x16x32_bf16 v[14:17], v[148:151], v[216:219], v[14:17]
	v_mfma_f32_16x16x32_bf16 v[6:9], v[156:159], v[216:219], v[6:9]
	v_mfma_f32_16x16x32_bf16 v[62:65], v[152:155], v[196:199], v[62:65]
	v_mfma_f32_16x16x32_bf16 v[54:57], v[160:163], v[196:199], v[54:57]
	v_mfma_f32_16x16x32_bf16 v[46:49], v[152:155], v[204:207], v[46:49]
	v_mfma_f32_16x16x32_bf16 v[38:41], v[160:163], v[204:207], v[38:41]
	v_mfma_f32_16x16x32_bf16 v[30:33], v[152:155], v[212:215], v[30:33]
	v_mfma_f32_16x16x32_bf16 v[22:25], v[160:163], v[212:215], v[22:25]
	v_mfma_f32_16x16x32_bf16 v[14:17], v[152:155], v[220:223], v[14:17]
	v_mfma_f32_16x16x32_bf16 v[6:9], v[160:163], v[220:223], v[6:9]
	s_setprio 0
	s_setprio 1
	v_mfma_f32_16x16x32_bf16 v[58:61], v[164:167], v[180:183], v[58:61]
	v_mfma_f32_16x16x32_bf16 v[50:53], v[172:175], v[180:183], v[50:53]
	v_mfma_f32_16x16x32_bf16 v[42:45], v[164:167], v[200:203], v[42:45]
	v_mfma_f32_16x16x32_bf16 v[34:37], v[172:175], v[200:203], v[34:37]
	v_mfma_f32_16x16x32_bf16 v[26:29], v[164:167], v[208:211], v[26:29]
	v_mfma_f32_16x16x32_bf16 v[18:21], v[172:175], v[208:211], v[18:21]
	v_mfma_f32_16x16x32_bf16 v[10:13], v[164:167], v[216:219], v[10:13]
	v_mfma_f32_16x16x32_bf16 v[2:5], v[172:175], v[216:219], v[2:5]
	v_mfma_f32_16x16x32_bf16 v[58:61], v[168:171], v[196:199], v[58:61]
	v_mfma_f32_16x16x32_bf16 v[50:53], v[176:179], v[196:199], v[50:53]
	v_mfma_f32_16x16x32_bf16 v[42:45], v[168:171], v[204:207], v[42:45]
	v_mfma_f32_16x16x32_bf16 v[34:37], v[176:179], v[204:207], v[34:37]
	v_mfma_f32_16x16x32_bf16 v[26:29], v[168:171], v[212:215], v[26:29]
	v_mfma_f32_16x16x32_bf16 v[18:21], v[176:179], v[212:215], v[18:21]
	v_mfma_f32_16x16x32_bf16 v[10:13], v[168:171], v[220:223], v[10:13]
	v_mfma_f32_16x16x32_bf16 v[2:5], v[176:179], v[220:223], v[2:5]
	s_setprio 0
	s_barrier
	s_add_i32 s83, s83, 2
	s_add_u32 s26, s26, 0x10000
	s_addc_u32 s27, s27, 0
	s_add_u32 s73, s73, 0x10000
	s_addc_u32 s81, s81, 0
	s_cmp_gt_u32 s83, 29
	s_cbranch_scc0 .LBB0_1340
	s_and_b64 vcc, exec, s[12:13]
	s_cbranch_vccz .LBB0_1343
	s_barrier

; #define PG8_STAGE(bufoff, gbase, voff) do { _Pragma("unroll") for (int _i = 0; _i < 2; ++_i) \
;         __builtin_amdgcn_global_load_lds((const unsigned*)((const char*)(gbase) + (voff)[_i]), (PG8_LAS unsigned*)(lds + (bufoff) + ldsw + _i * 8192), 16, 0, 0); } while (0)
; #define PG8_LDA(dst, b, h) do { _Pragma("unroll") for (int m = 0; m < 4; ++m) _Pragma("unroll") for (int k = 0; k < 2; ++k) dst[m][k] = *(const PG8_LAS bf16x8*)(lds + PG8_SA(b, h) + aoff + m * 2048 + k * 1024); } while (0)
; #define PG8_LDB(dst, b, h) do { _Pragma("unroll") for (int n = 0; n < 2; ++n) _Pragma("unroll") for (int k = 0; k < 2; ++k) dst[n][k] = *(const PG8_LAS bf16x8*)(lds + PG8_SB(b, h) + boff + n * 2048 + k * 1024); } while (0)
; #define PG8_WAIT_V(n) asm volatile("s_waitcnt vmcnt(" #n ")" ::: "memory")
; #define PG8_WAIT_L(n) asm volatile("s_waitcnt lgkmcnt(" #n ")" ::: "memory")
; #define PG8_BAR __builtin_amdgcn_s_barrier()
; #define PG8_SCHED __builtin_amdgcn_sched_barrier(0)
; template <class Epi, class Sched, bool ALIGN_EPI = false, bool SP2 = false, bool ABLK = false, bool BBLK = false>
; __device__ __forceinline__ void gemm_phase(PG8_LAS unsigned char* lds, const Gemm g, const Sched& S, const Epi& E) {
;     ...
;         const bool has_next = S.next(ui + 1, nxt);
;         const char* nA = has_next ? (const char*)g.A + (size_t)nxt.pm * tstepA : cA; const char* nB = has_next ? (const char*)g.Bt + (size_t)nxt.pn * tstepB : cB;
;         for (int t = 0; t < nt; t += 2) {
;             const bool last = (t == nt - 2);
;             const char* a1 = cA + (size_t)(t + 1) * kstepA;
;             const char* a2 = last ? nA : cA + (size_t)(t + 2) * kstepA; const char* b2 = last ? nB : cB + (size_t)(t + 2) * kstepB;
;             const char* a3 = a2 + kstepA; const char* b3 = b2 + kstepB;
;             if (last && has_next) S.a_ready(nxt);
;             if constexpr (SP2) {
;             PG8_LDB(B0, 0, 0); PG8_LDB(B1, 0, 1); PG8_SCHED; PG8_LDA(At, 0, 0); PG8_STAGE(PG8_SA(1, 1), a1 + hstepA, voffA);
;             PG8_WAIT_V(8); PG8_WAIT_L(0); PG8_BAR; PG8_MMA(0, 0, At, B0); PG8_MMA(0, 1, At, B1); PG8_BAR; PG8_SCHED;
;             PG8_LDA(At, 0, 1); PG8_STAGE(PG8_SB(0, 0), b2, voffB); PG8_STAGE(PG8_SB(0, 1), b2 + hstepB, voffB); PG8_STAGE(PG8_SA(0, 0), a2, voffA);
;             PG8_WAIT_V(8); PG8_WAIT_L(0); PG8_BAR; PG8_MMA(1, 0, At, B0); PG8_MMA(1, 1, At, B1); PG8_BAR; PG8_SCHED;
.LBB0_1419:
	s_add_u32 s0, s0, 0xc000
	s_addc_u32 s1, s1, 0
	s_add_u32 s23, s26, 0x10000
	v_mov_b32_e32 v2, 0
	s_addc_u32 s25, s27, 0
	s_mov_b32 s73, -2
	s_add_u32 s8, s0, 0x4000
	s_addc_u32 s9, s1, 0
	s_cmpk_eq_i32 s73, 0x54
	s_cselect_b32 s28, s18, s8
	s_cselect_b32 s29, s19, s9
	s_cselect_b32 s26, s20, s23
	s_cselect_b32 s27, s21, s25
	s_add_u32 s8, s28, 0x8000
	s_addc_u32 s9, s29, 0
	s_add_i32 s52, 0, 0x10000
	s_add_i32 s75, 0, 0x14000
	v_add_u32_e32 v142, s52, v180
	v_add_u32_e32 v168, s75, v180
	ds_read_b128 v[130:133], v142
	ds_read_b128 v[134:137], v142 offset:1024
	ds_read_b128 v[138:141], v142 offset:2048
	ds_read_b128 v[142:145], v142 offset:3072
	ds_read_b128 v[156:159], v168
	ds_read_b128 v[160:163], v168 offset:1024
	ds_read_b128 v[164:167], v168 offset:2048
	ds_read_b128 v[168:171], v168 offset:3072
	v_lshl_add_u64 v[176:177], s[0:1], 0, v[152:153]
	s_add_i32 m0, s3, 0xc000
	ds_read_b128 v[172:175], v181
	ds_read_b128 v[182:185], v181 offset:1024
	ds_read_b128 v[196:199], v181 offset:2048
	ds_read_b128 v[200:203], v181 offset:3072
	ds_read_b128 v[204:207], v181 offset:4096
	ds_read_b128 v[208:211], v181 offset:5120
	ds_read_b128 v[212:215], v181 offset:6144
	ds_read_b128 v[216:219], v181 offset:7168
	global_load_lds_dwordx4 v[176:177], off
	v_lshl_add_u64 v[176:177], s[0:1], 0, v[154:155]
	s_add_i32 m0, s3, 0xe000
	s_nop 0
	global_load_lds_dwordx4 v[176:177], off
	s_waitcnt vmcnt(8)
	s_waitcnt lgkmcnt(0)
	s_barrier
	s_setprio 1
	s_waitcnt lgkmcnt(0)
	v_mfma_f32_16x16x32_bf16 v[58:61], v[130:133], v[172:175], 0
	v_mfma_f32_16x16x32_bf16 v[50:53], v[138:141], v[172:175], 0
	v_mfma_f32_16x16x32_bf16 v[78:81], v[130:133], v[196:199], 0
	v_mfma_f32_16x16x32_bf16 v[70:73], v[138:141], v[196:199], 0
	v_mfma_f32_16x16x32_bf16 v[98:101], v[130:133], v[204:207], 0
	v_mfma_f32_16x16x32_bf16 v[102:105], v[138:141], v[204:207], 0
	v_mfma_f32_16x16x32_bf16 v[114:117], v[130:133], v[212:215], 0
	v_mfma_f32_16x16x32_bf16 v[118:121], v[138:141], v[212:215], 0
	v_mfma_f32_16x16x32_bf16 v[58:61], v[134:137], v[182:185], v[58:61]
	v_mfma_f32_16x16x32_bf16 v[50:53], v[142:145], v[182:185], v[50:53]
	v_mfma_f32_16x16x32_bf16 v[78:81], v[134:137], v[200:203], v[78:81]
	v_mfma_f32_16x16x32_bf16 v[70:73], v[142:145], v[200:203], v[70:73]
	v_mfma_f32_16x16x32_bf16 v[98:101], v[134:137], v[208:211], v[98:101]
	v_mfma_f32_16x16x32_bf16 v[102:105], v[142:145], v[208:211], v[102:105]
	v_mfma_f32_16x16x32_bf16 v[114:117], v[134:137], v[216:219], v[114:117]
	v_mfma_f32_16x16x32_bf16 v[118:121], v[142:145], v[216:219], v[118:121]
	s_setprio 0
	s_setprio 1
	v_mfma_f32_16x16x32_bf16 v[66:69], v[156:159], v[172:175], 0
	v_mfma_f32_16x16x32_bf16 v[54:57], v[164:167], v[172:175], 0
	v_mfma_f32_16x16x32_bf16 v[86:89], v[156:159], v[196:199], 0
	v_mfma_f32_16x16x32_bf16 v[94:97], v[164:167], v[196:199], 0
	v_mfma_f32_16x16x32_bf16 v[106:109], v[156:159], v[204:207], 0
	v_mfma_f32_16x16x32_bf16 v[110:113], v[164:167], v[204:207], 0
	v_mfma_f32_16x16x32_bf16 v[122:125], v[156:159], v[212:215], 0
	v_mfma_f32_16x16x32_bf16 v[126:129], v[164:167], v[212:215], 0
	v_mfma_f32_16x16x32_bf16 v[66:69], v[160:163], v[182:185], v[66:69]
	v_mfma_f32_16x16x32_bf16 v[54:57], v[168:171], v[182:185], v[54:57]
	v_mfma_f32_16x16x32_bf16 v[86:89], v[160:163], v[200:203], v[86:89]
	v_mfma_f32_16x16x32_bf16 v[94:97], v[168:171], v[200:203], v[94:97]
	v_mfma_f32_16x16x32_bf16 v[106:109], v[160:163], v[208:211], v[106:109]
	v_mfma_f32_16x16x32_bf16 v[110:113], v[168:171], v[208:211], v[110:113]
	v_mfma_f32_16x16x32_bf16 v[122:125], v[160:163], v[216:219], v[122:125]
	v_mfma_f32_16x16x32_bf16 v[126:129], v[168:171], v[216:219], v[126:129]
	s_setprio 0
	s_barrier
	s_add_i32 s52, s52, s2
	v_lshl_add_u64 v[176:177], s[26:27], 0, v[186:187]
	s_mov_b32 m0, s52
	ds_read_b128 v[172:175], v181 offset:16384
	ds_read_b128 v[182:185], v181 offset:17408
	ds_read_b128 v[196:199], v181 offset:18432
	ds_read_b128 v[200:203], v181 offset:19456
	ds_read_b128 v[204:207], v181 offset:20480
	ds_read_b128 v[208:211], v181 offset:21504
	ds_read_b128 v[212:215], v181 offset:22528
	ds_read_b128 v[216:219], v181 offset:23552
	global_load_lds_dwordx4 v[176:177], off
	s_add_i32 m0, s52, 0x2000
	s_add_u32 s80, s26, 0x4000
	v_lshl_add_u64 v[176:177], s[26:27], 0, v[150:151]
	s_addc_u32 s81, s27, 0
	s_add_i32 s52, s75, s2
	global_load_lds_dwordx4 v[176:177], off
	v_lshl_add_u64 v[176:177], s[80:81], 0, v[186:187]
	s_mov_b32 m0, s52
	s_nop 0
	global_load_lds_dwordx4 v[176:177], off
	v_lshl_add_u64 v[176:177], s[80:81], 0, v[150:151]
	s_add_i32 m0, s52, 0x2000
	s_nop 0
	global_load_lds_dwordx4 v[176:177], off
	v_lshl_add_u64 v[176:177], s[28:29], 0, v[146:147]
	s_mov_b32 m0, s3
	s_nop 0
	global_load_lds_dwordx4 v[176:177], off
	v_lshl_add_u64 v[176:177], s[28:29], 0, v[148:149]
	s_mov_b32 m0, s16
	s_nop 0
	global_load_lds_dwordx4 v[176:177], off
	s_waitcnt vmcnt(8)
	s_waitcnt lgkmcnt(0)
	s_barrier
; #define PG8_STAGE(bufoff, gbase, voff) do { _Pragma("unroll") for (int _i = 0; _i < 2; ++_i) \
;         __builtin_amdgcn_global_load_lds((const unsigned*)((const char*)(gbase) + (voff)[_i]), (PG8_LAS unsigned*)(lds + (bufoff) + ldsw + _i * 8192), 16, 0, 0); } while (0)
; #define PG8_LDA(dst, b, h) do { _Pragma("unroll") for (int m = 0; m < 4; ++m) _Pragma("unroll") for (int k = 0; k < 2; ++k) dst[m][k] = *(const PG8_LAS bf16x8*)(lds + PG8_SA(b, h) + aoff + m * 2048 + k * 1024); } while (0)
; #define PG8_LDB(dst, b, h) do { _Pragma("unroll") for (int n = 0; n < 2; ++n) _Pragma("unroll") for (int k = 0; k < 2; ++k) dst[n][k] = *(const PG8_LAS bf16x8*)(lds + PG8_SB(b, h) + boff + n * 2048 + k * 1024); } while (0)
; #define PG8_MMA(ai, bj, At, Bt) do { __builtin_amdgcn_s_setprio(1); _Pragma("unroll") for (int m = 0; m < 4; ++m) _Pragma("unroll") for (int n = 0; n < 2; ++n) _Pragma("unroll") for (int k = 0; k < 2; ++k) \
;         acc[ai][bj][m][n] = __builtin_amdgcn_mfma_f32_16x16x32_bf16(Bt[n][k], At[m][k], acc[ai][bj][m][n], 0, 0, 0); __builtin_amdgcn_s_setprio(0); } while (0)
; #define PG8_WAIT_V(n) asm volatile("s_waitcnt vmcnt(" #n ")" ::: "memory")
; template <class Epi, class Sched, bool ALIGN_EPI = false, bool SP2 = false, bool ABLK = false, bool BBLK = false>
; __device__ __forceinline__ void gemm_phase(PG8_LAS unsigned char* lds, const Gemm g, const Sched& S, const Epi& E) {
;     ...
;         for (int t = 0; t < nt; t += 2) {
;             const bool last = (t == nt - 2);
;             const char* a1 = cA + (size_t)(t + 1) * kstepA;
;             const char* a2 = last ? nA : cA + (size_t)(t + 2) * kstepA; const char* b2 = last ? nB : cB + (size_t)(t + 2) * kstepB;
;             const char* a3 = a2 + kstepA; const char* b3 = b2 + kstepB;
;             if (last && has_next) S.a_ready(nxt);
;             if constexpr (SP2) {
;             PG8_LDB(B0, 0, 0); PG8_LDB(B1, 0, 1); PG8_SCHED; PG8_LDA(At, 0, 0); PG8_STAGE(PG8_SA(1, 1), a1 + hstepA, voffA);
;             PG8_WAIT_V(8); PG8_WAIT_L(0); PG8_BAR; PG8_MMA(0, 0, At, B0); PG8_MMA(0, 1, At, B1); PG8_BAR; PG8_SCHED;
;             PG8_LDA(At, 0, 1); PG8_STAGE(PG8_SB(0, 0), b2, voffB); PG8_STAGE(PG8_SB(0, 1), b2 + hstepB, voffB); PG8_STAGE(PG8_SA(0, 0), a2, voffA);
;             PG8_WAIT_V(8); PG8_WAIT_L(0); PG8_BAR; PG8_MMA(1, 0, At, B0); PG8_MMA(1, 1, At, B1); PG8_BAR; PG8_SCHED;
	s_setprio 1
	s_waitcnt lgkmcnt(0)
	v_mfma_f32_16x16x32_bf16 v[90:93], v[130:133], v[172:175], 0
	v_mfma_f32_16x16x32_bf16 v[82:85], v[138:141], v[172:175], 0
	v_mfma_f32_16x16x32_bf16 v[46:49], v[130:133], v[196:199], 0
	v_mfma_f32_16x16x32_bf16 v[42:45], v[138:141], v[196:199], 0
	v_mfma_f32_16x16x32_bf16 v[30:33], v[130:133], v[204:207], 0
	v_mfma_f32_16x16x32_bf16 v[26:29], v[138:141], v[204:207], 0
	v_mfma_f32_16x16x32_bf16 v[14:17], v[130:133], v[212:215], 0
	v_mfma_f32_16x16x32_bf16 v[10:13], v[138:141], v[212:215], 0
	v_mfma_f32_16x16x32_bf16 v[90:93], v[134:137], v[182:185], v[90:93]
	v_mfma_f32_16x16x32_bf16 v[82:85], v[142:145], v[182:185], v[82:85]
	v_mfma_f32_16x16x32_bf16 v[46:49], v[134:137], v[200:203], v[46:49]
	v_mfma_f32_16x16x32_bf16 v[42:45], v[142:145], v[200:203], v[42:45]
	v_mfma_f32_16x16x32_bf16 v[30:33], v[134:137], v[208:211], v[30:33]
	v_mfma_f32_16x16x32_bf16 v[26:29], v[142:145], v[208:211], v[26:29]
	v_mfma_f32_16x16x32_bf16 v[14:17], v[134:137], v[216:219], v[14:17]
	v_mfma_f32_16x16x32_bf16 v[10:13], v[142:145], v[216:219], v[10:13]
	s_setprio 0
	s_setprio 1
	v_mfma_f32_16x16x32_bf16 v[74:77], v[156:159], v[172:175], 0
	v_mfma_f32_16x16x32_bf16 v[62:65], v[164:167], v[172:175], 0
	v_mfma_f32_16x16x32_bf16 v[38:41], v[156:159], v[196:199], 0
	v_mfma_f32_16x16x32_bf16 v[34:37], v[164:167], v[196:199], 0
	v_mfma_f32_16x16x32_bf16 v[22:25], v[156:159], v[204:207], 0
	v_mfma_f32_16x16x32_bf16 v[18:21], v[164:167], v[204:207], 0
	v_mfma_f32_16x16x32_bf16 v[6:9], v[156:159], v[212:215], 0
	v_mfma_f32_16x16x32_bf16 v[2:5], v[164:167], v[212:215], 0
	v_mfma_f32_16x16x32_bf16 v[74:77], v[160:163], v[182:185], v[74:77]
	v_mfma_f32_16x16x32_bf16 v[62:65], v[168:171], v[182:185], v[62:65]
	v_mfma_f32_16x16x32_bf16 v[38:41], v[160:163], v[200:203], v[38:41]
	v_mfma_f32_16x16x32_bf16 v[34:37], v[168:171], v[200:203], v[34:37]
	v_mfma_f32_16x16x32_bf16 v[22:25], v[160:163], v[208:211], v[22:25]
	v_mfma_f32_16x16x32_bf16 v[18:21], v[168:171], v[208:211], v[18:21]
	v_mfma_f32_16x16x32_bf16 v[6:9], v[160:163], v[216:219], v[6:9]
	v_mfma_f32_16x16x32_bf16 v[2:5], v[168:171], v[216:219], v[2:5]
	s_setprio 0
	s_barrier
	s_branch .Lmid_1420
.LBB0_1420:
	s_add_u32 s8, s0, 0x4000
	s_addc_u32 s9, s1, 0
	s_cmpk_eq_i32 s73, 0x54
	s_cselect_b32 s28, s18, s8
	s_cselect_b32 s29, s19, s9
	s_cselect_b32 s26, s20, s23
	s_cselect_b32 s27, s21, s25
	s_add_u32 s8, s28, 0x8000
	s_addc_u32 s9, s29, 0
	s_add_i32 s52, 0, 0x10000
	s_add_i32 s75, 0, 0x14000
	v_add_u32_e32 v142, s52, v180
	v_add_u32_e32 v168, s75, v180
	ds_read_b128 v[130:133], v142
	ds_read_b128 v[134:137], v142 offset:1024
	ds_read_b128 v[138:141], v142 offset:2048
	ds_read_b128 v[142:145], v142 offset:3072
	ds_read_b128 v[156:159], v168
	ds_read_b128 v[160:163], v168 offset:1024
	ds_read_b128 v[164:167], v168 offset:2048
	ds_read_b128 v[168:171], v168 offset:3072
	v_lshl_add_u64 v[176:177], s[0:1], 0, v[152:153]
	s_add_i32 m0, s3, 0xc000
	ds_read_b128 v[172:175], v181
	ds_read_b128 v[182:185], v181 offset:1024
	ds_read_b128 v[196:199], v181 offset:2048
	ds_read_b128 v[200:203], v181 offset:3072
	ds_read_b128 v[204:207], v181 offset:4096
	ds_read_b128 v[208:211], v181 offset:5120
	ds_read_b128 v[212:215], v181 offset:6144
	ds_read_b128 v[216:219], v181 offset:7168
	global_load_lds_dwordx4 v[176:177], off
	v_lshl_add_u64 v[176:177], s[0:1], 0, v[154:155]
	s_add_i32 m0, s3, 0xe000
	s_nop 0
	global_load_lds_dwordx4 v[176:177], off
	s_waitcnt vmcnt(8)
	s_waitcnt lgkmcnt(0)
	s_barrier
	s_setprio 1
	s_waitcnt lgkmcnt(0)
	v_mfma_f32_16x16x32_bf16 v[58:61], v[130:133], v[172:175], v[58:61]
	v_mfma_f32_16x16x32_bf16 v[50:53], v[138:141], v[172:175], v[50:53]
	v_mfma_f32_16x16x32_bf16 v[78:81], v[130:133], v[196:199], v[78:81]
	v_mfma_f32_16x16x32_bf16 v[70:73], v[138:141], v[196:199], v[70:73]
	v_mfma_f32_16x16x32_bf16 v[98:101], v[130:133], v[204:207], v[98:101]
	v_mfma_f32_16x16x32_bf16 v[102:105], v[138:141], v[204:207], v[102:105]
	v_mfma_f32_16x16x32_bf16 v[114:117], v[130:133], v[212:215], v[114:117]
	v_mfma_f32_16x16x32_bf16 v[118:121], v[138:141], v[212:215], v[118:121]
	v_mfma_f32_16x16x32_bf16 v[58:61], v[134:137], v[182:185], v[58:61]
	v_mfma_f32_16x16x32_bf16 v[50:53], v[142:145], v[182:185], v[50:53]
	v_mfma_f32_16x16x32_bf16 v[78:81], v[134:137], v[200:203], v[78:81]
	v_mfma_f32_16x16x32_bf16 v[70:73], v[142:145], v[200:203], v[70:73]
	v_mfma_f32_16x16x32_bf16 v[98:101], v[134:137], v[208:211], v[98:101]
	v_mfma_f32_16x16x32_bf16 v[102:105], v[142:145], v[208:211], v[102:105]
	v_mfma_f32_16x16x32_bf16 v[114:117], v[134:137], v[216:219], v[114:117]
	v_mfma_f32_16x16x32_bf16 v[118:121], v[142:145], v[216:219], v[118:121]
	s_setprio 0
	s_setprio 1
	v_mfma_f32_16x16x32_bf16 v[66:69], v[156:159], v[172:175], v[66:69]
	v_mfma_f32_16x16x32_bf16 v[54:57], v[164:167], v[172:175], v[54:57]
	v_mfma_f32_16x16x32_bf16 v[86:89], v[156:159], v[196:199], v[86:89]
	v_mfma_f32_16x16x32_bf16 v[94:97], v[164:167], v[196:199], v[94:97]
	v_mfma_f32_16x16x32_bf16 v[106:109], v[156:159], v[204:207], v[106:109]
	v_mfma_f32_16x16x32_bf16 v[110:113], v[164:167], v[204:207], v[110:113]
	v_mfma_f32_16x16x32_bf16 v[122:125], v[156:159], v[212:215], v[122:125]
	v_mfma_f32_16x16x32_bf16 v[126:129], v[164:167], v[212:215], v[126:129]
	v_mfma_f32_16x16x32_bf16 v[66:69], v[160:163], v[182:185], v[66:69]
	v_mfma_f32_16x16x32_bf16 v[54:57], v[168:171], v[182:185], v[54:57]
	v_mfma_f32_16x16x32_bf16 v[86:89], v[160:163], v[200:203], v[86:89]
	v_mfma_f32_16x16x32_bf16 v[94:97], v[168:171], v[200:203], v[94:97]
	v_mfma_f32_16x16x32_bf16 v[106:109], v[160:163], v[208:211], v[106:109]
	v_mfma_f32_16x16x32_bf16 v[110:113], v[168:171], v[208:211], v[110:113]
	v_mfma_f32_16x16x32_bf16 v[122:125], v[160:163], v[216:219], v[122:125]
	v_mfma_f32_16x16x32_bf16 v[126:129], v[168:171], v[216:219], v[126:129]
	s_setprio 0
	s_barrier
; #define PG8_STAGE(bufoff, gbase, voff) do { _Pragma("unroll") for (int _i = 0; _i < 2; ++_i) \
;         __builtin_amdgcn_global_load_lds((const unsigned*)((const char*)(gbase) + (voff)[_i]), (PG8_LAS unsigned*)(lds + (bufoff) + ldsw + _i * 8192), 16, 0, 0); } while (0)
; #define PG8_LDA(dst, b, h) do { _Pragma("unroll") for (int m = 0; m < 4; ++m) _Pragma("unroll") for (int k = 0; k < 2; ++k) dst[m][k] = *(const PG8_LAS bf16x8*)(lds + PG8_SA(b, h) + aoff + m * 2048 + k * 1024); } while (0)
; #define PG8_LDB(dst, b, h) do { _Pragma("unroll") for (int n = 0; n < 2; ++n) _Pragma("unroll") for (int k = 0; k < 2; ++k) dst[n][k] = *(const PG8_LAS bf16x8*)(lds + PG8_SB(b, h) + boff + n * 2048 + k * 1024); } while (0)
; #define PG8_MMA(ai, bj, At, Bt) do { __builtin_amdgcn_s_setprio(1); _Pragma("unroll") for (int m = 0; m < 4; ++m) _Pragma("unroll") for (int n = 0; n < 2; ++n) _Pragma("unroll") for (int k = 0; k < 2; ++k) \
;         acc[ai][bj][m][n] = __builtin_amdgcn_mfma_f32_16x16x32_bf16(Bt[n][k], At[m][k], acc[ai][bj][m][n], 0, 0, 0); __builtin_amdgcn_s_setprio(0); } while (0)
; #define PG8_WAIT_V(n) asm volatile("s_waitcnt vmcnt(" #n ")" ::: "memory")
; #define PG8_WAIT_L(n) asm volatile("s_waitcnt lgkmcnt(" #n ")" ::: "memory")
; #define PG8_BAR __builtin_amdgcn_s_barrier()
; #define PG8_SCHED __builtin_amdgcn_sched_barrier(0)
; template <class Epi, class Sched, bool ALIGN_EPI = false, bool SP2 = false, bool ABLK = false, bool BBLK = false>
; __device__ __forceinline__ void gemm_phase(PG8_LAS unsigned char* lds, const Gemm g, const Sched& S, const Epi& E) {
;     ...
;             PG8_LDA(At, 0, 1); PG8_STAGE(PG8_SB(0, 0), b2, voffB); PG8_STAGE(PG8_SB(0, 1), b2 + hstepB, voffB); PG8_STAGE(PG8_SA(0, 0), a2, voffA);
;             PG8_WAIT_V(8); PG8_WAIT_L(0); PG8_BAR; PG8_MMA(1, 0, At, B0); PG8_MMA(1, 1, At, B1); PG8_BAR; PG8_SCHED;
;             PG8_LDB(B0, 1, 0); PG8_LDB(B1, 1, 1); PG8_SCHED; PG8_LDA(At, 1, 0); PG8_STAGE(PG8_SA(0, 1), a2 + hstepA, voffA);
;             PG8_WAIT_V(8); PG8_WAIT_L(0); PG8_BAR; PG8_MMA(0, 0, At, B0); PG8_MMA(0, 1, At, B1); PG8_BAR; PG8_SCHED;
	s_add_i32 s52, s52, s2
	v_lshl_add_u64 v[176:177], s[26:27], 0, v[186:187]
	s_mov_b32 m0, s52
	ds_read_b128 v[172:175], v181 offset:16384
	ds_read_b128 v[182:185], v181 offset:17408
	ds_read_b128 v[196:199], v181 offset:18432
	ds_read_b128 v[200:203], v181 offset:19456
	ds_read_b128 v[204:207], v181 offset:20480
	ds_read_b128 v[208:211], v181 offset:21504
	ds_read_b128 v[212:215], v181 offset:22528
	ds_read_b128 v[216:219], v181 offset:23552
	global_load_lds_dwordx4 v[176:177], off
	s_add_i32 m0, s52, 0x2000
	s_add_u32 s80, s26, 0x4000
	v_lshl_add_u64 v[176:177], s[26:27], 0, v[150:151]
	s_addc_u32 s81, s27, 0
	s_add_i32 s52, s75, s2
	global_load_lds_dwordx4 v[176:177], off
	v_lshl_add_u64 v[176:177], s[80:81], 0, v[186:187]
	s_mov_b32 m0, s52
	s_nop 0
	global_load_lds_dwordx4 v[176:177], off
	v_lshl_add_u64 v[176:177], s[80:81], 0, v[150:151]
	s_add_i32 m0, s52, 0x2000
	s_nop 0
	global_load_lds_dwordx4 v[176:177], off
	v_lshl_add_u64 v[176:177], s[28:29], 0, v[146:147]
	s_mov_b32 m0, s3
	s_nop 0
	global_load_lds_dwordx4 v[176:177], off
	v_lshl_add_u64 v[176:177], s[28:29], 0, v[148:149]
	s_mov_b32 m0, s16
	s_nop 0
	global_load_lds_dwordx4 v[176:177], off
	s_waitcnt vmcnt(8)
	s_waitcnt lgkmcnt(0)
	s_barrier
	s_setprio 1
	s_waitcnt lgkmcnt(0)
	v_mfma_f32_16x16x32_bf16 v[90:93], v[130:133], v[172:175], v[90:93]
	v_mfma_f32_16x16x32_bf16 v[82:85], v[138:141], v[172:175], v[82:85]
	v_mfma_f32_16x16x32_bf16 v[46:49], v[130:133], v[196:199], v[46:49]
	v_mfma_f32_16x16x32_bf16 v[42:45], v[138:141], v[196:199], v[42:45]
	v_mfma_f32_16x16x32_bf16 v[30:33], v[130:133], v[204:207], v[30:33]
	v_mfma_f32_16x16x32_bf16 v[26:29], v[138:141], v[204:207], v[26:29]
	v_mfma_f32_16x16x32_bf16 v[14:17], v[130:133], v[212:215], v[14:17]
	v_mfma_f32_16x16x32_bf16 v[10:13], v[138:141], v[212:215], v[10:13]
	v_mfma_f32_16x16x32_bf16 v[90:93], v[134:137], v[182:185], v[90:93]
	v_mfma_f32_16x16x32_bf16 v[82:85], v[142:145], v[182:185], v[82:85]
	v_mfma_f32_16x16x32_bf16 v[46:49], v[134:137], v[200:203], v[46:49]
	v_mfma_f32_16x16x32_bf16 v[42:45], v[142:145], v[200:203], v[42:45]
	v_mfma_f32_16x16x32_bf16 v[30:33], v[134:137], v[208:211], v[30:33]
	v_mfma_f32_16x16x32_bf16 v[26:29], v[142:145], v[208:211], v[26:29]
	v_mfma_f32_16x16x32_bf16 v[14:17], v[134:137], v[216:219], v[14:17]
	v_mfma_f32_16x16x32_bf16 v[10:13], v[142:145], v[216:219], v[10:13]
	s_setprio 0
	s_setprio 1
	v_mfma_f32_16x16x32_bf16 v[74:77], v[156:159], v[172:175], v[74:77]
	v_mfma_f32_16x16x32_bf16 v[62:65], v[164:167], v[172:175], v[62:65]
	v_mfma_f32_16x16x32_bf16 v[38:41], v[156:159], v[196:199], v[38:41]
	v_mfma_f32_16x16x32_bf16 v[34:37], v[164:167], v[196:199], v[34:37]
	v_mfma_f32_16x16x32_bf16 v[22:25], v[156:159], v[204:207], v[22:25]
	v_mfma_f32_16x16x32_bf16 v[18:21], v[164:167], v[204:207], v[18:21]
	v_mfma_f32_16x16x32_bf16 v[6:9], v[156:159], v[212:215], v[6:9]
	v_mfma_f32_16x16x32_bf16 v[2:5], v[164:167], v[212:215], v[2:5]
	v_mfma_f32_16x16x32_bf16 v[74:77], v[160:163], v[182:185], v[74:77]
	v_mfma_f32_16x16x32_bf16 v[62:65], v[168:171], v[182:185], v[62:65]
	v_mfma_f32_16x16x32_bf16 v[38:41], v[160:163], v[200:203], v[38:41]
	v_mfma_f32_16x16x32_bf16 v[34:37], v[168:171], v[200:203], v[34:37]
	v_mfma_f32_16x16x32_bf16 v[22:25], v[160:163], v[208:211], v[22:25]
	v_mfma_f32_16x16x32_bf16 v[18:21], v[168:171], v[208:211], v[18:21]
	v_mfma_f32_16x16x32_bf16 v[6:9], v[160:163], v[216:219], v[6:9]
	v_mfma_f32_16x16x32_bf16 v[2:5], v[168:171], v[216:219], v[2:5]
	s_setprio 0
	s_barrier
.Lmid_1420:
	s_add_i32 s52, 0, 0x18000
	s_add_i32 s75, 0, 0x1c000
	v_add_u32_e32 v142, s52, v180
	v_add_u32_e32 v168, s75, v180
	ds_read_b128 v[130:133], v142
	ds_read_b128 v[134:137], v142 offset:1024
	ds_read_b128 v[138:141], v142 offset:2048
	ds_read_b128 v[142:145], v142 offset:3072
	ds_read_b128 v[156:159], v168
	ds_read_b128 v[160:163], v168 offset:1024
	ds_read_b128 v[164:167], v168 offset:2048
	ds_read_b128 v[168:171], v168 offset:3072
	s_add_u32 s28, s28, 0x4000
	s_addc_u32 s29, s29, 0
	s_mov_b32 m0, s30
	v_lshl_add_u64 v[176:177], s[28:29], 0, v[146:147]
	ds_read_b128 v[172:175], v181 offset:32768
	ds_read_b128 v[182:185], v181 offset:33792
	ds_read_b128 v[196:199], v181 offset:34816
	ds_read_b128 v[200:203], v181 offset:35840
	ds_read_b128 v[204:207], v181 offset:36864
	ds_read_b128 v[208:211], v181 offset:37888
	ds_read_b128 v[212:215], v181 offset:38912
	ds_read_b128 v[216:219], v181 offset:39936
	global_load_lds_dwordx4 v[176:177], off
	v_lshl_add_u64 v[176:177], s[28:29], 0, v[148:149]
	s_mov_b32 m0, s31
	s_nop 0
	global_load_lds_dwordx4 v[176:177], off
	s_waitcnt vmcnt(8)
	s_waitcnt lgkmcnt(0)
	s_barrier
; #define PG8_STAGE(bufoff, gbase, voff) do { _Pragma("unroll") for (int _i = 0; _i < 2; ++_i) \
;         __builtin_amdgcn_global_load_lds((const unsigned*)((const char*)(gbase) + (voff)[_i]), (PG8_LAS unsigned*)(lds + (bufoff) + ldsw + _i * 8192), 16, 0, 0); } while (0)
; #define PG8_WAIT_V(n) asm volatile("s_waitcnt vmcnt(" #n ")" ::: "memory")
; #define PG8_BAR __builtin_amdgcn_s_barrier()
; template <class Epi, class Sched, bool ALIGN_EPI = false, bool SP2 = false, bool ABLK = false, bool BBLK = false>
; __device__ __forceinline__ void gemm_phase(PG8_LAS unsigned char* lds, const Gemm g, const Sched& S, const Epi& E) {
;     ...
;             PG8_WAIT_V(8); PG8_WAIT_L(0); PG8_BAR; PG8_MMA(0, 0, At, B0); PG8_MMA(0, 1, At, B1); PG8_BAR; PG8_SCHED;
;             PG8_LDA(At, 1, 1); PG8_STAGE(PG8_SB(1, 0), b3, voffB); PG8_STAGE(PG8_SB(1, 1), b3 + hstepB, voffB); PG8_STAGE(PG8_SA(1, 0), a3, voffA);
;             PG8_WAIT_V(8); PG8_WAIT_L(0); PG8_BAR; PG8_MMA(1, 0, At, B0); PG8_MMA(1, 1, At, B1); PG8_BAR; PG8_SCHED;
;             } else {
;             PG8_LDB(B0, 0, 0); PG8_SCHED; PG8_LDA(At, 0, 0); PG8_STAGE(PG8_SA(1, 1), a1 + hstepA, voffA);
;             PG8_WAIT_L(8); PG8_BAR; PG8_WAIT_L(0); PG8_MMA(0, 0, At, B0); PG8_BAR; PG8_SCHED;
;             PG8_LDB(B1, 0, 1); PG8_STAGE(PG8_SB(0, 0), b2, voffB);
;             PG8_BAR; PG8_WAIT_L(0); PG8_MMA(0, 1, At, B1); PG8_BAR;
;             PG8_LDA(At, 0, 1); PG8_STAGE(PG8_SA(0, 0), a2, voffA);
;             PG8_BAR; PG8_WAIT_L(0); PG8_MMA(1, 0, At, B0); PG8_BAR; PG8_SCHED;
;             PG8_STAGE(PG8_SB(0, 1), b2 + hstepB, voffB);
;             PG8_WAIT_V(6); PG8_BAR; PG8_MMA(1, 1, At, B1); PG8_BAR;
;             PG8_LDB(B0, 1, 0); PG8_SCHED; PG8_LDA(At, 1, 0); PG8_STAGE(PG8_SA(0, 1), a2 + hstepA, voffA);
;             PG8_WAIT_L(8); PG8_BAR; PG8_WAIT_L(0); PG8_MMA(0, 0, At, B0); PG8_BAR; PG8_SCHED;
;             PG8_LDB(B1, 1, 1); PG8_STAGE(PG8_SB(1, 0), b3, voffB);
;             PG8_BAR; PG8_WAIT_L(0); PG8_MMA(0, 1, At, B1); PG8_BAR;
;             PG8_LDA(At, 1, 1); PG8_STAGE(PG8_SA(1, 0), a3, voffA);
;             PG8_BAR; PG8_WAIT_L(0); PG8_MMA(1, 0, At, B0); PG8_BAR; PG8_SCHED;
;             PG8_STAGE(PG8_SB(1, 1), b3 + hstepB, voffB);
;             PG8_WAIT_V(6); PG8_BAR; PG8_MMA(1, 1, At, B1); PG8_BAR;
;             }
;         }
;         if constexpr (ALIGN_EPI) { if (wr == 0) PG8_BAR; }
	s_setprio 1
	s_waitcnt lgkmcnt(0)
	v_mfma_f32_16x16x32_bf16 v[58:61], v[130:133], v[172:175], v[58:61]
	v_mfma_f32_16x16x32_bf16 v[50:53], v[138:141], v[172:175], v[50:53]
	v_mfma_f32_16x16x32_bf16 v[78:81], v[130:133], v[196:199], v[78:81]
	v_mfma_f32_16x16x32_bf16 v[70:73], v[138:141], v[196:199], v[70:73]
	v_mfma_f32_16x16x32_bf16 v[98:101], v[130:133], v[204:207], v[98:101]
	v_mfma_f32_16x16x32_bf16 v[102:105], v[138:141], v[204:207], v[102:105]
	v_mfma_f32_16x16x32_bf16 v[114:117], v[130:133], v[212:215], v[114:117]
	v_mfma_f32_16x16x32_bf16 v[118:121], v[138:141], v[212:215], v[118:121]
	v_mfma_f32_16x16x32_bf16 v[58:61], v[134:137], v[182:185], v[58:61]
	v_mfma_f32_16x16x32_bf16 v[50:53], v[142:145], v[182:185], v[50:53]
	v_mfma_f32_16x16x32_bf16 v[78:81], v[134:137], v[200:203], v[78:81]
	v_mfma_f32_16x16x32_bf16 v[70:73], v[142:145], v[200:203], v[70:73]
	v_mfma_f32_16x16x32_bf16 v[98:101], v[134:137], v[208:211], v[98:101]
	v_mfma_f32_16x16x32_bf16 v[102:105], v[142:145], v[208:211], v[102:105]
	v_mfma_f32_16x16x32_bf16 v[114:117], v[134:137], v[216:219], v[114:117]
	v_mfma_f32_16x16x32_bf16 v[118:121], v[142:145], v[216:219], v[118:121]
	s_setprio 0
	s_setprio 1
	v_mfma_f32_16x16x32_bf16 v[66:69], v[156:159], v[172:175], v[66:69]
	v_mfma_f32_16x16x32_bf16 v[54:57], v[164:167], v[172:175], v[54:57]
	v_mfma_f32_16x16x32_bf16 v[86:89], v[156:159], v[196:199], v[86:89]
	v_mfma_f32_16x16x32_bf16 v[94:97], v[164:167], v[196:199], v[94:97]
	v_mfma_f32_16x16x32_bf16 v[106:109], v[156:159], v[204:207], v[106:109]
	v_mfma_f32_16x16x32_bf16 v[110:113], v[164:167], v[204:207], v[110:113]
	v_mfma_f32_16x16x32_bf16 v[122:125], v[156:159], v[212:215], v[122:125]
	v_mfma_f32_16x16x32_bf16 v[126:129], v[164:167], v[212:215], v[126:129]
	v_mfma_f32_16x16x32_bf16 v[66:69], v[160:163], v[182:185], v[66:69]
	v_mfma_f32_16x16x32_bf16 v[54:57], v[168:171], v[182:185], v[54:57]
	v_mfma_f32_16x16x32_bf16 v[86:89], v[160:163], v[200:203], v[86:89]
	v_mfma_f32_16x16x32_bf16 v[94:97], v[168:171], v[200:203], v[94:97]
	v_mfma_f32_16x16x32_bf16 v[106:109], v[160:163], v[208:211], v[106:109]
	v_mfma_f32_16x16x32_bf16 v[110:113], v[168:171], v[208:211], v[110:113]
	v_mfma_f32_16x16x32_bf16 v[122:125], v[160:163], v[216:219], v[122:125]
	v_mfma_f32_16x16x32_bf16 v[126:129], v[168:171], v[216:219], v[126:129]
	s_setprio 0
	s_barrier
	s_add_u32 s28, s26, 0x8000
	s_addc_u32 s29, s27, 0
	s_add_i32 s52, s52, s2
	v_lshl_add_u64 v[176:177], s[28:29], 0, v[186:187]
	s_mov_b32 m0, s52
	ds_read_b128 v[172:175], v181 offset:49152
	ds_read_b128 v[182:185], v181 offset:50176
	ds_read_b128 v[196:199], v181 offset:51200
	ds_read_b128 v[200:203], v181 offset:52224
	ds_read_b128 v[204:207], v181 offset:53248
	ds_read_b128 v[208:211], v181 offset:54272
	ds_read_b128 v[212:215], v181 offset:55296
	ds_read_b128 v[216:219], v181 offset:56320
	global_load_lds_dwordx4 v[176:177], off
	s_add_i32 m0, s52, 0x2000
	s_add_u32 s26, s26, 0xc000
	v_lshl_add_u64 v[176:177], s[28:29], 0, v[150:151]
	s_addc_u32 s27, s27, 0
	s_add_i32 s28, s75, s2
	global_load_lds_dwordx4 v[176:177], off
	v_lshl_add_u64 v[176:177], s[26:27], 0, v[186:187]
	s_mov_b32 m0, s28
	s_nop 0
	global_load_lds_dwordx4 v[176:177], off
	v_lshl_add_u64 v[176:177], s[26:27], 0, v[150:151]
	s_add_i32 m0, s28, 0x2000
	s_nop 0
	global_load_lds_dwordx4 v[176:177], off
	v_lshl_add_u64 v[176:177], s[8:9], 0, v[146:147]
	s_mov_b32 m0, s45
	s_nop 0
	global_load_lds_dwordx4 v[176:177], off
	v_lshl_add_u64 v[176:177], s[8:9], 0, v[148:149]
	s_mov_b32 m0, s46
	s_nop 0
	global_load_lds_dwordx4 v[176:177], off
	s_waitcnt vmcnt(8)
	s_waitcnt lgkmcnt(0)
	s_barrier
	s_setprio 1
	s_waitcnt lgkmcnt(0)
	v_mfma_f32_16x16x32_bf16 v[90:93], v[130:133], v[172:175], v[90:93]
	v_mfma_f32_16x16x32_bf16 v[82:85], v[138:141], v[172:175], v[82:85]
	v_mfma_f32_16x16x32_bf16 v[46:49], v[130:133], v[196:199], v[46:49]
	v_mfma_f32_16x16x32_bf16 v[42:45], v[138:141], v[196:199], v[42:45]
	v_mfma_f32_16x16x32_bf16 v[30:33], v[130:133], v[204:207], v[30:33]
	v_mfma_f32_16x16x32_bf16 v[26:29], v[138:141], v[204:207], v[26:29]
	v_mfma_f32_16x16x32_bf16 v[14:17], v[130:133], v[212:215], v[14:17]
	v_mfma_f32_16x16x32_bf16 v[10:13], v[138:141], v[212:215], v[10:13]
	v_mfma_f32_16x16x32_bf16 v[90:93], v[134:137], v[182:185], v[90:93]
	v_mfma_f32_16x16x32_bf16 v[82:85], v[142:145], v[182:185], v[82:85]
	v_mfma_f32_16x16x32_bf16 v[46:49], v[134:137], v[200:203], v[46:49]
	v_mfma_f32_16x16x32_bf16 v[42:45], v[142:145], v[200:203], v[42:45]
	v_mfma_f32_16x16x32_bf16 v[30:33], v[134:137], v[208:211], v[30:33]
	v_mfma_f32_16x16x32_bf16 v[26:29], v[142:145], v[208:211], v[26:29]
	v_mfma_f32_16x16x32_bf16 v[14:17], v[134:137], v[216:219], v[14:17]
	v_mfma_f32_16x16x32_bf16 v[10:13], v[142:145], v[216:219], v[10:13]
	s_setprio 0
	s_setprio 1
	v_mfma_f32_16x16x32_bf16 v[74:77], v[156:159], v[172:175], v[74:77]
	v_mfma_f32_16x16x32_bf16 v[62:65], v[164:167], v[172:175], v[62:65]
	v_mfma_f32_16x16x32_bf16 v[38:41], v[156:159], v[196:199], v[38:41]
	v_mfma_f32_16x16x32_bf16 v[34:37], v[164:167], v[196:199], v[34:37]
	v_mfma_f32_16x16x32_bf16 v[22:25], v[156:159], v[204:207], v[22:25]
	v_mfma_f32_16x16x32_bf16 v[18:21], v[164:167], v[204:207], v[18:21]
	v_mfma_f32_16x16x32_bf16 v[6:9], v[156:159], v[212:215], v[6:9]
	v_mfma_f32_16x16x32_bf16 v[2:5], v[164:167], v[212:215], v[2:5]
	v_mfma_f32_16x16x32_bf16 v[74:77], v[160:163], v[182:185], v[74:77]
	v_mfma_f32_16x16x32_bf16 v[62:65], v[168:171], v[182:185], v[62:65]
	v_mfma_f32_16x16x32_bf16 v[38:41], v[160:163], v[200:203], v[38:41]
	v_mfma_f32_16x16x32_bf16 v[34:37], v[168:171], v[200:203], v[34:37]
	v_mfma_f32_16x16x32_bf16 v[22:25], v[160:163], v[208:211], v[22:25]
	v_mfma_f32_16x16x32_bf16 v[18:21], v[168:171], v[208:211], v[18:21]
	v_mfma_f32_16x16x32_bf16 v[6:9], v[160:163], v[216:219], v[6:9]
	v_mfma_f32_16x16x32_bf16 v[2:5], v[168:171], v[216:219], v[2:5]
	s_setprio 0
	s_barrier
	s_add_i32 s73, s73, 2
	s_add_u32 s0, s0, 0x10000
	s_addc_u32 s1, s1, 0
	s_add_u32 s23, s23, 0x10000
	s_addc_u32 s25, s25, 0
	s_cmpk_gt_u32 s73, 0x55
	s_cbranch_scc0 .LBB0_1420
	s_and_b64 vcc, exec, s[14:15]
	s_cbranch_vccz .LBB0_1423
	s_barrier

; #define PG8_STAGE(bufoff, gbase, voff) do { _Pragma("unroll") for (int _i = 0; _i < 2; ++_i) \
;         __builtin_amdgcn_global_load_lds((const unsigned*)((const char*)(gbase) + (voff)[_i]), (PG8_LAS unsigned*)(lds + (bufoff) + ldsw + _i * 8192), 16, 0, 0); } while (0)
; #define PG8_LDA(dst, b, h) do { _Pragma("unroll") for (int m = 0; m < 4; ++m) _Pragma("unroll") for (int k = 0; k < 2; ++k) dst[m][k] = *(const PG8_LAS bf16x8*)(lds + PG8_SA(b, h) + aoff + m * 2048 + k * 1024); } while (0)
; #define PG8_LDB(dst, b, h) do { _Pragma("unroll") for (int n = 0; n < 2; ++n) _Pragma("unroll") for (int k = 0; k < 2; ++k) dst[n][k] = *(const PG8_LAS bf16x8*)(lds + PG8_SB(b, h) + boff + n * 2048 + k * 1024); } while (0)
; #define PG8_WAIT_V(n) asm volatile("s_waitcnt vmcnt(" #n ")" ::: "memory")
; #define PG8_WAIT_L(n) asm volatile("s_waitcnt lgkmcnt(" #n ")" ::: "memory")
; #define PG8_BAR __builtin_amdgcn_s_barrier()
; #define PG8_SCHED __builtin_amdgcn_sched_barrier(0)
; template <class Epi, class Sched, bool ALIGN_EPI = false, bool SP2 = false, bool ABLK = false, bool BBLK = false>
; __device__ __forceinline__ void gemm_phase(PG8_LAS unsigned char* lds, const Gemm g, const Sched& S, const Epi& E) {
;     ...
;         const bool has_next = S.next(ui + 1, nxt);
;         const char* nA = has_next ? (const char*)g.A + (size_t)nxt.pm * tstepA : cA; const char* nB = has_next ? (const char*)g.Bt + (size_t)nxt.pn * tstepB : cB;
;         for (int t = 0; t < nt; t += 2) {
;             const bool last = (t == nt - 2);
;             const char* a1 = cA + (size_t)(t + 1) * kstepA;
;             const char* a2 = last ? nA : cA + (size_t)(t + 2) * kstepA; const char* b2 = last ? nB : cB + (size_t)(t + 2) * kstepB;
;             const char* a3 = a2 + kstepA; const char* b3 = b2 + kstepB;
;             if (last && has_next) S.a_ready(nxt);
;             if constexpr (SP2) {
;             PG8_LDB(B0, 0, 0); PG8_LDB(B1, 0, 1); PG8_SCHED; PG8_LDA(At, 0, 0); PG8_STAGE(PG8_SA(1, 1), a1 + hstepA, voffA);
;             PG8_WAIT_V(8); PG8_WAIT_L(0); PG8_BAR; PG8_MMA(0, 0, At, B0); PG8_MMA(0, 1, At, B1); PG8_BAR; PG8_SCHED;
;             PG8_LDA(At, 0, 1); PG8_STAGE(PG8_SB(0, 0), b2, voffB); PG8_STAGE(PG8_SB(0, 1), b2 + hstepB, voffB); PG8_STAGE(PG8_SA(0, 0), a2, voffA);
;             PG8_WAIT_V(8); PG8_WAIT_L(0); PG8_BAR; PG8_MMA(1, 0, At, B0); PG8_MMA(1, 1, At, B1); PG8_BAR; PG8_SCHED;
.LBB0_1482:
	s_add_u32 s0, s0, 0xc000
	s_addc_u32 s1, s1, 0
	s_add_u32 s31, s36, 0x10000
	v_mov_b32_e32 v2, 0
	s_addc_u32 s33, s37, 0
	s_mov_b32 s35, -2
	s_add_u32 s8, s0, 0x4000
	s_addc_u32 s9, s1, 0
	s_cmpk_eq_i32 s35, 0x54
	s_cselect_b32 s40, s26, s8
	s_cselect_b32 s41, s27, s9
	s_cselect_b32 s36, s28, s31
	s_cselect_b32 s37, s29, s33
	s_add_u32 s8, s40, 0x8000
	s_addc_u32 s9, s41, 0
	s_add_i32 s44, 0, 0x10000
	s_add_i32 s52, 0, 0x14000
	v_add_u32_e32 v142, s44, v206
	v_add_u32_e32 v158, s52, v206
	ds_read_b128 v[130:133], v142
	ds_read_b128 v[134:137], v142 offset:1024
	ds_read_b128 v[138:141], v142 offset:2048
	ds_read_b128 v[142:145], v142 offset:3072
	ds_read_b128 v[146:149], v158
	ds_read_b128 v[150:153], v158 offset:1024
	ds_read_b128 v[154:157], v158 offset:2048
	ds_read_b128 v[158:161], v158 offset:3072
	v_lshl_add_u64 v[188:189], s[0:1], 0, v[184:185]
	s_add_i32 m0, s68, 0xc000
	ds_read_b128 v[162:165], v207
	ds_read_b128 v[166:169], v207 offset:1024
	ds_read_b128 v[170:173], v207 offset:2048
	ds_read_b128 v[174:177], v207 offset:3072
	ds_read_b128 v[198:201], v207 offset:4096
	ds_read_b128 v[208:211], v207 offset:5120
	ds_read_b128 v[212:215], v207 offset:6144
	ds_read_b128 v[216:219], v207 offset:7168
	global_load_lds_dwordx4 v[188:189], off
	v_lshl_add_u64 v[188:189], s[0:1], 0, v[196:197]
	s_add_i32 m0, s68, 0xe000
	s_nop 0
	global_load_lds_dwordx4 v[188:189], off
	s_waitcnt vmcnt(8)
	s_waitcnt lgkmcnt(0)
	s_barrier
	s_setprio 1
	s_waitcnt lgkmcnt(0)
	v_mfma_f32_16x16x32_bf16 v[30:33], v[130:133], v[162:165], 0
	v_mfma_f32_16x16x32_bf16 v[22:25], v[138:141], v[162:165], 0
	v_mfma_f32_16x16x32_bf16 v[18:21], v[130:133], v[170:173], 0
	v_mfma_f32_16x16x32_bf16 v[10:13], v[138:141], v[170:173], 0
	v_mfma_f32_16x16x32_bf16 v[50:53], v[130:133], v[198:201], 0
	v_mfma_f32_16x16x32_bf16 v[54:57], v[138:141], v[198:201], 0
	v_mfma_f32_16x16x32_bf16 v[74:77], v[130:133], v[212:215], 0
	v_mfma_f32_16x16x32_bf16 v[78:81], v[138:141], v[212:215], 0
	v_mfma_f32_16x16x32_bf16 v[30:33], v[134:137], v[166:169], v[30:33]
	v_mfma_f32_16x16x32_bf16 v[22:25], v[142:145], v[166:169], v[22:25]
	v_mfma_f32_16x16x32_bf16 v[18:21], v[134:137], v[174:177], v[18:21]
	v_mfma_f32_16x16x32_bf16 v[10:13], v[142:145], v[174:177], v[10:13]
	v_mfma_f32_16x16x32_bf16 v[50:53], v[134:137], v[208:211], v[50:53]
	v_mfma_f32_16x16x32_bf16 v[54:57], v[142:145], v[208:211], v[54:57]
	v_mfma_f32_16x16x32_bf16 v[74:77], v[134:137], v[216:219], v[74:77]
	v_mfma_f32_16x16x32_bf16 v[78:81], v[142:145], v[216:219], v[78:81]
	s_setprio 0
	s_setprio 1
	v_mfma_f32_16x16x32_bf16 v[26:29], v[146:149], v[162:165], 0
	v_mfma_f32_16x16x32_bf16 v[14:17], v[154:157], v[162:165], 0
	v_mfma_f32_16x16x32_bf16 v[42:45], v[146:149], v[170:173], 0
	v_mfma_f32_16x16x32_bf16 v[46:49], v[154:157], v[170:173], 0
	v_mfma_f32_16x16x32_bf16 v[66:69], v[146:149], v[198:201], 0
	v_mfma_f32_16x16x32_bf16 v[70:73], v[154:157], v[198:201], 0
	v_mfma_f32_16x16x32_bf16 v[82:85], v[146:149], v[212:215], 0
	v_mfma_f32_16x16x32_bf16 v[86:89], v[154:157], v[212:215], 0
	v_mfma_f32_16x16x32_bf16 v[26:29], v[150:153], v[166:169], v[26:29]
	v_mfma_f32_16x16x32_bf16 v[14:17], v[158:161], v[166:169], v[14:17]
	v_mfma_f32_16x16x32_bf16 v[42:45], v[150:153], v[174:177], v[42:45]
	v_mfma_f32_16x16x32_bf16 v[46:49], v[158:161], v[174:177], v[46:49]
	v_mfma_f32_16x16x32_bf16 v[66:69], v[150:153], v[208:211], v[66:69]
	v_mfma_f32_16x16x32_bf16 v[70:73], v[158:161], v[208:211], v[70:73]
	v_mfma_f32_16x16x32_bf16 v[82:85], v[150:153], v[216:219], v[82:85]
	v_mfma_f32_16x16x32_bf16 v[86:89], v[158:161], v[216:219], v[86:89]
	s_setprio 0
	s_barrier
	s_add_i32 s44, s44, s65
	v_lshl_add_u64 v[188:189], s[36:37], 0, v[186:187]
	s_mov_b32 m0, s44
	ds_read_b128 v[162:165], v207 offset:16384
	ds_read_b128 v[166:169], v207 offset:17408
	ds_read_b128 v[170:173], v207 offset:18432
	ds_read_b128 v[174:177], v207 offset:19456
	ds_read_b128 v[198:201], v207 offset:20480
	ds_read_b128 v[208:211], v207 offset:21504
	ds_read_b128 v[212:215], v207 offset:22528
	ds_read_b128 v[216:219], v207 offset:23552
	global_load_lds_dwordx4 v[188:189], off
	s_add_i32 m0, s44, 0x2000
	s_add_u32 s44, s36, 0x4000
	v_lshl_add_u64 v[188:189], s[36:37], 0, v[182:183]
	s_addc_u32 s45, s37, 0
	s_add_i32 s52, s52, s65
	global_load_lds_dwordx4 v[188:189], off
	v_lshl_add_u64 v[188:189], s[44:45], 0, v[186:187]
	s_mov_b32 m0, s52
	s_nop 0
	global_load_lds_dwordx4 v[188:189], off
	v_lshl_add_u64 v[188:189], s[44:45], 0, v[182:183]
	s_add_i32 m0, s52, 0x2000
	s_nop 0
	global_load_lds_dwordx4 v[188:189], off
	v_lshl_add_u64 v[188:189], s[40:41], 0, v[178:179]
	s_mov_b32 m0, s68
	s_nop 0
	global_load_lds_dwordx4 v[188:189], off
	v_lshl_add_u64 v[188:189], s[40:41], 0, v[180:181]
	s_mov_b32 m0, s72
	s_nop 0
	global_load_lds_dwordx4 v[188:189], off
	s_waitcnt vmcnt(8)
	s_waitcnt lgkmcnt(0)
	s_barrier
; #define PG8_STAGE(bufoff, gbase, voff) do { _Pragma("unroll") for (int _i = 0; _i < 2; ++_i) \
;         __builtin_amdgcn_global_load_lds((const unsigned*)((const char*)(gbase) + (voff)[_i]), (PG8_LAS unsigned*)(lds + (bufoff) + ldsw + _i * 8192), 16, 0, 0); } while (0)
; #define PG8_LDA(dst, b, h) do { _Pragma("unroll") for (int m = 0; m < 4; ++m) _Pragma("unroll") for (int k = 0; k < 2; ++k) dst[m][k] = *(const PG8_LAS bf16x8*)(lds + PG8_SA(b, h) + aoff + m * 2048 + k * 1024); } while (0)
; #define PG8_LDB(dst, b, h) do { _Pragma("unroll") for (int n = 0; n < 2; ++n) _Pragma("unroll") for (int k = 0; k < 2; ++k) dst[n][k] = *(const PG8_LAS bf16x8*)(lds + PG8_SB(b, h) + boff + n * 2048 + k * 1024); } while (0)
; #define PG8_MMA(ai, bj, At, Bt) do { __builtin_amdgcn_s_setprio(1); _Pragma("unroll") for (int m = 0; m < 4; ++m) _Pragma("unroll") for (int n = 0; n < 2; ++n) _Pragma("unroll") for (int k = 0; k < 2; ++k) \
;         acc[ai][bj][m][n] = __builtin_amdgcn_mfma_f32_16x16x32_bf16(Bt[n][k], At[m][k], acc[ai][bj][m][n], 0, 0, 0); __builtin_amdgcn_s_setprio(0); } while (0)
; #define PG8_WAIT_V(n) asm volatile("s_waitcnt vmcnt(" #n ")" ::: "memory")
; template <class Epi, class Sched, bool ALIGN_EPI = false, bool SP2 = false, bool ABLK = false, bool BBLK = false>
; __device__ __forceinline__ void gemm_phase(PG8_LAS unsigned char* lds, const Gemm g, const Sched& S, const Epi& E) {
;     ...
;         for (int t = 0; t < nt; t += 2) {
;             const bool last = (t == nt - 2);
;             const char* a1 = cA + (size_t)(t + 1) * kstepA;
;             const char* a2 = last ? nA : cA + (size_t)(t + 2) * kstepA; const char* b2 = last ? nB : cB + (size_t)(t + 2) * kstepB;
;             const char* a3 = a2 + kstepA; const char* b3 = b2 + kstepB;
;             if (last && has_next) S.a_ready(nxt);
;             if constexpr (SP2) {
;             PG8_LDB(B0, 0, 0); PG8_LDB(B1, 0, 1); PG8_SCHED; PG8_LDA(At, 0, 0); PG8_STAGE(PG8_SA(1, 1), a1 + hstepA, voffA);
;             PG8_WAIT_V(8); PG8_WAIT_L(0); PG8_BAR; PG8_MMA(0, 0, At, B0); PG8_MMA(0, 1, At, B1); PG8_BAR; PG8_SCHED;
;             PG8_LDA(At, 0, 1); PG8_STAGE(PG8_SB(0, 0), b2, voffB); PG8_STAGE(PG8_SB(0, 1), b2 + hstepB, voffB); PG8_STAGE(PG8_SA(0, 0), a2, voffA);
;             PG8_WAIT_V(8); PG8_WAIT_L(0); PG8_BAR; PG8_MMA(1, 0, At, B0); PG8_MMA(1, 1, At, B1); PG8_BAR; PG8_SCHED;
	s_setprio 1
	s_waitcnt lgkmcnt(0)
	v_mfma_f32_16x16x32_bf16 v[106:109], v[130:133], v[162:165], 0
	v_mfma_f32_16x16x32_bf16 v[110:113], v[138:141], v[162:165], 0
	v_mfma_f32_16x16x32_bf16 v[122:125], v[130:133], v[170:173], 0
	v_mfma_f32_16x16x32_bf16 v[126:129], v[138:141], v[170:173], 0
	v_mfma_f32_16x16x32_bf16 v[94:97], v[130:133], v[198:201], 0
	v_mfma_f32_16x16x32_bf16 v[90:93], v[138:141], v[198:201], 0
	v_mfma_f32_16x16x32_bf16 v[38:41], v[130:133], v[212:215], 0
	v_mfma_f32_16x16x32_bf16 v[34:37], v[138:141], v[212:215], 0
	v_mfma_f32_16x16x32_bf16 v[106:109], v[134:137], v[166:169], v[106:109]
	v_mfma_f32_16x16x32_bf16 v[110:113], v[142:145], v[166:169], v[110:113]
	v_mfma_f32_16x16x32_bf16 v[122:125], v[134:137], v[174:177], v[122:125]
	v_mfma_f32_16x16x32_bf16 v[126:129], v[142:145], v[174:177], v[126:129]
	v_mfma_f32_16x16x32_bf16 v[94:97], v[134:137], v[208:211], v[94:97]
	v_mfma_f32_16x16x32_bf16 v[90:93], v[142:145], v[208:211], v[90:93]
	v_mfma_f32_16x16x32_bf16 v[38:41], v[134:137], v[216:219], v[38:41]
	v_mfma_f32_16x16x32_bf16 v[34:37], v[142:145], v[216:219], v[34:37]
	s_setprio 0
	s_setprio 1
	v_mfma_f32_16x16x32_bf16 v[114:117], v[146:149], v[162:165], 0
	v_mfma_f32_16x16x32_bf16 v[118:121], v[154:157], v[162:165], 0
	v_mfma_f32_16x16x32_bf16 v[102:105], v[146:149], v[170:173], 0
	v_mfma_f32_16x16x32_bf16 v[98:101], v[154:157], v[170:173], 0
	v_mfma_f32_16x16x32_bf16 v[62:65], v[146:149], v[198:201], 0
	v_mfma_f32_16x16x32_bf16 v[58:61], v[154:157], v[198:201], 0
	v_mfma_f32_16x16x32_bf16 v[6:9], v[146:149], v[212:215], 0
	v_mfma_f32_16x16x32_bf16 v[2:5], v[154:157], v[212:215], 0
	v_mfma_f32_16x16x32_bf16 v[114:117], v[150:153], v[166:169], v[114:117]
	v_mfma_f32_16x16x32_bf16 v[118:121], v[158:161], v[166:169], v[118:121]
	v_mfma_f32_16x16x32_bf16 v[102:105], v[150:153], v[174:177], v[102:105]
	v_mfma_f32_16x16x32_bf16 v[98:101], v[158:161], v[174:177], v[98:101]
	v_mfma_f32_16x16x32_bf16 v[62:65], v[150:153], v[208:211], v[62:65]
	v_mfma_f32_16x16x32_bf16 v[58:61], v[158:161], v[208:211], v[58:61]
	v_mfma_f32_16x16x32_bf16 v[6:9], v[150:153], v[216:219], v[6:9]
	v_mfma_f32_16x16x32_bf16 v[2:5], v[158:161], v[216:219], v[2:5]
	s_setprio 0
	s_barrier
	s_branch .Lmid_1483
.LBB0_1483:
	s_add_u32 s8, s0, 0x4000
	s_addc_u32 s9, s1, 0
	s_cmpk_eq_i32 s35, 0x54
	s_cselect_b32 s40, s26, s8
	s_cselect_b32 s41, s27, s9
	s_cselect_b32 s36, s28, s31
	s_cselect_b32 s37, s29, s33
	s_add_u32 s8, s40, 0x8000
	s_addc_u32 s9, s41, 0
	s_add_i32 s44, 0, 0x10000
	s_add_i32 s52, 0, 0x14000
	v_add_u32_e32 v142, s44, v206
	v_add_u32_e32 v158, s52, v206
	ds_read_b128 v[130:133], v142
	ds_read_b128 v[134:137], v142 offset:1024
	ds_read_b128 v[138:141], v142 offset:2048
	ds_read_b128 v[142:145], v142 offset:3072
	ds_read_b128 v[146:149], v158
	ds_read_b128 v[150:153], v158 offset:1024
	ds_read_b128 v[154:157], v158 offset:2048
	ds_read_b128 v[158:161], v158 offset:3072
	v_lshl_add_u64 v[188:189], s[0:1], 0, v[184:185]
	s_add_i32 m0, s68, 0xc000
	ds_read_b128 v[162:165], v207
	ds_read_b128 v[166:169], v207 offset:1024
	ds_read_b128 v[170:173], v207 offset:2048
	ds_read_b128 v[174:177], v207 offset:3072
	ds_read_b128 v[198:201], v207 offset:4096
	ds_read_b128 v[208:211], v207 offset:5120
	ds_read_b128 v[212:215], v207 offset:6144
	ds_read_b128 v[216:219], v207 offset:7168
	global_load_lds_dwordx4 v[188:189], off
	v_lshl_add_u64 v[188:189], s[0:1], 0, v[196:197]
	s_add_i32 m0, s68, 0xe000
	s_nop 0
	global_load_lds_dwordx4 v[188:189], off
	s_waitcnt vmcnt(8)
	s_waitcnt lgkmcnt(0)
	s_barrier
	s_setprio 1
	s_waitcnt lgkmcnt(0)
	v_mfma_f32_16x16x32_bf16 v[30:33], v[130:133], v[162:165], v[30:33]
	v_mfma_f32_16x16x32_bf16 v[22:25], v[138:141], v[162:165], v[22:25]
	v_mfma_f32_16x16x32_bf16 v[18:21], v[130:133], v[170:173], v[18:21]
	v_mfma_f32_16x16x32_bf16 v[10:13], v[138:141], v[170:173], v[10:13]
	v_mfma_f32_16x16x32_bf16 v[50:53], v[130:133], v[198:201], v[50:53]
	v_mfma_f32_16x16x32_bf16 v[54:57], v[138:141], v[198:201], v[54:57]
	v_mfma_f32_16x16x32_bf16 v[74:77], v[130:133], v[212:215], v[74:77]
	v_mfma_f32_16x16x32_bf16 v[78:81], v[138:141], v[212:215], v[78:81]
	v_mfma_f32_16x16x32_bf16 v[30:33], v[134:137], v[166:169], v[30:33]
	v_mfma_f32_16x16x32_bf16 v[22:25], v[142:145], v[166:169], v[22:25]
	v_mfma_f32_16x16x32_bf16 v[18:21], v[134:137], v[174:177], v[18:21]
	v_mfma_f32_16x16x32_bf16 v[10:13], v[142:145], v[174:177], v[10:13]
	v_mfma_f32_16x16x32_bf16 v[50:53], v[134:137], v[208:211], v[50:53]
	v_mfma_f32_16x16x32_bf16 v[54:57], v[142:145], v[208:211], v[54:57]
	v_mfma_f32_16x16x32_bf16 v[74:77], v[134:137], v[216:219], v[74:77]
	v_mfma_f32_16x16x32_bf16 v[78:81], v[142:145], v[216:219], v[78:81]
	s_setprio 0
	s_setprio 1
	v_mfma_f32_16x16x32_bf16 v[26:29], v[146:149], v[162:165], v[26:29]
	v_mfma_f32_16x16x32_bf16 v[14:17], v[154:157], v[162:165], v[14:17]
	v_mfma_f32_16x16x32_bf16 v[42:45], v[146:149], v[170:173], v[42:45]
	v_mfma_f32_16x16x32_bf16 v[46:49], v[154:157], v[170:173], v[46:49]
	v_mfma_f32_16x16x32_bf16 v[66:69], v[146:149], v[198:201], v[66:69]
	v_mfma_f32_16x16x32_bf16 v[70:73], v[154:157], v[198:201], v[70:73]
	v_mfma_f32_16x16x32_bf16 v[82:85], v[146:149], v[212:215], v[82:85]
	v_mfma_f32_16x16x32_bf16 v[86:89], v[154:157], v[212:215], v[86:89]
	v_mfma_f32_16x16x32_bf16 v[26:29], v[150:153], v[166:169], v[26:29]
	v_mfma_f32_16x16x32_bf16 v[14:17], v[158:161], v[166:169], v[14:17]
	v_mfma_f32_16x16x32_bf16 v[42:45], v[150:153], v[174:177], v[42:45]
	v_mfma_f32_16x16x32_bf16 v[46:49], v[158:161], v[174:177], v[46:49]
	v_mfma_f32_16x16x32_bf16 v[66:69], v[150:153], v[208:211], v[66:69]
	v_mfma_f32_16x16x32_bf16 v[70:73], v[158:161], v[208:211], v[70:73]
	v_mfma_f32_16x16x32_bf16 v[82:85], v[150:153], v[216:219], v[82:85]
	v_mfma_f32_16x16x32_bf16 v[86:89], v[158:161], v[216:219], v[86:89]
	s_setprio 0
	s_barrier
; #define PG8_STAGE(bufoff, gbase, voff) do { _Pragma("unroll") for (int _i = 0; _i < 2; ++_i) \
;         __builtin_amdgcn_global_load_lds((const unsigned*)((const char*)(gbase) + (voff)[_i]), (PG8_LAS unsigned*)(lds + (bufoff) + ldsw + _i * 8192), 16, 0, 0); } while (0)
; #define PG8_LDA(dst, b, h) do { _Pragma("unroll") for (int m = 0; m < 4; ++m) _Pragma("unroll") for (int k = 0; k < 2; ++k) dst[m][k] = *(const PG8_LAS bf16x8*)(lds + PG8_SA(b, h) + aoff + m * 2048 + k * 1024); } while (0)
; #define PG8_LDB(dst, b, h) do { _Pragma("unroll") for (int n = 0; n < 2; ++n) _Pragma("unroll") for (int k = 0; k < 2; ++k) dst[n][k] = *(const PG8_LAS bf16x8*)(lds + PG8_SB(b, h) + boff + n * 2048 + k * 1024); } while (0)
; #define PG8_MMA(ai, bj, At, Bt) do { __builtin_amdgcn_s_setprio(1); _Pragma("unroll") for (int m = 0; m < 4; ++m) _Pragma("unroll") for (int n = 0; n < 2; ++n) _Pragma("unroll") for (int k = 0; k < 2; ++k) \
;         acc[ai][bj][m][n] = __builtin_amdgcn_mfma_f32_16x16x32_bf16(Bt[n][k], At[m][k], acc[ai][bj][m][n], 0, 0, 0); __builtin_amdgcn_s_setprio(0); } while (0)
; #define PG8_WAIT_V(n) asm volatile("s_waitcnt vmcnt(" #n ")" ::: "memory")
; #define PG8_WAIT_L(n) asm volatile("s_waitcnt lgkmcnt(" #n ")" ::: "memory")
; #define PG8_BAR __builtin_amdgcn_s_barrier()
; #define PG8_SCHED __builtin_amdgcn_sched_barrier(0)
; template <class Epi, class Sched, bool ALIGN_EPI = false, bool SP2 = false, bool ABLK = false, bool BBLK = false>
; __device__ __forceinline__ void gemm_phase(PG8_LAS unsigned char* lds, const Gemm g, const Sched& S, const Epi& E) {
;     ...
;             PG8_LDA(At, 0, 1); PG8_STAGE(PG8_SB(0, 0), b2, voffB); PG8_STAGE(PG8_SB(0, 1), b2 + hstepB, voffB); PG8_STAGE(PG8_SA(0, 0), a2, voffA);
;             PG8_WAIT_V(8); PG8_WAIT_L(0); PG8_BAR; PG8_MMA(1, 0, At, B0); PG8_MMA(1, 1, At, B1); PG8_BAR; PG8_SCHED;
;             PG8_LDB(B0, 1, 0); PG8_LDB(B1, 1, 1); PG8_SCHED; PG8_LDA(At, 1, 0); PG8_STAGE(PG8_SA(0, 1), a2 + hstepA, voffA);
;             PG8_WAIT_V(8); PG8_WAIT_L(0); PG8_BAR; PG8_MMA(0, 0, At, B0); PG8_MMA(0, 1, At, B1); PG8_BAR; PG8_SCHED;
	s_add_i32 s44, s44, s65
	v_lshl_add_u64 v[188:189], s[36:37], 0, v[186:187]
	s_mov_b32 m0, s44
	ds_read_b128 v[162:165], v207 offset:16384
	ds_read_b128 v[166:169], v207 offset:17408
	ds_read_b128 v[170:173], v207 offset:18432
	ds_read_b128 v[174:177], v207 offset:19456
	ds_read_b128 v[198:201], v207 offset:20480
	ds_read_b128 v[208:211], v207 offset:21504
	ds_read_b128 v[212:215], v207 offset:22528
	ds_read_b128 v[216:219], v207 offset:23552
	global_load_lds_dwordx4 v[188:189], off
	s_add_i32 m0, s44, 0x2000
	s_add_u32 s44, s36, 0x4000
	v_lshl_add_u64 v[188:189], s[36:37], 0, v[182:183]
	s_addc_u32 s45, s37, 0
	s_add_i32 s52, s52, s65
	global_load_lds_dwordx4 v[188:189], off
	v_lshl_add_u64 v[188:189], s[44:45], 0, v[186:187]
	s_mov_b32 m0, s52
	s_nop 0
	global_load_lds_dwordx4 v[188:189], off
	v_lshl_add_u64 v[188:189], s[44:45], 0, v[182:183]
	s_add_i32 m0, s52, 0x2000
	s_nop 0
	global_load_lds_dwordx4 v[188:189], off
	v_lshl_add_u64 v[188:189], s[40:41], 0, v[178:179]
	s_mov_b32 m0, s68
	s_nop 0
	global_load_lds_dwordx4 v[188:189], off
	v_lshl_add_u64 v[188:189], s[40:41], 0, v[180:181]
	s_mov_b32 m0, s72
	s_nop 0
	global_load_lds_dwordx4 v[188:189], off
	s_waitcnt vmcnt(8)
	s_waitcnt lgkmcnt(0)
	s_barrier
	s_setprio 1
	s_waitcnt lgkmcnt(0)
	v_mfma_f32_16x16x32_bf16 v[106:109], v[130:133], v[162:165], v[106:109]
	v_mfma_f32_16x16x32_bf16 v[110:113], v[138:141], v[162:165], v[110:113]
	v_mfma_f32_16x16x32_bf16 v[122:125], v[130:133], v[170:173], v[122:125]
	v_mfma_f32_16x16x32_bf16 v[126:129], v[138:141], v[170:173], v[126:129]
	v_mfma_f32_16x16x32_bf16 v[94:97], v[130:133], v[198:201], v[94:97]
	v_mfma_f32_16x16x32_bf16 v[90:93], v[138:141], v[198:201], v[90:93]
	v_mfma_f32_16x16x32_bf16 v[38:41], v[130:133], v[212:215], v[38:41]
	v_mfma_f32_16x16x32_bf16 v[34:37], v[138:141], v[212:215], v[34:37]
	v_mfma_f32_16x16x32_bf16 v[106:109], v[134:137], v[166:169], v[106:109]
	v_mfma_f32_16x16x32_bf16 v[110:113], v[142:145], v[166:169], v[110:113]
	v_mfma_f32_16x16x32_bf16 v[122:125], v[134:137], v[174:177], v[122:125]
	v_mfma_f32_16x16x32_bf16 v[126:129], v[142:145], v[174:177], v[126:129]
	v_mfma_f32_16x16x32_bf16 v[94:97], v[134:137], v[208:211], v[94:97]
	v_mfma_f32_16x16x32_bf16 v[90:93], v[142:145], v[208:211], v[90:93]
	v_mfma_f32_16x16x32_bf16 v[38:41], v[134:137], v[216:219], v[38:41]
	v_mfma_f32_16x16x32_bf16 v[34:37], v[142:145], v[216:219], v[34:37]
	s_setprio 0
	s_setprio 1
	v_mfma_f32_16x16x32_bf16 v[114:117], v[146:149], v[162:165], v[114:117]
	v_mfma_f32_16x16x32_bf16 v[118:121], v[154:157], v[162:165], v[118:121]
	v_mfma_f32_16x16x32_bf16 v[102:105], v[146:149], v[170:173], v[102:105]
	v_mfma_f32_16x16x32_bf16 v[98:101], v[154:157], v[170:173], v[98:101]
	v_mfma_f32_16x16x32_bf16 v[62:65], v[146:149], v[198:201], v[62:65]
	v_mfma_f32_16x16x32_bf16 v[58:61], v[154:157], v[198:201], v[58:61]
	v_mfma_f32_16x16x32_bf16 v[6:9], v[146:149], v[212:215], v[6:9]
	v_mfma_f32_16x16x32_bf16 v[2:5], v[154:157], v[212:215], v[2:5]
	v_mfma_f32_16x16x32_bf16 v[114:117], v[150:153], v[166:169], v[114:117]
	v_mfma_f32_16x16x32_bf16 v[118:121], v[158:161], v[166:169], v[118:121]
	v_mfma_f32_16x16x32_bf16 v[102:105], v[150:153], v[174:177], v[102:105]
	v_mfma_f32_16x16x32_bf16 v[98:101], v[158:161], v[174:177], v[98:101]
	v_mfma_f32_16x16x32_bf16 v[62:65], v[150:153], v[208:211], v[62:65]
	v_mfma_f32_16x16x32_bf16 v[58:61], v[158:161], v[208:211], v[58:61]
	v_mfma_f32_16x16x32_bf16 v[6:9], v[150:153], v[216:219], v[6:9]
	v_mfma_f32_16x16x32_bf16 v[2:5], v[158:161], v[216:219], v[2:5]
	s_setprio 0
	s_barrier
.Lmid_1483:
	s_add_i32 s44, 0, 0x18000
	s_add_i32 s45, 0, 0x1c000
	v_add_u32_e32 v142, s44, v206
	v_add_u32_e32 v158, s45, v206
	ds_read_b128 v[130:133], v142
	ds_read_b128 v[134:137], v142 offset:1024
	ds_read_b128 v[138:141], v142 offset:2048
	ds_read_b128 v[142:145], v142 offset:3072
	ds_read_b128 v[146:149], v158
	ds_read_b128 v[150:153], v158 offset:1024
	ds_read_b128 v[154:157], v158 offset:2048
	ds_read_b128 v[158:161], v158 offset:3072
	s_add_u32 s40, s40, 0x4000
	s_addc_u32 s41, s41, 0
	s_mov_b32 m0, s73
	v_lshl_add_u64 v[188:189], s[40:41], 0, v[178:179]
	ds_read_b128 v[162:165], v207 offset:32768
	ds_read_b128 v[166:169], v207 offset:33792
	ds_read_b128 v[170:173], v207 offset:34816
	ds_read_b128 v[174:177], v207 offset:35840
	ds_read_b128 v[198:201], v207 offset:36864
	ds_read_b128 v[208:211], v207 offset:37888
	ds_read_b128 v[212:215], v207 offset:38912
	ds_read_b128 v[216:219], v207 offset:39936
	global_load_lds_dwordx4 v[188:189], off
	v_lshl_add_u64 v[188:189], s[40:41], 0, v[180:181]
	s_mov_b32 m0, s84
	s_nop 0
	global_load_lds_dwordx4 v[188:189], off
	s_waitcnt vmcnt(8)
	s_waitcnt lgkmcnt(0)
	s_barrier
; #define PG8_STAGE(bufoff, gbase, voff) do { _Pragma("unroll") for (int _i = 0; _i < 2; ++_i) \
;         __builtin_amdgcn_global_load_lds((const unsigned*)((const char*)(gbase) + (voff)[_i]), (PG8_LAS unsigned*)(lds + (bufoff) + ldsw + _i * 8192), 16, 0, 0); } while (0)
; #define PG8_WAIT_V(n) asm volatile("s_waitcnt vmcnt(" #n ")" ::: "memory")
; #define PG8_BAR __builtin_amdgcn_s_barrier()
; template <class Epi, class Sched, bool ALIGN_EPI = false, bool SP2 = false, bool ABLK = false, bool BBLK = false>
; __device__ __forceinline__ void gemm_phase(PG8_LAS unsigned char* lds, const Gemm g, const Sched& S, const Epi& E) {
;     ...
;             PG8_WAIT_V(8); PG8_WAIT_L(0); PG8_BAR; PG8_MMA(0, 0, At, B0); PG8_MMA(0, 1, At, B1); PG8_BAR; PG8_SCHED;
;             PG8_LDA(At, 1, 1); PG8_STAGE(PG8_SB(1, 0), b3, voffB); PG8_STAGE(PG8_SB(1, 1), b3 + hstepB, voffB); PG8_STAGE(PG8_SA(1, 0), a3, voffA);
;             PG8_WAIT_V(8); PG8_WAIT_L(0); PG8_BAR; PG8_MMA(1, 0, At, B0); PG8_MMA(1, 1, At, B1); PG8_BAR; PG8_SCHED;
;             } else {
;             PG8_LDB(B0, 0, 0); PG8_SCHED; PG8_LDA(At, 0, 0); PG8_STAGE(PG8_SA(1, 1), a1 + hstepA, voffA);
;             PG8_WAIT_L(8); PG8_BAR; PG8_WAIT_L(0); PG8_MMA(0, 0, At, B0); PG8_BAR; PG8_SCHED;
;             PG8_LDB(B1, 0, 1); PG8_STAGE(PG8_SB(0, 0), b2, voffB);
;             PG8_BAR; PG8_WAIT_L(0); PG8_MMA(0, 1, At, B1); PG8_BAR;
;             PG8_LDA(At, 0, 1); PG8_STAGE(PG8_SA(0, 0), a2, voffA);
;             PG8_BAR; PG8_WAIT_L(0); PG8_MMA(1, 0, At, B0); PG8_BAR; PG8_SCHED;
;             PG8_STAGE(PG8_SB(0, 1), b2 + hstepB, voffB);
;             PG8_WAIT_V(6); PG8_BAR; PG8_MMA(1, 1, At, B1); PG8_BAR;
;             PG8_LDB(B0, 1, 0); PG8_SCHED; PG8_LDA(At, 1, 0); PG8_STAGE(PG8_SA(0, 1), a2 + hstepA, voffA);
;             PG8_WAIT_L(8); PG8_BAR; PG8_WAIT_L(0); PG8_MMA(0, 0, At, B0); PG8_BAR; PG8_SCHED;
;             PG8_LDB(B1, 1, 1); PG8_STAGE(PG8_SB(1, 0), b3, voffB);
;             PG8_BAR; PG8_WAIT_L(0); PG8_MMA(0, 1, At, B1); PG8_BAR;
;             PG8_LDA(At, 1, 1); PG8_STAGE(PG8_SA(1, 0), a3, voffA);
;             PG8_BAR; PG8_WAIT_L(0); PG8_MMA(1, 0, At, B0); PG8_BAR; PG8_SCHED;
;             PG8_STAGE(PG8_SB(1, 1), b3 + hstepB, voffB);
;             PG8_WAIT_V(6); PG8_BAR; PG8_MMA(1, 1, At, B1); PG8_BAR;
;             }
;         }
;         if constexpr (ALIGN_EPI) { if (wr == 0) PG8_BAR; }
	s_setprio 1
	s_waitcnt lgkmcnt(0)
	v_mfma_f32_16x16x32_bf16 v[30:33], v[130:133], v[162:165], v[30:33]
	v_mfma_f32_16x16x32_bf16 v[22:25], v[138:141], v[162:165], v[22:25]
	v_mfma_f32_16x16x32_bf16 v[18:21], v[130:133], v[170:173], v[18:21]
	v_mfma_f32_16x16x32_bf16 v[10:13], v[138:141], v[170:173], v[10:13]
	v_mfma_f32_16x16x32_bf16 v[50:53], v[130:133], v[198:201], v[50:53]
	v_mfma_f32_16x16x32_bf16 v[54:57], v[138:141], v[198:201], v[54:57]
	v_mfma_f32_16x16x32_bf16 v[74:77], v[130:133], v[212:215], v[74:77]
	v_mfma_f32_16x16x32_bf16 v[78:81], v[138:141], v[212:215], v[78:81]
	v_mfma_f32_16x16x32_bf16 v[30:33], v[134:137], v[166:169], v[30:33]
	v_mfma_f32_16x16x32_bf16 v[22:25], v[142:145], v[166:169], v[22:25]
	v_mfma_f32_16x16x32_bf16 v[18:21], v[134:137], v[174:177], v[18:21]
	v_mfma_f32_16x16x32_bf16 v[10:13], v[142:145], v[174:177], v[10:13]
	v_mfma_f32_16x16x32_bf16 v[50:53], v[134:137], v[208:211], v[50:53]
	v_mfma_f32_16x16x32_bf16 v[54:57], v[142:145], v[208:211], v[54:57]
	v_mfma_f32_16x16x32_bf16 v[74:77], v[134:137], v[216:219], v[74:77]
	v_mfma_f32_16x16x32_bf16 v[78:81], v[142:145], v[216:219], v[78:81]
	s_setprio 0
	s_setprio 1
	v_mfma_f32_16x16x32_bf16 v[26:29], v[146:149], v[162:165], v[26:29]
	v_mfma_f32_16x16x32_bf16 v[14:17], v[154:157], v[162:165], v[14:17]
	v_mfma_f32_16x16x32_bf16 v[42:45], v[146:149], v[170:173], v[42:45]
	v_mfma_f32_16x16x32_bf16 v[46:49], v[154:157], v[170:173], v[46:49]
	v_mfma_f32_16x16x32_bf16 v[66:69], v[146:149], v[198:201], v[66:69]
	v_mfma_f32_16x16x32_bf16 v[70:73], v[154:157], v[198:201], v[70:73]
	v_mfma_f32_16x16x32_bf16 v[82:85], v[146:149], v[212:215], v[82:85]
	v_mfma_f32_16x16x32_bf16 v[86:89], v[154:157], v[212:215], v[86:89]
	v_mfma_f32_16x16x32_bf16 v[26:29], v[150:153], v[166:169], v[26:29]
	v_mfma_f32_16x16x32_bf16 v[14:17], v[158:161], v[166:169], v[14:17]
	v_mfma_f32_16x16x32_bf16 v[42:45], v[150:153], v[174:177], v[42:45]
	v_mfma_f32_16x16x32_bf16 v[46:49], v[158:161], v[174:177], v[46:49]
	v_mfma_f32_16x16x32_bf16 v[66:69], v[150:153], v[208:211], v[66:69]
	v_mfma_f32_16x16x32_bf16 v[70:73], v[158:161], v[208:211], v[70:73]
	v_mfma_f32_16x16x32_bf16 v[82:85], v[150:153], v[216:219], v[82:85]
	v_mfma_f32_16x16x32_bf16 v[86:89], v[158:161], v[216:219], v[86:89]
	s_setprio 0
	s_barrier
	s_add_u32 s40, s36, 0x8000
	s_addc_u32 s41, s37, 0
	s_add_i32 s44, s44, s65
	v_lshl_add_u64 v[188:189], s[40:41], 0, v[186:187]
	s_mov_b32 m0, s44
	ds_read_b128 v[162:165], v207 offset:49152
	ds_read_b128 v[166:169], v207 offset:50176
	ds_read_b128 v[170:173], v207 offset:51200
	ds_read_b128 v[174:177], v207 offset:52224
	ds_read_b128 v[198:201], v207 offset:53248
	ds_read_b128 v[208:211], v207 offset:54272
	ds_read_b128 v[212:215], v207 offset:55296
	ds_read_b128 v[216:219], v207 offset:56320
	global_load_lds_dwordx4 v[188:189], off
	s_add_i32 m0, s44, 0x2000
	s_add_u32 s36, s36, 0xc000
	v_lshl_add_u64 v[188:189], s[40:41], 0, v[182:183]
	s_addc_u32 s37, s37, 0
	s_add_i32 s40, s45, s65
	global_load_lds_dwordx4 v[188:189], off
	v_lshl_add_u64 v[188:189], s[36:37], 0, v[186:187]
	s_mov_b32 m0, s40
	s_nop 0
	global_load_lds_dwordx4 v[188:189], off
	v_lshl_add_u64 v[188:189], s[36:37], 0, v[182:183]
	s_add_i32 m0, s40, 0x2000
	s_nop 0
	global_load_lds_dwordx4 v[188:189], off
	v_lshl_add_u64 v[188:189], s[8:9], 0, v[178:179]
	s_mov_b32 m0, s24
	s_nop 0
	global_load_lds_dwordx4 v[188:189], off
	v_lshl_add_u64 v[188:189], s[8:9], 0, v[180:181]
	s_mov_b32 m0, s25
	s_nop 0
	global_load_lds_dwordx4 v[188:189], off
	s_waitcnt vmcnt(8)
	s_waitcnt lgkmcnt(0)
	s_barrier
	s_setprio 1
	s_waitcnt lgkmcnt(0)
	v_mfma_f32_16x16x32_bf16 v[106:109], v[130:133], v[162:165], v[106:109]
	v_mfma_f32_16x16x32_bf16 v[110:113], v[138:141], v[162:165], v[110:113]
	v_mfma_f32_16x16x32_bf16 v[122:125], v[130:133], v[170:173], v[122:125]
	v_mfma_f32_16x16x32_bf16 v[126:129], v[138:141], v[170:173], v[126:129]
	v_mfma_f32_16x16x32_bf16 v[94:97], v[130:133], v[198:201], v[94:97]
	v_mfma_f32_16x16x32_bf16 v[90:93], v[138:141], v[198:201], v[90:93]
	v_mfma_f32_16x16x32_bf16 v[38:41], v[130:133], v[212:215], v[38:41]
	v_mfma_f32_16x16x32_bf16 v[34:37], v[138:141], v[212:215], v[34:37]
	v_mfma_f32_16x16x32_bf16 v[106:109], v[134:137], v[166:169], v[106:109]
	v_mfma_f32_16x16x32_bf16 v[110:113], v[142:145], v[166:169], v[110:113]
	v_mfma_f32_16x16x32_bf16 v[122:125], v[134:137], v[174:177], v[122:125]
	v_mfma_f32_16x16x32_bf16 v[126:129], v[142:145], v[174:177], v[126:129]
	v_mfma_f32_16x16x32_bf16 v[94:97], v[134:137], v[208:211], v[94:97]
	v_mfma_f32_16x16x32_bf16 v[90:93], v[142:145], v[208:211], v[90:93]
	v_mfma_f32_16x16x32_bf16 v[38:41], v[134:137], v[216:219], v[38:41]
	v_mfma_f32_16x16x32_bf16 v[34:37], v[142:145], v[216:219], v[34:37]
	s_setprio 0
	s_setprio 1
	v_mfma_f32_16x16x32_bf16 v[114:117], v[146:149], v[162:165], v[114:117]
	v_mfma_f32_16x16x32_bf16 v[118:121], v[154:157], v[162:165], v[118:121]
	v_mfma_f32_16x16x32_bf16 v[102:105], v[146:149], v[170:173], v[102:105]
	v_mfma_f32_16x16x32_bf16 v[98:101], v[154:157], v[170:173], v[98:101]
	v_mfma_f32_16x16x32_bf16 v[62:65], v[146:149], v[198:201], v[62:65]
	v_mfma_f32_16x16x32_bf16 v[58:61], v[154:157], v[198:201], v[58:61]
	v_mfma_f32_16x16x32_bf16 v[6:9], v[146:149], v[212:215], v[6:9]
	v_mfma_f32_16x16x32_bf16 v[2:5], v[154:157], v[212:215], v[2:5]
	v_mfma_f32_16x16x32_bf16 v[114:117], v[150:153], v[166:169], v[114:117]
	v_mfma_f32_16x16x32_bf16 v[118:121], v[158:161], v[166:169], v[118:121]
	v_mfma_f32_16x16x32_bf16 v[102:105], v[150:153], v[174:177], v[102:105]
	v_mfma_f32_16x16x32_bf16 v[98:101], v[158:161], v[174:177], v[98:101]
	v_mfma_f32_16x16x32_bf16 v[62:65], v[150:153], v[208:211], v[62:65]
	v_mfma_f32_16x16x32_bf16 v[58:61], v[158:161], v[208:211], v[58:61]
	v_mfma_f32_16x16x32_bf16 v[6:9], v[150:153], v[216:219], v[6:9]
	v_mfma_f32_16x16x32_bf16 v[2:5], v[158:161], v[216:219], v[2:5]
	s_setprio 0
	s_barrier
	s_add_i32 s35, s35, 2
	s_add_u32 s0, s0, 0x10000
	s_addc_u32 s1, s1, 0
	s_add_u32 s31, s31, 0x10000
	s_addc_u32 s33, s33, 0
	s_cmpk_gt_u32 s35, 0x55
	s_cbranch_scc0 .LBB0_1483
	s_and_b64 vcc, exec, s[20:21]
	s_cbranch_vccz .LBB0_1486
	s_barrier
